# GEMM main loops: per-MFMA-group s_setprio 1/0 toggles removed (544 scalar instructions)
# speedup vs baseline: 1.0031x; 1.0031x over previous
.Lg1x_join:
	s_waitcnt lgkmcnt(0)
	s_barrier
	global_load_dwordx4 v[120:123], v[106:107], off offset:256
	global_load_dwordx4 v[136:139], v[108:109], off offset:256
	global_load_dwordx4 v[140:143], v[102:103], off offset:256
	global_load_dwordx4 v[144:147], v[104:105], off offset:256
	global_load_dwordx4 v[148:151], v[110:111], off offset:256
	global_load_dwordx4 v[152:155], v[112:113], off offset:256
	global_load_dwordx4 v[156:159], v[116:117], off offset:256
	v_and_b32_e32 v3, 31, v58
	v_lshrrev_b32_e32 v2, 1, v58
	v_and_or_b32 v4, v2, s3, v3
	v_bfe_i32 v5, v58, 6, 1
	s_movk_i32 s3, 0x60
	v_and_b32_e32 v2, 16, v2
	v_and_or_b32 v3, v5, s3, v3
	v_mad_u32_u24 v115, v3, s50, v2
	v_add_u32_e32 v98, 0x12000, v115
	s_waitcnt vmcnt(13)
	ds_write_b128 v119, v[30:33]
	s_waitcnt vmcnt(12)
	ds_write_b128 v119, v[34:37] offset:9216
	s_waitcnt vmcnt(11)
	ds_write_b128 v119, v[38:41] offset:18432
	s_waitcnt vmcnt(10)
	ds_write_b128 v119, v[42:45] offset:27648
	s_waitcnt vmcnt(9)
	ds_write_b128 v119, v[46:49] offset:36864
	s_waitcnt vmcnt(8)
	ds_write_b128 v119, v[50:53] offset:46080
	s_waitcnt vmcnt(7)
	ds_write_b128 v119, v[54:57] offset:55296
	v_mad_u64_u32 v[100:101], s[10:11], v4, s50, v[2:3]
	ds_read_b128 v[18:21], v115 offset:36864
	ds_read_b128 v[162:165], v115 offset:36896
	ds_read_b128 v[22:25], v115 offset:41472
	ds_read_b128 v[166:169], v115 offset:41504
	ds_read_b128 v[26:29], v115 offset:46080
	ds_read_b128 v[170:173], v115 offset:46112
	ds_read_b128 v[2:5], v100
	ds_read_b128 v[174:177], v100 offset:32
	ds_read_b128 v[30:33], v100 offset:4608
	ds_read_b128 v[178:181], v100 offset:4640
	s_waitcnt lgkmcnt(3)
	v_mfma_f32_32x32x16_bf16 v[82:97], v[2:5], v[18:21], 0
	v_mfma_f32_32x32x16_bf16 v[50:65], v[2:5], v[22:25], 0
	v_mfma_f32_32x32x16_bf16 v[2:17], v[2:5], v[26:29], 0
	s_waitcnt lgkmcnt(1)
	v_mfma_f32_32x32x16_bf16 v[66:81], v[30:33], v[18:21], 0
	v_mfma_f32_32x32x16_bf16 v[34:49], v[30:33], v[22:25], 0
	v_mfma_f32_32x32x16_bf16 v[18:33], v[30:33], v[26:29], 0
	ds_read_b128 v[182:185], v115 offset:36928
	ds_read_b128 v[186:189], v115 offset:41536
	ds_read_b128 v[190:193], v115 offset:46144
	ds_read_b128 v[194:197], v100 offset:64
	ds_read_b128 v[198:201], v100 offset:4672
	v_mfma_f32_32x32x16_bf16 v[82:97], v[174:177], v[162:165], v[82:97]
	v_mfma_f32_32x32x16_bf16 v[50:65], v[174:177], v[166:169], v[50:65]
	v_mfma_f32_32x32x16_bf16 v[2:17], v[174:177], v[170:173], v[2:17]
	s_waitcnt lgkmcnt(5)
	v_mfma_f32_32x32x16_bf16 v[66:81], v[178:181], v[162:165], v[66:81]
	v_mfma_f32_32x32x16_bf16 v[34:49], v[178:181], v[166:169], v[34:49]
	v_mfma_f32_32x32x16_bf16 v[18:33], v[178:181], v[170:173], v[18:33]
	ds_read_b128 v[162:165], v115 offset:36960
	ds_read_b128 v[166:169], v115 offset:41568
	ds_read_b128 v[170:173], v115 offset:46176
	ds_read_b128 v[174:177], v100 offset:96
	ds_read_b128 v[178:181], v100 offset:4704
	s_waitcnt lgkmcnt(6)
	v_mfma_f32_32x32x16_bf16 v[82:97], v[194:197], v[182:185], v[82:97]
	v_mfma_f32_32x32x16_bf16 v[50:65], v[194:197], v[186:189], v[50:65]
	v_mfma_f32_32x32x16_bf16 v[2:17], v[194:197], v[190:193], v[2:17]
	s_waitcnt lgkmcnt(5)
	v_mfma_f32_32x32x16_bf16 v[66:81], v[198:201], v[182:185], v[66:81]
	v_mfma_f32_32x32x16_bf16 v[34:49], v[198:201], v[186:189], v[34:49]
	v_mfma_f32_32x32x16_bf16 v[18:33], v[198:201], v[190:193], v[18:33]
	s_waitcnt lgkmcnt(1)
	v_mfma_f32_32x32x16_bf16 v[82:97], v[174:177], v[162:165], v[82:97]
	v_mfma_f32_32x32x16_bf16 v[50:65], v[174:177], v[166:169], v[50:65]
	v_mfma_f32_32x32x16_bf16 v[2:17], v[174:177], v[170:173], v[2:17]
	s_waitcnt lgkmcnt(0)
	v_mfma_f32_32x32x16_bf16 v[66:81], v[178:181], v[162:165], v[66:81]
	v_mfma_f32_32x32x16_bf16 v[34:49], v[178:181], v[166:169], v[34:49]
	v_mfma_f32_32x32x16_bf16 v[18:33], v[178:181], v[170:173], v[18:33]
	s_barrier
	global_load_dwordx4 v[162:165], v[106:107], off offset:384
	global_load_dwordx4 v[166:169], v[108:109], off offset:384
	global_load_dwordx4 v[170:173], v[102:103], off offset:384
	global_load_dwordx4 v[174:177], v[104:105], off offset:384
	global_load_dwordx4 v[178:181], v[110:111], off offset:384
	global_load_dwordx4 v[182:185], v[112:113], off offset:384
	global_load_dwordx4 v[186:189], v[116:117], off offset:384
	s_waitcnt vmcnt(11)
	ds_write_b128 v114, v[140:143]
	ds_write_b128 v114, v[120:123] offset:9216
	ds_write_b128 v114, v[136:139] offset:18432
	s_waitcnt vmcnt(9)
	ds_write_b128 v114, v[148:151] offset:27648
	ds_write_b128 v114, v[144:147] offset:36864
	s_waitcnt vmcnt(8)
	ds_write_b128 v114, v[152:155] offset:46080
	s_waitcnt vmcnt(7)
	ds_write_b128 v114, v[156:159] offset:55296
	v_add_u32_e32 v101, 0x12000, v100
	ds_read_b128 v[120:123], v98 offset:36864
	ds_read_b128 v[136:139], v98 offset:36896
	ds_read_b128 v[140:143], v98 offset:41472
	ds_read_b128 v[144:147], v98 offset:41504
	ds_read_b128 v[148:151], v98 offset:46080
	ds_read_b128 v[152:155], v98 offset:46112
	ds_read_b128 v[156:159], v101
	ds_read_b128 v[190:193], v101 offset:32
	ds_read_b128 v[194:197], v101 offset:4608
	ds_read_b128 v[198:201], v101 offset:4640
	s_waitcnt lgkmcnt(3)
	v_mfma_f32_32x32x16_bf16 v[82:97], v[156:159], v[120:123], v[82:97]
	v_mfma_f32_32x32x16_bf16 v[50:65], v[156:159], v[140:143], v[50:65]
	v_mfma_f32_32x32x16_bf16 v[2:17], v[156:159], v[148:151], v[2:17]
	s_waitcnt lgkmcnt(1)
	v_mfma_f32_32x32x16_bf16 v[66:81], v[194:197], v[120:123], v[66:81]
	v_mfma_f32_32x32x16_bf16 v[34:49], v[194:197], v[140:143], v[34:49]
	v_mfma_f32_32x32x16_bf16 v[18:33], v[194:197], v[148:151], v[18:33]
	ds_read_b128 v[120:123], v98 offset:36928
	ds_read_b128 v[140:143], v98 offset:41536
	ds_read_b128 v[148:151], v98 offset:46144
	ds_read_b128 v[156:159], v101 offset:64
	ds_read_b128 v[194:197], v101 offset:4672
	v_mfma_f32_32x32x16_bf16 v[82:97], v[190:193], v[136:139], v[82:97]
	v_mfma_f32_32x32x16_bf16 v[50:65], v[190:193], v[144:147], v[50:65]
	v_mfma_f32_32x32x16_bf16 v[2:17], v[190:193], v[152:155], v[2:17]
	s_waitcnt lgkmcnt(5)
	v_mfma_f32_32x32x16_bf16 v[66:81], v[198:201], v[136:139], v[66:81]
	v_mfma_f32_32x32x16_bf16 v[34:49], v[198:201], v[144:147], v[34:49]
	v_mfma_f32_32x32x16_bf16 v[18:33], v[198:201], v[152:155], v[18:33]
	ds_read_b128 v[136:139], v98 offset:36960
	ds_read_b128 v[144:147], v98 offset:41568
	ds_read_b128 v[152:155], v98 offset:46176
	ds_read_b128 v[190:193], v101 offset:96
	ds_read_b128 v[198:201], v101 offset:4704
	s_waitcnt lgkmcnt(6)
	v_mfma_f32_32x32x16_bf16 v[82:97], v[156:159], v[120:123], v[82:97]
	v_mfma_f32_32x32x16_bf16 v[50:65], v[156:159], v[140:143], v[50:65]
	v_mfma_f32_32x32x16_bf16 v[2:17], v[156:159], v[148:151], v[2:17]
	s_waitcnt lgkmcnt(5)
	v_mfma_f32_32x32x16_bf16 v[66:81], v[194:197], v[120:123], v[66:81]
	v_mfma_f32_32x32x16_bf16 v[34:49], v[194:197], v[140:143], v[34:49]
	v_mfma_f32_32x32x16_bf16 v[18:33], v[194:197], v[148:151], v[18:33]
	s_waitcnt lgkmcnt(1)
	v_mfma_f32_32x32x16_bf16 v[82:97], v[190:193], v[136:139], v[82:97]
	v_mfma_f32_32x32x16_bf16 v[50:65], v[190:193], v[144:147], v[50:65]
	v_mfma_f32_32x32x16_bf16 v[2:17], v[190:193], v[152:155], v[2:17]
	s_waitcnt lgkmcnt(0)
	v_mfma_f32_32x32x16_bf16 v[66:81], v[198:201], v[136:139], v[66:81]
	v_mfma_f32_32x32x16_bf16 v[34:49], v[198:201], v[144:147], v[34:49]
	v_mfma_f32_32x32x16_bf16 v[18:33], v[198:201], v[152:155], v[18:33]
	s_barrier
	global_load_dwordx4 v[120:123], v[106:107], off offset:512
	global_load_dwordx4 v[136:139], v[108:109], off offset:512
	global_load_dwordx4 v[140:143], v[102:103], off offset:512
	global_load_dwordx4 v[144:147], v[104:105], off offset:512
	global_load_dwordx4 v[148:151], v[110:111], off offset:512
	global_load_dwordx4 v[152:155], v[112:113], off offset:512
	global_load_dwordx4 v[156:159], v[116:117], off offset:512
	s_waitcnt vmcnt(11)
	ds_write_b128 v119, v[170:173]
	ds_write_b128 v119, v[162:165] offset:9216
	ds_write_b128 v119, v[166:169] offset:18432
	s_waitcnt vmcnt(9)
	ds_write_b128 v119, v[178:181] offset:27648
	ds_write_b128 v119, v[174:177] offset:36864
	s_waitcnt vmcnt(8)
	ds_write_b128 v119, v[182:185] offset:46080
	s_waitcnt vmcnt(7)
	ds_write_b128 v119, v[186:189] offset:55296
	ds_read_b128 v[162:165], v115 offset:36864
	ds_read_b128 v[166:169], v115 offset:36896
	ds_read_b128 v[170:173], v115 offset:41472
	ds_read_b128 v[174:177], v115 offset:41504
	ds_read_b128 v[178:181], v115 offset:46080
	ds_read_b128 v[182:185], v115 offset:46112
	ds_read_b128 v[186:189], v100
	ds_read_b128 v[190:193], v100 offset:32
	ds_read_b128 v[194:197], v100 offset:4608
	ds_read_b128 v[198:201], v100 offset:4640
	s_waitcnt lgkmcnt(3)
	v_mfma_f32_32x32x16_bf16 v[82:97], v[186:189], v[162:165], v[82:97]
	v_mfma_f32_32x32x16_bf16 v[50:65], v[186:189], v[170:173], v[50:65]
	v_mfma_f32_32x32x16_bf16 v[2:17], v[186:189], v[178:181], v[2:17]
	s_waitcnt lgkmcnt(1)
	v_mfma_f32_32x32x16_bf16 v[66:81], v[194:197], v[162:165], v[66:81]
	v_mfma_f32_32x32x16_bf16 v[34:49], v[194:197], v[170:173], v[34:49]
	v_mfma_f32_32x32x16_bf16 v[18:33], v[194:197], v[178:181], v[18:33]
	ds_read_b128 v[162:165], v115 offset:36928
	ds_read_b128 v[170:173], v115 offset:41536
	ds_read_b128 v[178:181], v115 offset:46144
	ds_read_b128 v[186:189], v100 offset:64
	ds_read_b128 v[194:197], v100 offset:4672
	v_mfma_f32_32x32x16_bf16 v[82:97], v[190:193], v[166:169], v[82:97]
	v_mfma_f32_32x32x16_bf16 v[50:65], v[190:193], v[174:177], v[50:65]
	v_mfma_f32_32x32x16_bf16 v[2:17], v[190:193], v[182:185], v[2:17]
	s_waitcnt lgkmcnt(5)
	v_mfma_f32_32x32x16_bf16 v[66:81], v[198:201], v[166:169], v[66:81]
	v_mfma_f32_32x32x16_bf16 v[34:49], v[198:201], v[174:177], v[34:49]
	v_mfma_f32_32x32x16_bf16 v[18:33], v[198:201], v[182:185], v[18:33]
	ds_read_b128 v[166:169], v115 offset:36960
	ds_read_b128 v[174:177], v115 offset:41568
	ds_read_b128 v[182:185], v115 offset:46176
	ds_read_b128 v[190:193], v100 offset:96
	ds_read_b128 v[198:201], v100 offset:4704
	s_waitcnt lgkmcnt(6)
	v_mfma_f32_32x32x16_bf16 v[82:97], v[186:189], v[162:165], v[82:97]
	v_mfma_f32_32x32x16_bf16 v[50:65], v[186:189], v[170:173], v[50:65]
	v_mfma_f32_32x32x16_bf16 v[2:17], v[186:189], v[178:181], v[2:17]
	s_waitcnt lgkmcnt(5)
	v_mfma_f32_32x32x16_bf16 v[66:81], v[194:197], v[162:165], v[66:81]
	v_mfma_f32_32x32x16_bf16 v[34:49], v[194:197], v[170:173], v[34:49]
	v_mfma_f32_32x32x16_bf16 v[18:33], v[194:197], v[178:181], v[18:33]
	s_waitcnt lgkmcnt(1)
	v_mfma_f32_32x32x16_bf16 v[82:97], v[190:193], v[166:169], v[82:97]
	v_mfma_f32_32x32x16_bf16 v[50:65], v[190:193], v[174:177], v[50:65]
	v_mfma_f32_32x32x16_bf16 v[2:17], v[190:193], v[182:185], v[2:17]
	s_waitcnt lgkmcnt(0)
	v_mfma_f32_32x32x16_bf16 v[66:81], v[198:201], v[166:169], v[66:81]
	v_mfma_f32_32x32x16_bf16 v[34:49], v[198:201], v[174:177], v[34:49]
	v_mfma_f32_32x32x16_bf16 v[18:33], v[198:201], v[182:185], v[18:33]
	s_barrier
	global_load_dwordx4 v[162:165], v[106:107], off offset:640
	global_load_dwordx4 v[166:169], v[108:109], off offset:640
	global_load_dwordx4 v[170:173], v[102:103], off offset:640
	global_load_dwordx4 v[174:177], v[104:105], off offset:640
	global_load_dwordx4 v[178:181], v[110:111], off offset:640
	global_load_dwordx4 v[182:185], v[112:113], off offset:640
	global_load_dwordx4 v[186:189], v[116:117], off offset:640
	s_waitcnt vmcnt(11)
	ds_write_b128 v114, v[140:143]
	ds_write_b128 v114, v[120:123] offset:9216
	ds_write_b128 v114, v[136:139] offset:18432
	s_waitcnt vmcnt(9)
	ds_write_b128 v114, v[148:151] offset:27648
	ds_write_b128 v114, v[144:147] offset:36864
	s_waitcnt vmcnt(8)
	ds_write_b128 v114, v[152:155] offset:46080
	s_waitcnt vmcnt(7)
	ds_write_b128 v114, v[156:159] offset:55296
	ds_read_b128 v[120:123], v98 offset:36864
	ds_read_b128 v[136:139], v98 offset:36896
	ds_read_b128 v[140:143], v98 offset:41472
	ds_read_b128 v[144:147], v98 offset:41504
	ds_read_b128 v[148:151], v98 offset:46080
	ds_read_b128 v[152:155], v98 offset:46112
	ds_read_b128 v[156:159], v101
	ds_read_b128 v[190:193], v101 offset:32
	ds_read_b128 v[194:197], v101 offset:4608
	ds_read_b128 v[198:201], v101 offset:4640
	s_waitcnt lgkmcnt(3)
	v_mfma_f32_32x32x16_bf16 v[82:97], v[156:159], v[120:123], v[82:97]
	v_mfma_f32_32x32x16_bf16 v[50:65], v[156:159], v[140:143], v[50:65]
	v_mfma_f32_32x32x16_bf16 v[2:17], v[156:159], v[148:151], v[2:17]
	s_waitcnt lgkmcnt(1)
	v_mfma_f32_32x32x16_bf16 v[66:81], v[194:197], v[120:123], v[66:81]
	v_mfma_f32_32x32x16_bf16 v[34:49], v[194:197], v[140:143], v[34:49]
	v_mfma_f32_32x32x16_bf16 v[18:33], v[194:197], v[148:151], v[18:33]
	ds_read_b128 v[120:123], v98 offset:36928
	ds_read_b128 v[140:143], v98 offset:41536
	ds_read_b128 v[148:151], v98 offset:46144
	ds_read_b128 v[156:159], v101 offset:64
	ds_read_b128 v[194:197], v101 offset:4672
	v_mfma_f32_32x32x16_bf16 v[82:97], v[190:193], v[136:139], v[82:97]
	v_mfma_f32_32x32x16_bf16 v[50:65], v[190:193], v[144:147], v[50:65]
	v_mfma_f32_32x32x16_bf16 v[2:17], v[190:193], v[152:155], v[2:17]
	s_waitcnt lgkmcnt(5)
	v_mfma_f32_32x32x16_bf16 v[66:81], v[198:201], v[136:139], v[66:81]
	v_mfma_f32_32x32x16_bf16 v[34:49], v[198:201], v[144:147], v[34:49]
	v_mfma_f32_32x32x16_bf16 v[18:33], v[198:201], v[152:155], v[18:33]
	ds_read_b128 v[136:139], v98 offset:36960
	ds_read_b128 v[144:147], v98 offset:41568
	ds_read_b128 v[152:155], v98 offset:46176
	ds_read_b128 v[190:193], v101 offset:96
	ds_read_b128 v[198:201], v101 offset:4704
	s_waitcnt lgkmcnt(6)
	v_mfma_f32_32x32x16_bf16 v[82:97], v[156:159], v[120:123], v[82:97]
	v_mfma_f32_32x32x16_bf16 v[50:65], v[156:159], v[140:143], v[50:65]
	v_mfma_f32_32x32x16_bf16 v[2:17], v[156:159], v[148:151], v[2:17]
	s_waitcnt lgkmcnt(5)
	v_mfma_f32_32x32x16_bf16 v[66:81], v[194:197], v[120:123], v[66:81]
	v_mfma_f32_32x32x16_bf16 v[34:49], v[194:197], v[140:143], v[34:49]
	v_mfma_f32_32x32x16_bf16 v[18:33], v[194:197], v[148:151], v[18:33]
	s_waitcnt lgkmcnt(1)
	v_mfma_f32_32x32x16_bf16 v[82:97], v[190:193], v[136:139], v[82:97]
	v_mfma_f32_32x32x16_bf16 v[50:65], v[190:193], v[144:147], v[50:65]
	v_mfma_f32_32x32x16_bf16 v[2:17], v[190:193], v[152:155], v[2:17]
	s_waitcnt lgkmcnt(0)
	v_mfma_f32_32x32x16_bf16 v[66:81], v[198:201], v[136:139], v[66:81]
	v_mfma_f32_32x32x16_bf16 v[34:49], v[198:201], v[144:147], v[34:49]
	v_mfma_f32_32x32x16_bf16 v[18:33], v[198:201], v[152:155], v[18:33]
	s_barrier
	global_load_dwordx4 v[120:123], v[106:107], off offset:768
	global_load_dwordx4 v[136:139], v[108:109], off offset:768
	global_load_dwordx4 v[140:143], v[102:103], off offset:768
	global_load_dwordx4 v[144:147], v[104:105], off offset:768
	global_load_dwordx4 v[148:151], v[110:111], off offset:768
	global_load_dwordx4 v[152:155], v[112:113], off offset:768
	global_load_dwordx4 v[156:159], v[116:117], off offset:768
	s_waitcnt vmcnt(11)
	ds_write_b128 v119, v[170:173]
	ds_write_b128 v119, v[162:165] offset:9216
	ds_write_b128 v119, v[166:169] offset:18432
	s_waitcnt vmcnt(9)
	ds_write_b128 v119, v[178:181] offset:27648
	ds_write_b128 v119, v[174:177] offset:36864
	s_waitcnt vmcnt(8)
	ds_write_b128 v119, v[182:185] offset:46080
	s_waitcnt vmcnt(7)
	ds_write_b128 v119, v[186:189] offset:55296
	ds_read_b128 v[162:165], v115 offset:36864
	ds_read_b128 v[166:169], v115 offset:36896
	ds_read_b128 v[170:173], v115 offset:41472
	ds_read_b128 v[174:177], v115 offset:41504
	ds_read_b128 v[178:181], v115 offset:46080
	ds_read_b128 v[182:185], v115 offset:46112
	ds_read_b128 v[186:189], v100
	ds_read_b128 v[190:193], v100 offset:32
	ds_read_b128 v[194:197], v100 offset:4608
	ds_read_b128 v[198:201], v100 offset:4640
	s_waitcnt lgkmcnt(3)
	v_mfma_f32_32x32x16_bf16 v[82:97], v[186:189], v[162:165], v[82:97]
	v_mfma_f32_32x32x16_bf16 v[50:65], v[186:189], v[170:173], v[50:65]
	v_mfma_f32_32x32x16_bf16 v[2:17], v[186:189], v[178:181], v[2:17]
	s_waitcnt lgkmcnt(1)
	v_mfma_f32_32x32x16_bf16 v[66:81], v[194:197], v[162:165], v[66:81]
	v_mfma_f32_32x32x16_bf16 v[34:49], v[194:197], v[170:173], v[34:49]
	v_mfma_f32_32x32x16_bf16 v[18:33], v[194:197], v[178:181], v[18:33]
	ds_read_b128 v[162:165], v115 offset:36928
	ds_read_b128 v[170:173], v115 offset:41536
	ds_read_b128 v[178:181], v115 offset:46144
	ds_read_b128 v[186:189], v100 offset:64
	ds_read_b128 v[194:197], v100 offset:4672
	v_mfma_f32_32x32x16_bf16 v[82:97], v[190:193], v[166:169], v[82:97]
	v_mfma_f32_32x32x16_bf16 v[50:65], v[190:193], v[174:177], v[50:65]
	v_mfma_f32_32x32x16_bf16 v[2:17], v[190:193], v[182:185], v[2:17]
	s_waitcnt lgkmcnt(5)
	v_mfma_f32_32x32x16_bf16 v[66:81], v[198:201], v[166:169], v[66:81]
	v_mfma_f32_32x32x16_bf16 v[34:49], v[198:201], v[174:177], v[34:49]
	v_mfma_f32_32x32x16_bf16 v[18:33], v[198:201], v[182:185], v[18:33]
	ds_read_b128 v[166:169], v115 offset:36960
	ds_read_b128 v[174:177], v115 offset:41568
	ds_read_b128 v[182:185], v115 offset:46176
	ds_read_b128 v[190:193], v100 offset:96
	ds_read_b128 v[198:201], v100 offset:4704
	s_waitcnt lgkmcnt(6)
	v_mfma_f32_32x32x16_bf16 v[82:97], v[186:189], v[162:165], v[82:97]
	v_mfma_f32_32x32x16_bf16 v[50:65], v[186:189], v[170:173], v[50:65]
	v_mfma_f32_32x32x16_bf16 v[2:17], v[186:189], v[178:181], v[2:17]
	s_waitcnt lgkmcnt(5)
	v_mfma_f32_32x32x16_bf16 v[66:81], v[194:197], v[162:165], v[66:81]
	v_mfma_f32_32x32x16_bf16 v[34:49], v[194:197], v[170:173], v[34:49]
	v_mfma_f32_32x32x16_bf16 v[18:33], v[194:197], v[178:181], v[18:33]
	s_waitcnt lgkmcnt(1)
	v_mfma_f32_32x32x16_bf16 v[82:97], v[190:193], v[166:169], v[82:97]
	v_mfma_f32_32x32x16_bf16 v[50:65], v[190:193], v[174:177], v[50:65]
	v_mfma_f32_32x32x16_bf16 v[2:17], v[190:193], v[182:185], v[2:17]
	s_waitcnt lgkmcnt(0)
	v_mfma_f32_32x32x16_bf16 v[66:81], v[198:201], v[166:169], v[66:81]
	v_mfma_f32_32x32x16_bf16 v[34:49], v[198:201], v[174:177], v[34:49]
	v_mfma_f32_32x32x16_bf16 v[18:33], v[198:201], v[182:185], v[18:33]
	s_barrier
	global_load_dwordx4 v[162:165], v[106:107], off offset:896
	global_load_dwordx4 v[166:169], v[108:109], off offset:896
	global_load_dwordx4 v[170:173], v[102:103], off offset:896
	global_load_dwordx4 v[174:177], v[104:105], off offset:896
	global_load_dwordx4 v[178:181], v[110:111], off offset:896
	global_load_dwordx4 v[182:185], v[112:113], off offset:896
	global_load_dwordx4 v[186:189], v[116:117], off offset:896
	s_waitcnt vmcnt(11)
	ds_write_b128 v114, v[140:143]
	ds_write_b128 v114, v[120:123] offset:9216
	ds_write_b128 v114, v[136:139] offset:18432
	s_waitcnt vmcnt(9)
	ds_write_b128 v114, v[148:151] offset:27648
	ds_write_b128 v114, v[144:147] offset:36864
	s_waitcnt vmcnt(8)
	ds_write_b128 v114, v[152:155] offset:46080
	s_waitcnt vmcnt(7)
	ds_write_b128 v114, v[156:159] offset:55296
	ds_read_b128 v[120:123], v98 offset:36864
	ds_read_b128 v[136:139], v98 offset:36896
	ds_read_b128 v[140:143], v98 offset:41472
	ds_read_b128 v[144:147], v98 offset:41504
	ds_read_b128 v[148:151], v98 offset:46080
	ds_read_b128 v[152:155], v98 offset:46112
	ds_read_b128 v[156:159], v101
	ds_read_b128 v[190:193], v101 offset:32
	ds_read_b128 v[194:197], v101 offset:4608
	ds_read_b128 v[198:201], v101 offset:4640
	s_waitcnt lgkmcnt(3)
	v_mfma_f32_32x32x16_bf16 v[82:97], v[156:159], v[120:123], v[82:97]
	v_mfma_f32_32x32x16_bf16 v[50:65], v[156:159], v[140:143], v[50:65]
	v_mfma_f32_32x32x16_bf16 v[2:17], v[156:159], v[148:151], v[2:17]
	s_waitcnt lgkmcnt(1)
	v_mfma_f32_32x32x16_bf16 v[66:81], v[194:197], v[120:123], v[66:81]
	v_mfma_f32_32x32x16_bf16 v[34:49], v[194:197], v[140:143], v[34:49]
	v_mfma_f32_32x32x16_bf16 v[18:33], v[194:197], v[148:151], v[18:33]
	ds_read_b128 v[120:123], v98 offset:36928
	ds_read_b128 v[140:143], v98 offset:41536
	ds_read_b128 v[148:151], v98 offset:46144
	ds_read_b128 v[156:159], v101 offset:64
	ds_read_b128 v[194:197], v101 offset:4672
	v_mfma_f32_32x32x16_bf16 v[82:97], v[190:193], v[136:139], v[82:97]
	v_mfma_f32_32x32x16_bf16 v[50:65], v[190:193], v[144:147], v[50:65]
	v_mfma_f32_32x32x16_bf16 v[2:17], v[190:193], v[152:155], v[2:17]
	s_waitcnt lgkmcnt(5)
	v_mfma_f32_32x32x16_bf16 v[66:81], v[198:201], v[136:139], v[66:81]
	v_mfma_f32_32x32x16_bf16 v[34:49], v[198:201], v[144:147], v[34:49]
	v_mfma_f32_32x32x16_bf16 v[18:33], v[198:201], v[152:155], v[18:33]
	ds_read_b128 v[136:139], v98 offset:36960
	ds_read_b128 v[144:147], v98 offset:41568
	ds_read_b128 v[152:155], v98 offset:46176
	ds_read_b128 v[190:193], v101 offset:96
	ds_read_b128 v[198:201], v101 offset:4704
	s_waitcnt lgkmcnt(6)
	v_mfma_f32_32x32x16_bf16 v[82:97], v[156:159], v[120:123], v[82:97]
	v_mfma_f32_32x32x16_bf16 v[50:65], v[156:159], v[140:143], v[50:65]
	v_mfma_f32_32x32x16_bf16 v[2:17], v[156:159], v[148:151], v[2:17]
	s_waitcnt lgkmcnt(5)
	v_mfma_f32_32x32x16_bf16 v[66:81], v[194:197], v[120:123], v[66:81]
	v_mfma_f32_32x32x16_bf16 v[34:49], v[194:197], v[140:143], v[34:49]
	v_mfma_f32_32x32x16_bf16 v[18:33], v[194:197], v[148:151], v[18:33]
	s_waitcnt lgkmcnt(1)
	v_mfma_f32_32x32x16_bf16 v[82:97], v[190:193], v[136:139], v[82:97]
	v_mfma_f32_32x32x16_bf16 v[50:65], v[190:193], v[144:147], v[50:65]
	v_mfma_f32_32x32x16_bf16 v[2:17], v[190:193], v[152:155], v[2:17]
	s_waitcnt lgkmcnt(0)
	v_mfma_f32_32x32x16_bf16 v[66:81], v[198:201], v[136:139], v[66:81]
	v_mfma_f32_32x32x16_bf16 v[34:49], v[198:201], v[144:147], v[34:49]
	v_mfma_f32_32x32x16_bf16 v[18:33], v[198:201], v[152:155], v[18:33]
	s_barrier
	global_load_dwordx4 v[120:123], v[106:107], off offset:1024
	global_load_dwordx4 v[136:139], v[108:109], off offset:1024
	global_load_dwordx4 v[140:143], v[102:103], off offset:1024
	global_load_dwordx4 v[144:147], v[104:105], off offset:1024
	global_load_dwordx4 v[148:151], v[110:111], off offset:1024
	global_load_dwordx4 v[152:155], v[112:113], off offset:1024
	global_load_dwordx4 v[156:159], v[116:117], off offset:1024
	s_waitcnt vmcnt(11)
	ds_write_b128 v119, v[170:173]
	ds_write_b128 v119, v[162:165] offset:9216
	ds_write_b128 v119, v[166:169] offset:18432
	s_waitcnt vmcnt(9)
	ds_write_b128 v119, v[178:181] offset:27648
	ds_write_b128 v119, v[174:177] offset:36864
	s_waitcnt vmcnt(8)
	ds_write_b128 v119, v[182:185] offset:46080
	s_waitcnt vmcnt(7)
	ds_write_b128 v119, v[186:189] offset:55296
	ds_read_b128 v[162:165], v115 offset:36864
	ds_read_b128 v[166:169], v115 offset:36896
	ds_read_b128 v[170:173], v115 offset:41472
	ds_read_b128 v[174:177], v115 offset:41504
	ds_read_b128 v[178:181], v115 offset:46080
	ds_read_b128 v[182:185], v115 offset:46112
	ds_read_b128 v[186:189], v100
	ds_read_b128 v[190:193], v100 offset:32
	ds_read_b128 v[194:197], v100 offset:4608
	ds_read_b128 v[198:201], v100 offset:4640
	s_waitcnt lgkmcnt(3)
	v_mfma_f32_32x32x16_bf16 v[82:97], v[186:189], v[162:165], v[82:97]
	v_mfma_f32_32x32x16_bf16 v[50:65], v[186:189], v[170:173], v[50:65]
	v_mfma_f32_32x32x16_bf16 v[2:17], v[186:189], v[178:181], v[2:17]
	s_waitcnt lgkmcnt(1)
	v_mfma_f32_32x32x16_bf16 v[66:81], v[194:197], v[162:165], v[66:81]
	v_mfma_f32_32x32x16_bf16 v[34:49], v[194:197], v[170:173], v[34:49]
	v_mfma_f32_32x32x16_bf16 v[18:33], v[194:197], v[178:181], v[18:33]
	ds_read_b128 v[162:165], v115 offset:36928
	ds_read_b128 v[170:173], v115 offset:41536
	ds_read_b128 v[178:181], v115 offset:46144
	ds_read_b128 v[186:189], v100 offset:64
	ds_read_b128 v[194:197], v100 offset:4672
	v_mfma_f32_32x32x16_bf16 v[82:97], v[190:193], v[166:169], v[82:97]
	v_mfma_f32_32x32x16_bf16 v[50:65], v[190:193], v[174:177], v[50:65]
	v_mfma_f32_32x32x16_bf16 v[2:17], v[190:193], v[182:185], v[2:17]
	s_waitcnt lgkmcnt(5)
	v_mfma_f32_32x32x16_bf16 v[66:81], v[198:201], v[166:169], v[66:81]
	v_mfma_f32_32x32x16_bf16 v[34:49], v[198:201], v[174:177], v[34:49]
	v_mfma_f32_32x32x16_bf16 v[18:33], v[198:201], v[182:185], v[18:33]
	ds_read_b128 v[166:169], v115 offset:36960
	ds_read_b128 v[174:177], v115 offset:41568
	ds_read_b128 v[182:185], v115 offset:46176
	ds_read_b128 v[190:193], v100 offset:96
	ds_read_b128 v[198:201], v100 offset:4704
	s_waitcnt lgkmcnt(6)
	v_mfma_f32_32x32x16_bf16 v[82:97], v[186:189], v[162:165], v[82:97]
	v_mfma_f32_32x32x16_bf16 v[50:65], v[186:189], v[170:173], v[50:65]
	v_mfma_f32_32x32x16_bf16 v[2:17], v[186:189], v[178:181], v[2:17]
	s_waitcnt lgkmcnt(5)
	v_mfma_f32_32x32x16_bf16 v[66:81], v[194:197], v[162:165], v[66:81]
	v_mfma_f32_32x32x16_bf16 v[34:49], v[194:197], v[170:173], v[34:49]
	v_mfma_f32_32x32x16_bf16 v[18:33], v[194:197], v[178:181], v[18:33]
	s_waitcnt lgkmcnt(1)
	v_mfma_f32_32x32x16_bf16 v[82:97], v[190:193], v[166:169], v[82:97]
	v_mfma_f32_32x32x16_bf16 v[50:65], v[190:193], v[174:177], v[50:65]
	v_mfma_f32_32x32x16_bf16 v[2:17], v[190:193], v[182:185], v[2:17]
	s_waitcnt lgkmcnt(0)
	v_mfma_f32_32x32x16_bf16 v[66:81], v[198:201], v[166:169], v[66:81]
	v_mfma_f32_32x32x16_bf16 v[34:49], v[198:201], v[174:177], v[34:49]
	v_mfma_f32_32x32x16_bf16 v[18:33], v[198:201], v[182:185], v[18:33]
	s_barrier
	global_load_dwordx4 v[162:165], v[106:107], off offset:1152
	global_load_dwordx4 v[166:169], v[108:109], off offset:1152
	global_load_dwordx4 v[170:173], v[102:103], off offset:1152
	global_load_dwordx4 v[174:177], v[104:105], off offset:1152
	global_load_dwordx4 v[178:181], v[110:111], off offset:1152
	global_load_dwordx4 v[182:185], v[112:113], off offset:1152
	global_load_dwordx4 v[186:189], v[116:117], off offset:1152
	s_waitcnt vmcnt(11)
	ds_write_b128 v114, v[140:143]
	ds_write_b128 v114, v[120:123] offset:9216
	ds_write_b128 v114, v[136:139] offset:18432
	s_waitcnt vmcnt(9)
	ds_write_b128 v114, v[148:151] offset:27648
	ds_write_b128 v114, v[144:147] offset:36864
	s_waitcnt vmcnt(8)
	ds_write_b128 v114, v[152:155] offset:46080
	s_waitcnt vmcnt(7)
	ds_write_b128 v114, v[156:159] offset:55296
	ds_read_b128 v[120:123], v98 offset:36864
	ds_read_b128 v[136:139], v98 offset:36896
	ds_read_b128 v[140:143], v98 offset:41472
	ds_read_b128 v[144:147], v98 offset:41504
	ds_read_b128 v[148:151], v98 offset:46080
	ds_read_b128 v[152:155], v98 offset:46112
	ds_read_b128 v[156:159], v101
	ds_read_b128 v[190:193], v101 offset:32
	ds_read_b128 v[194:197], v101 offset:4608
	ds_read_b128 v[198:201], v101 offset:4640
	s_waitcnt lgkmcnt(3)
	v_mfma_f32_32x32x16_bf16 v[82:97], v[156:159], v[120:123], v[82:97]
	v_mfma_f32_32x32x16_bf16 v[50:65], v[156:159], v[140:143], v[50:65]
	v_mfma_f32_32x32x16_bf16 v[2:17], v[156:159], v[148:151], v[2:17]
	s_waitcnt lgkmcnt(1)
	v_mfma_f32_32x32x16_bf16 v[66:81], v[194:197], v[120:123], v[66:81]
	v_mfma_f32_32x32x16_bf16 v[34:49], v[194:197], v[140:143], v[34:49]
	v_mfma_f32_32x32x16_bf16 v[18:33], v[194:197], v[148:151], v[18:33]
	ds_read_b128 v[120:123], v98 offset:36928
	ds_read_b128 v[140:143], v98 offset:41536
	ds_read_b128 v[148:151], v98 offset:46144
	ds_read_b128 v[156:159], v101 offset:64
	ds_read_b128 v[194:197], v101 offset:4672
	v_mfma_f32_32x32x16_bf16 v[82:97], v[190:193], v[136:139], v[82:97]
	v_mfma_f32_32x32x16_bf16 v[50:65], v[190:193], v[144:147], v[50:65]
	v_mfma_f32_32x32x16_bf16 v[2:17], v[190:193], v[152:155], v[2:17]
	s_waitcnt lgkmcnt(5)
	v_mfma_f32_32x32x16_bf16 v[66:81], v[198:201], v[136:139], v[66:81]
	v_mfma_f32_32x32x16_bf16 v[34:49], v[198:201], v[144:147], v[34:49]
	v_mfma_f32_32x32x16_bf16 v[18:33], v[198:201], v[152:155], v[18:33]
	ds_read_b128 v[136:139], v98 offset:36960
	ds_read_b128 v[144:147], v98 offset:41568
	ds_read_b128 v[152:155], v98 offset:46176
	ds_read_b128 v[190:193], v101 offset:96
	ds_read_b128 v[198:201], v101 offset:4704
	s_waitcnt lgkmcnt(6)
	v_mfma_f32_32x32x16_bf16 v[82:97], v[156:159], v[120:123], v[82:97]
	v_mfma_f32_32x32x16_bf16 v[50:65], v[156:159], v[140:143], v[50:65]
	v_mfma_f32_32x32x16_bf16 v[2:17], v[156:159], v[148:151], v[2:17]
	s_waitcnt lgkmcnt(5)
	v_mfma_f32_32x32x16_bf16 v[66:81], v[194:197], v[120:123], v[66:81]
	v_mfma_f32_32x32x16_bf16 v[34:49], v[194:197], v[140:143], v[34:49]
	v_mfma_f32_32x32x16_bf16 v[18:33], v[194:197], v[148:151], v[18:33]
	s_waitcnt lgkmcnt(1)
	v_mfma_f32_32x32x16_bf16 v[82:97], v[190:193], v[136:139], v[82:97]
	v_mfma_f32_32x32x16_bf16 v[50:65], v[190:193], v[144:147], v[50:65]
	v_mfma_f32_32x32x16_bf16 v[2:17], v[190:193], v[152:155], v[2:17]
	s_waitcnt lgkmcnt(0)
	v_mfma_f32_32x32x16_bf16 v[66:81], v[198:201], v[136:139], v[66:81]
	v_mfma_f32_32x32x16_bf16 v[34:49], v[198:201], v[144:147], v[34:49]
	v_mfma_f32_32x32x16_bf16 v[18:33], v[198:201], v[152:155], v[18:33]
	s_barrier
	global_load_dwordx4 v[120:123], v[106:107], off offset:1280
	global_load_dwordx4 v[136:139], v[108:109], off offset:1280
	global_load_dwordx4 v[140:143], v[102:103], off offset:1280
	global_load_dwordx4 v[144:147], v[104:105], off offset:1280
	global_load_dwordx4 v[148:151], v[110:111], off offset:1280
	global_load_dwordx4 v[152:155], v[112:113], off offset:1280
	global_load_dwordx4 v[156:159], v[116:117], off offset:1280
	s_waitcnt vmcnt(11)
	ds_write_b128 v119, v[170:173]
	ds_write_b128 v119, v[162:165] offset:9216
	ds_write_b128 v119, v[166:169] offset:18432
	s_waitcnt vmcnt(9)
	ds_write_b128 v119, v[178:181] offset:27648
	ds_write_b128 v119, v[174:177] offset:36864
	s_waitcnt vmcnt(8)
	ds_write_b128 v119, v[182:185] offset:46080
	s_waitcnt vmcnt(7)
	ds_write_b128 v119, v[186:189] offset:55296
	ds_read_b128 v[162:165], v115 offset:36864
	ds_read_b128 v[166:169], v115 offset:36896
	ds_read_b128 v[170:173], v115 offset:41472
	ds_read_b128 v[174:177], v115 offset:41504
	ds_read_b128 v[178:181], v115 offset:46080
	ds_read_b128 v[182:185], v115 offset:46112
	ds_read_b128 v[186:189], v100
	ds_read_b128 v[190:193], v100 offset:32
	ds_read_b128 v[194:197], v100 offset:4608
	ds_read_b128 v[198:201], v100 offset:4640
	s_waitcnt lgkmcnt(3)
	v_mfma_f32_32x32x16_bf16 v[82:97], v[186:189], v[162:165], v[82:97]
	v_mfma_f32_32x32x16_bf16 v[50:65], v[186:189], v[170:173], v[50:65]
	v_mfma_f32_32x32x16_bf16 v[2:17], v[186:189], v[178:181], v[2:17]
	s_waitcnt lgkmcnt(1)
	v_mfma_f32_32x32x16_bf16 v[66:81], v[194:197], v[162:165], v[66:81]
	v_mfma_f32_32x32x16_bf16 v[34:49], v[194:197], v[170:173], v[34:49]
	v_mfma_f32_32x32x16_bf16 v[18:33], v[194:197], v[178:181], v[18:33]
	ds_read_b128 v[162:165], v115 offset:36928
	ds_read_b128 v[170:173], v115 offset:41536
	ds_read_b128 v[178:181], v115 offset:46144
	ds_read_b128 v[186:189], v100 offset:64
	ds_read_b128 v[194:197], v100 offset:4672
	v_mfma_f32_32x32x16_bf16 v[82:97], v[190:193], v[166:169], v[82:97]
	v_mfma_f32_32x32x16_bf16 v[50:65], v[190:193], v[174:177], v[50:65]
	v_mfma_f32_32x32x16_bf16 v[2:17], v[190:193], v[182:185], v[2:17]
	s_waitcnt lgkmcnt(5)
	v_mfma_f32_32x32x16_bf16 v[66:81], v[198:201], v[166:169], v[66:81]
	v_mfma_f32_32x32x16_bf16 v[34:49], v[198:201], v[174:177], v[34:49]
	v_mfma_f32_32x32x16_bf16 v[18:33], v[198:201], v[182:185], v[18:33]
	ds_read_b128 v[166:169], v115 offset:36960
	ds_read_b128 v[174:177], v115 offset:41568
	ds_read_b128 v[182:185], v115 offset:46176
	ds_read_b128 v[190:193], v100 offset:96
	ds_read_b128 v[198:201], v100 offset:4704
	s_waitcnt lgkmcnt(6)
	v_mfma_f32_32x32x16_bf16 v[82:97], v[186:189], v[162:165], v[82:97]
	v_mfma_f32_32x32x16_bf16 v[50:65], v[186:189], v[170:173], v[50:65]
	v_mfma_f32_32x32x16_bf16 v[2:17], v[186:189], v[178:181], v[2:17]
	s_waitcnt lgkmcnt(5)
	v_mfma_f32_32x32x16_bf16 v[66:81], v[194:197], v[162:165], v[66:81]
	v_mfma_f32_32x32x16_bf16 v[34:49], v[194:197], v[170:173], v[34:49]
	v_mfma_f32_32x32x16_bf16 v[18:33], v[194:197], v[178:181], v[18:33]
	s_waitcnt lgkmcnt(1)
	v_mfma_f32_32x32x16_bf16 v[82:97], v[190:193], v[166:169], v[82:97]
	v_mfma_f32_32x32x16_bf16 v[50:65], v[190:193], v[174:177], v[50:65]
	v_mfma_f32_32x32x16_bf16 v[2:17], v[190:193], v[182:185], v[2:17]
	s_waitcnt lgkmcnt(0)
	v_mfma_f32_32x32x16_bf16 v[66:81], v[198:201], v[166:169], v[66:81]
	v_mfma_f32_32x32x16_bf16 v[34:49], v[198:201], v[174:177], v[34:49]
	v_mfma_f32_32x32x16_bf16 v[18:33], v[198:201], v[182:185], v[18:33]
	s_barrier
	global_load_dwordx4 v[162:165], v[106:107], off offset:1408
	global_load_dwordx4 v[166:169], v[108:109], off offset:1408
	global_load_dwordx4 v[170:173], v[102:103], off offset:1408
	global_load_dwordx4 v[174:177], v[104:105], off offset:1408
	global_load_dwordx4 v[178:181], v[110:111], off offset:1408
	global_load_dwordx4 v[182:185], v[112:113], off offset:1408
	global_load_dwordx4 v[186:189], v[116:117], off offset:1408
	s_waitcnt vmcnt(11)
	ds_write_b128 v114, v[140:143]
	ds_write_b128 v114, v[120:123] offset:9216
	ds_write_b128 v114, v[136:139] offset:18432
	s_waitcnt vmcnt(9)
	ds_write_b128 v114, v[148:151] offset:27648
	ds_write_b128 v114, v[144:147] offset:36864
	s_waitcnt vmcnt(8)
	ds_write_b128 v114, v[152:155] offset:46080
	s_waitcnt vmcnt(7)
	ds_write_b128 v114, v[156:159] offset:55296
	ds_read_b128 v[120:123], v98 offset:36864
	ds_read_b128 v[136:139], v98 offset:36896
	ds_read_b128 v[140:143], v98 offset:41472
	ds_read_b128 v[144:147], v98 offset:41504
	ds_read_b128 v[148:151], v98 offset:46080
	ds_read_b128 v[152:155], v98 offset:46112
	ds_read_b128 v[156:159], v101
	ds_read_b128 v[190:193], v101 offset:32
	ds_read_b128 v[194:197], v101 offset:4608
	ds_read_b128 v[198:201], v101 offset:4640
	s_waitcnt lgkmcnt(3)
	v_mfma_f32_32x32x16_bf16 v[82:97], v[156:159], v[120:123], v[82:97]
	v_mfma_f32_32x32x16_bf16 v[50:65], v[156:159], v[140:143], v[50:65]
	v_mfma_f32_32x32x16_bf16 v[2:17], v[156:159], v[148:151], v[2:17]
	s_waitcnt lgkmcnt(1)
	v_mfma_f32_32x32x16_bf16 v[66:81], v[194:197], v[120:123], v[66:81]
	v_mfma_f32_32x32x16_bf16 v[34:49], v[194:197], v[140:143], v[34:49]
	v_mfma_f32_32x32x16_bf16 v[18:33], v[194:197], v[148:151], v[18:33]
	ds_read_b128 v[120:123], v98 offset:36928
	ds_read_b128 v[140:143], v98 offset:41536
	ds_read_b128 v[148:151], v98 offset:46144
	ds_read_b128 v[156:159], v101 offset:64
	ds_read_b128 v[194:197], v101 offset:4672
	v_mfma_f32_32x32x16_bf16 v[82:97], v[190:193], v[136:139], v[82:97]
	v_mfma_f32_32x32x16_bf16 v[50:65], v[190:193], v[144:147], v[50:65]
	v_mfma_f32_32x32x16_bf16 v[2:17], v[190:193], v[152:155], v[2:17]
	s_waitcnt lgkmcnt(5)
	v_mfma_f32_32x32x16_bf16 v[66:81], v[198:201], v[136:139], v[66:81]
	v_mfma_f32_32x32x16_bf16 v[34:49], v[198:201], v[144:147], v[34:49]
	v_mfma_f32_32x32x16_bf16 v[18:33], v[198:201], v[152:155], v[18:33]
	ds_read_b128 v[136:139], v98 offset:36960
	ds_read_b128 v[144:147], v98 offset:41568
	ds_read_b128 v[152:155], v98 offset:46176
	ds_read_b128 v[190:193], v101 offset:96
	ds_read_b128 v[198:201], v101 offset:4704
	s_waitcnt lgkmcnt(6)
	v_mfma_f32_32x32x16_bf16 v[82:97], v[156:159], v[120:123], v[82:97]
	v_mfma_f32_32x32x16_bf16 v[50:65], v[156:159], v[140:143], v[50:65]
	v_mfma_f32_32x32x16_bf16 v[2:17], v[156:159], v[148:151], v[2:17]
	s_waitcnt lgkmcnt(5)
	v_mfma_f32_32x32x16_bf16 v[66:81], v[194:197], v[120:123], v[66:81]
	v_mfma_f32_32x32x16_bf16 v[34:49], v[194:197], v[140:143], v[34:49]
	v_mfma_f32_32x32x16_bf16 v[18:33], v[194:197], v[148:151], v[18:33]
	s_waitcnt lgkmcnt(1)
	v_mfma_f32_32x32x16_bf16 v[82:97], v[190:193], v[136:139], v[82:97]
	v_mfma_f32_32x32x16_bf16 v[50:65], v[190:193], v[144:147], v[50:65]
	v_mfma_f32_32x32x16_bf16 v[2:17], v[190:193], v[152:155], v[2:17]
	s_waitcnt lgkmcnt(0)
	v_mfma_f32_32x32x16_bf16 v[66:81], v[198:201], v[136:139], v[66:81]
	v_mfma_f32_32x32x16_bf16 v[34:49], v[198:201], v[144:147], v[34:49]
	v_mfma_f32_32x32x16_bf16 v[18:33], v[198:201], v[152:155], v[18:33]
	s_barrier
	global_load_dwordx4 v[120:123], v[106:107], off offset:1536
	global_load_dwordx4 v[136:139], v[108:109], off offset:1536
	global_load_dwordx4 v[140:143], v[102:103], off offset:1536
	global_load_dwordx4 v[144:147], v[104:105], off offset:1536
	global_load_dwordx4 v[148:151], v[110:111], off offset:1536
	global_load_dwordx4 v[152:155], v[112:113], off offset:1536
	global_load_dwordx4 v[156:159], v[116:117], off offset:1536
	s_waitcnt vmcnt(11)
	ds_write_b128 v119, v[170:173]
	ds_write_b128 v119, v[162:165] offset:9216
	ds_write_b128 v119, v[166:169] offset:18432
	s_waitcnt vmcnt(9)
	ds_write_b128 v119, v[178:181] offset:27648
	ds_write_b128 v119, v[174:177] offset:36864
	s_waitcnt vmcnt(8)
	ds_write_b128 v119, v[182:185] offset:46080
	s_waitcnt vmcnt(7)
	ds_write_b128 v119, v[186:189] offset:55296
	ds_read_b128 v[162:165], v115 offset:36864
	ds_read_b128 v[166:169], v115 offset:36896
	ds_read_b128 v[170:173], v115 offset:41472
	ds_read_b128 v[174:177], v115 offset:41504
	ds_read_b128 v[178:181], v115 offset:46080
	ds_read_b128 v[182:185], v115 offset:46112
	ds_read_b128 v[186:189], v100
	ds_read_b128 v[190:193], v100 offset:32
	ds_read_b128 v[194:197], v100 offset:4608
	ds_read_b128 v[198:201], v100 offset:4640
	s_waitcnt lgkmcnt(3)
	v_mfma_f32_32x32x16_bf16 v[82:97], v[186:189], v[162:165], v[82:97]
	v_mfma_f32_32x32x16_bf16 v[50:65], v[186:189], v[170:173], v[50:65]
	v_mfma_f32_32x32x16_bf16 v[2:17], v[186:189], v[178:181], v[2:17]
	s_waitcnt lgkmcnt(1)
	v_mfma_f32_32x32x16_bf16 v[66:81], v[194:197], v[162:165], v[66:81]
	v_mfma_f32_32x32x16_bf16 v[34:49], v[194:197], v[170:173], v[34:49]
	v_mfma_f32_32x32x16_bf16 v[18:33], v[194:197], v[178:181], v[18:33]
	ds_read_b128 v[162:165], v115 offset:36928
	ds_read_b128 v[170:173], v115 offset:41536
	ds_read_b128 v[178:181], v115 offset:46144
	ds_read_b128 v[186:189], v100 offset:64
	ds_read_b128 v[194:197], v100 offset:4672
	v_mfma_f32_32x32x16_bf16 v[82:97], v[190:193], v[166:169], v[82:97]
	v_mfma_f32_32x32x16_bf16 v[50:65], v[190:193], v[174:177], v[50:65]
	v_mfma_f32_32x32x16_bf16 v[2:17], v[190:193], v[182:185], v[2:17]
	s_waitcnt lgkmcnt(5)
	v_mfma_f32_32x32x16_bf16 v[66:81], v[198:201], v[166:169], v[66:81]
	v_mfma_f32_32x32x16_bf16 v[34:49], v[198:201], v[174:177], v[34:49]
	v_mfma_f32_32x32x16_bf16 v[18:33], v[198:201], v[182:185], v[18:33]
	ds_read_b128 v[166:169], v115 offset:36960
	ds_read_b128 v[174:177], v115 offset:41568
	ds_read_b128 v[182:185], v115 offset:46176
	ds_read_b128 v[190:193], v100 offset:96
	ds_read_b128 v[198:201], v100 offset:4704
	s_waitcnt lgkmcnt(6)
	v_mfma_f32_32x32x16_bf16 v[82:97], v[186:189], v[162:165], v[82:97]
	v_mfma_f32_32x32x16_bf16 v[50:65], v[186:189], v[170:173], v[50:65]
	v_mfma_f32_32x32x16_bf16 v[2:17], v[186:189], v[178:181], v[2:17]
	s_waitcnt lgkmcnt(5)
	v_mfma_f32_32x32x16_bf16 v[66:81], v[194:197], v[162:165], v[66:81]
	v_mfma_f32_32x32x16_bf16 v[34:49], v[194:197], v[170:173], v[34:49]
	v_mfma_f32_32x32x16_bf16 v[18:33], v[194:197], v[178:181], v[18:33]
	s_waitcnt lgkmcnt(1)
	v_mfma_f32_32x32x16_bf16 v[82:97], v[190:193], v[166:169], v[82:97]
	v_mfma_f32_32x32x16_bf16 v[50:65], v[190:193], v[174:177], v[50:65]
	v_mfma_f32_32x32x16_bf16 v[2:17], v[190:193], v[182:185], v[2:17]
	s_waitcnt lgkmcnt(0)
	v_mfma_f32_32x32x16_bf16 v[66:81], v[198:201], v[166:169], v[66:81]
	v_mfma_f32_32x32x16_bf16 v[34:49], v[198:201], v[174:177], v[34:49]
	v_mfma_f32_32x32x16_bf16 v[18:33], v[198:201], v[182:185], v[18:33]
	s_barrier
	global_load_dwordx4 v[162:165], v[106:107], off offset:1664
	global_load_dwordx4 v[166:169], v[108:109], off offset:1664
	global_load_dwordx4 v[170:173], v[102:103], off offset:1664
	global_load_dwordx4 v[174:177], v[104:105], off offset:1664
	global_load_dwordx4 v[178:181], v[110:111], off offset:1664
	global_load_dwordx4 v[182:185], v[112:113], off offset:1664
	global_load_dwordx4 v[186:189], v[116:117], off offset:1664
	s_waitcnt vmcnt(11)
	ds_write_b128 v114, v[140:143]
	ds_write_b128 v114, v[120:123] offset:9216
	ds_write_b128 v114, v[136:139] offset:18432
	s_waitcnt vmcnt(9)
	ds_write_b128 v114, v[148:151] offset:27648
	ds_write_b128 v114, v[144:147] offset:36864
	s_waitcnt vmcnt(8)
	ds_write_b128 v114, v[152:155] offset:46080
	s_waitcnt vmcnt(7)
	ds_write_b128 v114, v[156:159] offset:55296
	ds_read_b128 v[120:123], v98 offset:36864
	ds_read_b128 v[136:139], v98 offset:36896
	ds_read_b128 v[140:143], v98 offset:41472
	ds_read_b128 v[144:147], v98 offset:41504
	ds_read_b128 v[148:151], v98 offset:46080
	ds_read_b128 v[152:155], v98 offset:46112
	ds_read_b128 v[156:159], v101
	ds_read_b128 v[190:193], v101 offset:32
	ds_read_b128 v[194:197], v101 offset:4608
	ds_read_b128 v[198:201], v101 offset:4640
	s_waitcnt lgkmcnt(3)
	v_mfma_f32_32x32x16_bf16 v[82:97], v[156:159], v[120:123], v[82:97]
	v_mfma_f32_32x32x16_bf16 v[50:65], v[156:159], v[140:143], v[50:65]
	v_mfma_f32_32x32x16_bf16 v[2:17], v[156:159], v[148:151], v[2:17]
	s_waitcnt lgkmcnt(1)
	v_mfma_f32_32x32x16_bf16 v[66:81], v[194:197], v[120:123], v[66:81]
	v_mfma_f32_32x32x16_bf16 v[34:49], v[194:197], v[140:143], v[34:49]
	v_mfma_f32_32x32x16_bf16 v[18:33], v[194:197], v[148:151], v[18:33]
	ds_read_b128 v[120:123], v98 offset:36928
	ds_read_b128 v[140:143], v98 offset:41536
	ds_read_b128 v[148:151], v98 offset:46144
	ds_read_b128 v[156:159], v101 offset:64
	ds_read_b128 v[194:197], v101 offset:4672
	v_mfma_f32_32x32x16_bf16 v[82:97], v[190:193], v[136:139], v[82:97]
	v_mfma_f32_32x32x16_bf16 v[50:65], v[190:193], v[144:147], v[50:65]
	v_mfma_f32_32x32x16_bf16 v[2:17], v[190:193], v[152:155], v[2:17]
	s_waitcnt lgkmcnt(5)
	v_mfma_f32_32x32x16_bf16 v[66:81], v[198:201], v[136:139], v[66:81]
	v_mfma_f32_32x32x16_bf16 v[34:49], v[198:201], v[144:147], v[34:49]
	v_mfma_f32_32x32x16_bf16 v[18:33], v[198:201], v[152:155], v[18:33]
	ds_read_b128 v[136:139], v98 offset:36960
	ds_read_b128 v[144:147], v98 offset:41568
	ds_read_b128 v[152:155], v98 offset:46176
	ds_read_b128 v[190:193], v101 offset:96
	ds_read_b128 v[198:201], v101 offset:4704
	s_waitcnt lgkmcnt(6)
	v_mfma_f32_32x32x16_bf16 v[82:97], v[156:159], v[120:123], v[82:97]
	v_mfma_f32_32x32x16_bf16 v[50:65], v[156:159], v[140:143], v[50:65]
	v_mfma_f32_32x32x16_bf16 v[2:17], v[156:159], v[148:151], v[2:17]
	s_waitcnt lgkmcnt(5)
	v_mfma_f32_32x32x16_bf16 v[66:81], v[194:197], v[120:123], v[66:81]
	v_mfma_f32_32x32x16_bf16 v[34:49], v[194:197], v[140:143], v[34:49]
	v_mfma_f32_32x32x16_bf16 v[18:33], v[194:197], v[148:151], v[18:33]
	s_waitcnt lgkmcnt(1)
	v_mfma_f32_32x32x16_bf16 v[82:97], v[190:193], v[136:139], v[82:97]
	v_mfma_f32_32x32x16_bf16 v[50:65], v[190:193], v[144:147], v[50:65]
	v_mfma_f32_32x32x16_bf16 v[2:17], v[190:193], v[152:155], v[2:17]
	s_waitcnt lgkmcnt(0)
	v_mfma_f32_32x32x16_bf16 v[66:81], v[198:201], v[136:139], v[66:81]
	v_mfma_f32_32x32x16_bf16 v[34:49], v[198:201], v[144:147], v[34:49]
	v_mfma_f32_32x32x16_bf16 v[18:33], v[198:201], v[152:155], v[18:33]
	s_barrier
	global_load_dwordx4 v[120:123], v[106:107], off offset:1792
	global_load_dwordx4 v[136:139], v[108:109], off offset:1792
	global_load_dwordx4 v[140:143], v[102:103], off offset:1792
	global_load_dwordx4 v[144:147], v[104:105], off offset:1792
	global_load_dwordx4 v[148:151], v[110:111], off offset:1792
	global_load_dwordx4 v[152:155], v[112:113], off offset:1792
	global_load_dwordx4 v[156:159], v[116:117], off offset:1792
	s_waitcnt vmcnt(11)
	ds_write_b128 v119, v[170:173]
	ds_write_b128 v119, v[162:165] offset:9216
	ds_write_b128 v119, v[166:169] offset:18432
	s_waitcnt vmcnt(9)
	ds_write_b128 v119, v[178:181] offset:27648
	ds_write_b128 v119, v[174:177] offset:36864
	s_waitcnt vmcnt(8)
	ds_write_b128 v119, v[182:185] offset:46080
	s_waitcnt vmcnt(7)
	ds_write_b128 v119, v[186:189] offset:55296
	ds_read_b128 v[162:165], v115 offset:36864
	ds_read_b128 v[166:169], v115 offset:36896
	ds_read_b128 v[170:173], v115 offset:41472
	ds_read_b128 v[174:177], v115 offset:41504
	ds_read_b128 v[178:181], v115 offset:46080
	ds_read_b128 v[182:185], v115 offset:46112
	ds_read_b128 v[186:189], v100
	ds_read_b128 v[190:193], v100 offset:32
	ds_read_b128 v[194:197], v100 offset:4608
	ds_read_b128 v[198:201], v100 offset:4640
	s_waitcnt lgkmcnt(3)
	v_mfma_f32_32x32x16_bf16 v[82:97], v[186:189], v[162:165], v[82:97]
	v_mfma_f32_32x32x16_bf16 v[50:65], v[186:189], v[170:173], v[50:65]
	v_mfma_f32_32x32x16_bf16 v[2:17], v[186:189], v[178:181], v[2:17]
	s_waitcnt lgkmcnt(1)
	v_mfma_f32_32x32x16_bf16 v[66:81], v[194:197], v[162:165], v[66:81]
	v_mfma_f32_32x32x16_bf16 v[34:49], v[194:197], v[170:173], v[34:49]
	v_mfma_f32_32x32x16_bf16 v[18:33], v[194:197], v[178:181], v[18:33]
	ds_read_b128 v[162:165], v115 offset:36928
	ds_read_b128 v[170:173], v115 offset:41536
	ds_read_b128 v[178:181], v115 offset:46144
	ds_read_b128 v[186:189], v100 offset:64
	ds_read_b128 v[194:197], v100 offset:4672
	v_mfma_f32_32x32x16_bf16 v[82:97], v[190:193], v[166:169], v[82:97]
	v_mfma_f32_32x32x16_bf16 v[50:65], v[190:193], v[174:177], v[50:65]
	v_mfma_f32_32x32x16_bf16 v[2:17], v[190:193], v[182:185], v[2:17]
	s_waitcnt lgkmcnt(5)
	v_mfma_f32_32x32x16_bf16 v[66:81], v[198:201], v[166:169], v[66:81]
	v_mfma_f32_32x32x16_bf16 v[34:49], v[198:201], v[174:177], v[34:49]
	v_mfma_f32_32x32x16_bf16 v[18:33], v[198:201], v[182:185], v[18:33]
	ds_read_b128 v[166:169], v115 offset:36960
	ds_read_b128 v[174:177], v115 offset:41568
	ds_read_b128 v[182:185], v115 offset:46176
	ds_read_b128 v[190:193], v100 offset:96
	ds_read_b128 v[198:201], v100 offset:4704
	s_waitcnt lgkmcnt(6)
	v_mfma_f32_32x32x16_bf16 v[82:97], v[186:189], v[162:165], v[82:97]
	v_mfma_f32_32x32x16_bf16 v[50:65], v[186:189], v[170:173], v[50:65]
	v_mfma_f32_32x32x16_bf16 v[2:17], v[186:189], v[178:181], v[2:17]
	s_waitcnt lgkmcnt(5)
	v_mfma_f32_32x32x16_bf16 v[66:81], v[194:197], v[162:165], v[66:81]
	v_mfma_f32_32x32x16_bf16 v[34:49], v[194:197], v[170:173], v[34:49]
	v_mfma_f32_32x32x16_bf16 v[18:33], v[194:197], v[178:181], v[18:33]
	s_waitcnt lgkmcnt(1)
	v_mfma_f32_32x32x16_bf16 v[82:97], v[190:193], v[166:169], v[82:97]
	v_mfma_f32_32x32x16_bf16 v[50:65], v[190:193], v[174:177], v[50:65]
	v_mfma_f32_32x32x16_bf16 v[2:17], v[190:193], v[182:185], v[2:17]
	s_waitcnt lgkmcnt(0)
	v_mfma_f32_32x32x16_bf16 v[66:81], v[198:201], v[166:169], v[66:81]
	v_mfma_f32_32x32x16_bf16 v[34:49], v[198:201], v[174:177], v[34:49]
	v_mfma_f32_32x32x16_bf16 v[18:33], v[198:201], v[182:185], v[18:33]
	s_barrier
	global_load_dwordx4 v[162:165], v[106:107], off offset:1920
	s_nop 0
	global_load_dwordx4 v[106:109], v[108:109], off offset:1920
	s_nop 0
	global_load_dwordx4 v[166:169], v[102:103], off offset:1920
	s_nop 0
	global_load_dwordx4 v[102:105], v[104:105], off offset:1920
	s_nop 0
	global_load_dwordx4 v[170:173], v[110:111], off offset:1920
	s_nop 0
	global_load_dwordx4 v[110:113], v[112:113], off offset:1920
	s_nop 0
	global_load_dwordx4 v[174:177], v[116:117], off offset:1920
	s_waitcnt vmcnt(11)
	ds_write_b128 v114, v[140:143]
	ds_write_b128 v114, v[120:123] offset:9216
	ds_write_b128 v114, v[136:139] offset:18432
	s_waitcnt vmcnt(9)
	ds_write_b128 v114, v[148:151] offset:27648
	ds_write_b128 v114, v[144:147] offset:36864
	s_waitcnt vmcnt(8)
	ds_write_b128 v114, v[152:155] offset:46080
	s_waitcnt vmcnt(7)
	ds_write_b128 v114, v[156:159] offset:55296
	ds_read_b128 v[120:123], v98 offset:36864
	ds_read_b128 v[136:139], v98 offset:36896
	ds_read_b128 v[140:143], v98 offset:41472
	ds_read_b128 v[144:147], v98 offset:41504
	ds_read_b128 v[148:151], v98 offset:46080
	ds_read_b128 v[152:155], v98 offset:46112
	ds_read_b128 v[156:159], v101
	ds_read_b128 v[178:181], v101 offset:32
	ds_read_b128 v[182:185], v101 offset:4608
	ds_read_b128 v[186:189], v101 offset:4640
	s_waitcnt lgkmcnt(3)
	v_mfma_f32_32x32x16_bf16 v[82:97], v[156:159], v[120:123], v[82:97]
	v_mfma_f32_32x32x16_bf16 v[50:65], v[156:159], v[140:143], v[50:65]
	v_mfma_f32_32x32x16_bf16 v[2:17], v[156:159], v[148:151], v[2:17]
	s_waitcnt lgkmcnt(1)
	v_mfma_f32_32x32x16_bf16 v[66:81], v[182:185], v[120:123], v[66:81]
	v_mfma_f32_32x32x16_bf16 v[34:49], v[182:185], v[140:143], v[34:49]
	v_mfma_f32_32x32x16_bf16 v[18:33], v[182:185], v[148:151], v[18:33]
	ds_read_b128 v[120:123], v98 offset:36928
	ds_read_b128 v[140:143], v98 offset:41536
	ds_read_b128 v[148:151], v98 offset:46144
	ds_read_b128 v[156:159], v101 offset:64
	ds_read_b128 v[182:185], v101 offset:4672
	v_mfma_f32_32x32x16_bf16 v[82:97], v[178:181], v[136:139], v[82:97]
	v_mfma_f32_32x32x16_bf16 v[50:65], v[178:181], v[144:147], v[50:65]
	v_mfma_f32_32x32x16_bf16 v[2:17], v[178:181], v[152:155], v[2:17]
	s_waitcnt lgkmcnt(5)
	v_mfma_f32_32x32x16_bf16 v[66:81], v[186:189], v[136:139], v[66:81]
	v_mfma_f32_32x32x16_bf16 v[34:49], v[186:189], v[144:147], v[34:49]
	v_mfma_f32_32x32x16_bf16 v[18:33], v[186:189], v[152:155], v[18:33]
	ds_read_b128 v[136:139], v98 offset:36960
	ds_read_b128 v[144:147], v98 offset:41568
	ds_read_b128 v[152:155], v98 offset:46176
	ds_read_b128 v[178:181], v101 offset:96
	ds_read_b128 v[186:189], v101 offset:4704
	s_waitcnt lgkmcnt(6)
	v_mfma_f32_32x32x16_bf16 v[82:97], v[156:159], v[120:123], v[82:97]
	v_mfma_f32_32x32x16_bf16 v[50:65], v[156:159], v[140:143], v[50:65]
	v_mfma_f32_32x32x16_bf16 v[2:17], v[156:159], v[148:151], v[2:17]
	s_waitcnt lgkmcnt(5)
	v_mfma_f32_32x32x16_bf16 v[66:81], v[182:185], v[120:123], v[66:81]
	v_mfma_f32_32x32x16_bf16 v[34:49], v[182:185], v[140:143], v[34:49]
	v_mfma_f32_32x32x16_bf16 v[18:33], v[182:185], v[148:151], v[18:33]
	s_waitcnt lgkmcnt(1)
	v_mfma_f32_32x32x16_bf16 v[82:97], v[178:181], v[136:139], v[82:97]
	v_mfma_f32_32x32x16_bf16 v[50:65], v[178:181], v[144:147], v[50:65]
	v_mfma_f32_32x32x16_bf16 v[2:17], v[178:181], v[152:155], v[2:17]
	s_waitcnt lgkmcnt(0)
	v_mfma_f32_32x32x16_bf16 v[66:81], v[186:189], v[136:139], v[66:81]
	v_mfma_f32_32x32x16_bf16 v[34:49], v[186:189], v[144:147], v[34:49]
	v_mfma_f32_32x32x16_bf16 v[18:33], v[186:189], v[152:155], v[18:33]
	s_barrier
	s_waitcnt vmcnt(4)
	ds_write_b128 v119, v[166:169]
	ds_write_b128 v119, v[162:165] offset:9216
	ds_write_b128 v119, v[106:109] offset:18432
	s_waitcnt vmcnt(2)
	ds_write_b128 v119, v[170:173] offset:27648
	ds_write_b128 v119, v[102:105] offset:36864
	s_waitcnt vmcnt(1)
	ds_write_b128 v119, v[110:113] offset:46080
	s_waitcnt vmcnt(0)
	ds_write_b128 v119, v[174:177] offset:55296
	ds_read_b128 v[102:105], v115 offset:36864
	ds_read_b128 v[106:109], v115 offset:36896
	ds_read_b128 v[110:113], v115 offset:41472
	ds_read_b128 v[120:123], v115 offset:41504
	ds_read_b128 v[136:139], v115 offset:46080
	ds_read_b128 v[140:143], v115 offset:46112
	ds_read_b128 v[144:147], v100
	ds_read_b128 v[148:151], v100 offset:32
	ds_read_b128 v[152:155], v100 offset:4608
	ds_read_b128 v[156:159], v100 offset:4640
	s_waitcnt lgkmcnt(3)
	v_mfma_f32_32x32x16_bf16 v[82:97], v[144:147], v[102:105], v[82:97]
	v_mfma_f32_32x32x16_bf16 v[50:65], v[144:147], v[110:113], v[50:65]
	v_mfma_f32_32x32x16_bf16 v[2:17], v[144:147], v[136:139], v[2:17]
	s_waitcnt lgkmcnt(1)
	v_mfma_f32_32x32x16_bf16 v[66:81], v[152:155], v[102:105], v[66:81]
	v_mfma_f32_32x32x16_bf16 v[34:49], v[152:155], v[110:113], v[34:49]
	v_mfma_f32_32x32x16_bf16 v[18:33], v[152:155], v[136:139], v[18:33]
	ds_read_b128 v[102:105], v115 offset:36928
	ds_read_b128 v[110:113], v115 offset:41536
	ds_read_b128 v[136:139], v115 offset:46144
	ds_read_b128 v[144:147], v100 offset:64
	ds_read_b128 v[152:155], v100 offset:4672
	v_mfma_f32_32x32x16_bf16 v[82:97], v[148:151], v[106:109], v[82:97]
	v_mfma_f32_32x32x16_bf16 v[50:65], v[148:151], v[120:123], v[50:65]
	v_mfma_f32_32x32x16_bf16 v[2:17], v[148:151], v[140:143], v[2:17]
	s_waitcnt lgkmcnt(5)
	v_mfma_f32_32x32x16_bf16 v[66:81], v[156:159], v[106:109], v[66:81]
	v_mfma_f32_32x32x16_bf16 v[34:49], v[156:159], v[120:123], v[34:49]
	v_mfma_f32_32x32x16_bf16 v[18:33], v[156:159], v[140:143], v[18:33]
	ds_read_b128 v[106:109], v115 offset:36960
	ds_read_b128 v[120:123], v115 offset:41568
	ds_read_b128 v[114:117], v115 offset:46176
	ds_read_b128 v[140:143], v100 offset:96
	ds_read_b128 v[148:151], v100 offset:4704
	s_waitcnt lgkmcnt(6)
	v_mfma_f32_32x32x16_bf16 v[82:97], v[144:147], v[102:105], v[82:97]
	v_mfma_f32_32x32x16_bf16 v[50:65], v[144:147], v[110:113], v[50:65]
	v_mfma_f32_32x32x16_bf16 v[2:17], v[144:147], v[136:139], v[2:17]
	s_waitcnt lgkmcnt(5)
	v_mfma_f32_32x32x16_bf16 v[66:81], v[152:155], v[102:105], v[66:81]
	v_mfma_f32_32x32x16_bf16 v[34:49], v[152:155], v[110:113], v[34:49]
	v_mfma_f32_32x32x16_bf16 v[18:33], v[152:155], v[136:139], v[18:33]
	s_waitcnt lgkmcnt(1)
	v_mfma_f32_32x32x16_bf16 v[82:97], v[140:143], v[106:109], v[82:97]
	v_mfma_f32_32x32x16_bf16 v[50:65], v[140:143], v[120:123], v[50:65]
	v_mfma_f32_32x32x16_bf16 v[2:17], v[140:143], v[114:117], v[2:17]
	s_waitcnt lgkmcnt(0)
	v_mfma_f32_32x32x16_bf16 v[66:81], v[148:151], v[106:109], v[66:81]
	v_mfma_f32_32x32x16_bf16 v[34:49], v[148:151], v[120:123], v[34:49]
	v_mfma_f32_32x32x16_bf16 v[18:33], v[148:151], v[114:117], v[18:33]
	s_barrier
	ds_read_b128 v[102:105], v98 offset:36864
	ds_read_b128 v[106:109], v98 offset:36896
	ds_read_b128 v[110:113], v98 offset:41472
	ds_read_b128 v[114:117], v98 offset:41504
	ds_read_b128 v[120:123], v98 offset:46080
	ds_read_b128 v[136:139], v98 offset:46112
	ds_read_b128 v[140:143], v101
	ds_read_b128 v[144:147], v101 offset:32
	ds_read_b128 v[148:151], v101 offset:4608
	ds_read_b128 v[152:155], v101 offset:4640
	s_waitcnt lgkmcnt(3)
	v_mfma_f32_32x32x16_bf16 v[82:97], v[140:143], v[102:105], v[82:97]
	v_mfma_f32_32x32x16_bf16 v[50:65], v[140:143], v[110:113], v[50:65]
	v_mfma_f32_32x32x16_bf16 v[2:17], v[140:143], v[120:123], v[2:17]
	s_waitcnt lgkmcnt(1)
	v_mfma_f32_32x32x16_bf16 v[66:81], v[148:151], v[102:105], v[66:81]
	v_mfma_f32_32x32x16_bf16 v[34:49], v[148:151], v[110:113], v[34:49]
	v_mfma_f32_32x32x16_bf16 v[18:33], v[148:151], v[120:123], v[18:33]
	ds_read_b128 v[102:105], v98 offset:36928
	ds_read_b128 v[110:113], v98 offset:41536
	ds_read_b128 v[120:123], v98 offset:46144
	ds_read_b128 v[140:143], v101 offset:64
	ds_read_b128 v[148:151], v101 offset:4672
	v_mfma_f32_32x32x16_bf16 v[82:97], v[144:147], v[106:109], v[82:97]
	v_mfma_f32_32x32x16_bf16 v[50:65], v[144:147], v[114:117], v[50:65]
	v_mfma_f32_32x32x16_bf16 v[2:17], v[144:147], v[136:139], v[2:17]
	s_waitcnt lgkmcnt(5)
	v_mfma_f32_32x32x16_bf16 v[66:81], v[152:155], v[106:109], v[66:81]
	v_mfma_f32_32x32x16_bf16 v[34:49], v[152:155], v[114:117], v[34:49]
	v_mfma_f32_32x32x16_bf16 v[18:33], v[152:155], v[136:139], v[18:33]
	ds_read_b128 v[106:109], v98 offset:36960
	ds_read_b128 v[114:117], v98 offset:41568
	ds_read_b128 v[136:139], v98 offset:46176
	ds_read_b128 v[144:147], v101 offset:96
	ds_read_b128 v[152:155], v101 offset:4704
	s_waitcnt lgkmcnt(6)
	v_mfma_f32_32x32x16_bf16 v[82:97], v[140:143], v[102:105], v[82:97]
	v_mfma_f32_32x32x16_bf16 v[50:65], v[140:143], v[110:113], v[50:65]
	v_mfma_f32_32x32x16_bf16 v[2:17], v[140:143], v[120:123], v[2:17]
	s_waitcnt lgkmcnt(5)
	v_mfma_f32_32x32x16_bf16 v[66:81], v[148:151], v[102:105], v[66:81]
	v_mfma_f32_32x32x16_bf16 v[34:49], v[148:151], v[110:113], v[34:49]
	v_mfma_f32_32x32x16_bf16 v[18:33], v[148:151], v[120:123], v[18:33]
	s_waitcnt lgkmcnt(1)
	v_mfma_f32_32x32x16_bf16 v[82:97], v[144:147], v[106:109], v[82:97]
	v_mfma_f32_32x32x16_bf16 v[50:65], v[144:147], v[114:117], v[50:65]
	v_mfma_f32_32x32x16_bf16 v[2:17], v[144:147], v[136:139], v[2:17]
	s_waitcnt lgkmcnt(0)
	v_mfma_f32_32x32x16_bf16 v[66:81], v[152:155], v[106:109], v[66:81]
	v_mfma_f32_32x32x16_bf16 v[34:49], v[152:155], v[114:117], v[34:49]
	v_mfma_f32_32x32x16_bf16 v[18:33], v[152:155], v[136:139], v[18:33]
	s_add_i32 s98, s61, s62
	s_cmpk_lt_i32 s98, 0x700
	s_cbranch_scc0 .Lg1x_nopf
	s_abs_i32 s33, s98
	s_mul_hi_u32 s94, s33, s53
	s_mul_i32 s95, s94, s49
	s_ashr_i32 s32, s98, 31
	s_sub_i32 s33, s33, s95
	s_xor_b32 s32, s32, s51
	s_add_i32 s95, s94, 1
	s_sub_i32 s100, s33, s49
	s_cmp_ge_u32 s33, s49
	s_cselect_b32 s94, s95, s94
	s_cselect_b32 s33, s100, s33
	s_add_i32 s95, s94, 1
	s_cmp_ge_u32 s33, s49
	s_cselect_b32 s33, s95, s94
	s_xor_b32 s33, s33, s32
	s_sub_i32 s32, s33, s32
	s_mul_i32 s33, s52, s32
	s_add_i32 s33, s98, s33
	s_and_b32 s94, s33, 7
	s_ashr_i32 s33, s33, 3
	s_mul_i32 s32, s32, s44
	s_add_i32 s32, s32, s33
	s_mul_hi_i32 s33, s32, 0x92492493
	s_add_i32 s33, s33, s32
	s_lshr_b32 s95, s33, 31
	s_ashr_i32 s33, s33, 5
	s_add_i32 s33, s33, s95
	s_mul_i32 s95, s33, 0xffffffc8
	s_add_i32 s95, s95, s32
	s_lshl_b32 s32, s33, 3
	s_or_b32 s32, s32, s94
	s_lshr_b32 s33, s32, 31
	s_add_i32 s33, s32, s33
	s_and_b32 s94, s33, -2
	s_sub_i32 s32, s32, s94
	s_mul_hi_i32 s94, s95, 0x92492493
	s_add_i32 s94, s94, s95
	s_lshr_b32 s100, s94, 31
	s_ashr_i32 s94, s94, 2
	s_add_i32 s94, s94, s100
	s_mul_i32 s100, s94, 7
	s_mul_i32 s32, s32, 7
	s_sub_i32 s95, s95, s100
	s_add_i32 s101, s32, s95
	s_lshl_b32 s32, s33, 2
	s_and_b32 s32, s32, -8
	s_add_i32 s99, s32, s94
	s_lshl_b32 s32, s101, 19
	s_add_u32 s32, s45, s32
	s_addc_u32 s33, s46, 0
	s_mul_i32 s94, s99, 0x60000
	s_add_u32 s94, s47, s94
	s_addc_u32 s95, s48, 0
	v_lshrrev_b32_e32 v162, 3, v212
	v_and_b32_e32 v163, 7, v212
	v_lshlrev_b32_e32 v162, 11, v162
	v_lshl_or_b32 v162, v163, 4, v162
	v_add_u32_e32 v163, 0x20000, v162
	v_add_u32_e32 v164, 0x40000, v162
	v_add_u32_e32 v165, 0x60000, v162
	global_load_dwordx4 v[214:217], v162, s[32:33]
	global_load_dwordx4 v[218:221], v163, s[32:33]
	global_load_dwordx4 v[222:225], v164, s[32:33]
	global_load_dwordx4 v[226:229], v165, s[32:33]
	global_load_dwordx4 v[230:233], v162, s[94:95]
	global_load_dwordx4 v[234:237], v163, s[94:95]
	global_load_dwordx4 v[238:241], v164, s[94:95]
	global_load_dwordx4 v[194:197], v162, s[32:33] offset:128
	global_load_dwordx4 v[198:201], v163, s[32:33] offset:128
	global_load_dwordx4 v[246:249], v164, s[32:33] offset:128
	global_load_dwordx4 v[250:253], v165, s[32:33] offset:128
	global_load_dwordx4 v[186:189], v162, s[94:95] offset:128
	global_load_dwordx4 v[190:193], v163, s[94:95] offset:128
	global_load_dwordx2 v[242:243], v164, s[94:95] offset:128
	global_load_dwordx2 v[254:255], v164, s[94:95] offset:136
	s_mov_b32 s101, 1
	s_branch .Lg1x_pfd

.LBB0_629:
	s_ashr_i32 s4, s3, 31
	s_lshr_b32 s4, s4, 30
	s_add_i32 s4, s3, s4
	s_and_b32 s4, s4, 0xfffffc
	s_sub_i32 s3, s3, s4
	s_lshl_b32 s4, s3, 8
	s_ashr_i32 s5, s4, 31
	v_mov_b32_e32 v50, v212
	s_lshl_b32 s12, s14, 7
	s_lshl_b64 s[16:17], s[4:5], 11
	s_add_u32 s16, s19, s16
	v_ashrrev_i32_e32 v26, 3, v50
	v_ashrrev_i32_e32 v27, 31, v26
	s_addc_u32 s17, s20, s17
	v_lshlrev_b64 v[2:3], 11, v[26:27]
	v_lshlrev_b32_e32 v6, 4, v50
	v_lshl_add_u64 v[4:5], s[16:17], 0, v[2:3]
	v_and_b32_e32 v66, 0x70, v6
	v_lshl_add_u64 v[74:75], v[4:5], 0, v[66:67]
	v_add_co_u32_e32 v78, vcc, s36, v74
	s_ashr_i32 s13, s12, 31
	s_nop 0
	v_addc_co_u32_e32 v79, vcc, 0, v75, vcc
	s_lshl_b64 s[44:45], s[12:13], 11
	v_add_co_u32_e32 v80, vcc, s37, v74
	s_add_u32 s44, s21, s44
	s_nop 0
	v_addc_co_u32_e32 v81, vcc, 0, v75, vcc
	s_addc_u32 s45, s22, s45
	v_add_co_u32_e32 v82, vcc, s38, v74
	v_lshl_add_u64 v[2:3], s[44:45], 0, v[2:3]
	s_nop 0
	v_addc_co_u32_e32 v83, vcc, 0, v75, vcc
	v_lshl_add_u64 v[76:77], v[2:3], 0, v[66:67]
	global_load_dwordx4 v[2:5], v[74:75], off
	global_load_dwordx4 v[6:9], v[78:79], off
	global_load_dwordx4 v[10:13], v[80:81], off
	global_load_dwordx4 v[14:17], v[82:83], off
	global_load_dwordx4 v[18:21], v[76:77], off
	v_add_co_u32_e32 v84, vcc, s36, v76
	v_mad_u64_u32 v[72:73], s[16:17], v26, s34, v[66:67]
	s_nop 0
	v_addc_co_u32_e32 v85, vcc, 0, v77, vcc
	global_load_dwordx4 v[22:25], v[84:85], off
	global_load_dwordx4 v[26:29], v[74:75], off offset:128
	global_load_dwordx4 v[30:33], v[78:79], off offset:128
	global_load_dwordx4 v[34:37], v[82:83], off offset:128
	global_load_dwordx4 v[98:101], v[78:79], off offset:256
	global_load_dwordx4 v[38:41], v[80:81], off offset:128
	global_load_dwordx4 v[102:105], v[80:81], off offset:256
	global_load_dwordx4 v[106:109], v[74:75], off offset:256
	global_load_dwordx4 v[42:45], v[76:77], off offset:128
	global_load_dwordx4 v[110:113], v[76:77], off offset:256
	global_load_dwordx4 v[114:117], v[82:83], off offset:256
	global_load_dwordx4 v[46:49], v[84:85], off offset:128
	global_load_dwordx4 v[118:121], v[84:85], off offset:256
	v_and_b32_e32 v68, 63, v69
	v_add_u32_e32 v97, 0x12000, v72
	s_waitcnt vmcnt(17)
	ds_write_b128 v72, v[2:5]
	s_waitcnt vmcnt(16)
	ds_write_b128 v72, v[6:9] offset:9216
	s_waitcnt vmcnt(15)
	ds_write_b128 v72, v[10:13] offset:18432
	s_waitcnt vmcnt(14)
	ds_write_b128 v72, v[14:17] offset:27648
	s_waitcnt vmcnt(13)
	ds_write_b128 v72, v[18:21] offset:36864
	s_waitcnt vmcnt(12)
	ds_write_b128 v72, v[22:25] offset:46080
	s_waitcnt lgkmcnt(0)
	s_barrier
	global_load_dwordx4 v[122:125], v[78:79], off offset:384
	global_load_dwordx4 v[126:129], v[80:81], off offset:384
	global_load_dwordx4 v[130:133], v[74:75], off offset:384
	global_load_dwordx4 v[134:137], v[76:77], off offset:384
	global_load_dwordx4 v[138:141], v[82:83], off offset:384
	global_load_dwordx4 v[142:145], v[84:85], off offset:384
	v_and_b32_e32 v2, 31, v50
	v_lshrrev_b32_e32 v3, 1, v50
	v_and_or_b32 v4, v3, s35, v2
	v_and_b32_e32 v2, 16, v3
	v_and_b32_e32 v3, 0x5f, v50
	v_mad_u32_u24 v73, v3, s34, v2
	v_add_u32_e32 v66, 0x12000, v73
	s_waitcnt vmcnt(17)
	ds_write_b128 v97, v[26:29]
	s_waitcnt vmcnt(16)
	ds_write_b128 v97, v[30:33] offset:9216
	s_waitcnt vmcnt(13)
	ds_write_b128 v97, v[38:41] offset:18432
	ds_write_b128 v97, v[34:37] offset:27648
	s_waitcnt vmcnt(10)
	ds_write_b128 v97, v[42:45] offset:36864
	s_waitcnt vmcnt(7)
	ds_write_b128 v97, v[46:49] offset:46080
	v_mad_u64_u32 v[70:71], s[16:17], v4, s34, v[2:3]
	ds_read_b128 v[2:5], v73 offset:36864
	ds_read_b128 v[146:149], v73 offset:36896
	ds_read_b128 v[6:9], v73 offset:41472
	ds_read_b128 v[150:153], v73 offset:41504
	ds_read_b128 v[10:13], v70
	ds_read_b128 v[154:157], v70 offset:32
	ds_read_b128 v[14:17], v70 offset:4608
	ds_read_b128 v[158:161], v70 offset:4640
	s_waitcnt lgkmcnt(3)
	v_mfma_f32_32x32x16_bf16 v[50:65], v[10:13], v[2:5], 0
	v_mfma_f32_32x32x16_bf16 v[18:33], v[10:13], v[6:9], 0
	s_waitcnt lgkmcnt(1)
	v_mfma_f32_32x32x16_bf16 v[34:49], v[14:17], v[2:5], 0
	v_mfma_f32_32x32x16_bf16 v[2:17], v[14:17], v[6:9], 0
	ds_read_b128 v[162:165], v73 offset:36928
	ds_read_b128 v[166:169], v73 offset:41536
	ds_read_b128 v[170:173], v70 offset:64
	ds_read_b128 v[174:177], v70 offset:4672
	v_mfma_f32_32x32x16_bf16 v[50:65], v[154:157], v[146:149], v[50:65]
	s_waitcnt lgkmcnt(4)
	v_mfma_f32_32x32x16_bf16 v[2:17], v[158:161], v[150:153], v[2:17]
	v_mfma_f32_32x32x16_bf16 v[18:33], v[154:157], v[150:153], v[18:33]
	v_mfma_f32_32x32x16_bf16 v[34:49], v[158:161], v[146:149], v[34:49]
	ds_read_b128 v[146:149], v73 offset:36960
	ds_read_b128 v[150:153], v73 offset:41568
	ds_read_b128 v[154:157], v70 offset:96
	ds_read_b128 v[158:161], v70 offset:4704
	s_waitcnt lgkmcnt(5)
	v_mfma_f32_32x32x16_bf16 v[50:65], v[170:173], v[162:165], v[50:65]
	s_waitcnt lgkmcnt(4)
	v_mfma_f32_32x32x16_bf16 v[2:17], v[174:177], v[166:169], v[2:17]
	v_mfma_f32_32x32x16_bf16 v[18:33], v[170:173], v[166:169], v[18:33]
	v_mfma_f32_32x32x16_bf16 v[34:49], v[174:177], v[162:165], v[34:49]
	s_waitcnt lgkmcnt(1)
	v_mfma_f32_32x32x16_bf16 v[50:65], v[154:157], v[146:149], v[50:65]
	s_waitcnt lgkmcnt(0)
	v_mfma_f32_32x32x16_bf16 v[2:17], v[158:161], v[150:153], v[2:17]
	v_mfma_f32_32x32x16_bf16 v[18:33], v[154:157], v[150:153], v[18:33]
	v_mfma_f32_32x32x16_bf16 v[34:49], v[158:161], v[146:149], v[34:49]
	s_barrier
	global_load_dwordx4 v[146:149], v[78:79], off offset:512
	global_load_dwordx4 v[150:153], v[80:81], off offset:512
	global_load_dwordx4 v[154:157], v[74:75], off offset:512
	global_load_dwordx4 v[158:161], v[76:77], off offset:512
	global_load_dwordx4 v[162:165], v[82:83], off offset:512
	global_load_dwordx4 v[166:169], v[84:85], off offset:512
	ds_write_b128 v72, v[106:109]
	ds_write_b128 v72, v[98:101] offset:9216
	ds_write_b128 v72, v[102:105] offset:18432
	ds_write_b128 v72, v[114:117] offset:27648
	ds_write_b128 v72, v[110:113] offset:36864
	s_waitcnt vmcnt(12)
	ds_write_b128 v72, v[118:121] offset:46080
	v_add_u32_e32 v71, 0x12000, v70
	ds_read_b128 v[98:101], v66 offset:36864
	ds_read_b128 v[102:105], v66 offset:36896
	ds_read_b128 v[106:109], v66 offset:41472
	ds_read_b128 v[110:113], v66 offset:41504
	ds_read_b128 v[114:117], v71
	ds_read_b128 v[118:121], v71 offset:32
	ds_read_b128 v[170:173], v71 offset:4608
	ds_read_b128 v[174:177], v71 offset:4640
	s_waitcnt lgkmcnt(3)
	v_mfma_f32_32x32x16_bf16 v[50:65], v[114:117], v[98:101], v[50:65]
	s_waitcnt lgkmcnt(1)
	v_mfma_f32_32x32x16_bf16 v[2:17], v[170:173], v[106:109], v[2:17]
	v_mfma_f32_32x32x16_bf16 v[18:33], v[114:117], v[106:109], v[18:33]
	v_mfma_f32_32x32x16_bf16 v[34:49], v[170:173], v[98:101], v[34:49]
	ds_read_b128 v[98:101], v66 offset:36928
	ds_read_b128 v[106:109], v66 offset:41536
	ds_read_b128 v[114:117], v71 offset:64
	ds_read_b128 v[170:173], v71 offset:4672
	v_mfma_f32_32x32x16_bf16 v[50:65], v[118:121], v[102:105], v[50:65]
	s_waitcnt lgkmcnt(4)
	v_mfma_f32_32x32x16_bf16 v[2:17], v[174:177], v[110:113], v[2:17]
	v_mfma_f32_32x32x16_bf16 v[18:33], v[118:121], v[110:113], v[18:33]
	v_mfma_f32_32x32x16_bf16 v[34:49], v[174:177], v[102:105], v[34:49]
	ds_read_b128 v[102:105], v66 offset:36960
	ds_read_b128 v[110:113], v66 offset:41568
	ds_read_b128 v[118:121], v71 offset:96
	ds_read_b128 v[174:177], v71 offset:4704
	s_waitcnt lgkmcnt(5)
	v_mfma_f32_32x32x16_bf16 v[50:65], v[114:117], v[98:101], v[50:65]
	s_waitcnt lgkmcnt(4)
	v_mfma_f32_32x32x16_bf16 v[2:17], v[170:173], v[106:109], v[2:17]
	v_mfma_f32_32x32x16_bf16 v[18:33], v[114:117], v[106:109], v[18:33]
	v_mfma_f32_32x32x16_bf16 v[34:49], v[170:173], v[98:101], v[34:49]
	s_waitcnt lgkmcnt(1)
	v_mfma_f32_32x32x16_bf16 v[50:65], v[118:121], v[102:105], v[50:65]
	s_waitcnt lgkmcnt(0)
	v_mfma_f32_32x32x16_bf16 v[2:17], v[174:177], v[110:113], v[2:17]
	v_mfma_f32_32x32x16_bf16 v[18:33], v[118:121], v[110:113], v[18:33]
	v_mfma_f32_32x32x16_bf16 v[34:49], v[174:177], v[102:105], v[34:49]
	s_barrier
	global_load_dwordx4 v[98:101], v[78:79], off offset:640
	global_load_dwordx4 v[102:105], v[80:81], off offset:640
	global_load_dwordx4 v[106:109], v[74:75], off offset:640
	global_load_dwordx4 v[110:113], v[76:77], off offset:640
	global_load_dwordx4 v[114:117], v[82:83], off offset:640
	global_load_dwordx4 v[118:121], v[84:85], off offset:640
	v_readfirstlane_b32 s98, v212
	v_readlane_b32 s100, v245, 32
	v_readlane_b32 s101, v245, 33
	v_and_b32_e32 v246, 63, v212
	s_lshr_b32 s98, s98, 2
	s_add_i32 s98, s98, s12
	s_cmpk_lt_i32 s98, 0x2000
	s_cbranch_scc1 .Lg2p_a
	v_readlane_b32 s100, v245, 34
	v_readlane_b32 s101, v245, 35
	s_addk_i32 s98, 0xe000
.Lg2p_a:
	v_lshlrev_b32_e32 v246, 4, v246
	s_lshl_b32 s98, s98, 12
	s_lshl_b32 s99, s4, 2
	s_add_u32 s100, s100, s98
	s_addc_u32 s101, s101, 0
	s_add_u32 s100, s100, s99
	s_addc_u32 s101, s101, 0
	s_add_u32 s100, s100, 0x1000
	s_addc_u32 s101, s101, 0
	global_load_dwordx4 v[178:181], v246, s[100:101] offset:-4096
	global_load_dwordx4 v[182:185], v246, s[100:101]
	s_add_u32 s100, s100, 0x2000
	s_addc_u32 s101, s101, 0
	global_load_dwordx4 v[186:189], v246, s[100:101] offset:-4096
	global_load_dwordx4 v[190:193], v246, s[100:101]
	s_add_u32 s100, s100, 0x2000
	s_addc_u32 s101, s101, 0
	global_load_dwordx4 v[194:197], v246, s[100:101] offset:-4096
	global_load_dwordx4 v[198:201], v246, s[100:101]
	s_add_u32 s100, s100, 0x2000
	s_addc_u32 s101, s101, 0
	global_load_dwordx4 v[202:205], v246, s[100:101] offset:-4096
	global_load_dwordx4 v[206:209], v246, s[100:101]
	s_add_u32 s100, s100, 0x2000
	s_addc_u32 s101, s101, 0
	global_load_dwordx4 v[214:217], v246, s[100:101] offset:-4096
	global_load_dwordx4 v[218:221], v246, s[100:101]
	s_add_u32 s100, s100, 0x2000
	s_addc_u32 s101, s101, 0
	global_load_dwordx4 v[222:225], v246, s[100:101] offset:-4096
	global_load_dwordx4 v[226:229], v246, s[100:101]
	s_add_u32 s100, s100, 0x2000
	s_addc_u32 s101, s101, 0
	global_load_dwordx4 v[230:233], v246, s[100:101] offset:-4096
	global_load_dwordx4 v[234:237], v246, s[100:101]
	s_add_u32 s100, s100, 0x2000
	s_addc_u32 s101, s101, 0
	global_load_dwordx4 v[238:241], v246, s[100:101] offset:-4096
	global_load_dwordx4 v[248:251], v246, s[100:101]
	s_waitcnt vmcnt(31)
	ds_write_b128 v97, v[130:133]
	ds_write_b128 v97, v[122:125] offset:9216
	ds_write_b128 v97, v[126:129] offset:18432
	s_waitcnt vmcnt(29)
	ds_write_b128 v97, v[138:141] offset:27648
	ds_write_b128 v97, v[134:137] offset:36864
	s_waitcnt vmcnt(28)
	ds_write_b128 v97, v[142:145] offset:46080
	ds_read_b128 v[122:125], v73 offset:36864
	ds_read_b128 v[126:129], v73 offset:36896
	ds_read_b128 v[130:133], v73 offset:41472
	ds_read_b128 v[134:137], v73 offset:41504
	ds_read_b128 v[138:141], v70
	ds_read_b128 v[142:145], v70 offset:32
	ds_read_b128 v[170:173], v70 offset:4608
	ds_read_b128 v[174:177], v70 offset:4640
	s_waitcnt lgkmcnt(3)
	v_mfma_f32_32x32x16_bf16 v[50:65], v[138:141], v[122:125], v[50:65]
	s_waitcnt lgkmcnt(1)
	v_mfma_f32_32x32x16_bf16 v[2:17], v[170:173], v[130:133], v[2:17]
	v_mfma_f32_32x32x16_bf16 v[18:33], v[138:141], v[130:133], v[18:33]
	v_mfma_f32_32x32x16_bf16 v[34:49], v[170:173], v[122:125], v[34:49]
	ds_read_b128 v[122:125], v73 offset:36928
	ds_read_b128 v[130:133], v73 offset:41536
	ds_read_b128 v[138:141], v70 offset:64
	ds_read_b128 v[170:173], v70 offset:4672
	v_mfma_f32_32x32x16_bf16 v[50:65], v[142:145], v[126:129], v[50:65]
	s_waitcnt lgkmcnt(4)
	v_mfma_f32_32x32x16_bf16 v[2:17], v[174:177], v[134:137], v[2:17]
	v_mfma_f32_32x32x16_bf16 v[18:33], v[142:145], v[134:137], v[18:33]
	v_mfma_f32_32x32x16_bf16 v[34:49], v[174:177], v[126:129], v[34:49]
	ds_read_b128 v[126:129], v73 offset:36960
	ds_read_b128 v[134:137], v73 offset:41568
	ds_read_b128 v[142:145], v70 offset:96
	ds_read_b128 v[174:177], v70 offset:4704
	s_waitcnt lgkmcnt(5)
	v_mfma_f32_32x32x16_bf16 v[50:65], v[138:141], v[122:125], v[50:65]
	s_waitcnt lgkmcnt(4)
	v_mfma_f32_32x32x16_bf16 v[2:17], v[170:173], v[130:133], v[2:17]
	v_mfma_f32_32x32x16_bf16 v[18:33], v[138:141], v[130:133], v[18:33]
	v_mfma_f32_32x32x16_bf16 v[34:49], v[170:173], v[122:125], v[34:49]
	s_waitcnt lgkmcnt(1)
	v_mfma_f32_32x32x16_bf16 v[50:65], v[142:145], v[126:129], v[50:65]
	s_waitcnt lgkmcnt(0)
	v_mfma_f32_32x32x16_bf16 v[2:17], v[174:177], v[134:137], v[2:17]
	v_mfma_f32_32x32x16_bf16 v[18:33], v[142:145], v[134:137], v[18:33]
	v_mfma_f32_32x32x16_bf16 v[34:49], v[174:177], v[126:129], v[34:49]
	s_barrier
	global_load_dwordx4 v[122:125], v[78:79], off offset:768
	global_load_dwordx4 v[126:129], v[80:81], off offset:768
	global_load_dwordx4 v[130:133], v[74:75], off offset:768
	global_load_dwordx4 v[134:137], v[76:77], off offset:768
	global_load_dwordx4 v[138:141], v[82:83], off offset:768
	global_load_dwordx4 v[142:145], v[84:85], off offset:768
	s_waitcnt vmcnt(31)
	ds_write_b128 v72, v[154:157]
	ds_write_b128 v72, v[146:149] offset:9216
	ds_write_b128 v72, v[150:153] offset:18432
	s_waitcnt vmcnt(29)
	ds_write_b128 v72, v[162:165] offset:27648
	ds_write_b128 v72, v[158:161] offset:36864
	s_waitcnt vmcnt(28)
	ds_write_b128 v72, v[166:169] offset:46080
	ds_read_b128 v[146:149], v66 offset:36864
	ds_read_b128 v[150:153], v66 offset:36896
	ds_read_b128 v[154:157], v66 offset:41472
	ds_read_b128 v[158:161], v66 offset:41504
	ds_read_b128 v[162:165], v71
	ds_read_b128 v[166:169], v71 offset:32
	ds_read_b128 v[170:173], v71 offset:4608
	ds_read_b128 v[174:177], v71 offset:4640
	s_waitcnt lgkmcnt(3)
	v_mfma_f32_32x32x16_bf16 v[50:65], v[162:165], v[146:149], v[50:65]
	s_waitcnt lgkmcnt(1)
	v_mfma_f32_32x32x16_bf16 v[2:17], v[170:173], v[154:157], v[2:17]
	v_mfma_f32_32x32x16_bf16 v[18:33], v[162:165], v[154:157], v[18:33]
	v_mfma_f32_32x32x16_bf16 v[34:49], v[170:173], v[146:149], v[34:49]
	ds_read_b128 v[146:149], v66 offset:36928
	ds_read_b128 v[154:157], v66 offset:41536
	ds_read_b128 v[162:165], v71 offset:64
	ds_read_b128 v[170:173], v71 offset:4672
	v_mfma_f32_32x32x16_bf16 v[50:65], v[166:169], v[150:153], v[50:65]
	s_waitcnt lgkmcnt(4)
	v_mfma_f32_32x32x16_bf16 v[2:17], v[174:177], v[158:161], v[2:17]
	v_mfma_f32_32x32x16_bf16 v[18:33], v[166:169], v[158:161], v[18:33]
	v_mfma_f32_32x32x16_bf16 v[34:49], v[174:177], v[150:153], v[34:49]
	ds_read_b128 v[150:153], v66 offset:36960
	ds_read_b128 v[158:161], v66 offset:41568
	ds_read_b128 v[166:169], v71 offset:96
	ds_read_b128 v[174:177], v71 offset:4704
	s_waitcnt lgkmcnt(5)
	v_mfma_f32_32x32x16_bf16 v[50:65], v[162:165], v[146:149], v[50:65]
	s_waitcnt lgkmcnt(4)
	v_mfma_f32_32x32x16_bf16 v[2:17], v[170:173], v[154:157], v[2:17]
	v_mfma_f32_32x32x16_bf16 v[18:33], v[162:165], v[154:157], v[18:33]
	v_mfma_f32_32x32x16_bf16 v[34:49], v[170:173], v[146:149], v[34:49]
	s_waitcnt lgkmcnt(1)
	v_mfma_f32_32x32x16_bf16 v[50:65], v[166:169], v[150:153], v[50:65]
	s_waitcnt lgkmcnt(0)
	v_mfma_f32_32x32x16_bf16 v[2:17], v[174:177], v[158:161], v[2:17]
	v_mfma_f32_32x32x16_bf16 v[18:33], v[166:169], v[158:161], v[18:33]
	v_mfma_f32_32x32x16_bf16 v[34:49], v[174:177], v[150:153], v[34:49]
	s_barrier
	global_load_dwordx4 v[146:149], v[78:79], off offset:896
	global_load_dwordx4 v[150:153], v[80:81], off offset:896
	global_load_dwordx4 v[154:157], v[74:75], off offset:896
	global_load_dwordx4 v[158:161], v[76:77], off offset:896
	global_load_dwordx4 v[162:165], v[82:83], off offset:896
	global_load_dwordx4 v[166:169], v[84:85], off offset:896
	s_waitcnt vmcnt(31)
	ds_write_b128 v97, v[106:109]
	ds_write_b128 v97, v[98:101] offset:9216
	ds_write_b128 v97, v[102:105] offset:18432
	s_waitcnt vmcnt(29)
	ds_write_b128 v97, v[114:117] offset:27648
	ds_write_b128 v97, v[110:113] offset:36864
	s_waitcnt vmcnt(28)
	ds_write_b128 v97, v[118:121] offset:46080
	ds_read_b128 v[98:101], v73 offset:36864
	ds_read_b128 v[102:105], v73 offset:36896
	ds_read_b128 v[106:109], v73 offset:41472
	ds_read_b128 v[110:113], v73 offset:41504
	ds_read_b128 v[114:117], v70
	ds_read_b128 v[118:121], v70 offset:32
	ds_read_b128 v[170:173], v70 offset:4608
	ds_read_b128 v[174:177], v70 offset:4640
	s_waitcnt lgkmcnt(3)
	v_mfma_f32_32x32x16_bf16 v[50:65], v[114:117], v[98:101], v[50:65]
	s_waitcnt lgkmcnt(1)
	v_mfma_f32_32x32x16_bf16 v[2:17], v[170:173], v[106:109], v[2:17]
	v_mfma_f32_32x32x16_bf16 v[18:33], v[114:117], v[106:109], v[18:33]
	v_mfma_f32_32x32x16_bf16 v[34:49], v[170:173], v[98:101], v[34:49]
	ds_read_b128 v[98:101], v73 offset:36928
	ds_read_b128 v[106:109], v73 offset:41536
	ds_read_b128 v[114:117], v70 offset:64
	ds_read_b128 v[170:173], v70 offset:4672
	v_mfma_f32_32x32x16_bf16 v[50:65], v[118:121], v[102:105], v[50:65]
	s_waitcnt lgkmcnt(4)
	v_mfma_f32_32x32x16_bf16 v[2:17], v[174:177], v[110:113], v[2:17]
	v_mfma_f32_32x32x16_bf16 v[18:33], v[118:121], v[110:113], v[18:33]
	v_mfma_f32_32x32x16_bf16 v[34:49], v[174:177], v[102:105], v[34:49]
	ds_read_b128 v[102:105], v73 offset:36960
	ds_read_b128 v[110:113], v73 offset:41568
	ds_read_b128 v[118:121], v70 offset:96
	ds_read_b128 v[174:177], v70 offset:4704
	s_waitcnt lgkmcnt(5)
	v_mfma_f32_32x32x16_bf16 v[50:65], v[114:117], v[98:101], v[50:65]
	s_waitcnt lgkmcnt(4)
	v_mfma_f32_32x32x16_bf16 v[2:17], v[170:173], v[106:109], v[2:17]
	v_mfma_f32_32x32x16_bf16 v[18:33], v[114:117], v[106:109], v[18:33]
	v_mfma_f32_32x32x16_bf16 v[34:49], v[170:173], v[98:101], v[34:49]
	s_waitcnt lgkmcnt(1)
	v_mfma_f32_32x32x16_bf16 v[50:65], v[118:121], v[102:105], v[50:65]
	s_waitcnt lgkmcnt(0)
	v_mfma_f32_32x32x16_bf16 v[2:17], v[174:177], v[110:113], v[2:17]
	v_mfma_f32_32x32x16_bf16 v[18:33], v[118:121], v[110:113], v[18:33]
	v_mfma_f32_32x32x16_bf16 v[34:49], v[174:177], v[102:105], v[34:49]
	s_barrier
	global_load_dwordx4 v[98:101], v[78:79], off offset:1024
	global_load_dwordx4 v[102:105], v[80:81], off offset:1024
	global_load_dwordx4 v[106:109], v[74:75], off offset:1024
	global_load_dwordx4 v[110:113], v[76:77], off offset:1024
	global_load_dwordx4 v[114:117], v[82:83], off offset:1024
	global_load_dwordx4 v[118:121], v[84:85], off offset:1024
	s_waitcnt vmcnt(15)
	ds_write_b128 v72, v[130:133]
	ds_write_b128 v72, v[122:125] offset:9216
	ds_write_b128 v72, v[126:129] offset:18432
	s_waitcnt vmcnt(13)
	ds_write_b128 v72, v[138:141] offset:27648
	ds_write_b128 v72, v[134:137] offset:36864
	s_waitcnt vmcnt(12)
	ds_write_b128 v72, v[142:145] offset:46080
	ds_read_b128 v[122:125], v66 offset:36864
	ds_read_b128 v[126:129], v66 offset:36896
	ds_read_b128 v[130:133], v66 offset:41472
	ds_read_b128 v[134:137], v66 offset:41504
	ds_read_b128 v[138:141], v71
	ds_read_b128 v[142:145], v71 offset:32
	ds_read_b128 v[170:173], v71 offset:4608
	ds_read_b128 v[174:177], v71 offset:4640
	s_waitcnt lgkmcnt(3)
	v_mfma_f32_32x32x16_bf16 v[50:65], v[138:141], v[122:125], v[50:65]
	s_waitcnt lgkmcnt(1)
	v_mfma_f32_32x32x16_bf16 v[2:17], v[170:173], v[130:133], v[2:17]
	v_mfma_f32_32x32x16_bf16 v[18:33], v[138:141], v[130:133], v[18:33]
	v_mfma_f32_32x32x16_bf16 v[34:49], v[170:173], v[122:125], v[34:49]
	ds_read_b128 v[122:125], v66 offset:36928
	ds_read_b128 v[130:133], v66 offset:41536
	ds_read_b128 v[138:141], v71 offset:64
	ds_read_b128 v[170:173], v71 offset:4672
	v_mfma_f32_32x32x16_bf16 v[50:65], v[142:145], v[126:129], v[50:65]
	s_waitcnt lgkmcnt(4)
	v_mfma_f32_32x32x16_bf16 v[2:17], v[174:177], v[134:137], v[2:17]
	v_mfma_f32_32x32x16_bf16 v[18:33], v[142:145], v[134:137], v[18:33]
	v_mfma_f32_32x32x16_bf16 v[34:49], v[174:177], v[126:129], v[34:49]
	ds_read_b128 v[126:129], v66 offset:36960
	ds_read_b128 v[134:137], v66 offset:41568
	ds_read_b128 v[142:145], v71 offset:96
	ds_read_b128 v[174:177], v71 offset:4704
	s_waitcnt lgkmcnt(5)
	v_mfma_f32_32x32x16_bf16 v[50:65], v[138:141], v[122:125], v[50:65]
	s_waitcnt lgkmcnt(4)
	v_mfma_f32_32x32x16_bf16 v[2:17], v[170:173], v[130:133], v[2:17]
	v_mfma_f32_32x32x16_bf16 v[18:33], v[138:141], v[130:133], v[18:33]
	v_mfma_f32_32x32x16_bf16 v[34:49], v[170:173], v[122:125], v[34:49]
	s_waitcnt lgkmcnt(1)
	v_mfma_f32_32x32x16_bf16 v[50:65], v[142:145], v[126:129], v[50:65]
	s_waitcnt lgkmcnt(0)
	v_mfma_f32_32x32x16_bf16 v[2:17], v[174:177], v[134:137], v[2:17]
	v_mfma_f32_32x32x16_bf16 v[18:33], v[142:145], v[134:137], v[18:33]
	v_mfma_f32_32x32x16_bf16 v[34:49], v[174:177], v[126:129], v[34:49]
	s_barrier
	global_load_dwordx4 v[122:125], v[78:79], off offset:1152
	global_load_dwordx4 v[126:129], v[80:81], off offset:1152
	global_load_dwordx4 v[130:133], v[74:75], off offset:1152
	global_load_dwordx4 v[134:137], v[76:77], off offset:1152
	global_load_dwordx4 v[138:141], v[82:83], off offset:1152
	global_load_dwordx4 v[142:145], v[84:85], off offset:1152
	s_waitcnt vmcnt(15)
	ds_write_b128 v97, v[154:157]
	ds_write_b128 v97, v[146:149] offset:9216
	ds_write_b128 v97, v[150:153] offset:18432
	s_waitcnt vmcnt(13)
	ds_write_b128 v97, v[162:165] offset:27648
	ds_write_b128 v97, v[158:161] offset:36864
	s_waitcnt vmcnt(12)
	ds_write_b128 v97, v[166:169] offset:46080
	ds_read_b128 v[146:149], v73 offset:36864
	ds_read_b128 v[150:153], v73 offset:36896
	ds_read_b128 v[154:157], v73 offset:41472
	ds_read_b128 v[158:161], v73 offset:41504
	ds_read_b128 v[162:165], v70
	ds_read_b128 v[166:169], v70 offset:32
	ds_read_b128 v[170:173], v70 offset:4608
	ds_read_b128 v[174:177], v70 offset:4640
	s_waitcnt lgkmcnt(3)
	v_mfma_f32_32x32x16_bf16 v[50:65], v[162:165], v[146:149], v[50:65]
	s_waitcnt lgkmcnt(1)
	v_mfma_f32_32x32x16_bf16 v[2:17], v[170:173], v[154:157], v[2:17]
	v_mfma_f32_32x32x16_bf16 v[18:33], v[162:165], v[154:157], v[18:33]
	v_mfma_f32_32x32x16_bf16 v[34:49], v[170:173], v[146:149], v[34:49]
	ds_read_b128 v[146:149], v73 offset:36928
	ds_read_b128 v[154:157], v73 offset:41536
	ds_read_b128 v[162:165], v70 offset:64
	ds_read_b128 v[170:173], v70 offset:4672
	v_mfma_f32_32x32x16_bf16 v[50:65], v[166:169], v[150:153], v[50:65]
	s_waitcnt lgkmcnt(4)
	v_mfma_f32_32x32x16_bf16 v[2:17], v[174:177], v[158:161], v[2:17]
	v_mfma_f32_32x32x16_bf16 v[18:33], v[166:169], v[158:161], v[18:33]
	v_mfma_f32_32x32x16_bf16 v[34:49], v[174:177], v[150:153], v[34:49]
	ds_read_b128 v[150:153], v73 offset:36960
	ds_read_b128 v[158:161], v73 offset:41568
	ds_read_b128 v[166:169], v70 offset:96
	ds_read_b128 v[174:177], v70 offset:4704
	s_waitcnt lgkmcnt(5)
	v_mfma_f32_32x32x16_bf16 v[50:65], v[162:165], v[146:149], v[50:65]
	s_waitcnt lgkmcnt(4)
	v_mfma_f32_32x32x16_bf16 v[2:17], v[170:173], v[154:157], v[2:17]
	v_mfma_f32_32x32x16_bf16 v[18:33], v[162:165], v[154:157], v[18:33]
	v_mfma_f32_32x32x16_bf16 v[34:49], v[170:173], v[146:149], v[34:49]
	s_waitcnt lgkmcnt(1)
	v_mfma_f32_32x32x16_bf16 v[50:65], v[166:169], v[150:153], v[50:65]
	s_waitcnt lgkmcnt(0)
	v_mfma_f32_32x32x16_bf16 v[2:17], v[174:177], v[158:161], v[2:17]
	v_mfma_f32_32x32x16_bf16 v[18:33], v[166:169], v[158:161], v[18:33]
	v_mfma_f32_32x32x16_bf16 v[34:49], v[174:177], v[150:153], v[34:49]
	s_barrier
	global_load_dwordx4 v[146:149], v[78:79], off offset:1280
	global_load_dwordx4 v[150:153], v[80:81], off offset:1280
	global_load_dwordx4 v[154:157], v[74:75], off offset:1280
	global_load_dwordx4 v[158:161], v[76:77], off offset:1280
	global_load_dwordx4 v[162:165], v[82:83], off offset:1280
	global_load_dwordx4 v[166:169], v[84:85], off offset:1280
	s_waitcnt vmcnt(15)
	ds_write_b128 v72, v[106:109]
	ds_write_b128 v72, v[98:101] offset:9216
	ds_write_b128 v72, v[102:105] offset:18432
	s_waitcnt vmcnt(13)
	ds_write_b128 v72, v[114:117] offset:27648
	ds_write_b128 v72, v[110:113] offset:36864
	s_waitcnt vmcnt(12)
	ds_write_b128 v72, v[118:121] offset:46080
	ds_read_b128 v[98:101], v66 offset:36864
	ds_read_b128 v[102:105], v66 offset:36896
	ds_read_b128 v[106:109], v66 offset:41472
	ds_read_b128 v[110:113], v66 offset:41504
	ds_read_b128 v[114:117], v71
	ds_read_b128 v[118:121], v71 offset:32
	ds_read_b128 v[170:173], v71 offset:4608
	ds_read_b128 v[174:177], v71 offset:4640
	s_waitcnt lgkmcnt(3)
	v_mfma_f32_32x32x16_bf16 v[50:65], v[114:117], v[98:101], v[50:65]
	s_waitcnt lgkmcnt(1)
	v_mfma_f32_32x32x16_bf16 v[2:17], v[170:173], v[106:109], v[2:17]
	v_mfma_f32_32x32x16_bf16 v[18:33], v[114:117], v[106:109], v[18:33]
	v_mfma_f32_32x32x16_bf16 v[34:49], v[170:173], v[98:101], v[34:49]
	ds_read_b128 v[98:101], v66 offset:36928
	ds_read_b128 v[106:109], v66 offset:41536
	ds_read_b128 v[114:117], v71 offset:64
	ds_read_b128 v[170:173], v71 offset:4672
	v_mfma_f32_32x32x16_bf16 v[50:65], v[118:121], v[102:105], v[50:65]
	s_waitcnt lgkmcnt(4)
	v_mfma_f32_32x32x16_bf16 v[2:17], v[174:177], v[110:113], v[2:17]
	v_mfma_f32_32x32x16_bf16 v[18:33], v[118:121], v[110:113], v[18:33]
	v_mfma_f32_32x32x16_bf16 v[34:49], v[174:177], v[102:105], v[34:49]
	ds_read_b128 v[102:105], v66 offset:36960
	ds_read_b128 v[110:113], v66 offset:41568
	ds_read_b128 v[118:121], v71 offset:96
	ds_read_b128 v[174:177], v71 offset:4704
	s_waitcnt lgkmcnt(5)
	v_mfma_f32_32x32x16_bf16 v[50:65], v[114:117], v[98:101], v[50:65]
	s_waitcnt lgkmcnt(4)
	v_mfma_f32_32x32x16_bf16 v[2:17], v[170:173], v[106:109], v[2:17]
	v_mfma_f32_32x32x16_bf16 v[18:33], v[114:117], v[106:109], v[18:33]
	v_mfma_f32_32x32x16_bf16 v[34:49], v[170:173], v[98:101], v[34:49]
	s_waitcnt lgkmcnt(1)
	v_mfma_f32_32x32x16_bf16 v[50:65], v[118:121], v[102:105], v[50:65]
	s_waitcnt lgkmcnt(0)
	v_mfma_f32_32x32x16_bf16 v[2:17], v[174:177], v[110:113], v[2:17]
	v_mfma_f32_32x32x16_bf16 v[18:33], v[118:121], v[110:113], v[18:33]
	v_mfma_f32_32x32x16_bf16 v[34:49], v[174:177], v[102:105], v[34:49]
	s_barrier
	global_load_dwordx4 v[98:101], v[78:79], off offset:1408
	global_load_dwordx4 v[102:105], v[80:81], off offset:1408
	global_load_dwordx4 v[106:109], v[74:75], off offset:1408
	global_load_dwordx4 v[110:113], v[76:77], off offset:1408
	global_load_dwordx4 v[114:117], v[82:83], off offset:1408
	global_load_dwordx4 v[118:121], v[84:85], off offset:1408
	s_waitcnt vmcnt(15)
	ds_write_b128 v97, v[130:133]
	ds_write_b128 v97, v[122:125] offset:9216
	ds_write_b128 v97, v[126:129] offset:18432
	s_waitcnt vmcnt(13)
	ds_write_b128 v97, v[138:141] offset:27648
	ds_write_b128 v97, v[134:137] offset:36864
	s_waitcnt vmcnt(12)
	ds_write_b128 v97, v[142:145] offset:46080
	ds_read_b128 v[122:125], v73 offset:36864
	ds_read_b128 v[126:129], v73 offset:36896
	ds_read_b128 v[130:133], v73 offset:41472
	ds_read_b128 v[134:137], v73 offset:41504
	ds_read_b128 v[138:141], v70
	ds_read_b128 v[142:145], v70 offset:32
	ds_read_b128 v[170:173], v70 offset:4608
	ds_read_b128 v[174:177], v70 offset:4640
	s_waitcnt lgkmcnt(3)
	v_mfma_f32_32x32x16_bf16 v[50:65], v[138:141], v[122:125], v[50:65]
	s_waitcnt lgkmcnt(1)
	v_mfma_f32_32x32x16_bf16 v[2:17], v[170:173], v[130:133], v[2:17]
	v_mfma_f32_32x32x16_bf16 v[18:33], v[138:141], v[130:133], v[18:33]
	v_mfma_f32_32x32x16_bf16 v[34:49], v[170:173], v[122:125], v[34:49]
	ds_read_b128 v[122:125], v73 offset:36928
	ds_read_b128 v[130:133], v73 offset:41536
	ds_read_b128 v[138:141], v70 offset:64
	ds_read_b128 v[170:173], v70 offset:4672
	v_mfma_f32_32x32x16_bf16 v[50:65], v[142:145], v[126:129], v[50:65]
	s_waitcnt lgkmcnt(4)
	v_mfma_f32_32x32x16_bf16 v[2:17], v[174:177], v[134:137], v[2:17]
	v_mfma_f32_32x32x16_bf16 v[18:33], v[142:145], v[134:137], v[18:33]
	v_mfma_f32_32x32x16_bf16 v[34:49], v[174:177], v[126:129], v[34:49]
	ds_read_b128 v[126:129], v73 offset:36960
	ds_read_b128 v[134:137], v73 offset:41568
	ds_read_b128 v[142:145], v70 offset:96
	ds_read_b128 v[174:177], v70 offset:4704
	s_waitcnt lgkmcnt(5)
	v_mfma_f32_32x32x16_bf16 v[50:65], v[138:141], v[122:125], v[50:65]
	s_waitcnt lgkmcnt(4)
	v_mfma_f32_32x32x16_bf16 v[2:17], v[170:173], v[130:133], v[2:17]
	v_mfma_f32_32x32x16_bf16 v[18:33], v[138:141], v[130:133], v[18:33]
	v_mfma_f32_32x32x16_bf16 v[34:49], v[170:173], v[122:125], v[34:49]
	s_waitcnt lgkmcnt(1)
	v_mfma_f32_32x32x16_bf16 v[50:65], v[142:145], v[126:129], v[50:65]
	s_waitcnt lgkmcnt(0)
	v_mfma_f32_32x32x16_bf16 v[2:17], v[174:177], v[134:137], v[2:17]
	v_mfma_f32_32x32x16_bf16 v[18:33], v[142:145], v[134:137], v[18:33]
	v_mfma_f32_32x32x16_bf16 v[34:49], v[174:177], v[126:129], v[34:49]
	s_barrier
	global_load_dwordx4 v[122:125], v[78:79], off offset:1536
	global_load_dwordx4 v[126:129], v[80:81], off offset:1536
	global_load_dwordx4 v[130:133], v[74:75], off offset:1536
	global_load_dwordx4 v[134:137], v[76:77], off offset:1536
	global_load_dwordx4 v[138:141], v[82:83], off offset:1536
	global_load_dwordx4 v[142:145], v[84:85], off offset:1536
	s_waitcnt vmcnt(15)
	ds_write_b128 v72, v[154:157]
	ds_write_b128 v72, v[146:149] offset:9216
	ds_write_b128 v72, v[150:153] offset:18432
	s_waitcnt vmcnt(13)
	ds_write_b128 v72, v[162:165] offset:27648
	ds_write_b128 v72, v[158:161] offset:36864
	s_waitcnt vmcnt(12)
	ds_write_b128 v72, v[166:169] offset:46080
	ds_read_b128 v[146:149], v66 offset:36864
	ds_read_b128 v[150:153], v66 offset:36896
	ds_read_b128 v[154:157], v66 offset:41472
	ds_read_b128 v[158:161], v66 offset:41504
	ds_read_b128 v[162:165], v71
	ds_read_b128 v[166:169], v71 offset:32
	ds_read_b128 v[170:173], v71 offset:4608
	ds_read_b128 v[174:177], v71 offset:4640
	s_waitcnt lgkmcnt(3)
	v_mfma_f32_32x32x16_bf16 v[50:65], v[162:165], v[146:149], v[50:65]
	s_waitcnt lgkmcnt(1)
	v_mfma_f32_32x32x16_bf16 v[2:17], v[170:173], v[154:157], v[2:17]
	v_mfma_f32_32x32x16_bf16 v[18:33], v[162:165], v[154:157], v[18:33]
	v_mfma_f32_32x32x16_bf16 v[34:49], v[170:173], v[146:149], v[34:49]
	ds_read_b128 v[146:149], v66 offset:36928
	ds_read_b128 v[154:157], v66 offset:41536
	ds_read_b128 v[162:165], v71 offset:64
	ds_read_b128 v[170:173], v71 offset:4672
	v_mfma_f32_32x32x16_bf16 v[50:65], v[166:169], v[150:153], v[50:65]
	s_waitcnt lgkmcnt(4)
	v_mfma_f32_32x32x16_bf16 v[2:17], v[174:177], v[158:161], v[2:17]
	v_mfma_f32_32x32x16_bf16 v[18:33], v[166:169], v[158:161], v[18:33]
	v_mfma_f32_32x32x16_bf16 v[34:49], v[174:177], v[150:153], v[34:49]
	ds_read_b128 v[150:153], v66 offset:36960
	ds_read_b128 v[158:161], v66 offset:41568
	ds_read_b128 v[166:169], v71 offset:96
	ds_read_b128 v[174:177], v71 offset:4704
	s_waitcnt lgkmcnt(5)
	v_mfma_f32_32x32x16_bf16 v[50:65], v[162:165], v[146:149], v[50:65]
	s_waitcnt lgkmcnt(4)
	v_mfma_f32_32x32x16_bf16 v[2:17], v[170:173], v[154:157], v[2:17]
	v_mfma_f32_32x32x16_bf16 v[18:33], v[162:165], v[154:157], v[18:33]
	v_mfma_f32_32x32x16_bf16 v[34:49], v[170:173], v[146:149], v[34:49]
	s_waitcnt lgkmcnt(1)
	v_mfma_f32_32x32x16_bf16 v[50:65], v[166:169], v[150:153], v[50:65]
	s_waitcnt lgkmcnt(0)
	v_mfma_f32_32x32x16_bf16 v[2:17], v[174:177], v[158:161], v[2:17]
	v_mfma_f32_32x32x16_bf16 v[18:33], v[166:169], v[158:161], v[18:33]
	v_mfma_f32_32x32x16_bf16 v[34:49], v[174:177], v[150:153], v[34:49]
	s_barrier
	global_load_dwordx4 v[146:149], v[78:79], off offset:1664
	global_load_dwordx4 v[150:153], v[80:81], off offset:1664
	global_load_dwordx4 v[154:157], v[74:75], off offset:1664
	global_load_dwordx4 v[158:161], v[76:77], off offset:1664
	global_load_dwordx4 v[162:165], v[82:83], off offset:1664
	global_load_dwordx4 v[166:169], v[84:85], off offset:1664
	s_waitcnt vmcnt(15)
	ds_write_b128 v97, v[106:109]
	ds_write_b128 v97, v[98:101] offset:9216
	ds_write_b128 v97, v[102:105] offset:18432
	s_waitcnt vmcnt(13)
	ds_write_b128 v97, v[114:117] offset:27648
	ds_write_b128 v97, v[110:113] offset:36864
	s_waitcnt vmcnt(12)
	ds_write_b128 v97, v[118:121] offset:46080
	ds_read_b128 v[98:101], v73 offset:36864
	ds_read_b128 v[102:105], v73 offset:36896
	ds_read_b128 v[106:109], v73 offset:41472
	ds_read_b128 v[110:113], v73 offset:41504
	ds_read_b128 v[114:117], v70
	ds_read_b128 v[118:121], v70 offset:32
	ds_read_b128 v[170:173], v70 offset:4608
	ds_read_b128 v[174:177], v70 offset:4640
	s_waitcnt lgkmcnt(3)
	v_mfma_f32_32x32x16_bf16 v[50:65], v[114:117], v[98:101], v[50:65]
	s_waitcnt lgkmcnt(1)
	v_mfma_f32_32x32x16_bf16 v[2:17], v[170:173], v[106:109], v[2:17]
	v_mfma_f32_32x32x16_bf16 v[18:33], v[114:117], v[106:109], v[18:33]
	v_mfma_f32_32x32x16_bf16 v[34:49], v[170:173], v[98:101], v[34:49]
	ds_read_b128 v[98:101], v73 offset:36928
	ds_read_b128 v[106:109], v73 offset:41536
	ds_read_b128 v[114:117], v70 offset:64
	ds_read_b128 v[170:173], v70 offset:4672
	v_mfma_f32_32x32x16_bf16 v[50:65], v[118:121], v[102:105], v[50:65]
	s_waitcnt lgkmcnt(4)
	v_mfma_f32_32x32x16_bf16 v[2:17], v[174:177], v[110:113], v[2:17]
	v_mfma_f32_32x32x16_bf16 v[18:33], v[118:121], v[110:113], v[18:33]
	v_mfma_f32_32x32x16_bf16 v[34:49], v[174:177], v[102:105], v[34:49]
	ds_read_b128 v[102:105], v73 offset:36960
	ds_read_b128 v[110:113], v73 offset:41568
	ds_read_b128 v[118:121], v70 offset:96
	ds_read_b128 v[174:177], v70 offset:4704
	s_waitcnt lgkmcnt(5)
	v_mfma_f32_32x32x16_bf16 v[50:65], v[114:117], v[98:101], v[50:65]
	s_waitcnt lgkmcnt(4)
	v_mfma_f32_32x32x16_bf16 v[2:17], v[170:173], v[106:109], v[2:17]
	v_mfma_f32_32x32x16_bf16 v[18:33], v[114:117], v[106:109], v[18:33]
	v_mfma_f32_32x32x16_bf16 v[34:49], v[170:173], v[98:101], v[34:49]
	s_waitcnt lgkmcnt(1)
	v_mfma_f32_32x32x16_bf16 v[50:65], v[118:121], v[102:105], v[50:65]
	s_waitcnt lgkmcnt(0)
	v_mfma_f32_32x32x16_bf16 v[2:17], v[174:177], v[110:113], v[2:17]
	v_mfma_f32_32x32x16_bf16 v[18:33], v[118:121], v[110:113], v[18:33]
	v_mfma_f32_32x32x16_bf16 v[34:49], v[174:177], v[102:105], v[34:49]
	s_barrier
	global_load_dwordx4 v[98:101], v[78:79], off offset:1792
	global_load_dwordx4 v[102:105], v[80:81], off offset:1792
	global_load_dwordx4 v[106:109], v[74:75], off offset:1792
	global_load_dwordx4 v[110:113], v[76:77], off offset:1792
	global_load_dwordx4 v[114:117], v[82:83], off offset:1792
	global_load_dwordx4 v[118:121], v[84:85], off offset:1792
	s_waitcnt vmcnt(15)
	ds_write_b128 v72, v[130:133]
	ds_write_b128 v72, v[122:125] offset:9216
	ds_write_b128 v72, v[126:129] offset:18432
	s_waitcnt vmcnt(13)
	ds_write_b128 v72, v[138:141] offset:27648
	ds_write_b128 v72, v[134:137] offset:36864
	s_waitcnt vmcnt(12)
	ds_write_b128 v72, v[142:145] offset:46080
	ds_read_b128 v[122:125], v66 offset:36864
	ds_read_b128 v[126:129], v66 offset:36896
	ds_read_b128 v[130:133], v66 offset:41472
	ds_read_b128 v[134:137], v66 offset:41504
	ds_read_b128 v[138:141], v71
	ds_read_b128 v[142:145], v71 offset:32
	ds_read_b128 v[170:173], v71 offset:4608
	ds_read_b128 v[174:177], v71 offset:4640
	s_waitcnt lgkmcnt(3)
	v_mfma_f32_32x32x16_bf16 v[50:65], v[138:141], v[122:125], v[50:65]
	s_waitcnt lgkmcnt(1)
	v_mfma_f32_32x32x16_bf16 v[2:17], v[170:173], v[130:133], v[2:17]
	v_mfma_f32_32x32x16_bf16 v[18:33], v[138:141], v[130:133], v[18:33]
	v_mfma_f32_32x32x16_bf16 v[34:49], v[170:173], v[122:125], v[34:49]
	ds_read_b128 v[122:125], v66 offset:36928
	ds_read_b128 v[130:133], v66 offset:41536
	ds_read_b128 v[138:141], v71 offset:64
	ds_read_b128 v[170:173], v71 offset:4672
	v_mfma_f32_32x32x16_bf16 v[50:65], v[142:145], v[126:129], v[50:65]
	s_waitcnt lgkmcnt(4)
	v_mfma_f32_32x32x16_bf16 v[2:17], v[174:177], v[134:137], v[2:17]
	v_mfma_f32_32x32x16_bf16 v[18:33], v[142:145], v[134:137], v[18:33]
	v_mfma_f32_32x32x16_bf16 v[34:49], v[174:177], v[126:129], v[34:49]
	ds_read_b128 v[126:129], v66 offset:36960
	ds_read_b128 v[134:137], v66 offset:41568
	ds_read_b128 v[142:145], v71 offset:96
	ds_read_b128 v[174:177], v71 offset:4704
	s_waitcnt lgkmcnt(5)
	v_mfma_f32_32x32x16_bf16 v[50:65], v[138:141], v[122:125], v[50:65]
	s_waitcnt lgkmcnt(4)
	v_mfma_f32_32x32x16_bf16 v[2:17], v[170:173], v[130:133], v[2:17]
	v_mfma_f32_32x32x16_bf16 v[18:33], v[138:141], v[130:133], v[18:33]
	v_mfma_f32_32x32x16_bf16 v[34:49], v[170:173], v[122:125], v[34:49]
	s_waitcnt lgkmcnt(1)
	v_mfma_f32_32x32x16_bf16 v[50:65], v[142:145], v[126:129], v[50:65]
	s_waitcnt lgkmcnt(0)
	v_mfma_f32_32x32x16_bf16 v[2:17], v[174:177], v[134:137], v[2:17]
	v_mfma_f32_32x32x16_bf16 v[18:33], v[142:145], v[134:137], v[18:33]
	v_mfma_f32_32x32x16_bf16 v[34:49], v[174:177], v[126:129], v[34:49]
	s_barrier
	global_load_dwordx4 v[122:125], v[78:79], off offset:1920
	s_nop 0
	global_load_dwordx4 v[78:81], v[80:81], off offset:1920
	s_nop 0
	global_load_dwordx4 v[126:129], v[74:75], off offset:1920
	s_nop 0
	global_load_dwordx4 v[74:77], v[76:77], off offset:1920
	s_nop 0
	global_load_dwordx4 v[130:133], v[82:83], off offset:1920
	s_nop 0
	global_load_dwordx4 v[82:85], v[84:85], off offset:1920
	s_waitcnt vmcnt(15)
	ds_write_b128 v97, v[154:157]
	ds_write_b128 v97, v[146:149] offset:9216
	ds_write_b128 v97, v[150:153] offset:18432
	s_waitcnt vmcnt(13)
	ds_write_b128 v97, v[162:165] offset:27648
	ds_write_b128 v97, v[158:161] offset:36864
	s_waitcnt vmcnt(12)
	ds_write_b128 v97, v[166:169] offset:46080
	ds_read_b128 v[134:137], v73 offset:36864
	ds_read_b128 v[138:141], v73 offset:36896
	ds_read_b128 v[142:145], v73 offset:41472
	ds_read_b128 v[146:149], v73 offset:41504
	ds_read_b128 v[150:153], v70
	ds_read_b128 v[154:157], v70 offset:32
	ds_read_b128 v[158:161], v70 offset:4608
	ds_read_b128 v[162:165], v70 offset:4640
	s_waitcnt lgkmcnt(3)
	v_mfma_f32_32x32x16_bf16 v[50:65], v[150:153], v[134:137], v[50:65]
	s_waitcnt lgkmcnt(1)
	v_mfma_f32_32x32x16_bf16 v[2:17], v[158:161], v[142:145], v[2:17]
	v_mfma_f32_32x32x16_bf16 v[18:33], v[150:153], v[142:145], v[18:33]
	v_mfma_f32_32x32x16_bf16 v[34:49], v[158:161], v[134:137], v[34:49]
	ds_read_b128 v[134:137], v73 offset:36928
	ds_read_b128 v[142:145], v73 offset:41536
	ds_read_b128 v[150:153], v70 offset:64
	ds_read_b128 v[158:161], v70 offset:4672
	v_mfma_f32_32x32x16_bf16 v[50:65], v[154:157], v[138:141], v[50:65]
	s_waitcnt lgkmcnt(4)
	v_mfma_f32_32x32x16_bf16 v[2:17], v[162:165], v[146:149], v[2:17]
	v_mfma_f32_32x32x16_bf16 v[18:33], v[154:157], v[146:149], v[18:33]
	v_mfma_f32_32x32x16_bf16 v[34:49], v[162:165], v[138:141], v[34:49]
	ds_read_b128 v[138:141], v73 offset:36960
	ds_read_b128 v[146:149], v73 offset:41568
	ds_read_b128 v[154:157], v70 offset:96
	ds_read_b128 v[162:165], v70 offset:4704
	s_waitcnt lgkmcnt(5)
	v_mfma_f32_32x32x16_bf16 v[50:65], v[150:153], v[134:137], v[50:65]
	s_waitcnt lgkmcnt(4)
	v_mfma_f32_32x32x16_bf16 v[2:17], v[158:161], v[142:145], v[2:17]
	v_mfma_f32_32x32x16_bf16 v[18:33], v[150:153], v[142:145], v[18:33]
	v_mfma_f32_32x32x16_bf16 v[34:49], v[158:161], v[134:137], v[34:49]
	s_waitcnt lgkmcnt(1)
	v_mfma_f32_32x32x16_bf16 v[50:65], v[154:157], v[138:141], v[50:65]
	s_waitcnt lgkmcnt(0)
	v_mfma_f32_32x32x16_bf16 v[2:17], v[162:165], v[146:149], v[2:17]
	v_mfma_f32_32x32x16_bf16 v[18:33], v[154:157], v[146:149], v[18:33]
	v_mfma_f32_32x32x16_bf16 v[34:49], v[162:165], v[138:141], v[34:49]
	s_barrier
	s_waitcnt vmcnt(9)
	ds_write_b128 v72, v[106:109]
	ds_write_b128 v72, v[98:101] offset:9216
	ds_write_b128 v72, v[102:105] offset:18432
	s_waitcnt vmcnt(7)
	ds_write_b128 v72, v[114:117] offset:27648
	ds_write_b128 v72, v[110:113] offset:36864
	s_waitcnt vmcnt(6)
	ds_write_b128 v72, v[118:121] offset:46080
	ds_read_b128 v[98:101], v66 offset:36864
	ds_read_b128 v[102:105], v66 offset:36896
	ds_read_b128 v[106:109], v66 offset:41472
	ds_read_b128 v[110:113], v66 offset:41504
	ds_read_b128 v[114:117], v71
	ds_read_b128 v[118:121], v71 offset:32
	ds_read_b128 v[134:137], v71 offset:4608
	ds_read_b128 v[138:141], v71 offset:4640
	s_waitcnt lgkmcnt(3)
	v_mfma_f32_32x32x16_bf16 v[50:65], v[114:117], v[98:101], v[50:65]
	s_waitcnt lgkmcnt(1)
	v_mfma_f32_32x32x16_bf16 v[2:17], v[134:137], v[106:109], v[2:17]
	v_mfma_f32_32x32x16_bf16 v[18:33], v[114:117], v[106:109], v[18:33]
	v_mfma_f32_32x32x16_bf16 v[34:49], v[134:137], v[98:101], v[34:49]
	ds_read_b128 v[98:101], v66 offset:36928
	ds_read_b128 v[106:109], v66 offset:41536
	ds_read_b128 v[114:117], v71 offset:64
	ds_read_b128 v[134:137], v71 offset:4672
	v_mfma_f32_32x32x16_bf16 v[50:65], v[118:121], v[102:105], v[50:65]
	s_waitcnt lgkmcnt(4)
	v_mfma_f32_32x32x16_bf16 v[2:17], v[138:141], v[110:113], v[2:17]
	v_mfma_f32_32x32x16_bf16 v[18:33], v[118:121], v[110:113], v[18:33]
	v_mfma_f32_32x32x16_bf16 v[34:49], v[138:141], v[102:105], v[34:49]
	ds_read_b128 v[102:105], v66 offset:36960
	ds_read_b128 v[110:113], v66 offset:41568
	ds_read_b128 v[118:121], v71 offset:96
	ds_read_b128 v[138:141], v71 offset:4704
	s_waitcnt lgkmcnt(5)
	v_mfma_f32_32x32x16_bf16 v[50:65], v[114:117], v[98:101], v[50:65]
	s_waitcnt lgkmcnt(4)
	v_mfma_f32_32x32x16_bf16 v[2:17], v[134:137], v[106:109], v[2:17]
	v_mfma_f32_32x32x16_bf16 v[18:33], v[114:117], v[106:109], v[18:33]
	v_mfma_f32_32x32x16_bf16 v[34:49], v[134:137], v[98:101], v[34:49]
	s_waitcnt lgkmcnt(1)
	v_mfma_f32_32x32x16_bf16 v[50:65], v[118:121], v[102:105], v[50:65]
	s_waitcnt lgkmcnt(0)
	v_mfma_f32_32x32x16_bf16 v[2:17], v[138:141], v[110:113], v[2:17]
	v_mfma_f32_32x32x16_bf16 v[18:33], v[118:121], v[110:113], v[18:33]
	v_mfma_f32_32x32x16_bf16 v[34:49], v[138:141], v[102:105], v[34:49]
	s_barrier
	s_waitcnt vmcnt(3)
	ds_write_b128 v97, v[126:129]
	ds_write_b128 v97, v[122:125] offset:9216
	ds_write_b128 v97, v[78:81] offset:18432
	s_waitcnt vmcnt(1)
	ds_write_b128 v97, v[130:133] offset:27648
	ds_write_b128 v97, v[74:77] offset:36864
	s_waitcnt vmcnt(0)
	ds_write_b128 v97, v[82:85] offset:46080
	ds_read_b128 v[74:77], v73 offset:36864
	ds_read_b128 v[78:81], v73 offset:36896
	ds_read_b128 v[82:85], v73 offset:41472
	ds_read_b128 v[98:101], v73 offset:41504
	ds_read_b128 v[102:105], v70
	ds_read_b128 v[106:109], v70 offset:32
	ds_read_b128 v[110:113], v70 offset:4608
	ds_read_b128 v[114:117], v70 offset:4640
	s_waitcnt lgkmcnt(3)
	v_mfma_f32_32x32x16_bf16 v[50:65], v[102:105], v[74:77], v[50:65]
	s_waitcnt lgkmcnt(1)
	v_mfma_f32_32x32x16_bf16 v[2:17], v[110:113], v[82:85], v[2:17]
	v_mfma_f32_32x32x16_bf16 v[18:33], v[102:105], v[82:85], v[18:33]
	v_mfma_f32_32x32x16_bf16 v[34:49], v[110:113], v[74:77], v[34:49]
	ds_read_b128 v[74:77], v73 offset:36928
	ds_read_b128 v[82:85], v73 offset:41536
	ds_read_b128 v[102:105], v70 offset:64
	ds_read_b128 v[110:113], v70 offset:4672
	v_mfma_f32_32x32x16_bf16 v[50:65], v[106:109], v[78:81], v[50:65]
	s_waitcnt lgkmcnt(4)
	v_mfma_f32_32x32x16_bf16 v[2:17], v[114:117], v[98:101], v[2:17]
	v_mfma_f32_32x32x16_bf16 v[18:33], v[106:109], v[98:101], v[18:33]
	v_mfma_f32_32x32x16_bf16 v[34:49], v[114:117], v[78:81], v[34:49]
	ds_read_b128 v[78:81], v73 offset:36960
	ds_read_b128 v[98:101], v73 offset:41568
	ds_read_b128 v[106:109], v70 offset:96
	ds_read_b128 v[114:117], v70 offset:4704
	s_waitcnt lgkmcnt(5)
	v_mfma_f32_32x32x16_bf16 v[50:65], v[102:105], v[74:77], v[50:65]
	s_waitcnt lgkmcnt(4)
	v_mfma_f32_32x32x16_bf16 v[2:17], v[110:113], v[82:85], v[2:17]
	v_mfma_f32_32x32x16_bf16 v[18:33], v[102:105], v[82:85], v[18:33]
	v_mfma_f32_32x32x16_bf16 v[34:49], v[110:113], v[74:77], v[34:49]
	s_waitcnt lgkmcnt(1)
	v_mfma_f32_32x32x16_bf16 v[50:65], v[106:109], v[78:81], v[50:65]
	s_waitcnt lgkmcnt(0)
	v_mfma_f32_32x32x16_bf16 v[2:17], v[114:117], v[98:101], v[2:17]
	v_mfma_f32_32x32x16_bf16 v[18:33], v[106:109], v[98:101], v[18:33]
	v_mfma_f32_32x32x16_bf16 v[34:49], v[114:117], v[78:81], v[34:49]
	s_barrier
	ds_read_b128 v[72:75], v66 offset:36864
	ds_read_b128 v[76:79], v66 offset:36896
	ds_read_b128 v[80:83], v66 offset:41472
	ds_read_b128 v[98:101], v66 offset:41504
	ds_read_b128 v[102:105], v71
	ds_read_b128 v[106:109], v71 offset:32
	ds_read_b128 v[110:113], v71 offset:4608
	ds_read_b128 v[114:117], v71 offset:4640
	s_waitcnt lgkmcnt(3)
	v_mfma_f32_32x32x16_bf16 v[50:65], v[102:105], v[72:75], v[50:65]
	s_waitcnt lgkmcnt(1)
	v_mfma_f32_32x32x16_bf16 v[2:17], v[110:113], v[80:83], v[2:17]
	v_mfma_f32_32x32x16_bf16 v[18:33], v[102:105], v[80:83], v[18:33]
	v_mfma_f32_32x32x16_bf16 v[34:49], v[110:113], v[72:75], v[34:49]
	ds_read_b128 v[72:75], v66 offset:36928
	ds_read_b128 v[80:83], v66 offset:41536
	ds_read_b128 v[102:105], v71 offset:64
	ds_read_b128 v[110:113], v71 offset:4672
	v_mfma_f32_32x32x16_bf16 v[50:65], v[106:109], v[76:79], v[50:65]
	s_waitcnt lgkmcnt(4)
	v_mfma_f32_32x32x16_bf16 v[2:17], v[114:117], v[98:101], v[2:17]
	v_mfma_f32_32x32x16_bf16 v[18:33], v[106:109], v[98:101], v[18:33]
	v_mfma_f32_32x32x16_bf16 v[34:49], v[114:117], v[76:79], v[34:49]
	ds_read_b128 v[76:79], v66 offset:36960
	ds_read_b128 v[98:101], v66 offset:41568
	ds_read_b128 v[106:109], v71 offset:96
	ds_read_b128 v[114:117], v71 offset:4704
	s_waitcnt lgkmcnt(5)
	v_mfma_f32_32x32x16_bf16 v[50:65], v[102:105], v[72:75], v[50:65]
	s_waitcnt lgkmcnt(4)
	v_mfma_f32_32x32x16_bf16 v[2:17], v[110:113], v[80:83], v[2:17]
	v_mfma_f32_32x32x16_bf16 v[18:33], v[102:105], v[80:83], v[18:33]
	v_mfma_f32_32x32x16_bf16 v[34:49], v[110:113], v[72:75], v[34:49]
	s_waitcnt lgkmcnt(1)
	v_mfma_f32_32x32x16_bf16 v[50:65], v[106:109], v[76:79], v[50:65]
	s_waitcnt lgkmcnt(0)
	v_mfma_f32_32x32x16_bf16 v[2:17], v[114:117], v[98:101], v[2:17]
	v_mfma_f32_32x32x16_bf16 v[18:33], v[106:109], v[98:101], v[18:33]
	v_mfma_f32_32x32x16_bf16 v[34:49], v[114:117], v[76:79], v[34:49]
	s_add_i32 s3, s12, 0xffffe000
	s_lshr_b32 s3, s3, 12
	s_add_i32 s3, s3, 1
	s_cmp_gt_i32 s14, 63
	s_cselect_b32 s3, s3, 0
	v_lshrrev_b32_e32 v70, 1, v69
	s_mul_i32 s33, s3, 0x3000
	v_lshlrev_b32_e32 v71, 1, v69
	v_and_b32_e32 v70, 16, v70
	s_mul_hi_u32 s14, s3, 0x3000
	s_add_u32 s16, s96, s33
	v_and_b32_e32 v66, 0x5f, v69
	v_and_or_b32 v70, v71, s39, v70
	s_addc_u32 s17, s97, s14
	s_lshl_b64 s[14:15], s[4:5], 2
	v_readlane_b32 s44, v245, 0
	v_mad_u32_u24 v66, v66, s40, v70
	s_add_u32 s16, s16, s14
	v_readlane_b32 s45, v245, 1
	v_readlane_b32 s48, v245, 4
	v_readlane_b32 s49, v245, 5
	s_barrier
	ds_write_b128 v66, v[50:53]
	ds_write_b128 v66, v[54:57] offset:32
	ds_write_b128 v66, v[58:61] offset:64
	ds_write_b128 v66, v[62:65] offset:96
	ds_write_b128 v66, v[34:37] offset:128
	ds_write_b128 v66, v[38:41] offset:160
	ds_write_b128 v66, v[42:45] offset:192
	ds_write_b128 v66, v[46:49] offset:224
	ds_write_b128 v66, v[18:21] offset:33280
	ds_write_b128 v66, v[22:25] offset:33312
	ds_write_b128 v66, v[26:29] offset:33344
	ds_write_b128 v66, v[30:33] offset:33376
	ds_write_b128 v66, v[2:5] offset:33408
	ds_write_b128 v66, v[6:9] offset:33440
	ds_write_b128 v66, v[10:13] offset:33472
	ds_write_b128 v66, v[14:17] offset:33504
	s_addc_u32 s17, s17, s15
	v_lshlrev_b32_e32 v66, 4, v68
	s_mov_b64 s[44:45], s[48:49]
	v_lshl_add_u64 v[2:3], s[16:17], 0, v[66:67]
	s_add_u32 s16, s44, s14
	v_ashrrev_i32_e32 v59, 2, v69
	s_addc_u32 s17, s45, s15
	s_add_i32 s3, s3, 5
	s_add_i32 s33, s33, 0xf000
	v_and_b32_e32 v58, -16, v59
	s_mul_hi_u32 s3, s3, 0x3000
	s_add_u32 s33, s96, s33
	v_add_u32_e32 v60, s12, v58
	s_addc_u32 s3, s97, s3
	v_add_u32_e32 v6, 0xffffe000, v60
	v_ashrrev_i32_e32 v61, 31, v60
	v_cmp_gt_i32_e32 vcc, s41, v60
	s_add_u32 s44, s33, s14
	s_addc_u32 s45, s3, s15
	v_cndmask_b32_e32 v7, 0, v61, vcc
	v_cndmask_b32_e32 v6, v6, v60, vcc
	v_cndmask_b32_e32 v9, v1, v86, vcc
	v_cndmask_b32_e32 v8, v87, v88, vcc
	v_lshlrev_b64 v[6:7], 12, v[6:7]
	v_add_co_u32_e32 v2, vcc, s41, v2
	v_lshl_add_u64 v[4:5], s[44:45], 0, v[66:67]
	v_lshl_add_u64 v[6:7], v[8:9], 0, v[6:7]
	v_addc_co_u32_e32 v3, vcc, 0, v3, vcc
	v_lshl_add_u64 v[6:7], v[6:7], 0, s[14:15]
	v_add_co_u32_e32 v10, vcc, s42, v4
	v_lshl_add_u64 v[6:7], v[6:7], 0, v[66:67]
	s_nop 0
	v_addc_co_u32_e32 v11, vcc, 0, v5, vcc
	s_waitcnt lgkmcnt(0)
	s_barrier
	global_load_dwordx4 v[2:5], v[2:3], off
	s_nop 0
	global_load_dwordx4 v[10:13], v[10:11], off
	s_nop 0
	global_load_dwordx4 v[14:17], v66, s[16:17]
	v_lshlrev_b64 v[18:19], 12, v[60:61]
	v_lshl_add_u64 v[18:19], s[74:75], 0, v[18:19]
	v_lshl_add_u64 v[18:19], v[18:19], 0, s[14:15]
	v_mad_u64_u32 v[72:73], s[16:17], v58, s40, v[66:67]
	v_lshl_add_u64 v[26:27], v[18:19], 0, v[66:67]
	v_lshlrev_b64 v[18:19], 11, v[60:61]
	v_lshl_add_u64 v[18:19], s[10:11], 0, v[18:19]
	s_lshl_b64 s[16:17], s[4:5], 1
	v_lshl_add_u64 v[18:19], v[18:19], 0, s[16:17]
	v_lshlrev_b32_e32 v62, 3, v68
	v_mov_b32_e32 v63, v67
	v_or_b32_e32 v30, 1, v60
	v_lshl_add_u64 v[28:29], v[18:19], 0, v[62:63]
	v_add_u32_e32 v18, 0xffffe001, v60
	v_ashrrev_i32_e32 v31, 31, v30
	v_cmp_gt_i32_e32 vcc, s41, v30
	v_or_b32_e32 v36, 5, v60
	v_add_u32_e32 v40, 0xffffe005, v60
	v_cndmask_b32_e32 v19, 0, v31, vcc
	v_cndmask_b32_e32 v18, v18, v30, vcc
	v_lshlrev_b64 v[24:25], 12, v[18:19]
	ds_read_b128 v[18:21], v72
	v_cndmask_b32_e32 v23, v1, v86, vcc
	v_cndmask_b32_e32 v22, v87, v88, vcc
	v_lshl_add_u64 v[22:23], v[22:23], 0, v[24:25]
	v_lshl_add_u64 v[22:23], v[22:23], 0, s[14:15]
	v_lshl_add_u64 v[32:33], v[22:23], 0, v[66:67]
	ds_read_b128 v[22:25], v72 offset:1040
	v_ashrrev_i32_e32 v37, 31, v36
	v_or_b32_e32 v44, 7, v60
	v_add_u32_e32 v48, 0xffffe007, v60
	v_ashrrev_i32_e32 v45, 31, v44
	v_or_b32_e32 v52, 9, v60
	v_add_u32_e32 v56, 0xffffe009, v60
	v_ashrrev_i32_e32 v53, 31, v52
	v_or_b32_e32 v76, 11, v60
	v_add_u32_e32 v61, 0xffffe00b, v60
	v_ashrrev_i32_e32 v77, 31, v76
	v_or_b32_e32 v84, 13, v60
	v_ashrrev_i32_e32 v85, 31, v84
	v_or_b32_e32 v59, 15, v59
	v_and_b32_e32 v97, 32, v69
	v_and_b32_e32 v110, 16, v69
	v_and_b32_e32 v111, 8, v69
	v_and_b32_e32 v112, 4, v69
	v_readlane_b32 s46, v245, 2
	v_readlane_b32 s47, v245, 3
	v_readlane_b32 s50, v245, 6
	v_readlane_b32 s51, v245, 7
	v_readlane_b32 s52, v245, 8
	v_readlane_b32 s53, v245, 9
	v_readlane_b32 s54, v245, 10
	v_readlane_b32 s55, v245, 11
	v_readlane_b32 s56, v245, 12
	v_readlane_b32 s57, v245, 13
	v_readlane_b32 s58, v245, 14
	v_readlane_b32 s59, v245, 15
	s_waitcnt vmcnt(1)
	v_pk_add_f32 v[10:11], v[10:11], 1.0 op_sel_hi:[1,0]
	v_pk_add_f32 v[12:13], v[12:13], 1.0 op_sel_hi:[1,0]
	s_waitcnt lgkmcnt(1)
	v_pk_fma_f32 v[6:7], v[2:3], v[18:19], v[178:179]
	s_waitcnt vmcnt(0)
	v_pk_mul_f32 v[64:65], v[14:15], v[10:11]
	v_pk_fma_f32 v[8:9], v[4:5], v[20:21], v[180:181]
	v_pk_mul_f32 v[70:71], v[16:17], v[12:13]
	v_pk_mul_f32 v[10:11], v[64:65], v[6:7]
	v_pk_mul_f32 v[12:13], v[70:71], v[8:9]
	v_cvt_pk_bf16_f32 v10, v10, v11
	v_cvt_pk_bf16_f32 v11, v12, v13
	global_store_dwordx4 v[26:27], v[6:9], off
	global_store_dwordx2 v[28:29], v[10:11], off
	v_or_b32_e32 v26, 2, v60
	v_lshlrev_b64 v[14:15], 12, v[30:31]
	v_add_u32_e32 v18, 0xffffe002, v60
	v_ashrrev_i32_e32 v27, 31, v26
	v_cmp_gt_i32_e32 vcc, s41, v26
	v_lshl_add_u64 v[14:15], s[74:75], 0, v[14:15]
	v_lshlrev_b64 v[16:17], 11, v[30:31]
	v_cndmask_b32_e32 v19, 0, v27, vcc
	v_cndmask_b32_e32 v18, v18, v26, vcc
	v_lshl_add_u64 v[14:15], v[14:15], 0, s[14:15]
	v_cndmask_b32_e32 v21, v1, v86, vcc
	v_cndmask_b32_e32 v20, v87, v88, vcc
	v_lshl_add_u64 v[16:17], s[10:11], 0, v[16:17]
	v_lshlrev_b64 v[18:19], 12, v[18:19]
	v_lshl_add_u64 v[14:15], v[14:15], 0, v[66:67]
	v_lshl_add_u64 v[18:19], v[20:21], 0, v[18:19]
	v_lshl_add_u64 v[16:17], v[16:17], 0, s[16:17]
	v_lshl_add_u64 v[18:19], v[18:19], 0, s[14:15]
	v_lshl_add_u64 v[16:17], v[16:17], 0, v[62:63]
	v_lshl_add_u64 v[18:19], v[18:19], 0, v[66:67]
	v_or_b32_e32 v28, 3, v60
	v_add_u32_e32 v32, 0xffffe003, v60
	v_ashrrev_i32_e32 v29, 31, v28
	v_cmp_gt_i32_e32 vcc, s41, v28
	v_lshlrev_b64 v[30:31], 12, v[26:27]
	v_lshlrev_b64 v[26:27], 11, v[26:27]
	v_cndmask_b32_e32 v33, 0, v29, vcc
	v_cndmask_b32_e32 v32, v32, v28, vcc
	v_cndmask_b32_e32 v35, v1, v86, vcc
	v_cndmask_b32_e32 v34, v87, v88, vcc
	v_lshl_add_u64 v[30:31], s[74:75], 0, v[30:31]
	v_lshl_add_u64 v[26:27], s[10:11], 0, v[26:27]
	v_lshlrev_b64 v[32:33], 12, v[32:33]
	v_lshl_add_u64 v[32:33], v[34:35], 0, v[32:33]
	v_lshl_add_u64 v[30:31], v[30:31], 0, s[14:15]
	v_lshl_add_u64 v[26:27], v[26:27], 0, s[16:17]
	v_lshl_add_u64 v[32:33], v[32:33], 0, s[14:15]
	v_lshl_add_u64 v[30:31], v[30:31], 0, v[66:67]
	v_lshl_add_u64 v[26:27], v[26:27], 0, v[62:63]
	v_lshl_add_u64 v[32:33], v[32:33], 0, v[66:67]
	v_or_b32_e32 v34, 4, v60
	v_ashrrev_i32_e32 v35, 31, v34
	v_cmp_gt_i32_e32 vcc, s41, v34
	v_lshlrev_b64 v[38:39], 12, v[34:35]
	v_lshl_add_u64 v[38:39], s[74:75], 0, v[38:39]
	v_lshl_add_u64 v[38:39], v[38:39], 0, s[14:15]
	v_lshl_add_u64 v[38:39], v[38:39], 0, v[66:67]
	v_pk_mul_f32 v[6:7], v[6:7], v[6:7]
	v_pk_mul_f32 v[8:9], v[8:9], v[8:9]
	v_add_f32_e32 v6, v6, v7
	v_add_f32_e32 v6, v6, v8
	s_waitcnt lgkmcnt(0)
	v_pk_fma_f32 v[10:11], v[2:3], v[22:23], v[182:183]
	v_pk_fma_f32 v[12:13], v[4:5], v[24:25], v[184:185]
	global_store_dwordx4 v[14:15], v[10:13], off
	v_pk_mul_f32 v[14:15], v[64:65], v[10:11]
	v_pk_mul_f32 v[20:21], v[70:71], v[12:13]
	v_cvt_pk_bf16_f32 v14, v14, v15
	v_cvt_pk_bf16_f32 v15, v20, v21
	global_store_dwordx2 v[16:17], v[14:15], off
	ds_read_b128 v[18:21], v72 offset:2080
	ds_read_b128 v[22:25], v72 offset:3120
	s_waitcnt lgkmcnt(1)
	v_pk_fma_f32 v[14:15], v[2:3], v[18:19], v[186:187]
	v_pk_fma_f32 v[16:17], v[4:5], v[20:21], v[188:189]
	v_pk_mul_f32 v[18:19], v[64:65], v[14:15]
	v_pk_mul_f32 v[20:21], v[70:71], v[16:17]
	v_cvt_pk_bf16_f32 v18, v18, v19
	v_cvt_pk_bf16_f32 v19, v20, v21
	global_store_dwordx4 v[30:31], v[14:17], off
	global_store_dwordx2 v[26:27], v[18:19], off
	v_add_u32_e32 v30, 0xffffe004, v60
	v_lshlrev_b64 v[26:27], 12, v[28:29]
	v_lshlrev_b64 v[28:29], 11, v[28:29]
	v_cndmask_b32_e32 v31, 0, v35, vcc
	v_cndmask_b32_e32 v30, v30, v34, vcc
	v_cndmask_b32_e32 v33, v1, v86, vcc
	v_cndmask_b32_e32 v32, v87, v88, vcc
	v_lshl_add_u64 v[26:27], s[74:75], 0, v[26:27]
	v_lshl_add_u64 v[28:29], s[10:11], 0, v[28:29]
	v_lshlrev_b64 v[30:31], 12, v[30:31]
	v_lshl_add_u64 v[30:31], v[32:33], 0, v[30:31]
	v_lshl_add_u64 v[26:27], v[26:27], 0, s[14:15]
	v_lshl_add_u64 v[28:29], v[28:29], 0, s[16:17]
	v_lshl_add_u64 v[30:31], v[30:31], 0, s[14:15]
	v_lshl_add_u64 v[26:27], v[26:27], 0, v[66:67]
	v_lshl_add_u64 v[28:29], v[28:29], 0, v[62:63]
	v_lshl_add_u64 v[30:31], v[30:31], 0, v[66:67]
	v_cmp_gt_i32_e32 vcc, s41, v36
	v_lshlrev_b64 v[34:35], 11, v[34:35]
	v_lshl_add_u64 v[34:35], s[10:11], 0, v[34:35]
	v_cndmask_b32_e32 v41, 0, v37, vcc
	v_cndmask_b32_e32 v40, v40, v36, vcc
	v_cndmask_b32_e32 v43, v1, v86, vcc
	v_cndmask_b32_e32 v42, v87, v88, vcc
	v_lshlrev_b64 v[40:41], 12, v[40:41]
	v_lshl_add_u64 v[40:41], v[42:43], 0, v[40:41]
	v_lshl_add_u64 v[34:35], v[34:35], 0, s[16:17]
	v_lshl_add_u64 v[40:41], v[40:41], 0, s[14:15]
	v_lshl_add_u64 v[34:35], v[34:35], 0, v[62:63]
	v_lshl_add_u64 v[40:41], v[40:41], 0, v[66:67]
	v_or_b32_e32 v42, 6, v60
	v_ashrrev_i32_e32 v43, 31, v42
	v_cmp_gt_i32_e32 vcc, s41, v42
	v_lshlrev_b64 v[46:47], 12, v[42:43]
	v_lshl_add_u64 v[46:47], s[74:75], 0, v[46:47]
	v_lshl_add_u64 v[46:47], v[46:47], 0, s[14:15]
	v_lshl_add_u64 v[46:47], v[46:47], 0, v[66:67]
	s_waitcnt lgkmcnt(0)
	v_pk_fma_f32 v[18:19], v[2:3], v[22:23], v[190:191]
	v_pk_fma_f32 v[20:21], v[4:5], v[24:25], v[192:193]
	v_pk_mul_f32 v[22:23], v[64:65], v[18:19]
	v_pk_mul_f32 v[24:25], v[70:71], v[20:21]
	v_cvt_pk_bf16_f32 v22, v22, v23
	v_cvt_pk_bf16_f32 v23, v24, v25
	global_store_dwordx4 v[26:27], v[18:21], off
	global_store_dwordx2 v[28:29], v[22:23], off
	ds_read_b128 v[26:29], v72 offset:4160
	ds_read_b128 v[30:33], v72 offset:5200
	s_waitcnt lgkmcnt(1)
	v_pk_fma_f32 v[22:23], v[2:3], v[26:27], v[194:195]
	v_pk_fma_f32 v[24:25], v[4:5], v[28:29], v[196:197]
	v_pk_mul_f32 v[26:27], v[64:65], v[22:23]
	v_pk_mul_f32 v[28:29], v[70:71], v[24:25]
	v_cvt_pk_bf16_f32 v26, v26, v27
	v_cvt_pk_bf16_f32 v27, v28, v29
	global_store_dwordx4 v[38:39], v[22:25], off
	global_store_dwordx2 v[34:35], v[26:27], off
	v_add_u32_e32 v38, 0xffffe006, v60
	v_lshlrev_b64 v[34:35], 12, v[36:37]
	v_lshlrev_b64 v[36:37], 11, v[36:37]
	v_cndmask_b32_e32 v39, 0, v43, vcc
	v_cndmask_b32_e32 v38, v38, v42, vcc
	v_cndmask_b32_e32 v41, v1, v86, vcc
	v_cndmask_b32_e32 v40, v87, v88, vcc
	v_lshl_add_u64 v[34:35], s[74:75], 0, v[34:35]
	v_lshl_add_u64 v[36:37], s[10:11], 0, v[36:37]
	v_lshlrev_b64 v[38:39], 12, v[38:39]
	v_lshl_add_u64 v[38:39], v[40:41], 0, v[38:39]
	v_lshl_add_u64 v[34:35], v[34:35], 0, s[14:15]
	v_lshl_add_u64 v[36:37], v[36:37], 0, s[16:17]
	v_lshl_add_u64 v[38:39], v[38:39], 0, s[14:15]
	v_lshl_add_u64 v[34:35], v[34:35], 0, v[66:67]
	v_lshl_add_u64 v[36:37], v[36:37], 0, v[62:63]
	v_lshl_add_u64 v[38:39], v[38:39], 0, v[66:67]
	v_cmp_gt_i32_e32 vcc, s41, v44
	v_lshlrev_b64 v[42:43], 11, v[42:43]
	v_lshl_add_u64 v[42:43], s[10:11], 0, v[42:43]
	v_cndmask_b32_e32 v49, 0, v45, vcc
	v_cndmask_b32_e32 v48, v48, v44, vcc
	v_cndmask_b32_e32 v51, v1, v86, vcc
	v_cndmask_b32_e32 v50, v87, v88, vcc
	v_lshlrev_b64 v[48:49], 12, v[48:49]
	v_lshl_add_u64 v[48:49], v[50:51], 0, v[48:49]
	v_lshl_add_u64 v[42:43], v[42:43], 0, s[16:17]
	v_lshl_add_u64 v[48:49], v[48:49], 0, s[14:15]
	v_lshl_add_u64 v[42:43], v[42:43], 0, v[62:63]
	v_lshl_add_u64 v[48:49], v[48:49], 0, v[66:67]
	v_or_b32_e32 v50, 8, v60
	v_ashrrev_i32_e32 v51, 31, v50
	v_cmp_gt_i32_e32 vcc, s41, v50
	v_lshlrev_b64 v[54:55], 12, v[50:51]
	v_lshl_add_u64 v[54:55], s[74:75], 0, v[54:55]
	v_lshl_add_u64 v[54:55], v[54:55], 0, s[14:15]
	v_lshl_add_u64 v[54:55], v[54:55], 0, v[66:67]
	s_waitcnt lgkmcnt(0)
	v_pk_fma_f32 v[26:27], v[2:3], v[30:31], v[198:199]
	v_pk_fma_f32 v[28:29], v[4:5], v[32:33], v[200:201]
	v_pk_mul_f32 v[30:31], v[64:65], v[26:27]
	v_pk_mul_f32 v[32:33], v[70:71], v[28:29]
	v_cvt_pk_bf16_f32 v30, v30, v31
	v_cvt_pk_bf16_f32 v31, v32, v33
	global_store_dwordx4 v[34:35], v[26:29], off
	global_store_dwordx2 v[36:37], v[30:31], off
	ds_read_b128 v[34:37], v72 offset:6240
	ds_read_b128 v[38:41], v72 offset:7280
	s_waitcnt lgkmcnt(1)
	v_pk_fma_f32 v[30:31], v[2:3], v[34:35], v[202:203]
	v_pk_fma_f32 v[32:33], v[4:5], v[36:37], v[204:205]
	v_pk_mul_f32 v[34:35], v[64:65], v[30:31]
	v_pk_mul_f32 v[36:37], v[70:71], v[32:33]
	v_cvt_pk_bf16_f32 v34, v34, v35
	v_cvt_pk_bf16_f32 v35, v36, v37
	global_store_dwordx4 v[46:47], v[30:33], off
	global_store_dwordx2 v[42:43], v[34:35], off
	v_add_u32_e32 v46, 0xffffe008, v60
	v_lshlrev_b64 v[42:43], 12, v[44:45]
	v_lshlrev_b64 v[44:45], 11, v[44:45]
	v_cndmask_b32_e32 v47, 0, v51, vcc
	v_cndmask_b32_e32 v46, v46, v50, vcc
	v_cndmask_b32_e32 v49, v1, v86, vcc
	v_cndmask_b32_e32 v48, v87, v88, vcc
	v_lshl_add_u64 v[42:43], s[74:75], 0, v[42:43]
	v_lshl_add_u64 v[44:45], s[10:11], 0, v[44:45]
	v_lshlrev_b64 v[46:47], 12, v[46:47]
	v_lshl_add_u64 v[46:47], v[48:49], 0, v[46:47]
	v_lshl_add_u64 v[42:43], v[42:43], 0, s[14:15]
	v_lshl_add_u64 v[44:45], v[44:45], 0, s[16:17]
	v_lshl_add_u64 v[46:47], v[46:47], 0, s[14:15]
	v_lshl_add_u64 v[42:43], v[42:43], 0, v[66:67]
	v_lshl_add_u64 v[44:45], v[44:45], 0, v[62:63]
	v_lshl_add_u64 v[46:47], v[46:47], 0, v[66:67]
	v_cmp_gt_i32_e32 vcc, s41, v52
	v_lshlrev_b64 v[50:51], 11, v[50:51]
	v_lshl_add_u64 v[50:51], s[10:11], 0, v[50:51]
	v_cndmask_b32_e32 v57, 0, v53, vcc
	v_cndmask_b32_e32 v56, v56, v52, vcc
	v_cndmask_b32_e32 v75, v1, v86, vcc
	v_cndmask_b32_e32 v74, v87, v88, vcc
	v_lshlrev_b64 v[56:57], 12, v[56:57]
	v_lshl_add_u64 v[56:57], v[74:75], 0, v[56:57]
	v_lshl_add_u64 v[50:51], v[50:51], 0, s[16:17]
	v_lshl_add_u64 v[56:57], v[56:57], 0, s[14:15]
	v_lshl_add_u64 v[50:51], v[50:51], 0, v[62:63]
	v_lshl_add_u64 v[56:57], v[56:57], 0, v[66:67]
	v_or_b32_e32 v74, 10, v60
	v_ashrrev_i32_e32 v75, 31, v74
	v_cmp_gt_i32_e32 vcc, s41, v74
	v_lshlrev_b64 v[78:79], 12, v[74:75]
	v_lshl_add_u64 v[78:79], s[74:75], 0, v[78:79]
	v_lshl_add_u64 v[78:79], v[78:79], 0, s[14:15]
	v_lshl_add_u64 v[78:79], v[78:79], 0, v[66:67]
	s_waitcnt lgkmcnt(0)
	v_pk_fma_f32 v[34:35], v[2:3], v[38:39], v[206:207]
	v_pk_fma_f32 v[36:37], v[4:5], v[40:41], v[208:209]
	v_pk_mul_f32 v[38:39], v[64:65], v[34:35]
	v_pk_mul_f32 v[40:41], v[70:71], v[36:37]
	v_cvt_pk_bf16_f32 v38, v38, v39
	v_cvt_pk_bf16_f32 v39, v40, v41
	global_store_dwordx4 v[42:43], v[34:37], off
	global_store_dwordx2 v[44:45], v[38:39], off
	ds_read_b128 v[42:45], v72 offset:8320
	ds_read_b128 v[46:49], v72 offset:9360
	s_waitcnt lgkmcnt(1)
	v_pk_fma_f32 v[38:39], v[2:3], v[42:43], v[214:215]
	v_pk_fma_f32 v[40:41], v[4:5], v[44:45], v[216:217]
	v_pk_mul_f32 v[42:43], v[64:65], v[38:39]
	v_pk_mul_f32 v[44:45], v[70:71], v[40:41]
	v_cvt_pk_bf16_f32 v42, v42, v43
	v_cvt_pk_bf16_f32 v43, v44, v45
	global_store_dwordx4 v[54:55], v[38:41], off
	global_store_dwordx2 v[50:51], v[42:43], off
	v_add_u32_e32 v54, 0xffffe00a, v60
	v_lshlrev_b64 v[50:51], 12, v[52:53]
	v_lshlrev_b64 v[52:53], 11, v[52:53]
	v_cndmask_b32_e32 v55, 0, v75, vcc
	v_cndmask_b32_e32 v54, v54, v74, vcc
	v_cndmask_b32_e32 v57, v1, v86, vcc
	v_cndmask_b32_e32 v56, v87, v88, vcc
	v_lshl_add_u64 v[50:51], s[74:75], 0, v[50:51]
	v_lshl_add_u64 v[52:53], s[10:11], 0, v[52:53]
	v_lshlrev_b64 v[54:55], 12, v[54:55]
	v_lshl_add_u64 v[54:55], v[56:57], 0, v[54:55]
	v_lshl_add_u64 v[50:51], v[50:51], 0, s[14:15]
	v_lshl_add_u64 v[52:53], v[52:53], 0, s[16:17]
	v_lshl_add_u64 v[54:55], v[54:55], 0, s[14:15]
	v_lshl_add_u64 v[50:51], v[50:51], 0, v[66:67]
	v_lshl_add_u64 v[52:53], v[52:53], 0, v[62:63]
	v_lshl_add_u64 v[54:55], v[54:55], 0, v[66:67]
	v_cmp_gt_i32_e32 vcc, s41, v76
	v_lshlrev_b64 v[74:75], 11, v[74:75]
	v_lshl_add_u64 v[74:75], s[10:11], 0, v[74:75]
	v_cndmask_b32_e32 v81, 0, v77, vcc
	v_cndmask_b32_e32 v80, v61, v76, vcc
	v_cndmask_b32_e32 v83, v1, v86, vcc
	v_cndmask_b32_e32 v82, v87, v88, vcc
	v_lshlrev_b64 v[80:81], 12, v[80:81]
	v_lshl_add_u64 v[80:81], v[82:83], 0, v[80:81]
	v_lshl_add_u64 v[74:75], v[74:75], 0, s[16:17]
	v_lshl_add_u64 v[80:81], v[80:81], 0, s[14:15]
	v_lshl_add_u64 v[74:75], v[74:75], 0, v[62:63]
	v_lshl_add_u64 v[80:81], v[80:81], 0, v[66:67]
	v_or_b32_e32 v82, 12, v60
	v_add_u32_e32 v61, 0xffffe00c, v60
	v_ashrrev_i32_e32 v83, 31, v82
	v_cmp_gt_i32_e32 vcc, s41, v82
	v_lshlrev_b64 v[98:99], 12, v[82:83]
	v_lshl_add_u64 v[98:99], s[74:75], 0, v[98:99]
	v_lshl_add_u64 v[98:99], v[98:99], 0, s[14:15]
	v_lshl_add_u64 v[98:99], v[98:99], 0, v[66:67]
	s_waitcnt lgkmcnt(0)
	v_pk_fma_f32 v[42:43], v[2:3], v[46:47], v[218:219]
	v_pk_fma_f32 v[44:45], v[4:5], v[48:49], v[220:221]
	v_pk_mul_f32 v[46:47], v[64:65], v[42:43]
	v_pk_mul_f32 v[48:49], v[70:71], v[44:45]
	v_cvt_pk_bf16_f32 v46, v46, v47
	v_cvt_pk_bf16_f32 v47, v48, v49
	global_store_dwordx4 v[50:51], v[42:45], off
	global_store_dwordx2 v[52:53], v[46:47], off
	ds_read_b128 v[50:53], v72 offset:10400
	ds_read_b128 v[54:57], v72 offset:11440
	s_waitcnt lgkmcnt(1)
	v_pk_fma_f32 v[46:47], v[2:3], v[50:51], v[222:223]
	v_pk_fma_f32 v[48:49], v[4:5], v[52:53], v[224:225]
	v_pk_mul_f32 v[50:51], v[64:65], v[46:47]
	v_pk_mul_f32 v[52:53], v[70:71], v[48:49]
	v_cvt_pk_bf16_f32 v50, v50, v51
	v_cvt_pk_bf16_f32 v51, v52, v53
	global_store_dwordx4 v[78:79], v[46:49], off
	global_store_dwordx2 v[74:75], v[50:51], off
	v_lshlrev_b64 v[74:75], 12, v[76:77]
	v_lshlrev_b64 v[76:77], 11, v[76:77]
	v_cndmask_b32_e32 v79, 0, v83, vcc
	v_cndmask_b32_e32 v78, v61, v82, vcc
	v_cndmask_b32_e32 v81, v1, v86, vcc
	v_cndmask_b32_e32 v80, v87, v88, vcc
	v_lshl_add_u64 v[74:75], s[74:75], 0, v[74:75]
	v_lshl_add_u64 v[76:77], s[10:11], 0, v[76:77]
	v_lshlrev_b64 v[78:79], 12, v[78:79]
	v_lshl_add_u64 v[78:79], v[80:81], 0, v[78:79]
	v_lshl_add_u64 v[74:75], v[74:75], 0, s[14:15]
	v_lshl_add_u64 v[76:77], v[76:77], 0, s[16:17]
	v_lshl_add_u64 v[78:79], v[78:79], 0, s[14:15]
	v_lshl_add_u64 v[74:75], v[74:75], 0, v[66:67]
	v_lshl_add_u64 v[76:77], v[76:77], 0, v[62:63]
	v_lshl_add_u64 v[78:79], v[78:79], 0, v[66:67]
	v_add_u32_e32 v61, 0xffffe00d, v60
	v_cmp_gt_i32_e32 vcc, s41, v84
	v_lshlrev_b64 v[82:83], 11, v[82:83]
	v_lshl_add_u64 v[82:83], s[10:11], 0, v[82:83]
	v_cndmask_b32_e32 v101, 0, v85, vcc
	v_cndmask_b32_e32 v100, v61, v84, vcc
	v_cndmask_b32_e32 v103, v1, v86, vcc
	v_cndmask_b32_e32 v102, v87, v88, vcc
	v_lshlrev_b64 v[100:101], 12, v[100:101]
	v_lshl_add_u64 v[100:101], v[102:103], 0, v[100:101]
	v_lshl_add_u64 v[82:83], v[82:83], 0, s[16:17]
	v_lshl_add_u64 v[100:101], v[100:101], 0, s[14:15]
	v_lshl_add_u64 v[82:83], v[82:83], 0, v[62:63]
	v_lshl_add_u64 v[100:101], v[100:101], 0, v[66:67]
	v_cmp_lt_i32_e32 vcc, v91, v90
	v_or_b32_e32 v102, 14, v60
	v_ashrrev_i32_e32 v103, 31, v102
	v_cndmask_b32_e32 v73, v89, v91, vcc
	v_cmp_gt_i32_e32 vcc, s41, v102
	v_lshlrev_b32_e32 v114, 2, v73
	s_waitcnt lgkmcnt(0)
	v_pk_fma_f32 v[50:51], v[2:3], v[54:55], v[226:227]
	v_pk_fma_f32 v[52:53], v[4:5], v[56:57], v[228:229]
	v_pk_mul_f32 v[54:55], v[64:65], v[50:51]
	v_pk_mul_f32 v[56:57], v[70:71], v[52:53]
	v_cvt_pk_bf16_f32 v54, v54, v55
	v_cvt_pk_bf16_f32 v55, v56, v57
	global_store_dwordx4 v[74:75], v[50:53], off
	global_store_dwordx2 v[76:77], v[54:55], off
	ds_read_b128 v[74:77], v72 offset:12480
	ds_read_b128 v[78:81], v72 offset:13520
	s_waitcnt lgkmcnt(1)
	v_pk_fma_f32 v[54:55], v[2:3], v[74:75], v[230:231]
	v_pk_fma_f32 v[56:57], v[4:5], v[76:77], v[232:233]
	v_pk_mul_f32 v[74:75], v[64:65], v[54:55]
	v_pk_mul_f32 v[76:77], v[70:71], v[56:57]
	v_cvt_pk_bf16_f32 v74, v74, v75
	v_cvt_pk_bf16_f32 v75, v76, v77
	global_store_dwordx4 v[98:99], v[54:57], off
	global_store_dwordx2 v[82:83], v[74:75], off
	v_add_u32_e32 v98, 0xffffe00e, v60
	v_lshlrev_b64 v[60:61], 12, v[84:85]
	v_lshl_add_u64 v[60:61], s[74:75], 0, v[60:61]
	v_lshlrev_b64 v[82:83], 11, v[84:85]
	v_cndmask_b32_e32 v85, 0, v103, vcc
	v_cndmask_b32_e32 v84, v98, v102, vcc
	v_lshl_add_u64 v[60:61], v[60:61], 0, s[14:15]
	v_cndmask_b32_e32 v99, v1, v86, vcc
	v_cndmask_b32_e32 v98, v87, v88, vcc
	v_lshl_add_u64 v[82:83], s[10:11], 0, v[82:83]
	v_lshlrev_b64 v[84:85], 12, v[84:85]
	v_lshl_add_u64 v[60:61], v[60:61], 0, v[66:67]
	v_lshl_add_u64 v[84:85], v[98:99], 0, v[84:85]
	v_lshl_add_u64 v[82:83], v[82:83], 0, s[16:17]
	v_lshl_add_u64 v[84:85], v[84:85], 0, s[14:15]
	v_lshl_add_u64 v[82:83], v[82:83], 0, v[62:63]
	v_lshl_add_u64 v[84:85], v[84:85], 0, v[66:67]
	v_cmp_lt_i32_e32 vcc, v92, v90
	v_mad_u64_u32 v[98:99], s[4:5], v59, s40, v[66:67]
	v_cmp_eq_u32_e64 s[4:5], 0, v110
	s_waitcnt lgkmcnt(0)
	v_pk_fma_f32 v[74:75], v[2:3], v[78:79], v[234:235]
	v_pk_fma_f32 v[76:77], v[4:5], v[80:81], v[236:237]
	global_store_dwordx4 v[60:61], v[74:77], off
	v_pk_mul_f32 v[60:61], v[64:65], v[74:75]
	v_pk_mul_f32 v[78:79], v[70:71], v[76:77]
	v_cvt_pk_bf16_f32 v60, v60, v61
	v_cvt_pk_bf16_f32 v61, v78, v79
	global_store_dwordx2 v[82:83], v[60:61], off
	v_cndmask_b32_e32 v60, v89, v92, vcc
	v_cmp_lt_i32_e32 vcc, v93, v90
	v_lshlrev_b32_e32 v115, 2, v60
	v_add_u32_e32 v60, s12, v59
	v_cndmask_b32_e32 v61, v89, v93, vcc
	v_cmp_lt_i32_e32 vcc, v94, v90
	v_add_u32_e32 v59, 0xffffe000, v60
	v_lshlrev_b32_e32 v116, 2, v61
	v_cndmask_b32_e32 v82, v89, v94, vcc
	v_cmp_lt_i32_e32 vcc, v95, v90
	v_ashrrev_i32_e32 v61, 31, v60
	v_lshlrev_b32_e32 v117, 2, v82
	v_cndmask_b32_e32 v83, v89, v95, vcc
	v_cmp_lt_i32_e32 vcc, v96, v90
	v_lshlrev_b32_e32 v118, 2, v83
	ds_read_b128 v[82:85], v72 offset:14560
	ds_read_b128 v[98:101], v98
	v_cndmask_b32_e32 v113, v89, v96, vcc
	v_cmp_gt_i32_e32 vcc, s41, v60
	v_lshlrev_b64 v[72:73], 12, v[102:103]
	v_lshlrev_b64 v[102:103], 11, v[102:103]
	v_cndmask_b32_e32 v104, v59, v60, vcc
	v_add_f32_e32 v59, v6, v9
	v_pk_mul_f32 v[6:7], v[10:11], v[10:11]
	v_cndmask_b32_e32 v105, 0, v61, vcc
	v_pk_mul_f32 v[8:9], v[12:13], v[12:13]
	v_add_f32_e32 v6, v6, v7
	v_cndmask_b32_e32 v107, v1, v86, vcc
	v_cndmask_b32_e32 v106, v87, v88, vcc
	v_lshlrev_b64 v[104:105], 12, v[104:105]
	v_add_f32_e32 v6, v6, v8
	v_lshl_add_u64 v[104:105], v[106:107], 0, v[104:105]
	v_add_f32_e32 v106, v6, v9
	v_pk_mul_f32 v[6:7], v[14:15], v[14:15]
	v_pk_mul_f32 v[8:9], v[16:17], v[16:17]
	v_add_f32_e32 v6, v6, v7
	v_add_f32_e32 v6, v6, v8
	v_add_f32_e32 v107, v6, v9
	v_pk_mul_f32 v[6:7], v[18:19], v[18:19]
	v_pk_mul_f32 v[8:9], v[20:21], v[20:21]
	v_add_f32_e32 v6, v6, v7
	v_add_f32_e32 v6, v6, v8
	v_add_f32_e32 v20, v6, v9
	v_pk_mul_f32 v[6:7], v[22:23], v[22:23]
	v_pk_mul_f32 v[8:9], v[24:25], v[24:25]
	v_add_f32_e32 v6, v6, v7
	v_add_f32_e32 v6, v6, v8
	v_add_f32_e32 v21, v6, v9
	v_pk_mul_f32 v[6:7], v[26:27], v[26:27]
	v_pk_mul_f32 v[8:9], v[28:29], v[28:29]
	v_add_f32_e32 v6, v6, v7
	v_add_f32_e32 v6, v6, v8
	v_add_f32_e32 v22, v6, v9
	v_pk_mul_f32 v[6:7], v[30:31], v[30:31]
	v_pk_mul_f32 v[8:9], v[32:33], v[32:33]
	v_add_f32_e32 v6, v6, v7
	v_add_f32_e32 v6, v6, v8
	v_lshl_add_u64 v[72:73], s[74:75], 0, v[72:73]
	v_lshl_add_u64 v[102:103], s[10:11], 0, v[102:103]
	v_add_f32_e32 v23, v6, v9
	v_lshl_add_u64 v[72:73], v[72:73], 0, s[14:15]
	v_lshl_add_u64 v[102:103], v[102:103], 0, s[16:17]
	v_lshl_add_u64 v[104:105], v[104:105], 0, s[14:15]
	v_lshl_add_u64 v[72:73], v[72:73], 0, v[66:67]
	v_lshl_add_u64 v[102:103], v[102:103], 0, v[62:63]
	v_lshl_add_u64 v[104:105], v[104:105], 0, v[66:67]
	v_pk_mul_f32 v[14:15], v[34:35], v[34:35]
	v_pk_mul_f32 v[16:17], v[36:37], v[36:37]
	v_add_f32_e32 v14, v14, v15
	v_add_f32_e32 v14, v14, v16
	v_add_f32_e32 v24, v14, v17
	v_pk_mul_f32 v[14:15], v[38:39], v[38:39]
	v_pk_mul_f32 v[16:17], v[40:41], v[40:41]
	v_add_f32_e32 v14, v14, v15
	v_add_f32_e32 v14, v14, v16
	v_add_f32_e32 v14, v14, v17
	v_cmp_eq_u32_e32 vcc, 0, v97
	v_pk_mul_f32 v[16:17], v[44:45], v[44:45]
	v_lshlrev_b64 v[108:109], 12, v[60:61]
	v_cndmask_b32_e32 v18, v14, v59, vcc
	s_waitcnt lgkmcnt(1)
	v_pk_fma_f32 v[6:7], v[2:3], v[82:83], v[238:239]
	v_pk_fma_f32 v[8:9], v[4:5], v[84:85], v[240:241]
	v_pk_mul_f32 v[10:11], v[64:65], v[6:7]
	v_pk_mul_f32 v[12:13], v[70:71], v[8:9]
	v_cvt_pk_bf16_f32 v10, v10, v11
	v_cvt_pk_bf16_f32 v11, v12, v13
	global_store_dwordx4 v[72:73], v[6:9], off
	global_store_dwordx2 v[102:103], v[10:11], off
	v_cndmask_b32_e32 v14, v59, v14, vcc
	ds_bpermute_b32 v19, v114, v14
	v_pk_mul_f32 v[14:15], v[42:43], v[42:43]
	v_pk_mul_f32 v[6:7], v[6:7], v[6:7]
	v_add_f32_e32 v14, v14, v15
	v_add_f32_e32 v14, v14, v16
	v_add_f32_e32 v25, v14, v17
	v_cndmask_b32_e32 v14, v106, v25, vcc
	ds_bpermute_b32 v26, v114, v14
	v_pk_mul_f32 v[14:15], v[46:47], v[46:47]
	v_pk_mul_f32 v[16:17], v[48:49], v[48:49]
	v_add_f32_e32 v14, v14, v15
	v_add_f32_e32 v14, v14, v16
	v_add_f32_e32 v14, v14, v17
	v_cndmask_b32_e32 v15, v107, v14, vcc
	ds_bpermute_b32 v15, v114, v15
	v_cndmask_b32_e32 v16, v25, v106, vcc
	v_cndmask_b32_e32 v14, v14, v107, vcc
	s_waitcnt lgkmcnt(1)
	v_add_f32_e32 v25, v16, v26
	v_pk_mul_f32 v[16:17], v[52:53], v[52:53]
	s_waitcnt lgkmcnt(0)
	v_add_f32_e32 v26, v14, v15
	v_pk_mul_f32 v[14:15], v[50:51], v[50:51]
	v_add_f32_e32 v27, v18, v19
	v_add_f32_e32 v14, v14, v15
	v_add_f32_e32 v16, v14, v16
	v_pk_mul_f32 v[14:15], v[54:55], v[54:55]
	v_pk_mul_f32 v[18:19], v[56:57], v[56:57]
	v_add_f32_e32 v14, v14, v15
	v_add_f32_e32 v14, v14, v18
	v_add_f32_e32 v14, v14, v19
	v_cndmask_b32_e32 v15, v21, v14, vcc
	ds_bpermute_b32 v15, v114, v15
	v_cndmask_b32_e32 v14, v14, v21, vcc
	v_add_f32_e32 v18, v16, v17
	v_cndmask_b32_e32 v16, v20, v18, vcc
	v_pk_mul_f32 v[8:9], v[8:9], v[8:9]
	s_waitcnt lgkmcnt(0)
	v_add_f32_e32 v14, v14, v15
	v_cndmask_b32_e64 v21, v14, v27, s[4:5]
	v_cndmask_b32_e64 v14, v27, v14, s[4:5]
	ds_bpermute_b32 v27, v115, v14
	v_pk_mul_f32 v[14:15], v[74:75], v[74:75]
	v_add_f32_e32 v6, v6, v7
	ds_bpermute_b32 v19, v114, v16
	v_pk_mul_f32 v[16:17], v[76:77], v[76:77]
	v_add_f32_e32 v14, v14, v15
	v_add_f32_e32 v6, v6, v8
	v_add_f32_e32 v14, v14, v16
	v_add_f32_e32 v6, v6, v9
	v_add_f32_e32 v14, v14, v17
	v_cndmask_b32_e32 v7, v23, v6, vcc
	v_cndmask_b32_e32 v15, v22, v14, vcc
	ds_bpermute_b32 v7, v114, v7
	ds_bpermute_b32 v15, v114, v15
	v_cndmask_b32_e32 v6, v6, v23, vcc
	v_cndmask_b32_e32 v16, v18, v20, vcc
	v_cndmask_b32_e32 v14, v14, v22, vcc
	s_waitcnt lgkmcnt(1)
	v_add_f32_e32 v18, v6, v7
	s_waitcnt lgkmcnt(0)
	v_add_f32_e32 v14, v14, v15
	v_cndmask_b32_e64 v6, v26, v18, s[4:5]
	v_add_f32_e32 v16, v16, v19
	v_cndmask_b32_e64 v8, v25, v14, s[4:5]
	ds_bpermute_b32 v19, v115, v6
	v_cndmask_b32_e64 v15, v14, v25, s[4:5]
	ds_bpermute_b32 v14, v115, v8
	v_add_f32_e32 v17, v21, v27
	v_lshl_add_u64 v[108:109], s[74:75], 0, v[108:109]
	v_lshlrev_b64 v[60:61], 11, v[60:61]
	v_pk_fma_f32 v[2:3], v[2:3], v[98:99], v[248:249]
	v_pk_fma_f32 v[4:5], v[4:5], v[100:101], v[250:251]
	v_pk_mul_f32 v[6:7], v[2:3], v[2:3]
	v_pk_mul_f32 v[8:9], v[4:5], v[4:5]
	v_add_f32_e32 v6, v6, v7
	v_add_f32_e32 v6, v6, v8
	v_add_f32_e32 v6, v6, v9
	v_cndmask_b32_e32 v7, v24, v6, vcc
	ds_bpermute_b32 v7, v114, v7
	v_cndmask_b32_e32 v6, v6, v24, vcc
	v_cndmask_b32_e64 v8, v18, v26, s[4:5]
	s_waitcnt lgkmcnt(1)
	v_add_f32_e32 v10, v15, v14
	v_add_f32_e32 v8, v8, v19
	s_waitcnt lgkmcnt(0)
	v_add_f32_e32 v6, v6, v7
	v_cndmask_b32_e64 v7, v16, v6, s[4:5]
	ds_bpermute_b32 v7, v115, v7
	v_cndmask_b32_e64 v6, v6, v16, s[4:5]
	v_cmp_eq_u32_e32 vcc, 0, v111
	s_waitcnt lgkmcnt(0)
	v_add_f32_e32 v13, v6, v7
	v_cndmask_b32_e32 v11, v8, v17, vcc
	v_cndmask_b32_e32 v8, v17, v8, vcc
	v_cndmask_b32_e32 v6, v10, v13, vcc
	ds_bpermute_b32 v12, v116, v8
	ds_bpermute_b32 v14, v116, v6
	v_cndmask_b32_e32 v10, v13, v10, vcc
	v_cmp_eq_u32_e32 vcc, 0, v112
	v_lshl_add_u64 v[8:9], v[108:109], 0, s[14:15]
	s_waitcnt lgkmcnt(1)
	v_add_f32_e32 v11, v11, v12
	s_waitcnt lgkmcnt(0)
	v_add_f32_e32 v10, v10, v14
	v_cndmask_b32_e32 v12, v11, v10, vcc
	ds_bpermute_b32 v12, v117, v12
	v_lshl_add_u64 v[8:9], v[8:9], 0, v[66:67]
	global_store_dwordx4 v[8:9], v[2:5], off
	v_cndmask_b32_e32 v8, v10, v11, vcc
	v_lshl_add_u64 v[6:7], s[10:11], 0, v[60:61]
	s_waitcnt lgkmcnt(0)
	v_add_f32_e32 v10, v8, v12
	ds_bpermute_b32 v11, v118, v10
	v_pk_mul_f32 v[2:3], v[64:65], v[2:3]
	v_lshl_add_u64 v[6:7], v[6:7], 0, s[16:17]
	v_cvt_pk_bf16_f32 v8, v2, v3
	v_lshlrev_b32_e32 v3, 2, v113
	s_waitcnt lgkmcnt(0)
	v_add_f32_e32 v2, v10, v11
	ds_bpermute_b32 v3, v3, v2
	v_pk_mul_f32 v[4:5], v[70:71], v[4:5]
	s_nop 0
	v_cvt_pk_bf16_f32 v9, v4, v5
	v_lshl_add_u64 v[4:5], v[6:7], 0, v[62:63]
	global_store_dwordx2 v[4:5], v[8:9], off
	v_and_b32_e32 v4, 3, v69
	v_cmp_eq_u32_e32 vcc, 0, v4
	s_and_saveexec_b64 s[4:5], vcc
	s_cbranch_execz .LBB0_625
	s_lshl_b64 s[12:13], s[12:13], 2
	s_add_u32 s12, s23, s12
	s_addc_u32 s13, s24, s13
	v_ashrrev_i32_e32 v59, 31, v58
	s_waitcnt lgkmcnt(0)
	v_add_f32_e32 v4, v2, v3
	v_lshl_add_u64 v[2:3], v[58:59], 2, s[12:13]
	v_mov_b32_e32 v69, v67
	v_lshl_add_u64 v[2:3], v[2:3], 0, v[68:69]
	global_atomic_add_f32 v[2:3], v4, off
	s_branch .LBB0_625

.LBB0_704:
	s_lshl_b32 s16, s43, 8
	s_ashr_i32 s17, s16, 31
	v_mov_b32_e32 v66, v212
	s_lshl_b32 s14, s44, 8
	s_lshl_b64 s[4:5], s[16:17], 11
	s_add_u32 s4, s19, s4
	v_ashrrev_i32_e32 v34, 3, v66
	v_ashrrev_i32_e32 v35, 31, v34
	s_addc_u32 s5, s20, s5
	v_lshlrev_b64 v[2:3], 11, v[34:35]
	v_lshlrev_b32_e32 v6, 4, v66
	v_lshl_add_u64 v[4:5], s[4:5], 0, v[2:3]
	v_and_b32_e32 v130, 0x70, v6
	v_lshl_add_u64 v[134:135], v[4:5], 0, v[130:131]
	v_add_co_u32_e32 v138, vcc, s30, v134
	s_ashr_i32 s15, s14, 31
	s_nop 0
	v_addc_co_u32_e32 v139, vcc, 0, v135, vcc
	s_lshl_b64 s[46:47], s[14:15], 11
	v_add_co_u32_e32 v140, vcc, s31, v134
	s_add_u32 s46, s21, s46
	s_nop 0
	v_addc_co_u32_e32 v141, vcc, 0, v135, vcc
	s_addc_u32 s47, s22, s47
	v_add_co_u32_e32 v142, vcc, s34, v134
	v_lshl_add_u64 v[2:3], s[46:47], 0, v[2:3]
	s_nop 0
	v_addc_co_u32_e32 v143, vcc, 0, v135, vcc
	v_lshl_add_u64 v[136:137], v[2:3], 0, v[130:131]
	global_load_dwordx4 v[2:5], v[134:135], off
	global_load_dwordx4 v[6:9], v[138:139], off
	global_load_dwordx4 v[10:13], v[140:141], off
	global_load_dwordx4 v[14:17], v[142:143], off
	global_load_dwordx4 v[18:21], v[136:137], off
	v_add_co_u32_e32 v144, vcc, s30, v136
	v_mad_u64_u32 v[148:149], s[4:5], v34, s26, v[130:131]
	s_nop 0
	v_addc_co_u32_e32 v145, vcc, 0, v137, vcc
	v_add_co_u32_e32 v146, vcc, s31, v136
	global_load_dwordx4 v[22:25], v[144:145], off
	s_nop 0
	v_addc_co_u32_e32 v147, vcc, 0, v137, vcc
	v_add_co_u32_e32 v150, vcc, s34, v136
	global_load_dwordx4 v[26:29], v[146:147], off
	s_nop 0
	v_addc_co_u32_e32 v151, vcc, 0, v137, vcc
	global_load_dwordx4 v[30:33], v[150:151], off
	global_load_dwordx4 v[34:37], v[134:135], off offset:128
	global_load_dwordx4 v[38:41], v[138:139], off offset:128
	global_load_dwordx4 v[42:45], v[140:141], off offset:128
	global_load_dwordx4 v[46:49], v[142:143], off offset:128
	global_load_dwordx4 v[50:53], v[136:137], off offset:128
	global_load_dwordx4 v[54:57], v[144:145], off offset:128
	global_load_dwordx4 v[58:61], v[146:147], off offset:128
	global_load_dwordx4 v[62:65], v[150:151], off offset:128
	v_bfe_u32 v149, v153, 5, 1
	v_add_u32_e32 v155, 0x12000, v148
	s_waitcnt vmcnt(15)
	ds_write_b128 v148, v[2:5]
	s_waitcnt vmcnt(14)
	ds_write_b128 v148, v[6:9] offset:9216
	s_waitcnt vmcnt(13)
	ds_write_b128 v148, v[10:13] offset:18432
	s_waitcnt vmcnt(12)
	ds_write_b128 v148, v[14:17] offset:27648
	s_waitcnt vmcnt(11)
	ds_write_b128 v148, v[18:21] offset:36864
	s_waitcnt vmcnt(10)
	ds_write_b128 v148, v[22:25] offset:46080
	s_waitcnt vmcnt(9)
	ds_write_b128 v148, v[26:29] offset:55296
	s_waitcnt vmcnt(8)
	ds_write_b128 v148, v[30:33] offset:64512
	s_waitcnt lgkmcnt(0)
	s_barrier
	global_load_dwordx4 v[156:159], v[138:139], off offset:256
	global_load_dwordx4 v[160:163], v[140:141], off offset:256
	global_load_dwordx4 v[164:167], v[134:135], off offset:256
	global_load_dwordx4 v[168:171], v[136:137], off offset:256
	global_load_dwordx4 v[172:175], v[142:143], off offset:256
	global_load_dwordx4 v[176:179], v[144:145], off offset:256
	global_load_dwordx4 v[180:183], v[146:147], off offset:256
	global_load_dwordx4 v[184:187], v[150:151], off offset:256
	v_and_b32_e32 v2, 31, v66
	v_lshrrev_b32_e32 v3, 1, v66
	v_and_or_b32 v4, v3, s27, v2
	v_and_b32_e32 v2, 16, v3
	v_and_b32_e32 v3, 0xdf, v66
	v_mad_u32_u24 v154, v3, s26, v2
	v_add_u32_e32 v130, 0x12000, v154
	s_waitcnt vmcnt(15)
	ds_write_b128 v155, v[34:37]
	s_waitcnt vmcnt(14)
	ds_write_b128 v155, v[38:41] offset:9216
	s_waitcnt vmcnt(13)
	ds_write_b128 v155, v[42:45] offset:18432
	s_waitcnt vmcnt(12)
	ds_write_b128 v155, v[46:49] offset:27648
	s_waitcnt vmcnt(11)
	ds_write_b128 v155, v[50:53] offset:36864
	s_waitcnt vmcnt(10)
	ds_write_b128 v155, v[54:57] offset:46080
	s_waitcnt vmcnt(9)
	ds_write_b128 v155, v[58:61] offset:55296
	s_waitcnt vmcnt(8)
	ds_write_b128 v155, v[62:65] offset:64512
	v_mad_u64_u32 v[132:133], s[4:5], v4, s26, v[2:3]
	ds_read_b128 v[2:5], v154 offset:36864
	ds_read_b128 v[188:191], v154 offset:36896
	ds_read_b128 v[6:9], v154 offset:41472
	ds_read_b128 v[192:195], v154 offset:41504
	ds_read_b128 v[10:13], v132
	ds_read_b128 v[196:199], v132 offset:32
	ds_read_b128 v[14:17], v132 offset:4608
	ds_read_b128 v[200:203], v132 offset:4640
	ds_read_b128 v[18:21], v132 offset:9216
	ds_read_b128 v[204:207], v132 offset:9248
	ds_read_b128 v[208:211], v132 offset:13824
	ds_read_b128 v[214:217], v132 offset:13856
	s_waitcnt lgkmcnt(7)
	v_mfma_f32_32x32x16_bf16 v[114:129], v[10:13], v[2:5], 0
	v_mfma_f32_32x32x16_bf16 v[82:97], v[10:13], v[6:9], 0
	s_waitcnt lgkmcnt(5)
	v_mfma_f32_32x32x16_bf16 v[98:113], v[14:17], v[2:5], 0
	v_mfma_f32_32x32x16_bf16 v[66:81], v[14:17], v[6:9], 0
	s_waitcnt lgkmcnt(3)
	v_mfma_f32_32x32x16_bf16 v[50:65], v[18:21], v[2:5], 0
	v_mfma_f32_32x32x16_bf16 v[18:33], v[18:21], v[6:9], 0
	s_waitcnt lgkmcnt(1)
	v_mfma_f32_32x32x16_bf16 v[34:49], v[208:211], v[2:5], 0
	v_mfma_f32_32x32x16_bf16 v[2:17], v[208:211], v[6:9], 0
	ds_read_b128 v[208:211], v154 offset:36928
	ds_read_b128 v[218:221], v154 offset:41536
	ds_read_b128 v[222:225], v132 offset:64
	ds_read_b128 v[226:229], v132 offset:4672
	ds_read_b128 v[230:233], v132 offset:9280
	ds_read_b128 v[234:237], v132 offset:13888
	v_mfma_f32_32x32x16_bf16 v[114:129], v[196:199], v[188:191], v[114:129]
	v_mfma_f32_32x32x16_bf16 v[82:97], v[196:199], v[192:195], v[82:97]
	v_mfma_f32_32x32x16_bf16 v[98:113], v[200:203], v[188:191], v[98:113]
	v_mfma_f32_32x32x16_bf16 v[66:81], v[200:203], v[192:195], v[66:81]
	v_mfma_f32_32x32x16_bf16 v[50:65], v[204:207], v[188:191], v[50:65]
	v_mfma_f32_32x32x16_bf16 v[18:33], v[204:207], v[192:195], v[18:33]
	s_waitcnt lgkmcnt(6)
	v_mfma_f32_32x32x16_bf16 v[34:49], v[214:217], v[188:191], v[34:49]
	v_mfma_f32_32x32x16_bf16 v[2:17], v[214:217], v[192:195], v[2:17]
	ds_read_b128 v[188:191], v154 offset:36960
	ds_read_b128 v[192:195], v154 offset:41568
	ds_read_b128 v[196:199], v132 offset:96
	ds_read_b128 v[200:203], v132 offset:4704
	ds_read_b128 v[204:207], v132 offset:9312
	ds_read_b128 v[214:217], v132 offset:13920
	s_waitcnt lgkmcnt(9)
	v_mfma_f32_32x32x16_bf16 v[114:129], v[222:225], v[208:211], v[114:129]
	v_mfma_f32_32x32x16_bf16 v[82:97], v[222:225], v[218:221], v[82:97]
	s_waitcnt lgkmcnt(8)
	v_mfma_f32_32x32x16_bf16 v[98:113], v[226:229], v[208:211], v[98:113]
	v_mfma_f32_32x32x16_bf16 v[66:81], v[226:229], v[218:221], v[66:81]
	s_waitcnt lgkmcnt(7)
	v_mfma_f32_32x32x16_bf16 v[50:65], v[230:233], v[208:211], v[50:65]
	v_mfma_f32_32x32x16_bf16 v[18:33], v[230:233], v[218:221], v[18:33]
	s_waitcnt lgkmcnt(6)
	v_mfma_f32_32x32x16_bf16 v[34:49], v[234:237], v[208:211], v[34:49]
	v_mfma_f32_32x32x16_bf16 v[2:17], v[234:237], v[218:221], v[2:17]
	s_waitcnt lgkmcnt(3)
	v_mfma_f32_32x32x16_bf16 v[114:129], v[196:199], v[188:191], v[114:129]
	v_mfma_f32_32x32x16_bf16 v[82:97], v[196:199], v[192:195], v[82:97]
	s_waitcnt lgkmcnt(2)
	v_mfma_f32_32x32x16_bf16 v[98:113], v[200:203], v[188:191], v[98:113]
	v_mfma_f32_32x32x16_bf16 v[66:81], v[200:203], v[192:195], v[66:81]
	s_waitcnt lgkmcnt(1)
	v_mfma_f32_32x32x16_bf16 v[50:65], v[204:207], v[188:191], v[50:65]
	v_mfma_f32_32x32x16_bf16 v[18:33], v[204:207], v[192:195], v[18:33]
	s_waitcnt lgkmcnt(0)
	v_mfma_f32_32x32x16_bf16 v[34:49], v[214:217], v[188:191], v[34:49]
	v_mfma_f32_32x32x16_bf16 v[2:17], v[214:217], v[192:195], v[2:17]
	s_barrier
	global_load_dwordx4 v[188:191], v[138:139], off offset:384
	global_load_dwordx4 v[192:195], v[140:141], off offset:384
	global_load_dwordx4 v[196:199], v[134:135], off offset:384
	global_load_dwordx4 v[200:203], v[136:137], off offset:384
	global_load_dwordx4 v[204:207], v[142:143], off offset:384
	global_load_dwordx4 v[208:211], v[144:145], off offset:384
	global_load_dwordx4 v[214:217], v[146:147], off offset:384
	global_load_dwordx4 v[218:221], v[150:151], off offset:384
	s_waitcnt vmcnt(13)
	ds_write_b128 v148, v[164:167]
	ds_write_b128 v148, v[156:159] offset:9216
	ds_write_b128 v148, v[160:163] offset:18432
	s_waitcnt vmcnt(11)
	ds_write_b128 v148, v[172:175] offset:27648
	ds_write_b128 v148, v[168:171] offset:36864
	s_waitcnt vmcnt(10)
	ds_write_b128 v148, v[176:179] offset:46080
	s_waitcnt vmcnt(9)
	ds_write_b128 v148, v[180:183] offset:55296
	s_waitcnt vmcnt(8)
	ds_write_b128 v148, v[184:187] offset:64512
	v_add_u32_e32 v133, 0x12000, v132
	ds_read_b128 v[156:159], v130 offset:36864
	ds_read_b128 v[160:163], v130 offset:36896
	ds_read_b128 v[164:167], v130 offset:41472
	ds_read_b128 v[168:171], v130 offset:41504
	ds_read_b128 v[172:175], v133
	ds_read_b128 v[176:179], v133 offset:32
	ds_read_b128 v[180:183], v133 offset:4608
	ds_read_b128 v[184:187], v133 offset:4640
	ds_read_b128 v[222:225], v133 offset:9216
	ds_read_b128 v[226:229], v133 offset:9248
	ds_read_b128 v[230:233], v133 offset:13824
	ds_read_b128 v[234:237], v133 offset:13856
	s_waitcnt lgkmcnt(7)
	v_mfma_f32_32x32x16_bf16 v[114:129], v[172:175], v[156:159], v[114:129]
	v_mfma_f32_32x32x16_bf16 v[82:97], v[172:175], v[164:167], v[82:97]
	s_waitcnt lgkmcnt(5)
	v_mfma_f32_32x32x16_bf16 v[98:113], v[180:183], v[156:159], v[98:113]
	v_mfma_f32_32x32x16_bf16 v[66:81], v[180:183], v[164:167], v[66:81]
	s_waitcnt lgkmcnt(3)
	v_mfma_f32_32x32x16_bf16 v[50:65], v[222:225], v[156:159], v[50:65]
	v_mfma_f32_32x32x16_bf16 v[18:33], v[222:225], v[164:167], v[18:33]
	s_waitcnt lgkmcnt(1)
	v_mfma_f32_32x32x16_bf16 v[34:49], v[230:233], v[156:159], v[34:49]
	v_mfma_f32_32x32x16_bf16 v[2:17], v[230:233], v[164:167], v[2:17]
	ds_read_b128 v[156:159], v130 offset:36928
	ds_read_b128 v[164:167], v130 offset:41536
	ds_read_b128 v[172:175], v133 offset:64
	ds_read_b128 v[180:183], v133 offset:4672
	ds_read_b128 v[222:225], v133 offset:9280
	ds_read_b128 v[230:233], v133 offset:13888
	v_mfma_f32_32x32x16_bf16 v[114:129], v[176:179], v[160:163], v[114:129]
	v_mfma_f32_32x32x16_bf16 v[82:97], v[176:179], v[168:171], v[82:97]
	v_mfma_f32_32x32x16_bf16 v[98:113], v[184:187], v[160:163], v[98:113]
	v_mfma_f32_32x32x16_bf16 v[66:81], v[184:187], v[168:171], v[66:81]
	v_mfma_f32_32x32x16_bf16 v[50:65], v[226:229], v[160:163], v[50:65]
	v_mfma_f32_32x32x16_bf16 v[18:33], v[226:229], v[168:171], v[18:33]
	s_waitcnt lgkmcnt(6)
	v_mfma_f32_32x32x16_bf16 v[34:49], v[234:237], v[160:163], v[34:49]
	v_mfma_f32_32x32x16_bf16 v[2:17], v[234:237], v[168:171], v[2:17]
	ds_read_b128 v[160:163], v130 offset:36960
	ds_read_b128 v[168:171], v130 offset:41568
	ds_read_b128 v[176:179], v133 offset:96
	ds_read_b128 v[184:187], v133 offset:4704
	ds_read_b128 v[226:229], v133 offset:9312
	ds_read_b128 v[234:237], v133 offset:13920
	s_waitcnt lgkmcnt(9)
	v_mfma_f32_32x32x16_bf16 v[114:129], v[172:175], v[156:159], v[114:129]
	v_mfma_f32_32x32x16_bf16 v[82:97], v[172:175], v[164:167], v[82:97]
	s_waitcnt lgkmcnt(8)
	v_mfma_f32_32x32x16_bf16 v[98:113], v[180:183], v[156:159], v[98:113]
	v_mfma_f32_32x32x16_bf16 v[66:81], v[180:183], v[164:167], v[66:81]
	s_waitcnt lgkmcnt(7)
	v_mfma_f32_32x32x16_bf16 v[50:65], v[222:225], v[156:159], v[50:65]
	v_mfma_f32_32x32x16_bf16 v[18:33], v[222:225], v[164:167], v[18:33]
	s_waitcnt lgkmcnt(6)
	v_mfma_f32_32x32x16_bf16 v[34:49], v[230:233], v[156:159], v[34:49]
	v_mfma_f32_32x32x16_bf16 v[2:17], v[230:233], v[164:167], v[2:17]
	s_waitcnt lgkmcnt(3)
	v_mfma_f32_32x32x16_bf16 v[114:129], v[176:179], v[160:163], v[114:129]
	v_mfma_f32_32x32x16_bf16 v[82:97], v[176:179], v[168:171], v[82:97]
	s_waitcnt lgkmcnt(2)
	v_mfma_f32_32x32x16_bf16 v[98:113], v[184:187], v[160:163], v[98:113]
	v_mfma_f32_32x32x16_bf16 v[66:81], v[184:187], v[168:171], v[66:81]
	s_waitcnt lgkmcnt(1)
	v_mfma_f32_32x32x16_bf16 v[50:65], v[226:229], v[160:163], v[50:65]
	v_mfma_f32_32x32x16_bf16 v[18:33], v[226:229], v[168:171], v[18:33]
	s_waitcnt lgkmcnt(0)
	v_mfma_f32_32x32x16_bf16 v[34:49], v[234:237], v[160:163], v[34:49]
	v_mfma_f32_32x32x16_bf16 v[2:17], v[234:237], v[168:171], v[2:17]
	s_barrier
	global_load_dwordx4 v[156:159], v[138:139], off offset:512
	global_load_dwordx4 v[160:163], v[140:141], off offset:512
	global_load_dwordx4 v[164:167], v[134:135], off offset:512
	global_load_dwordx4 v[168:171], v[136:137], off offset:512
	global_load_dwordx4 v[172:175], v[142:143], off offset:512
	global_load_dwordx4 v[176:179], v[144:145], off offset:512
	global_load_dwordx4 v[180:183], v[146:147], off offset:512
	global_load_dwordx4 v[184:187], v[150:151], off offset:512
	s_waitcnt vmcnt(13)
	ds_write_b128 v155, v[196:199]
	ds_write_b128 v155, v[188:191] offset:9216
	ds_write_b128 v155, v[192:195] offset:18432
	s_waitcnt vmcnt(11)
	ds_write_b128 v155, v[204:207] offset:27648
	ds_write_b128 v155, v[200:203] offset:36864
	s_waitcnt vmcnt(10)
	ds_write_b128 v155, v[208:211] offset:46080
	s_waitcnt vmcnt(9)
	ds_write_b128 v155, v[214:217] offset:55296
	s_waitcnt vmcnt(8)
	ds_write_b128 v155, v[218:221] offset:64512
	ds_read_b128 v[188:191], v154 offset:36864
	ds_read_b128 v[192:195], v154 offset:36896
	ds_read_b128 v[196:199], v154 offset:41472
	ds_read_b128 v[200:203], v154 offset:41504
	ds_read_b128 v[204:207], v132
	ds_read_b128 v[208:211], v132 offset:32
	ds_read_b128 v[214:217], v132 offset:4608
	ds_read_b128 v[218:221], v132 offset:4640
	ds_read_b128 v[222:225], v132 offset:9216
	ds_read_b128 v[226:229], v132 offset:9248
	ds_read_b128 v[230:233], v132 offset:13824
	ds_read_b128 v[234:237], v132 offset:13856
	s_waitcnt lgkmcnt(7)
	v_mfma_f32_32x32x16_bf16 v[114:129], v[204:207], v[188:191], v[114:129]
	v_mfma_f32_32x32x16_bf16 v[82:97], v[204:207], v[196:199], v[82:97]
	s_waitcnt lgkmcnt(5)
	v_mfma_f32_32x32x16_bf16 v[98:113], v[214:217], v[188:191], v[98:113]
	v_mfma_f32_32x32x16_bf16 v[66:81], v[214:217], v[196:199], v[66:81]
	s_waitcnt lgkmcnt(3)
	v_mfma_f32_32x32x16_bf16 v[50:65], v[222:225], v[188:191], v[50:65]
	v_mfma_f32_32x32x16_bf16 v[18:33], v[222:225], v[196:199], v[18:33]
	s_waitcnt lgkmcnt(1)
	v_mfma_f32_32x32x16_bf16 v[34:49], v[230:233], v[188:191], v[34:49]
	v_mfma_f32_32x32x16_bf16 v[2:17], v[230:233], v[196:199], v[2:17]
	ds_read_b128 v[188:191], v154 offset:36928
	ds_read_b128 v[196:199], v154 offset:41536
	ds_read_b128 v[204:207], v132 offset:64
	ds_read_b128 v[214:217], v132 offset:4672
	ds_read_b128 v[222:225], v132 offset:9280
	ds_read_b128 v[230:233], v132 offset:13888
	v_mfma_f32_32x32x16_bf16 v[114:129], v[208:211], v[192:195], v[114:129]
	v_mfma_f32_32x32x16_bf16 v[82:97], v[208:211], v[200:203], v[82:97]
	v_mfma_f32_32x32x16_bf16 v[98:113], v[218:221], v[192:195], v[98:113]
	v_mfma_f32_32x32x16_bf16 v[66:81], v[218:221], v[200:203], v[66:81]
	v_mfma_f32_32x32x16_bf16 v[50:65], v[226:229], v[192:195], v[50:65]
	v_mfma_f32_32x32x16_bf16 v[18:33], v[226:229], v[200:203], v[18:33]
	s_waitcnt lgkmcnt(6)
	v_mfma_f32_32x32x16_bf16 v[34:49], v[234:237], v[192:195], v[34:49]
	v_mfma_f32_32x32x16_bf16 v[2:17], v[234:237], v[200:203], v[2:17]
	ds_read_b128 v[192:195], v154 offset:36960
	ds_read_b128 v[200:203], v154 offset:41568
	ds_read_b128 v[208:211], v132 offset:96
	ds_read_b128 v[218:221], v132 offset:4704
	ds_read_b128 v[226:229], v132 offset:9312
	ds_read_b128 v[234:237], v132 offset:13920
	s_waitcnt lgkmcnt(9)
	v_mfma_f32_32x32x16_bf16 v[114:129], v[204:207], v[188:191], v[114:129]
	v_mfma_f32_32x32x16_bf16 v[82:97], v[204:207], v[196:199], v[82:97]
	s_waitcnt lgkmcnt(8)
	v_mfma_f32_32x32x16_bf16 v[98:113], v[214:217], v[188:191], v[98:113]
	v_mfma_f32_32x32x16_bf16 v[66:81], v[214:217], v[196:199], v[66:81]
	s_waitcnt lgkmcnt(7)
	v_mfma_f32_32x32x16_bf16 v[50:65], v[222:225], v[188:191], v[50:65]
	v_mfma_f32_32x32x16_bf16 v[18:33], v[222:225], v[196:199], v[18:33]
	s_waitcnt lgkmcnt(6)
	v_mfma_f32_32x32x16_bf16 v[34:49], v[230:233], v[188:191], v[34:49]
	v_mfma_f32_32x32x16_bf16 v[2:17], v[230:233], v[196:199], v[2:17]
	s_waitcnt lgkmcnt(3)
	v_mfma_f32_32x32x16_bf16 v[114:129], v[208:211], v[192:195], v[114:129]
	v_mfma_f32_32x32x16_bf16 v[82:97], v[208:211], v[200:203], v[82:97]
	s_waitcnt lgkmcnt(2)
	v_mfma_f32_32x32x16_bf16 v[98:113], v[218:221], v[192:195], v[98:113]
	v_mfma_f32_32x32x16_bf16 v[66:81], v[218:221], v[200:203], v[66:81]
	s_waitcnt lgkmcnt(1)
	v_mfma_f32_32x32x16_bf16 v[50:65], v[226:229], v[192:195], v[50:65]
	v_mfma_f32_32x32x16_bf16 v[18:33], v[226:229], v[200:203], v[18:33]
	s_waitcnt lgkmcnt(0)
	v_mfma_f32_32x32x16_bf16 v[34:49], v[234:237], v[192:195], v[34:49]
	v_mfma_f32_32x32x16_bf16 v[2:17], v[234:237], v[200:203], v[2:17]
	s_barrier
	global_load_dwordx4 v[188:191], v[138:139], off offset:640
	global_load_dwordx4 v[192:195], v[140:141], off offset:640
	global_load_dwordx4 v[196:199], v[134:135], off offset:640
	global_load_dwordx4 v[200:203], v[136:137], off offset:640
	global_load_dwordx4 v[204:207], v[142:143], off offset:640
	global_load_dwordx4 v[208:211], v[144:145], off offset:640
	global_load_dwordx4 v[214:217], v[146:147], off offset:640
	global_load_dwordx4 v[218:221], v[150:151], off offset:640
	s_waitcnt vmcnt(13)
	ds_write_b128 v148, v[164:167]
	ds_write_b128 v148, v[156:159] offset:9216
	ds_write_b128 v148, v[160:163] offset:18432
	s_waitcnt vmcnt(11)
	ds_write_b128 v148, v[172:175] offset:27648
	ds_write_b128 v148, v[168:171] offset:36864
	s_waitcnt vmcnt(10)
	ds_write_b128 v148, v[176:179] offset:46080
	s_waitcnt vmcnt(9)
	ds_write_b128 v148, v[180:183] offset:55296
	s_waitcnt vmcnt(8)
	ds_write_b128 v148, v[184:187] offset:64512
	ds_read_b128 v[156:159], v130 offset:36864
	ds_read_b128 v[160:163], v130 offset:36896
	ds_read_b128 v[164:167], v130 offset:41472
	ds_read_b128 v[168:171], v130 offset:41504
	ds_read_b128 v[172:175], v133
	ds_read_b128 v[176:179], v133 offset:32
	ds_read_b128 v[180:183], v133 offset:4608
	ds_read_b128 v[184:187], v133 offset:4640
	ds_read_b128 v[222:225], v133 offset:9216
	ds_read_b128 v[226:229], v133 offset:9248
	ds_read_b128 v[230:233], v133 offset:13824
	ds_read_b128 v[234:237], v133 offset:13856
	s_waitcnt lgkmcnt(7)
	v_mfma_f32_32x32x16_bf16 v[114:129], v[172:175], v[156:159], v[114:129]
	v_mfma_f32_32x32x16_bf16 v[82:97], v[172:175], v[164:167], v[82:97]
	s_waitcnt lgkmcnt(5)
	v_mfma_f32_32x32x16_bf16 v[98:113], v[180:183], v[156:159], v[98:113]
	v_mfma_f32_32x32x16_bf16 v[66:81], v[180:183], v[164:167], v[66:81]
	s_waitcnt lgkmcnt(3)
	v_mfma_f32_32x32x16_bf16 v[50:65], v[222:225], v[156:159], v[50:65]
	v_mfma_f32_32x32x16_bf16 v[18:33], v[222:225], v[164:167], v[18:33]
	s_waitcnt lgkmcnt(1)
	v_mfma_f32_32x32x16_bf16 v[34:49], v[230:233], v[156:159], v[34:49]
	v_mfma_f32_32x32x16_bf16 v[2:17], v[230:233], v[164:167], v[2:17]
	ds_read_b128 v[156:159], v130 offset:36928
	ds_read_b128 v[164:167], v130 offset:41536
	ds_read_b128 v[172:175], v133 offset:64
	ds_read_b128 v[180:183], v133 offset:4672
	ds_read_b128 v[222:225], v133 offset:9280
	ds_read_b128 v[230:233], v133 offset:13888
	v_mfma_f32_32x32x16_bf16 v[114:129], v[176:179], v[160:163], v[114:129]
	v_mfma_f32_32x32x16_bf16 v[82:97], v[176:179], v[168:171], v[82:97]
	v_mfma_f32_32x32x16_bf16 v[98:113], v[184:187], v[160:163], v[98:113]
	v_mfma_f32_32x32x16_bf16 v[66:81], v[184:187], v[168:171], v[66:81]
	v_mfma_f32_32x32x16_bf16 v[50:65], v[226:229], v[160:163], v[50:65]
	v_mfma_f32_32x32x16_bf16 v[18:33], v[226:229], v[168:171], v[18:33]
	s_waitcnt lgkmcnt(6)
	v_mfma_f32_32x32x16_bf16 v[34:49], v[234:237], v[160:163], v[34:49]
	v_mfma_f32_32x32x16_bf16 v[2:17], v[234:237], v[168:171], v[2:17]
	ds_read_b128 v[160:163], v130 offset:36960
	ds_read_b128 v[168:171], v130 offset:41568
	ds_read_b128 v[176:179], v133 offset:96
	ds_read_b128 v[184:187], v133 offset:4704
	ds_read_b128 v[226:229], v133 offset:9312
	ds_read_b128 v[234:237], v133 offset:13920
	s_waitcnt lgkmcnt(9)
	v_mfma_f32_32x32x16_bf16 v[114:129], v[172:175], v[156:159], v[114:129]
	v_mfma_f32_32x32x16_bf16 v[82:97], v[172:175], v[164:167], v[82:97]
	s_waitcnt lgkmcnt(8)
	v_mfma_f32_32x32x16_bf16 v[98:113], v[180:183], v[156:159], v[98:113]
	v_mfma_f32_32x32x16_bf16 v[66:81], v[180:183], v[164:167], v[66:81]
	s_waitcnt lgkmcnt(7)
	v_mfma_f32_32x32x16_bf16 v[50:65], v[222:225], v[156:159], v[50:65]
	v_mfma_f32_32x32x16_bf16 v[18:33], v[222:225], v[164:167], v[18:33]
	s_waitcnt lgkmcnt(6)
	v_mfma_f32_32x32x16_bf16 v[34:49], v[230:233], v[156:159], v[34:49]
	v_mfma_f32_32x32x16_bf16 v[2:17], v[230:233], v[164:167], v[2:17]
	s_waitcnt lgkmcnt(3)
	v_mfma_f32_32x32x16_bf16 v[114:129], v[176:179], v[160:163], v[114:129]
	v_mfma_f32_32x32x16_bf16 v[82:97], v[176:179], v[168:171], v[82:97]
	s_waitcnt lgkmcnt(2)
	v_mfma_f32_32x32x16_bf16 v[98:113], v[184:187], v[160:163], v[98:113]
	v_mfma_f32_32x32x16_bf16 v[66:81], v[184:187], v[168:171], v[66:81]
	s_waitcnt lgkmcnt(1)
	v_mfma_f32_32x32x16_bf16 v[50:65], v[226:229], v[160:163], v[50:65]
	v_mfma_f32_32x32x16_bf16 v[18:33], v[226:229], v[168:171], v[18:33]
	s_waitcnt lgkmcnt(0)
	v_mfma_f32_32x32x16_bf16 v[34:49], v[234:237], v[160:163], v[34:49]
	v_mfma_f32_32x32x16_bf16 v[2:17], v[234:237], v[168:171], v[2:17]
	s_barrier
	global_load_dwordx4 v[156:159], v[138:139], off offset:768
	global_load_dwordx4 v[160:163], v[140:141], off offset:768
	global_load_dwordx4 v[164:167], v[134:135], off offset:768
	global_load_dwordx4 v[168:171], v[136:137], off offset:768
	global_load_dwordx4 v[172:175], v[142:143], off offset:768
	global_load_dwordx4 v[176:179], v[144:145], off offset:768
	global_load_dwordx4 v[180:183], v[146:147], off offset:768
	global_load_dwordx4 v[184:187], v[150:151], off offset:768
	s_waitcnt vmcnt(13)
	ds_write_b128 v155, v[196:199]
	ds_write_b128 v155, v[188:191] offset:9216
	ds_write_b128 v155, v[192:195] offset:18432
	s_waitcnt vmcnt(11)
	ds_write_b128 v155, v[204:207] offset:27648
	ds_write_b128 v155, v[200:203] offset:36864
	s_waitcnt vmcnt(10)
	ds_write_b128 v155, v[208:211] offset:46080
	s_waitcnt vmcnt(9)
	ds_write_b128 v155, v[214:217] offset:55296
	s_waitcnt vmcnt(8)
	ds_write_b128 v155, v[218:221] offset:64512
	ds_read_b128 v[188:191], v154 offset:36864
	ds_read_b128 v[192:195], v154 offset:36896
	ds_read_b128 v[196:199], v154 offset:41472
	ds_read_b128 v[200:203], v154 offset:41504
	ds_read_b128 v[204:207], v132
	ds_read_b128 v[208:211], v132 offset:32
	ds_read_b128 v[214:217], v132 offset:4608
	ds_read_b128 v[218:221], v132 offset:4640
	ds_read_b128 v[222:225], v132 offset:9216
	ds_read_b128 v[226:229], v132 offset:9248
	ds_read_b128 v[230:233], v132 offset:13824
	ds_read_b128 v[234:237], v132 offset:13856
	s_waitcnt lgkmcnt(7)
	v_mfma_f32_32x32x16_bf16 v[114:129], v[204:207], v[188:191], v[114:129]
	v_mfma_f32_32x32x16_bf16 v[82:97], v[204:207], v[196:199], v[82:97]
	s_waitcnt lgkmcnt(5)
	v_mfma_f32_32x32x16_bf16 v[98:113], v[214:217], v[188:191], v[98:113]
	v_mfma_f32_32x32x16_bf16 v[66:81], v[214:217], v[196:199], v[66:81]
	s_waitcnt lgkmcnt(3)
	v_mfma_f32_32x32x16_bf16 v[50:65], v[222:225], v[188:191], v[50:65]
	v_mfma_f32_32x32x16_bf16 v[18:33], v[222:225], v[196:199], v[18:33]
	s_waitcnt lgkmcnt(1)
	v_mfma_f32_32x32x16_bf16 v[34:49], v[230:233], v[188:191], v[34:49]
	v_mfma_f32_32x32x16_bf16 v[2:17], v[230:233], v[196:199], v[2:17]
	ds_read_b128 v[188:191], v154 offset:36928
	ds_read_b128 v[196:199], v154 offset:41536
	ds_read_b128 v[204:207], v132 offset:64
	ds_read_b128 v[214:217], v132 offset:4672
	ds_read_b128 v[222:225], v132 offset:9280
	ds_read_b128 v[230:233], v132 offset:13888
	v_mfma_f32_32x32x16_bf16 v[114:129], v[208:211], v[192:195], v[114:129]
	v_mfma_f32_32x32x16_bf16 v[82:97], v[208:211], v[200:203], v[82:97]
	v_mfma_f32_32x32x16_bf16 v[98:113], v[218:221], v[192:195], v[98:113]
	v_mfma_f32_32x32x16_bf16 v[66:81], v[218:221], v[200:203], v[66:81]
	v_mfma_f32_32x32x16_bf16 v[50:65], v[226:229], v[192:195], v[50:65]
	v_mfma_f32_32x32x16_bf16 v[18:33], v[226:229], v[200:203], v[18:33]
	s_waitcnt lgkmcnt(6)
	v_mfma_f32_32x32x16_bf16 v[34:49], v[234:237], v[192:195], v[34:49]
	v_mfma_f32_32x32x16_bf16 v[2:17], v[234:237], v[200:203], v[2:17]
	ds_read_b128 v[192:195], v154 offset:36960
	ds_read_b128 v[200:203], v154 offset:41568
	ds_read_b128 v[208:211], v132 offset:96
	ds_read_b128 v[218:221], v132 offset:4704
	ds_read_b128 v[226:229], v132 offset:9312
	ds_read_b128 v[234:237], v132 offset:13920
	s_waitcnt lgkmcnt(9)
	v_mfma_f32_32x32x16_bf16 v[114:129], v[204:207], v[188:191], v[114:129]
	v_mfma_f32_32x32x16_bf16 v[82:97], v[204:207], v[196:199], v[82:97]
	s_waitcnt lgkmcnt(8)
	v_mfma_f32_32x32x16_bf16 v[98:113], v[214:217], v[188:191], v[98:113]
	v_mfma_f32_32x32x16_bf16 v[66:81], v[214:217], v[196:199], v[66:81]
	s_waitcnt lgkmcnt(7)
	v_mfma_f32_32x32x16_bf16 v[50:65], v[222:225], v[188:191], v[50:65]
	v_mfma_f32_32x32x16_bf16 v[18:33], v[222:225], v[196:199], v[18:33]
	s_waitcnt lgkmcnt(6)
	v_mfma_f32_32x32x16_bf16 v[34:49], v[230:233], v[188:191], v[34:49]
	v_mfma_f32_32x32x16_bf16 v[2:17], v[230:233], v[196:199], v[2:17]
	s_waitcnt lgkmcnt(3)
	v_mfma_f32_32x32x16_bf16 v[114:129], v[208:211], v[192:195], v[114:129]
	v_mfma_f32_32x32x16_bf16 v[82:97], v[208:211], v[200:203], v[82:97]
	s_waitcnt lgkmcnt(2)
	v_mfma_f32_32x32x16_bf16 v[98:113], v[218:221], v[192:195], v[98:113]
	v_mfma_f32_32x32x16_bf16 v[66:81], v[218:221], v[200:203], v[66:81]
	s_waitcnt lgkmcnt(1)
	v_mfma_f32_32x32x16_bf16 v[50:65], v[226:229], v[192:195], v[50:65]
	v_mfma_f32_32x32x16_bf16 v[18:33], v[226:229], v[200:203], v[18:33]
	s_waitcnt lgkmcnt(0)
	v_mfma_f32_32x32x16_bf16 v[34:49], v[234:237], v[192:195], v[34:49]
	v_mfma_f32_32x32x16_bf16 v[2:17], v[234:237], v[200:203], v[2:17]
	s_barrier
	global_load_dwordx4 v[188:191], v[138:139], off offset:896
	global_load_dwordx4 v[192:195], v[140:141], off offset:896
	global_load_dwordx4 v[196:199], v[134:135], off offset:896
	global_load_dwordx4 v[200:203], v[136:137], off offset:896
	global_load_dwordx4 v[204:207], v[142:143], off offset:896
	global_load_dwordx4 v[208:211], v[144:145], off offset:896
	global_load_dwordx4 v[214:217], v[146:147], off offset:896
	global_load_dwordx4 v[218:221], v[150:151], off offset:896
	s_waitcnt vmcnt(13)
	ds_write_b128 v148, v[164:167]
	ds_write_b128 v148, v[156:159] offset:9216
	ds_write_b128 v148, v[160:163] offset:18432
	s_waitcnt vmcnt(11)
	ds_write_b128 v148, v[172:175] offset:27648
	ds_write_b128 v148, v[168:171] offset:36864
	s_waitcnt vmcnt(10)
	ds_write_b128 v148, v[176:179] offset:46080
	s_waitcnt vmcnt(9)
	ds_write_b128 v148, v[180:183] offset:55296
	s_waitcnt vmcnt(8)
	ds_write_b128 v148, v[184:187] offset:64512
	ds_read_b128 v[156:159], v130 offset:36864
	ds_read_b128 v[160:163], v130 offset:36896
	ds_read_b128 v[164:167], v130 offset:41472
	ds_read_b128 v[168:171], v130 offset:41504
	ds_read_b128 v[172:175], v133
	ds_read_b128 v[176:179], v133 offset:32
	ds_read_b128 v[180:183], v133 offset:4608
	ds_read_b128 v[184:187], v133 offset:4640
	ds_read_b128 v[222:225], v133 offset:9216
	ds_read_b128 v[226:229], v133 offset:9248
	ds_read_b128 v[230:233], v133 offset:13824
	ds_read_b128 v[234:237], v133 offset:13856
	s_waitcnt lgkmcnt(7)
	v_mfma_f32_32x32x16_bf16 v[114:129], v[172:175], v[156:159], v[114:129]
	v_mfma_f32_32x32x16_bf16 v[82:97], v[172:175], v[164:167], v[82:97]
	s_waitcnt lgkmcnt(5)
	v_mfma_f32_32x32x16_bf16 v[98:113], v[180:183], v[156:159], v[98:113]
	v_mfma_f32_32x32x16_bf16 v[66:81], v[180:183], v[164:167], v[66:81]
	s_waitcnt lgkmcnt(3)
	v_mfma_f32_32x32x16_bf16 v[50:65], v[222:225], v[156:159], v[50:65]
	v_mfma_f32_32x32x16_bf16 v[18:33], v[222:225], v[164:167], v[18:33]
	s_waitcnt lgkmcnt(1)
	v_mfma_f32_32x32x16_bf16 v[34:49], v[230:233], v[156:159], v[34:49]
	v_mfma_f32_32x32x16_bf16 v[2:17], v[230:233], v[164:167], v[2:17]
	ds_read_b128 v[156:159], v130 offset:36928
	ds_read_b128 v[164:167], v130 offset:41536
	ds_read_b128 v[172:175], v133 offset:64
	ds_read_b128 v[180:183], v133 offset:4672
	ds_read_b128 v[222:225], v133 offset:9280
	ds_read_b128 v[230:233], v133 offset:13888
	v_mfma_f32_32x32x16_bf16 v[114:129], v[176:179], v[160:163], v[114:129]
	v_mfma_f32_32x32x16_bf16 v[82:97], v[176:179], v[168:171], v[82:97]
	v_mfma_f32_32x32x16_bf16 v[98:113], v[184:187], v[160:163], v[98:113]
	v_mfma_f32_32x32x16_bf16 v[66:81], v[184:187], v[168:171], v[66:81]
	v_mfma_f32_32x32x16_bf16 v[50:65], v[226:229], v[160:163], v[50:65]
	v_mfma_f32_32x32x16_bf16 v[18:33], v[226:229], v[168:171], v[18:33]
	s_waitcnt lgkmcnt(6)
	v_mfma_f32_32x32x16_bf16 v[34:49], v[234:237], v[160:163], v[34:49]
	v_mfma_f32_32x32x16_bf16 v[2:17], v[234:237], v[168:171], v[2:17]
	ds_read_b128 v[160:163], v130 offset:36960
	ds_read_b128 v[168:171], v130 offset:41568
	ds_read_b128 v[176:179], v133 offset:96
	ds_read_b128 v[184:187], v133 offset:4704
	ds_read_b128 v[226:229], v133 offset:9312
	ds_read_b128 v[234:237], v133 offset:13920
	s_waitcnt lgkmcnt(9)
	v_mfma_f32_32x32x16_bf16 v[114:129], v[172:175], v[156:159], v[114:129]
	v_mfma_f32_32x32x16_bf16 v[82:97], v[172:175], v[164:167], v[82:97]
	s_waitcnt lgkmcnt(8)
	v_mfma_f32_32x32x16_bf16 v[98:113], v[180:183], v[156:159], v[98:113]
	v_mfma_f32_32x32x16_bf16 v[66:81], v[180:183], v[164:167], v[66:81]
	s_waitcnt lgkmcnt(7)
	v_mfma_f32_32x32x16_bf16 v[50:65], v[222:225], v[156:159], v[50:65]
	v_mfma_f32_32x32x16_bf16 v[18:33], v[222:225], v[164:167], v[18:33]
	s_waitcnt lgkmcnt(6)
	v_mfma_f32_32x32x16_bf16 v[34:49], v[230:233], v[156:159], v[34:49]
	v_mfma_f32_32x32x16_bf16 v[2:17], v[230:233], v[164:167], v[2:17]
	s_waitcnt lgkmcnt(3)
	v_mfma_f32_32x32x16_bf16 v[114:129], v[176:179], v[160:163], v[114:129]
	v_mfma_f32_32x32x16_bf16 v[82:97], v[176:179], v[168:171], v[82:97]
	s_waitcnt lgkmcnt(2)
	v_mfma_f32_32x32x16_bf16 v[98:113], v[184:187], v[160:163], v[98:113]
	v_mfma_f32_32x32x16_bf16 v[66:81], v[184:187], v[168:171], v[66:81]
	s_waitcnt lgkmcnt(1)
	v_mfma_f32_32x32x16_bf16 v[50:65], v[226:229], v[160:163], v[50:65]
	v_mfma_f32_32x32x16_bf16 v[18:33], v[226:229], v[168:171], v[18:33]
	s_waitcnt lgkmcnt(0)
	v_mfma_f32_32x32x16_bf16 v[34:49], v[234:237], v[160:163], v[34:49]
	v_mfma_f32_32x32x16_bf16 v[2:17], v[234:237], v[168:171], v[2:17]
	s_barrier
	global_load_dwordx4 v[156:159], v[138:139], off offset:1024
	global_load_dwordx4 v[160:163], v[140:141], off offset:1024
	global_load_dwordx4 v[164:167], v[134:135], off offset:1024
	global_load_dwordx4 v[168:171], v[136:137], off offset:1024
	global_load_dwordx4 v[172:175], v[142:143], off offset:1024
	global_load_dwordx4 v[176:179], v[144:145], off offset:1024
	global_load_dwordx4 v[180:183], v[146:147], off offset:1024
	global_load_dwordx4 v[184:187], v[150:151], off offset:1024
	s_waitcnt vmcnt(13)
	ds_write_b128 v155, v[196:199]
	ds_write_b128 v155, v[188:191] offset:9216
	ds_write_b128 v155, v[192:195] offset:18432
	s_waitcnt vmcnt(11)
	ds_write_b128 v155, v[204:207] offset:27648
	ds_write_b128 v155, v[200:203] offset:36864
	s_waitcnt vmcnt(10)
	ds_write_b128 v155, v[208:211] offset:46080
	s_waitcnt vmcnt(9)
	ds_write_b128 v155, v[214:217] offset:55296
	s_waitcnt vmcnt(8)
	ds_write_b128 v155, v[218:221] offset:64512
	ds_read_b128 v[188:191], v154 offset:36864
	ds_read_b128 v[192:195], v154 offset:36896
	ds_read_b128 v[196:199], v154 offset:41472
	ds_read_b128 v[200:203], v154 offset:41504
	ds_read_b128 v[204:207], v132
	ds_read_b128 v[208:211], v132 offset:32
	ds_read_b128 v[214:217], v132 offset:4608
	ds_read_b128 v[218:221], v132 offset:4640
	ds_read_b128 v[222:225], v132 offset:9216
	ds_read_b128 v[226:229], v132 offset:9248
	ds_read_b128 v[230:233], v132 offset:13824
	ds_read_b128 v[234:237], v132 offset:13856
	s_waitcnt lgkmcnt(7)
	v_mfma_f32_32x32x16_bf16 v[114:129], v[204:207], v[188:191], v[114:129]
	v_mfma_f32_32x32x16_bf16 v[82:97], v[204:207], v[196:199], v[82:97]
	s_waitcnt lgkmcnt(5)
	v_mfma_f32_32x32x16_bf16 v[98:113], v[214:217], v[188:191], v[98:113]
	v_mfma_f32_32x32x16_bf16 v[66:81], v[214:217], v[196:199], v[66:81]
	s_waitcnt lgkmcnt(3)
	v_mfma_f32_32x32x16_bf16 v[50:65], v[222:225], v[188:191], v[50:65]
	v_mfma_f32_32x32x16_bf16 v[18:33], v[222:225], v[196:199], v[18:33]
	s_waitcnt lgkmcnt(1)
	v_mfma_f32_32x32x16_bf16 v[34:49], v[230:233], v[188:191], v[34:49]
	v_mfma_f32_32x32x16_bf16 v[2:17], v[230:233], v[196:199], v[2:17]
	ds_read_b128 v[188:191], v154 offset:36928
	ds_read_b128 v[196:199], v154 offset:41536
	ds_read_b128 v[204:207], v132 offset:64
	ds_read_b128 v[214:217], v132 offset:4672
	ds_read_b128 v[222:225], v132 offset:9280
	ds_read_b128 v[230:233], v132 offset:13888
	v_mfma_f32_32x32x16_bf16 v[114:129], v[208:211], v[192:195], v[114:129]
	v_mfma_f32_32x32x16_bf16 v[82:97], v[208:211], v[200:203], v[82:97]
	v_mfma_f32_32x32x16_bf16 v[98:113], v[218:221], v[192:195], v[98:113]
	v_mfma_f32_32x32x16_bf16 v[66:81], v[218:221], v[200:203], v[66:81]
	v_mfma_f32_32x32x16_bf16 v[50:65], v[226:229], v[192:195], v[50:65]
	v_mfma_f32_32x32x16_bf16 v[18:33], v[226:229], v[200:203], v[18:33]
	s_waitcnt lgkmcnt(6)
	v_mfma_f32_32x32x16_bf16 v[34:49], v[234:237], v[192:195], v[34:49]
	v_mfma_f32_32x32x16_bf16 v[2:17], v[234:237], v[200:203], v[2:17]
	ds_read_b128 v[192:195], v154 offset:36960
	ds_read_b128 v[200:203], v154 offset:41568
	ds_read_b128 v[208:211], v132 offset:96
	ds_read_b128 v[218:221], v132 offset:4704
	ds_read_b128 v[226:229], v132 offset:9312
	ds_read_b128 v[234:237], v132 offset:13920
	s_waitcnt lgkmcnt(9)
	v_mfma_f32_32x32x16_bf16 v[114:129], v[204:207], v[188:191], v[114:129]
	v_mfma_f32_32x32x16_bf16 v[82:97], v[204:207], v[196:199], v[82:97]
	s_waitcnt lgkmcnt(8)
	v_mfma_f32_32x32x16_bf16 v[98:113], v[214:217], v[188:191], v[98:113]
	v_mfma_f32_32x32x16_bf16 v[66:81], v[214:217], v[196:199], v[66:81]
	s_waitcnt lgkmcnt(7)
	v_mfma_f32_32x32x16_bf16 v[50:65], v[222:225], v[188:191], v[50:65]
	v_mfma_f32_32x32x16_bf16 v[18:33], v[222:225], v[196:199], v[18:33]
	s_waitcnt lgkmcnt(6)
	v_mfma_f32_32x32x16_bf16 v[34:49], v[230:233], v[188:191], v[34:49]
	v_mfma_f32_32x32x16_bf16 v[2:17], v[230:233], v[196:199], v[2:17]
	s_waitcnt lgkmcnt(3)
	v_mfma_f32_32x32x16_bf16 v[114:129], v[208:211], v[192:195], v[114:129]
	v_mfma_f32_32x32x16_bf16 v[82:97], v[208:211], v[200:203], v[82:97]
	s_waitcnt lgkmcnt(2)
	v_mfma_f32_32x32x16_bf16 v[98:113], v[218:221], v[192:195], v[98:113]
	v_mfma_f32_32x32x16_bf16 v[66:81], v[218:221], v[200:203], v[66:81]
	s_waitcnt lgkmcnt(1)
	v_mfma_f32_32x32x16_bf16 v[50:65], v[226:229], v[192:195], v[50:65]
	v_mfma_f32_32x32x16_bf16 v[18:33], v[226:229], v[200:203], v[18:33]
	s_waitcnt lgkmcnt(0)
	v_mfma_f32_32x32x16_bf16 v[34:49], v[234:237], v[192:195], v[34:49]
	v_mfma_f32_32x32x16_bf16 v[2:17], v[234:237], v[200:203], v[2:17]
	s_barrier
	global_load_dwordx4 v[188:191], v[138:139], off offset:1152
	global_load_dwordx4 v[192:195], v[140:141], off offset:1152
	global_load_dwordx4 v[196:199], v[134:135], off offset:1152
	global_load_dwordx4 v[200:203], v[136:137], off offset:1152
	global_load_dwordx4 v[204:207], v[142:143], off offset:1152
	global_load_dwordx4 v[208:211], v[144:145], off offset:1152
	global_load_dwordx4 v[214:217], v[146:147], off offset:1152
	global_load_dwordx4 v[218:221], v[150:151], off offset:1152
	s_waitcnt vmcnt(13)
	ds_write_b128 v148, v[164:167]
	ds_write_b128 v148, v[156:159] offset:9216
	ds_write_b128 v148, v[160:163] offset:18432
	s_waitcnt vmcnt(11)
	ds_write_b128 v148, v[172:175] offset:27648
	ds_write_b128 v148, v[168:171] offset:36864
	s_waitcnt vmcnt(10)
	ds_write_b128 v148, v[176:179] offset:46080
	s_waitcnt vmcnt(9)
	ds_write_b128 v148, v[180:183] offset:55296
	s_waitcnt vmcnt(8)
	ds_write_b128 v148, v[184:187] offset:64512
	ds_read_b128 v[156:159], v130 offset:36864
	ds_read_b128 v[160:163], v130 offset:36896
	ds_read_b128 v[164:167], v130 offset:41472
	ds_read_b128 v[168:171], v130 offset:41504
	ds_read_b128 v[172:175], v133
	ds_read_b128 v[176:179], v133 offset:32
	ds_read_b128 v[180:183], v133 offset:4608
	ds_read_b128 v[184:187], v133 offset:4640
	ds_read_b128 v[222:225], v133 offset:9216
	ds_read_b128 v[226:229], v133 offset:9248
	ds_read_b128 v[230:233], v133 offset:13824
	ds_read_b128 v[234:237], v133 offset:13856
	s_waitcnt lgkmcnt(7)
	v_mfma_f32_32x32x16_bf16 v[114:129], v[172:175], v[156:159], v[114:129]
	v_mfma_f32_32x32x16_bf16 v[82:97], v[172:175], v[164:167], v[82:97]
	s_waitcnt lgkmcnt(5)
	v_mfma_f32_32x32x16_bf16 v[98:113], v[180:183], v[156:159], v[98:113]
	v_mfma_f32_32x32x16_bf16 v[66:81], v[180:183], v[164:167], v[66:81]
	s_waitcnt lgkmcnt(3)
	v_mfma_f32_32x32x16_bf16 v[50:65], v[222:225], v[156:159], v[50:65]
	v_mfma_f32_32x32x16_bf16 v[18:33], v[222:225], v[164:167], v[18:33]
	s_waitcnt lgkmcnt(1)
	v_mfma_f32_32x32x16_bf16 v[34:49], v[230:233], v[156:159], v[34:49]
	v_mfma_f32_32x32x16_bf16 v[2:17], v[230:233], v[164:167], v[2:17]
	ds_read_b128 v[156:159], v130 offset:36928
	ds_read_b128 v[164:167], v130 offset:41536
	ds_read_b128 v[172:175], v133 offset:64
	ds_read_b128 v[180:183], v133 offset:4672
	ds_read_b128 v[222:225], v133 offset:9280
	ds_read_b128 v[230:233], v133 offset:13888
	v_mfma_f32_32x32x16_bf16 v[114:129], v[176:179], v[160:163], v[114:129]
	v_mfma_f32_32x32x16_bf16 v[82:97], v[176:179], v[168:171], v[82:97]
	v_mfma_f32_32x32x16_bf16 v[98:113], v[184:187], v[160:163], v[98:113]
	v_mfma_f32_32x32x16_bf16 v[66:81], v[184:187], v[168:171], v[66:81]
	v_mfma_f32_32x32x16_bf16 v[50:65], v[226:229], v[160:163], v[50:65]
	v_mfma_f32_32x32x16_bf16 v[18:33], v[226:229], v[168:171], v[18:33]
	s_waitcnt lgkmcnt(6)
	v_mfma_f32_32x32x16_bf16 v[34:49], v[234:237], v[160:163], v[34:49]
	v_mfma_f32_32x32x16_bf16 v[2:17], v[234:237], v[168:171], v[2:17]
	ds_read_b128 v[160:163], v130 offset:36960
	ds_read_b128 v[168:171], v130 offset:41568
	ds_read_b128 v[176:179], v133 offset:96
	ds_read_b128 v[184:187], v133 offset:4704
	ds_read_b128 v[226:229], v133 offset:9312
	ds_read_b128 v[234:237], v133 offset:13920
	s_waitcnt lgkmcnt(9)
	v_mfma_f32_32x32x16_bf16 v[114:129], v[172:175], v[156:159], v[114:129]
	v_mfma_f32_32x32x16_bf16 v[82:97], v[172:175], v[164:167], v[82:97]
	s_waitcnt lgkmcnt(8)
	v_mfma_f32_32x32x16_bf16 v[98:113], v[180:183], v[156:159], v[98:113]
	v_mfma_f32_32x32x16_bf16 v[66:81], v[180:183], v[164:167], v[66:81]
	s_waitcnt lgkmcnt(7)
	v_mfma_f32_32x32x16_bf16 v[50:65], v[222:225], v[156:159], v[50:65]
	v_mfma_f32_32x32x16_bf16 v[18:33], v[222:225], v[164:167], v[18:33]
	s_waitcnt lgkmcnt(6)
	v_mfma_f32_32x32x16_bf16 v[34:49], v[230:233], v[156:159], v[34:49]
	v_mfma_f32_32x32x16_bf16 v[2:17], v[230:233], v[164:167], v[2:17]
	s_waitcnt lgkmcnt(3)
	v_mfma_f32_32x32x16_bf16 v[114:129], v[176:179], v[160:163], v[114:129]
	v_mfma_f32_32x32x16_bf16 v[82:97], v[176:179], v[168:171], v[82:97]
	s_waitcnt lgkmcnt(2)
	v_mfma_f32_32x32x16_bf16 v[98:113], v[184:187], v[160:163], v[98:113]
	v_mfma_f32_32x32x16_bf16 v[66:81], v[184:187], v[168:171], v[66:81]
	s_waitcnt lgkmcnt(1)
	v_mfma_f32_32x32x16_bf16 v[50:65], v[226:229], v[160:163], v[50:65]
	v_mfma_f32_32x32x16_bf16 v[18:33], v[226:229], v[168:171], v[18:33]
	s_waitcnt lgkmcnt(0)
	v_mfma_f32_32x32x16_bf16 v[34:49], v[234:237], v[160:163], v[34:49]
	v_mfma_f32_32x32x16_bf16 v[2:17], v[234:237], v[168:171], v[2:17]
	s_barrier
	global_load_dwordx4 v[156:159], v[138:139], off offset:1280
	global_load_dwordx4 v[160:163], v[140:141], off offset:1280
	global_load_dwordx4 v[164:167], v[134:135], off offset:1280
	global_load_dwordx4 v[168:171], v[136:137], off offset:1280
	global_load_dwordx4 v[172:175], v[142:143], off offset:1280
	global_load_dwordx4 v[176:179], v[144:145], off offset:1280
	global_load_dwordx4 v[180:183], v[146:147], off offset:1280
	global_load_dwordx4 v[184:187], v[150:151], off offset:1280
	s_waitcnt vmcnt(13)
	ds_write_b128 v155, v[196:199]
	ds_write_b128 v155, v[188:191] offset:9216
	ds_write_b128 v155, v[192:195] offset:18432
	s_waitcnt vmcnt(11)
	ds_write_b128 v155, v[204:207] offset:27648
	ds_write_b128 v155, v[200:203] offset:36864
	s_waitcnt vmcnt(10)
	ds_write_b128 v155, v[208:211] offset:46080
	s_waitcnt vmcnt(9)
	ds_write_b128 v155, v[214:217] offset:55296
	s_waitcnt vmcnt(8)
	ds_write_b128 v155, v[218:221] offset:64512
	ds_read_b128 v[188:191], v154 offset:36864
	ds_read_b128 v[192:195], v154 offset:36896
	ds_read_b128 v[196:199], v154 offset:41472
	ds_read_b128 v[200:203], v154 offset:41504
	ds_read_b128 v[204:207], v132
	ds_read_b128 v[208:211], v132 offset:32
	ds_read_b128 v[214:217], v132 offset:4608
	ds_read_b128 v[218:221], v132 offset:4640
	ds_read_b128 v[222:225], v132 offset:9216
	ds_read_b128 v[226:229], v132 offset:9248
	ds_read_b128 v[230:233], v132 offset:13824
	ds_read_b128 v[234:237], v132 offset:13856
	s_waitcnt lgkmcnt(7)
	v_mfma_f32_32x32x16_bf16 v[114:129], v[204:207], v[188:191], v[114:129]
	v_mfma_f32_32x32x16_bf16 v[82:97], v[204:207], v[196:199], v[82:97]
	s_waitcnt lgkmcnt(5)
	v_mfma_f32_32x32x16_bf16 v[98:113], v[214:217], v[188:191], v[98:113]
	v_mfma_f32_32x32x16_bf16 v[66:81], v[214:217], v[196:199], v[66:81]
	s_waitcnt lgkmcnt(3)
	v_mfma_f32_32x32x16_bf16 v[50:65], v[222:225], v[188:191], v[50:65]
	v_mfma_f32_32x32x16_bf16 v[18:33], v[222:225], v[196:199], v[18:33]
	s_waitcnt lgkmcnt(1)
	v_mfma_f32_32x32x16_bf16 v[34:49], v[230:233], v[188:191], v[34:49]
	v_mfma_f32_32x32x16_bf16 v[2:17], v[230:233], v[196:199], v[2:17]
	ds_read_b128 v[188:191], v154 offset:36928
	ds_read_b128 v[196:199], v154 offset:41536
	ds_read_b128 v[204:207], v132 offset:64
	ds_read_b128 v[214:217], v132 offset:4672
	ds_read_b128 v[222:225], v132 offset:9280
	ds_read_b128 v[230:233], v132 offset:13888
	v_mfma_f32_32x32x16_bf16 v[114:129], v[208:211], v[192:195], v[114:129]
	v_mfma_f32_32x32x16_bf16 v[82:97], v[208:211], v[200:203], v[82:97]
	v_mfma_f32_32x32x16_bf16 v[98:113], v[218:221], v[192:195], v[98:113]
	v_mfma_f32_32x32x16_bf16 v[66:81], v[218:221], v[200:203], v[66:81]
	v_mfma_f32_32x32x16_bf16 v[50:65], v[226:229], v[192:195], v[50:65]
	v_mfma_f32_32x32x16_bf16 v[18:33], v[226:229], v[200:203], v[18:33]
	s_waitcnt lgkmcnt(6)
	v_mfma_f32_32x32x16_bf16 v[34:49], v[234:237], v[192:195], v[34:49]
	v_mfma_f32_32x32x16_bf16 v[2:17], v[234:237], v[200:203], v[2:17]
	ds_read_b128 v[192:195], v154 offset:36960
	ds_read_b128 v[200:203], v154 offset:41568
	ds_read_b128 v[208:211], v132 offset:96
	ds_read_b128 v[218:221], v132 offset:4704
	ds_read_b128 v[226:229], v132 offset:9312
	ds_read_b128 v[234:237], v132 offset:13920
	s_waitcnt lgkmcnt(9)
	v_mfma_f32_32x32x16_bf16 v[114:129], v[204:207], v[188:191], v[114:129]
	v_mfma_f32_32x32x16_bf16 v[82:97], v[204:207], v[196:199], v[82:97]
	s_waitcnt lgkmcnt(8)
	v_mfma_f32_32x32x16_bf16 v[98:113], v[214:217], v[188:191], v[98:113]
	v_mfma_f32_32x32x16_bf16 v[66:81], v[214:217], v[196:199], v[66:81]
	s_waitcnt lgkmcnt(7)
	v_mfma_f32_32x32x16_bf16 v[50:65], v[222:225], v[188:191], v[50:65]
	v_mfma_f32_32x32x16_bf16 v[18:33], v[222:225], v[196:199], v[18:33]
	s_waitcnt lgkmcnt(6)
	v_mfma_f32_32x32x16_bf16 v[34:49], v[230:233], v[188:191], v[34:49]
	v_mfma_f32_32x32x16_bf16 v[2:17], v[230:233], v[196:199], v[2:17]
	s_waitcnt lgkmcnt(3)
	v_mfma_f32_32x32x16_bf16 v[114:129], v[208:211], v[192:195], v[114:129]
	v_mfma_f32_32x32x16_bf16 v[82:97], v[208:211], v[200:203], v[82:97]
	s_waitcnt lgkmcnt(2)
	v_mfma_f32_32x32x16_bf16 v[98:113], v[218:221], v[192:195], v[98:113]
	v_mfma_f32_32x32x16_bf16 v[66:81], v[218:221], v[200:203], v[66:81]
	s_waitcnt lgkmcnt(1)
	v_mfma_f32_32x32x16_bf16 v[50:65], v[226:229], v[192:195], v[50:65]
	v_mfma_f32_32x32x16_bf16 v[18:33], v[226:229], v[200:203], v[18:33]
	s_waitcnt lgkmcnt(0)
	v_mfma_f32_32x32x16_bf16 v[34:49], v[234:237], v[192:195], v[34:49]
	v_mfma_f32_32x32x16_bf16 v[2:17], v[234:237], v[200:203], v[2:17]
	s_barrier
	global_load_dwordx4 v[188:191], v[138:139], off offset:1408
	global_load_dwordx4 v[192:195], v[140:141], off offset:1408
	global_load_dwordx4 v[196:199], v[134:135], off offset:1408
	global_load_dwordx4 v[200:203], v[136:137], off offset:1408
	global_load_dwordx4 v[204:207], v[142:143], off offset:1408
	global_load_dwordx4 v[208:211], v[144:145], off offset:1408
	global_load_dwordx4 v[214:217], v[146:147], off offset:1408
	global_load_dwordx4 v[218:221], v[150:151], off offset:1408
	s_waitcnt vmcnt(13)
	ds_write_b128 v148, v[164:167]
	ds_write_b128 v148, v[156:159] offset:9216
	ds_write_b128 v148, v[160:163] offset:18432
	s_waitcnt vmcnt(11)
	ds_write_b128 v148, v[172:175] offset:27648
	ds_write_b128 v148, v[168:171] offset:36864
	s_waitcnt vmcnt(10)
	ds_write_b128 v148, v[176:179] offset:46080
	s_waitcnt vmcnt(9)
	ds_write_b128 v148, v[180:183] offset:55296
	s_waitcnt vmcnt(8)
	ds_write_b128 v148, v[184:187] offset:64512
	ds_read_b128 v[156:159], v130 offset:36864
	ds_read_b128 v[160:163], v130 offset:36896
	ds_read_b128 v[164:167], v130 offset:41472
	ds_read_b128 v[168:171], v130 offset:41504
	ds_read_b128 v[172:175], v133
	ds_read_b128 v[176:179], v133 offset:32
	ds_read_b128 v[180:183], v133 offset:4608
	ds_read_b128 v[184:187], v133 offset:4640
	ds_read_b128 v[222:225], v133 offset:9216
	ds_read_b128 v[226:229], v133 offset:9248
	ds_read_b128 v[230:233], v133 offset:13824
	ds_read_b128 v[234:237], v133 offset:13856
	s_waitcnt lgkmcnt(7)
	v_mfma_f32_32x32x16_bf16 v[114:129], v[172:175], v[156:159], v[114:129]
	v_mfma_f32_32x32x16_bf16 v[82:97], v[172:175], v[164:167], v[82:97]
	s_waitcnt lgkmcnt(5)
	v_mfma_f32_32x32x16_bf16 v[98:113], v[180:183], v[156:159], v[98:113]
	v_mfma_f32_32x32x16_bf16 v[66:81], v[180:183], v[164:167], v[66:81]
	s_waitcnt lgkmcnt(3)
	v_mfma_f32_32x32x16_bf16 v[50:65], v[222:225], v[156:159], v[50:65]
	v_mfma_f32_32x32x16_bf16 v[18:33], v[222:225], v[164:167], v[18:33]
	s_waitcnt lgkmcnt(1)
	v_mfma_f32_32x32x16_bf16 v[34:49], v[230:233], v[156:159], v[34:49]
	v_mfma_f32_32x32x16_bf16 v[2:17], v[230:233], v[164:167], v[2:17]
	ds_read_b128 v[156:159], v130 offset:36928
	ds_read_b128 v[164:167], v130 offset:41536
	ds_read_b128 v[172:175], v133 offset:64
	ds_read_b128 v[180:183], v133 offset:4672
	ds_read_b128 v[222:225], v133 offset:9280
	ds_read_b128 v[230:233], v133 offset:13888
	v_mfma_f32_32x32x16_bf16 v[114:129], v[176:179], v[160:163], v[114:129]
	v_mfma_f32_32x32x16_bf16 v[82:97], v[176:179], v[168:171], v[82:97]
	v_mfma_f32_32x32x16_bf16 v[98:113], v[184:187], v[160:163], v[98:113]
	v_mfma_f32_32x32x16_bf16 v[66:81], v[184:187], v[168:171], v[66:81]
	v_mfma_f32_32x32x16_bf16 v[50:65], v[226:229], v[160:163], v[50:65]
	v_mfma_f32_32x32x16_bf16 v[18:33], v[226:229], v[168:171], v[18:33]
	s_waitcnt lgkmcnt(6)
	v_mfma_f32_32x32x16_bf16 v[34:49], v[234:237], v[160:163], v[34:49]
	v_mfma_f32_32x32x16_bf16 v[2:17], v[234:237], v[168:171], v[2:17]
	ds_read_b128 v[160:163], v130 offset:36960
	ds_read_b128 v[168:171], v130 offset:41568
	ds_read_b128 v[176:179], v133 offset:96
	ds_read_b128 v[184:187], v133 offset:4704
	ds_read_b128 v[226:229], v133 offset:9312
	ds_read_b128 v[234:237], v133 offset:13920
	s_waitcnt lgkmcnt(9)
	v_mfma_f32_32x32x16_bf16 v[114:129], v[172:175], v[156:159], v[114:129]
	v_mfma_f32_32x32x16_bf16 v[82:97], v[172:175], v[164:167], v[82:97]
	s_waitcnt lgkmcnt(8)
	v_mfma_f32_32x32x16_bf16 v[98:113], v[180:183], v[156:159], v[98:113]
	v_mfma_f32_32x32x16_bf16 v[66:81], v[180:183], v[164:167], v[66:81]
	s_waitcnt lgkmcnt(7)
	v_mfma_f32_32x32x16_bf16 v[50:65], v[222:225], v[156:159], v[50:65]
	v_mfma_f32_32x32x16_bf16 v[18:33], v[222:225], v[164:167], v[18:33]
	s_waitcnt lgkmcnt(6)
	v_mfma_f32_32x32x16_bf16 v[34:49], v[230:233], v[156:159], v[34:49]
	v_mfma_f32_32x32x16_bf16 v[2:17], v[230:233], v[164:167], v[2:17]
	s_waitcnt lgkmcnt(3)
	v_mfma_f32_32x32x16_bf16 v[114:129], v[176:179], v[160:163], v[114:129]
	v_mfma_f32_32x32x16_bf16 v[82:97], v[176:179], v[168:171], v[82:97]
	s_waitcnt lgkmcnt(2)
	v_mfma_f32_32x32x16_bf16 v[98:113], v[184:187], v[160:163], v[98:113]
	v_mfma_f32_32x32x16_bf16 v[66:81], v[184:187], v[168:171], v[66:81]
	s_waitcnt lgkmcnt(1)
	v_mfma_f32_32x32x16_bf16 v[50:65], v[226:229], v[160:163], v[50:65]
	v_mfma_f32_32x32x16_bf16 v[18:33], v[226:229], v[168:171], v[18:33]
	s_waitcnt lgkmcnt(0)
	v_mfma_f32_32x32x16_bf16 v[34:49], v[234:237], v[160:163], v[34:49]
	v_mfma_f32_32x32x16_bf16 v[2:17], v[234:237], v[168:171], v[2:17]
	s_barrier
	global_load_dwordx4 v[156:159], v[138:139], off offset:1536
	global_load_dwordx4 v[160:163], v[140:141], off offset:1536
	global_load_dwordx4 v[164:167], v[134:135], off offset:1536
	global_load_dwordx4 v[168:171], v[136:137], off offset:1536
	global_load_dwordx4 v[172:175], v[142:143], off offset:1536
	global_load_dwordx4 v[176:179], v[144:145], off offset:1536
	global_load_dwordx4 v[180:183], v[146:147], off offset:1536
	global_load_dwordx4 v[184:187], v[150:151], off offset:1536
	s_waitcnt vmcnt(13)
	ds_write_b128 v155, v[196:199]
	ds_write_b128 v155, v[188:191] offset:9216
	ds_write_b128 v155, v[192:195] offset:18432
	s_waitcnt vmcnt(11)
	ds_write_b128 v155, v[204:207] offset:27648
	ds_write_b128 v155, v[200:203] offset:36864
	s_waitcnt vmcnt(10)
	ds_write_b128 v155, v[208:211] offset:46080
	s_waitcnt vmcnt(9)
	ds_write_b128 v155, v[214:217] offset:55296
	s_waitcnt vmcnt(8)
	ds_write_b128 v155, v[218:221] offset:64512
	ds_read_b128 v[188:191], v154 offset:36864
	ds_read_b128 v[192:195], v154 offset:36896
	ds_read_b128 v[196:199], v154 offset:41472
	ds_read_b128 v[200:203], v154 offset:41504
	ds_read_b128 v[204:207], v132
	ds_read_b128 v[208:211], v132 offset:32
	ds_read_b128 v[214:217], v132 offset:4608
	ds_read_b128 v[218:221], v132 offset:4640
	ds_read_b128 v[222:225], v132 offset:9216
	ds_read_b128 v[226:229], v132 offset:9248
	ds_read_b128 v[230:233], v132 offset:13824
	ds_read_b128 v[234:237], v132 offset:13856
	s_waitcnt lgkmcnt(7)
	v_mfma_f32_32x32x16_bf16 v[114:129], v[204:207], v[188:191], v[114:129]
	v_mfma_f32_32x32x16_bf16 v[82:97], v[204:207], v[196:199], v[82:97]
	s_waitcnt lgkmcnt(5)
	v_mfma_f32_32x32x16_bf16 v[98:113], v[214:217], v[188:191], v[98:113]
	v_mfma_f32_32x32x16_bf16 v[66:81], v[214:217], v[196:199], v[66:81]
	s_waitcnt lgkmcnt(3)
	v_mfma_f32_32x32x16_bf16 v[50:65], v[222:225], v[188:191], v[50:65]
	v_mfma_f32_32x32x16_bf16 v[18:33], v[222:225], v[196:199], v[18:33]
	s_waitcnt lgkmcnt(1)
	v_mfma_f32_32x32x16_bf16 v[34:49], v[230:233], v[188:191], v[34:49]
	v_mfma_f32_32x32x16_bf16 v[2:17], v[230:233], v[196:199], v[2:17]
	ds_read_b128 v[188:191], v154 offset:36928
	ds_read_b128 v[196:199], v154 offset:41536
	ds_read_b128 v[204:207], v132 offset:64
	ds_read_b128 v[214:217], v132 offset:4672
	ds_read_b128 v[222:225], v132 offset:9280
	ds_read_b128 v[230:233], v132 offset:13888
	v_mfma_f32_32x32x16_bf16 v[114:129], v[208:211], v[192:195], v[114:129]
	v_mfma_f32_32x32x16_bf16 v[82:97], v[208:211], v[200:203], v[82:97]
	v_mfma_f32_32x32x16_bf16 v[98:113], v[218:221], v[192:195], v[98:113]
	v_mfma_f32_32x32x16_bf16 v[66:81], v[218:221], v[200:203], v[66:81]
	v_mfma_f32_32x32x16_bf16 v[50:65], v[226:229], v[192:195], v[50:65]
	v_mfma_f32_32x32x16_bf16 v[18:33], v[226:229], v[200:203], v[18:33]
	s_waitcnt lgkmcnt(6)
	v_mfma_f32_32x32x16_bf16 v[34:49], v[234:237], v[192:195], v[34:49]
	v_mfma_f32_32x32x16_bf16 v[2:17], v[234:237], v[200:203], v[2:17]
	ds_read_b128 v[192:195], v154 offset:36960
	ds_read_b128 v[200:203], v154 offset:41568
	ds_read_b128 v[208:211], v132 offset:96
	ds_read_b128 v[218:221], v132 offset:4704
	ds_read_b128 v[226:229], v132 offset:9312
	ds_read_b128 v[234:237], v132 offset:13920
	s_waitcnt lgkmcnt(9)
	v_mfma_f32_32x32x16_bf16 v[114:129], v[204:207], v[188:191], v[114:129]
	v_mfma_f32_32x32x16_bf16 v[82:97], v[204:207], v[196:199], v[82:97]
	s_waitcnt lgkmcnt(8)
	v_mfma_f32_32x32x16_bf16 v[98:113], v[214:217], v[188:191], v[98:113]
	v_mfma_f32_32x32x16_bf16 v[66:81], v[214:217], v[196:199], v[66:81]
	s_waitcnt lgkmcnt(7)
	v_mfma_f32_32x32x16_bf16 v[50:65], v[222:225], v[188:191], v[50:65]
	v_mfma_f32_32x32x16_bf16 v[18:33], v[222:225], v[196:199], v[18:33]
	s_waitcnt lgkmcnt(6)
	v_mfma_f32_32x32x16_bf16 v[34:49], v[230:233], v[188:191], v[34:49]
	v_mfma_f32_32x32x16_bf16 v[2:17], v[230:233], v[196:199], v[2:17]
	s_waitcnt lgkmcnt(3)
	v_mfma_f32_32x32x16_bf16 v[114:129], v[208:211], v[192:195], v[114:129]
	v_mfma_f32_32x32x16_bf16 v[82:97], v[208:211], v[200:203], v[82:97]
	s_waitcnt lgkmcnt(2)
	v_mfma_f32_32x32x16_bf16 v[98:113], v[218:221], v[192:195], v[98:113]
	v_mfma_f32_32x32x16_bf16 v[66:81], v[218:221], v[200:203], v[66:81]
	s_waitcnt lgkmcnt(1)
	v_mfma_f32_32x32x16_bf16 v[50:65], v[226:229], v[192:195], v[50:65]
	v_mfma_f32_32x32x16_bf16 v[18:33], v[226:229], v[200:203], v[18:33]
	s_waitcnt lgkmcnt(0)
	v_mfma_f32_32x32x16_bf16 v[34:49], v[234:237], v[192:195], v[34:49]
	v_mfma_f32_32x32x16_bf16 v[2:17], v[234:237], v[200:203], v[2:17]
	s_barrier
	global_load_dwordx4 v[188:191], v[138:139], off offset:1664
	global_load_dwordx4 v[192:195], v[140:141], off offset:1664
	global_load_dwordx4 v[196:199], v[134:135], off offset:1664
	global_load_dwordx4 v[200:203], v[136:137], off offset:1664
	global_load_dwordx4 v[204:207], v[142:143], off offset:1664
	global_load_dwordx4 v[208:211], v[144:145], off offset:1664
	global_load_dwordx4 v[214:217], v[146:147], off offset:1664
	global_load_dwordx4 v[218:221], v[150:151], off offset:1664
	s_waitcnt vmcnt(13)
	ds_write_b128 v148, v[164:167]
	ds_write_b128 v148, v[156:159] offset:9216
	ds_write_b128 v148, v[160:163] offset:18432
	s_waitcnt vmcnt(11)
	ds_write_b128 v148, v[172:175] offset:27648
	ds_write_b128 v148, v[168:171] offset:36864
	s_waitcnt vmcnt(10)
	ds_write_b128 v148, v[176:179] offset:46080
	s_waitcnt vmcnt(9)
	ds_write_b128 v148, v[180:183] offset:55296
	s_waitcnt vmcnt(8)
	ds_write_b128 v148, v[184:187] offset:64512
	ds_read_b128 v[156:159], v130 offset:36864
	ds_read_b128 v[160:163], v130 offset:36896
	ds_read_b128 v[164:167], v130 offset:41472
	ds_read_b128 v[168:171], v130 offset:41504
	ds_read_b128 v[172:175], v133
	ds_read_b128 v[176:179], v133 offset:32
	ds_read_b128 v[180:183], v133 offset:4608
	ds_read_b128 v[184:187], v133 offset:4640
	ds_read_b128 v[222:225], v133 offset:9216
	ds_read_b128 v[226:229], v133 offset:9248
	ds_read_b128 v[230:233], v133 offset:13824
	ds_read_b128 v[234:237], v133 offset:13856
	s_waitcnt lgkmcnt(7)
	v_mfma_f32_32x32x16_bf16 v[114:129], v[172:175], v[156:159], v[114:129]
	v_mfma_f32_32x32x16_bf16 v[82:97], v[172:175], v[164:167], v[82:97]
	s_waitcnt lgkmcnt(5)
	v_mfma_f32_32x32x16_bf16 v[98:113], v[180:183], v[156:159], v[98:113]
	v_mfma_f32_32x32x16_bf16 v[66:81], v[180:183], v[164:167], v[66:81]
	s_waitcnt lgkmcnt(3)
	v_mfma_f32_32x32x16_bf16 v[50:65], v[222:225], v[156:159], v[50:65]
	v_mfma_f32_32x32x16_bf16 v[18:33], v[222:225], v[164:167], v[18:33]
	s_waitcnt lgkmcnt(1)
	v_mfma_f32_32x32x16_bf16 v[34:49], v[230:233], v[156:159], v[34:49]
	v_mfma_f32_32x32x16_bf16 v[2:17], v[230:233], v[164:167], v[2:17]
	ds_read_b128 v[156:159], v130 offset:36928
	ds_read_b128 v[164:167], v130 offset:41536
	ds_read_b128 v[172:175], v133 offset:64
	ds_read_b128 v[180:183], v133 offset:4672
	ds_read_b128 v[222:225], v133 offset:9280
	ds_read_b128 v[230:233], v133 offset:13888
	v_mfma_f32_32x32x16_bf16 v[114:129], v[176:179], v[160:163], v[114:129]
	v_mfma_f32_32x32x16_bf16 v[82:97], v[176:179], v[168:171], v[82:97]
	v_mfma_f32_32x32x16_bf16 v[98:113], v[184:187], v[160:163], v[98:113]
	v_mfma_f32_32x32x16_bf16 v[66:81], v[184:187], v[168:171], v[66:81]
	v_mfma_f32_32x32x16_bf16 v[50:65], v[226:229], v[160:163], v[50:65]
	v_mfma_f32_32x32x16_bf16 v[18:33], v[226:229], v[168:171], v[18:33]
	s_waitcnt lgkmcnt(6)
	v_mfma_f32_32x32x16_bf16 v[34:49], v[234:237], v[160:163], v[34:49]
	v_mfma_f32_32x32x16_bf16 v[2:17], v[234:237], v[168:171], v[2:17]
	ds_read_b128 v[160:163], v130 offset:36960
	ds_read_b128 v[168:171], v130 offset:41568
	ds_read_b128 v[176:179], v133 offset:96
	ds_read_b128 v[184:187], v133 offset:4704
	ds_read_b128 v[226:229], v133 offset:9312
	ds_read_b128 v[234:237], v133 offset:13920
	s_waitcnt lgkmcnt(9)
	v_mfma_f32_32x32x16_bf16 v[114:129], v[172:175], v[156:159], v[114:129]
	v_mfma_f32_32x32x16_bf16 v[82:97], v[172:175], v[164:167], v[82:97]
	s_waitcnt lgkmcnt(8)
	v_mfma_f32_32x32x16_bf16 v[98:113], v[180:183], v[156:159], v[98:113]
	v_mfma_f32_32x32x16_bf16 v[66:81], v[180:183], v[164:167], v[66:81]
	s_waitcnt lgkmcnt(7)
	v_mfma_f32_32x32x16_bf16 v[50:65], v[222:225], v[156:159], v[50:65]
	v_mfma_f32_32x32x16_bf16 v[18:33], v[222:225], v[164:167], v[18:33]
	s_waitcnt lgkmcnt(6)
	v_mfma_f32_32x32x16_bf16 v[34:49], v[230:233], v[156:159], v[34:49]
	v_mfma_f32_32x32x16_bf16 v[2:17], v[230:233], v[164:167], v[2:17]
	s_waitcnt lgkmcnt(3)
	v_mfma_f32_32x32x16_bf16 v[114:129], v[176:179], v[160:163], v[114:129]
	v_mfma_f32_32x32x16_bf16 v[82:97], v[176:179], v[168:171], v[82:97]
	s_waitcnt lgkmcnt(2)
	v_mfma_f32_32x32x16_bf16 v[98:113], v[184:187], v[160:163], v[98:113]
	v_mfma_f32_32x32x16_bf16 v[66:81], v[184:187], v[168:171], v[66:81]
	s_waitcnt lgkmcnt(1)
	v_mfma_f32_32x32x16_bf16 v[50:65], v[226:229], v[160:163], v[50:65]
	v_mfma_f32_32x32x16_bf16 v[18:33], v[226:229], v[168:171], v[18:33]
	s_waitcnt lgkmcnt(0)
	v_mfma_f32_32x32x16_bf16 v[34:49], v[234:237], v[160:163], v[34:49]
	v_mfma_f32_32x32x16_bf16 v[2:17], v[234:237], v[168:171], v[2:17]
	s_barrier
	global_load_dwordx4 v[156:159], v[138:139], off offset:1792
	global_load_dwordx4 v[160:163], v[140:141], off offset:1792
	global_load_dwordx4 v[164:167], v[134:135], off offset:1792
	global_load_dwordx4 v[168:171], v[136:137], off offset:1792
	global_load_dwordx4 v[172:175], v[142:143], off offset:1792
	global_load_dwordx4 v[176:179], v[144:145], off offset:1792
	global_load_dwordx4 v[180:183], v[146:147], off offset:1792
	global_load_dwordx4 v[184:187], v[150:151], off offset:1792
	s_waitcnt vmcnt(13)
	ds_write_b128 v155, v[196:199]
	ds_write_b128 v155, v[188:191] offset:9216
	ds_write_b128 v155, v[192:195] offset:18432
	s_waitcnt vmcnt(11)
	ds_write_b128 v155, v[204:207] offset:27648
	ds_write_b128 v155, v[200:203] offset:36864
	s_waitcnt vmcnt(10)
	ds_write_b128 v155, v[208:211] offset:46080
	s_waitcnt vmcnt(9)
	ds_write_b128 v155, v[214:217] offset:55296
	s_waitcnt vmcnt(8)
	ds_write_b128 v155, v[218:221] offset:64512
	ds_read_b128 v[188:191], v154 offset:36864
	ds_read_b128 v[192:195], v154 offset:36896
	ds_read_b128 v[196:199], v154 offset:41472
	ds_read_b128 v[200:203], v154 offset:41504
	ds_read_b128 v[204:207], v132
	ds_read_b128 v[208:211], v132 offset:32
	ds_read_b128 v[214:217], v132 offset:4608
	ds_read_b128 v[218:221], v132 offset:4640
	ds_read_b128 v[222:225], v132 offset:9216
	ds_read_b128 v[226:229], v132 offset:9248
	ds_read_b128 v[230:233], v132 offset:13824
	ds_read_b128 v[234:237], v132 offset:13856
	s_waitcnt lgkmcnt(7)
	v_mfma_f32_32x32x16_bf16 v[114:129], v[204:207], v[188:191], v[114:129]
	v_mfma_f32_32x32x16_bf16 v[82:97], v[204:207], v[196:199], v[82:97]
	s_waitcnt lgkmcnt(5)
	v_mfma_f32_32x32x16_bf16 v[98:113], v[214:217], v[188:191], v[98:113]
	v_mfma_f32_32x32x16_bf16 v[66:81], v[214:217], v[196:199], v[66:81]
	s_waitcnt lgkmcnt(3)
	v_mfma_f32_32x32x16_bf16 v[50:65], v[222:225], v[188:191], v[50:65]
	v_mfma_f32_32x32x16_bf16 v[18:33], v[222:225], v[196:199], v[18:33]
	s_waitcnt lgkmcnt(1)
	v_mfma_f32_32x32x16_bf16 v[34:49], v[230:233], v[188:191], v[34:49]
	v_mfma_f32_32x32x16_bf16 v[2:17], v[230:233], v[196:199], v[2:17]
	ds_read_b128 v[188:191], v154 offset:36928
	ds_read_b128 v[196:199], v154 offset:41536
	ds_read_b128 v[204:207], v132 offset:64
	ds_read_b128 v[214:217], v132 offset:4672
	ds_read_b128 v[222:225], v132 offset:9280
	ds_read_b128 v[230:233], v132 offset:13888
	v_mfma_f32_32x32x16_bf16 v[114:129], v[208:211], v[192:195], v[114:129]
	v_mfma_f32_32x32x16_bf16 v[82:97], v[208:211], v[200:203], v[82:97]
	v_mfma_f32_32x32x16_bf16 v[98:113], v[218:221], v[192:195], v[98:113]
	v_mfma_f32_32x32x16_bf16 v[66:81], v[218:221], v[200:203], v[66:81]
	v_mfma_f32_32x32x16_bf16 v[50:65], v[226:229], v[192:195], v[50:65]
	v_mfma_f32_32x32x16_bf16 v[18:33], v[226:229], v[200:203], v[18:33]
	s_waitcnt lgkmcnt(6)
	v_mfma_f32_32x32x16_bf16 v[34:49], v[234:237], v[192:195], v[34:49]
	v_mfma_f32_32x32x16_bf16 v[2:17], v[234:237], v[200:203], v[2:17]
	ds_read_b128 v[192:195], v154 offset:36960
	ds_read_b128 v[200:203], v154 offset:41568
	ds_read_b128 v[208:211], v132 offset:96
	ds_read_b128 v[218:221], v132 offset:4704
	ds_read_b128 v[226:229], v132 offset:9312
	ds_read_b128 v[234:237], v132 offset:13920
	s_waitcnt lgkmcnt(9)
	v_mfma_f32_32x32x16_bf16 v[114:129], v[204:207], v[188:191], v[114:129]
	v_mfma_f32_32x32x16_bf16 v[82:97], v[204:207], v[196:199], v[82:97]
	s_waitcnt lgkmcnt(8)
	v_mfma_f32_32x32x16_bf16 v[98:113], v[214:217], v[188:191], v[98:113]
	v_mfma_f32_32x32x16_bf16 v[66:81], v[214:217], v[196:199], v[66:81]
	s_waitcnt lgkmcnt(7)
	v_mfma_f32_32x32x16_bf16 v[50:65], v[222:225], v[188:191], v[50:65]
	v_mfma_f32_32x32x16_bf16 v[18:33], v[222:225], v[196:199], v[18:33]
	s_waitcnt lgkmcnt(6)
	v_mfma_f32_32x32x16_bf16 v[34:49], v[230:233], v[188:191], v[34:49]
	v_mfma_f32_32x32x16_bf16 v[2:17], v[230:233], v[196:199], v[2:17]
	s_waitcnt lgkmcnt(3)
	v_mfma_f32_32x32x16_bf16 v[114:129], v[208:211], v[192:195], v[114:129]
	v_mfma_f32_32x32x16_bf16 v[82:97], v[208:211], v[200:203], v[82:97]
	s_waitcnt lgkmcnt(2)
	v_mfma_f32_32x32x16_bf16 v[98:113], v[218:221], v[192:195], v[98:113]
	v_mfma_f32_32x32x16_bf16 v[66:81], v[218:221], v[200:203], v[66:81]
	s_waitcnt lgkmcnt(1)
	v_mfma_f32_32x32x16_bf16 v[50:65], v[226:229], v[192:195], v[50:65]
	v_mfma_f32_32x32x16_bf16 v[18:33], v[226:229], v[200:203], v[18:33]
	s_waitcnt lgkmcnt(0)
	v_mfma_f32_32x32x16_bf16 v[34:49], v[234:237], v[192:195], v[34:49]
	v_mfma_f32_32x32x16_bf16 v[2:17], v[234:237], v[200:203], v[2:17]
	s_barrier
	global_load_dwordx4 v[188:191], v[138:139], off offset:1920
	s_nop 0
	global_load_dwordx4 v[138:141], v[140:141], off offset:1920
	s_nop 0
	global_load_dwordx4 v[192:195], v[134:135], off offset:1920
	s_nop 0
	global_load_dwordx4 v[134:137], v[136:137], off offset:1920
	s_nop 0
	global_load_dwordx4 v[196:199], v[142:143], off offset:1920
	s_nop 0
	global_load_dwordx4 v[142:145], v[144:145], off offset:1920
	s_nop 0
	global_load_dwordx4 v[200:203], v[146:147], off offset:1920
	global_load_dwordx4 v[204:207], v[150:151], off offset:1920
	s_waitcnt vmcnt(13)
	ds_write_b128 v148, v[164:167]
	ds_write_b128 v148, v[156:159] offset:9216
	ds_write_b128 v148, v[160:163] offset:18432
	s_waitcnt vmcnt(11)
	ds_write_b128 v148, v[172:175] offset:27648
	ds_write_b128 v148, v[168:171] offset:36864
	s_waitcnt vmcnt(10)
	ds_write_b128 v148, v[176:179] offset:46080
	s_waitcnt vmcnt(9)
	ds_write_b128 v148, v[180:183] offset:55296
	s_waitcnt vmcnt(8)
	ds_write_b128 v148, v[184:187] offset:64512
	ds_read_b128 v[156:159], v130 offset:36864
	ds_read_b128 v[160:163], v130 offset:36896
	ds_read_b128 v[164:167], v130 offset:41472
	ds_read_b128 v[168:171], v130 offset:41504
	ds_read_b128 v[172:175], v133
	ds_read_b128 v[176:179], v133 offset:32
	ds_read_b128 v[180:183], v133 offset:4608
	ds_read_b128 v[184:187], v133 offset:4640
	ds_read_b128 v[208:211], v133 offset:9216
	ds_read_b128 v[214:217], v133 offset:9248
	ds_read_b128 v[218:221], v133 offset:13824
	ds_read_b128 v[222:225], v133 offset:13856
	s_waitcnt lgkmcnt(7)
	v_mfma_f32_32x32x16_bf16 v[114:129], v[172:175], v[156:159], v[114:129]
	v_mfma_f32_32x32x16_bf16 v[82:97], v[172:175], v[164:167], v[82:97]
	s_waitcnt lgkmcnt(5)
	v_mfma_f32_32x32x16_bf16 v[98:113], v[180:183], v[156:159], v[98:113]
	v_mfma_f32_32x32x16_bf16 v[66:81], v[180:183], v[164:167], v[66:81]
	s_waitcnt lgkmcnt(3)
	v_mfma_f32_32x32x16_bf16 v[50:65], v[208:211], v[156:159], v[50:65]
	v_mfma_f32_32x32x16_bf16 v[18:33], v[208:211], v[164:167], v[18:33]
	s_waitcnt lgkmcnt(1)
	v_mfma_f32_32x32x16_bf16 v[34:49], v[218:221], v[156:159], v[34:49]
	v_mfma_f32_32x32x16_bf16 v[2:17], v[218:221], v[164:167], v[2:17]
	ds_read_b128 v[156:159], v130 offset:36928
	ds_read_b128 v[164:167], v130 offset:41536
	ds_read_b128 v[172:175], v133 offset:64
	ds_read_b128 v[180:183], v133 offset:4672
	ds_read_b128 v[208:211], v133 offset:9280
	ds_read_b128 v[218:221], v133 offset:13888
	v_mfma_f32_32x32x16_bf16 v[114:129], v[176:179], v[160:163], v[114:129]
	v_mfma_f32_32x32x16_bf16 v[82:97], v[176:179], v[168:171], v[82:97]
	v_mfma_f32_32x32x16_bf16 v[98:113], v[184:187], v[160:163], v[98:113]
	v_mfma_f32_32x32x16_bf16 v[66:81], v[184:187], v[168:171], v[66:81]
	v_mfma_f32_32x32x16_bf16 v[50:65], v[214:217], v[160:163], v[50:65]
	v_mfma_f32_32x32x16_bf16 v[18:33], v[214:217], v[168:171], v[18:33]
	s_waitcnt lgkmcnt(6)
	v_mfma_f32_32x32x16_bf16 v[34:49], v[222:225], v[160:163], v[34:49]
	v_mfma_f32_32x32x16_bf16 v[2:17], v[222:225], v[168:171], v[2:17]
	ds_read_b128 v[160:163], v130 offset:36960
	ds_read_b128 v[168:171], v130 offset:41568
	ds_read_b128 v[176:179], v133 offset:96
	ds_read_b128 v[184:187], v133 offset:4704
	ds_read_b128 v[214:217], v133 offset:9312
	ds_read_b128 v[222:225], v133 offset:13920
	s_waitcnt lgkmcnt(9)
	v_mfma_f32_32x32x16_bf16 v[114:129], v[172:175], v[156:159], v[114:129]
	v_mfma_f32_32x32x16_bf16 v[82:97], v[172:175], v[164:167], v[82:97]
	s_waitcnt lgkmcnt(8)
	v_mfma_f32_32x32x16_bf16 v[98:113], v[180:183], v[156:159], v[98:113]
	v_mfma_f32_32x32x16_bf16 v[66:81], v[180:183], v[164:167], v[66:81]
	s_waitcnt lgkmcnt(7)
	v_mfma_f32_32x32x16_bf16 v[50:65], v[208:211], v[156:159], v[50:65]
	v_mfma_f32_32x32x16_bf16 v[18:33], v[208:211], v[164:167], v[18:33]
	s_waitcnt lgkmcnt(6)
	v_mfma_f32_32x32x16_bf16 v[34:49], v[218:221], v[156:159], v[34:49]
	v_mfma_f32_32x32x16_bf16 v[2:17], v[218:221], v[164:167], v[2:17]
	s_waitcnt lgkmcnt(3)
	v_mfma_f32_32x32x16_bf16 v[114:129], v[176:179], v[160:163], v[114:129]
	v_mfma_f32_32x32x16_bf16 v[82:97], v[176:179], v[168:171], v[82:97]
	s_waitcnt lgkmcnt(2)
	v_mfma_f32_32x32x16_bf16 v[98:113], v[184:187], v[160:163], v[98:113]
	v_mfma_f32_32x32x16_bf16 v[66:81], v[184:187], v[168:171], v[66:81]
	s_waitcnt lgkmcnt(1)
	v_mfma_f32_32x32x16_bf16 v[50:65], v[214:217], v[160:163], v[50:65]
	v_mfma_f32_32x32x16_bf16 v[18:33], v[214:217], v[168:171], v[18:33]
	s_waitcnt lgkmcnt(0)
	v_mfma_f32_32x32x16_bf16 v[34:49], v[222:225], v[160:163], v[34:49]
	v_mfma_f32_32x32x16_bf16 v[2:17], v[222:225], v[168:171], v[2:17]
	s_barrier
	s_waitcnt vmcnt(5)
	ds_write_b128 v155, v[192:195]
	ds_write_b128 v155, v[188:191] offset:9216
	ds_write_b128 v155, v[138:141] offset:18432
	s_waitcnt vmcnt(3)
	ds_write_b128 v155, v[196:199] offset:27648
	ds_write_b128 v155, v[134:137] offset:36864
	s_waitcnt vmcnt(2)
	ds_write_b128 v155, v[142:145] offset:46080
	s_waitcnt vmcnt(1)
	ds_write_b128 v155, v[200:203] offset:55296
	s_waitcnt vmcnt(0)
	ds_write_b128 v155, v[204:207] offset:64512
	ds_read_b128 v[134:137], v154 offset:36864
	ds_read_b128 v[138:141], v154 offset:36896
	ds_read_b128 v[142:145], v154 offset:41472
	ds_read_b128 v[156:159], v154 offset:41504
	ds_read_b128 v[160:163], v132
	ds_read_b128 v[164:167], v132 offset:32
	ds_read_b128 v[168:171], v132 offset:4608
	ds_read_b128 v[172:175], v132 offset:4640
	ds_read_b128 v[176:179], v132 offset:9216
	ds_read_b128 v[180:183], v132 offset:9248
	ds_read_b128 v[184:187], v132 offset:13824
	ds_read_b128 v[188:191], v132 offset:13856
	s_waitcnt lgkmcnt(7)
	v_mfma_f32_32x32x16_bf16 v[114:129], v[160:163], v[134:137], v[114:129]
	v_mfma_f32_32x32x16_bf16 v[82:97], v[160:163], v[142:145], v[82:97]
	s_waitcnt lgkmcnt(5)
	v_mfma_f32_32x32x16_bf16 v[98:113], v[168:171], v[134:137], v[98:113]
	v_mfma_f32_32x32x16_bf16 v[66:81], v[168:171], v[142:145], v[66:81]
	s_waitcnt lgkmcnt(3)
	v_mfma_f32_32x32x16_bf16 v[50:65], v[176:179], v[134:137], v[50:65]
	v_mfma_f32_32x32x16_bf16 v[18:33], v[176:179], v[142:145], v[18:33]
	s_waitcnt lgkmcnt(1)
	v_mfma_f32_32x32x16_bf16 v[34:49], v[184:187], v[134:137], v[34:49]
	v_mfma_f32_32x32x16_bf16 v[2:17], v[184:187], v[142:145], v[2:17]
	ds_read_b128 v[134:137], v154 offset:36928
	ds_read_b128 v[142:145], v154 offset:41536
	ds_read_b128 v[160:163], v132 offset:64
	ds_read_b128 v[168:171], v132 offset:4672
	ds_read_b128 v[176:179], v132 offset:9280
	ds_read_b128 v[184:187], v132 offset:13888
	v_mfma_f32_32x32x16_bf16 v[114:129], v[164:167], v[138:141], v[114:129]
	v_mfma_f32_32x32x16_bf16 v[82:97], v[164:167], v[156:159], v[82:97]
	v_mfma_f32_32x32x16_bf16 v[98:113], v[172:175], v[138:141], v[98:113]
	v_mfma_f32_32x32x16_bf16 v[66:81], v[172:175], v[156:159], v[66:81]
	v_mfma_f32_32x32x16_bf16 v[50:65], v[180:183], v[138:141], v[50:65]
	v_mfma_f32_32x32x16_bf16 v[18:33], v[180:183], v[156:159], v[18:33]
	s_waitcnt lgkmcnt(6)
	v_mfma_f32_32x32x16_bf16 v[34:49], v[188:191], v[138:141], v[34:49]
	v_mfma_f32_32x32x16_bf16 v[2:17], v[188:191], v[156:159], v[2:17]
	ds_read_b128 v[138:141], v154 offset:36960
	ds_read_b128 v[154:157], v154 offset:41568
	ds_read_b128 v[164:167], v132 offset:96
	ds_read_b128 v[172:175], v132 offset:4704
	ds_read_b128 v[180:183], v132 offset:9312
	ds_read_b128 v[188:191], v132 offset:13920
	s_waitcnt lgkmcnt(9)
	v_mfma_f32_32x32x16_bf16 v[114:129], v[160:163], v[134:137], v[114:129]
	v_mfma_f32_32x32x16_bf16 v[82:97], v[160:163], v[142:145], v[82:97]
	s_waitcnt lgkmcnt(8)
	v_mfma_f32_32x32x16_bf16 v[98:113], v[168:171], v[134:137], v[98:113]
	v_mfma_f32_32x32x16_bf16 v[66:81], v[168:171], v[142:145], v[66:81]
	s_waitcnt lgkmcnt(7)
	v_mfma_f32_32x32x16_bf16 v[50:65], v[176:179], v[134:137], v[50:65]
	v_mfma_f32_32x32x16_bf16 v[18:33], v[176:179], v[142:145], v[18:33]
	s_waitcnt lgkmcnt(6)
	v_mfma_f32_32x32x16_bf16 v[34:49], v[184:187], v[134:137], v[34:49]
	v_mfma_f32_32x32x16_bf16 v[2:17], v[184:187], v[142:145], v[2:17]
	s_waitcnt lgkmcnt(3)
	v_mfma_f32_32x32x16_bf16 v[114:129], v[164:167], v[138:141], v[114:129]
	v_mfma_f32_32x32x16_bf16 v[82:97], v[164:167], v[154:157], v[82:97]
	s_waitcnt lgkmcnt(2)
	v_mfma_f32_32x32x16_bf16 v[98:113], v[172:175], v[138:141], v[98:113]
	v_mfma_f32_32x32x16_bf16 v[66:81], v[172:175], v[154:157], v[66:81]
	s_waitcnt lgkmcnt(1)
	v_mfma_f32_32x32x16_bf16 v[50:65], v[180:183], v[138:141], v[50:65]
	v_mfma_f32_32x32x16_bf16 v[18:33], v[180:183], v[154:157], v[18:33]
	s_waitcnt lgkmcnt(0)
	v_mfma_f32_32x32x16_bf16 v[34:49], v[188:191], v[138:141], v[34:49]
	v_mfma_f32_32x32x16_bf16 v[2:17], v[188:191], v[154:157], v[2:17]
	s_barrier
	ds_read_b128 v[134:137], v130 offset:36864
	ds_read_b128 v[138:141], v130 offset:36896
	ds_read_b128 v[142:145], v130 offset:41472
	ds_read_b128 v[154:157], v130 offset:41504
	ds_read_b128 v[158:161], v133
	ds_read_b128 v[162:165], v133 offset:32
	ds_read_b128 v[166:169], v133 offset:4608
	ds_read_b128 v[170:173], v133 offset:4640
	ds_read_b128 v[174:177], v133 offset:9216
	ds_read_b128 v[178:181], v133 offset:9248
	ds_read_b128 v[182:185], v133 offset:13824
	ds_read_b128 v[186:189], v133 offset:13856
	s_waitcnt lgkmcnt(7)
	v_mfma_f32_32x32x16_bf16 v[114:129], v[158:161], v[134:137], v[114:129]
	v_mfma_f32_32x32x16_bf16 v[82:97], v[158:161], v[142:145], v[82:97]
	s_waitcnt lgkmcnt(5)
	v_mfma_f32_32x32x16_bf16 v[98:113], v[166:169], v[134:137], v[98:113]
	v_mfma_f32_32x32x16_bf16 v[66:81], v[166:169], v[142:145], v[66:81]
	s_waitcnt lgkmcnt(3)
	v_mfma_f32_32x32x16_bf16 v[50:65], v[174:177], v[134:137], v[50:65]
	v_mfma_f32_32x32x16_bf16 v[18:33], v[174:177], v[142:145], v[18:33]
	s_waitcnt lgkmcnt(1)
	v_mfma_f32_32x32x16_bf16 v[34:49], v[182:185], v[134:137], v[34:49]
	v_mfma_f32_32x32x16_bf16 v[2:17], v[182:185], v[142:145], v[2:17]
	ds_read_b128 v[134:137], v130 offset:36928
	ds_read_b128 v[142:145], v130 offset:41536
	ds_read_b128 v[158:161], v133 offset:64
	ds_read_b128 v[166:169], v133 offset:4672
	ds_read_b128 v[174:177], v133 offset:9280
	ds_read_b128 v[182:185], v133 offset:13888
	v_mfma_f32_32x32x16_bf16 v[114:129], v[162:165], v[138:141], v[114:129]
	v_mfma_f32_32x32x16_bf16 v[82:97], v[162:165], v[154:157], v[82:97]
	v_mfma_f32_32x32x16_bf16 v[98:113], v[170:173], v[138:141], v[98:113]
	v_mfma_f32_32x32x16_bf16 v[66:81], v[170:173], v[154:157], v[66:81]
	v_mfma_f32_32x32x16_bf16 v[50:65], v[178:181], v[138:141], v[50:65]
	v_mfma_f32_32x32x16_bf16 v[18:33], v[178:181], v[154:157], v[18:33]
	s_waitcnt lgkmcnt(6)
	v_mfma_f32_32x32x16_bf16 v[34:49], v[186:189], v[138:141], v[34:49]
	v_mfma_f32_32x32x16_bf16 v[2:17], v[186:189], v[154:157], v[2:17]
	ds_read_b128 v[138:141], v130 offset:36960
	ds_read_b128 v[154:157], v130 offset:41568
	ds_read_b128 v[162:165], v133 offset:96
	ds_read_b128 v[170:173], v133 offset:4704
	ds_read_b128 v[178:181], v133 offset:9312
	ds_read_b128 v[186:189], v133 offset:13920
	s_waitcnt lgkmcnt(9)
	v_mfma_f32_32x32x16_bf16 v[114:129], v[158:161], v[134:137], v[114:129]
	v_mfma_f32_32x32x16_bf16 v[82:97], v[158:161], v[142:145], v[82:97]
	s_waitcnt lgkmcnt(8)
	v_mfma_f32_32x32x16_bf16 v[98:113], v[166:169], v[134:137], v[98:113]
	v_mfma_f32_32x32x16_bf16 v[66:81], v[166:169], v[142:145], v[66:81]
	s_waitcnt lgkmcnt(7)
	v_mfma_f32_32x32x16_bf16 v[50:65], v[174:177], v[134:137], v[50:65]
	v_mfma_f32_32x32x16_bf16 v[18:33], v[174:177], v[142:145], v[18:33]
	s_waitcnt lgkmcnt(6)
	v_mfma_f32_32x32x16_bf16 v[34:49], v[182:185], v[134:137], v[34:49]
	v_mfma_f32_32x32x16_bf16 v[2:17], v[182:185], v[142:145], v[2:17]
	s_waitcnt lgkmcnt(3)
	v_mfma_f32_32x32x16_bf16 v[114:129], v[162:165], v[138:141], v[114:129]
	v_mfma_f32_32x32x16_bf16 v[82:97], v[162:165], v[154:157], v[82:97]
	s_waitcnt lgkmcnt(2)
	v_mfma_f32_32x32x16_bf16 v[98:113], v[170:173], v[138:141], v[98:113]
	v_mfma_f32_32x32x16_bf16 v[66:81], v[170:173], v[154:157], v[66:81]
	s_waitcnt lgkmcnt(1)
	v_mfma_f32_32x32x16_bf16 v[50:65], v[178:181], v[138:141], v[50:65]
	v_mfma_f32_32x32x16_bf16 v[18:33], v[178:181], v[154:157], v[18:33]
	s_waitcnt lgkmcnt(0)
	v_mfma_f32_32x32x16_bf16 v[34:49], v[186:189], v[138:141], v[34:49]
	v_mfma_f32_32x32x16_bf16 v[2:17], v[186:189], v[154:157], v[2:17]
	v_and_b32_e32 v145, 0xdf, v153
	v_or_b32_e32 v138, s14, v145
	v_ashrrev_i32_e32 v139, 31, v138
	v_lshl_add_u64 v[136:137], v[138:139], 2, s[10:11]
	s_barrier
	s_add_i32 s3, s14, 0xffffe000
	global_load_dword v139, v[136:137], off
	s_lshr_b32 s3, s3, 1
	s_and_b32 s3, s3, 0x7ffff800
	v_ashrrev_i32_e32 v144, 1, v153
	s_addk_i32 s3, 0x800
	v_and_b32_e32 v146, 0xffffff80, v144
	v_mov_b32_e32 v130, s3
	v_cmp_lt_i32_e32 vcc, s37, v138
	v_add_u32_e32 v132, s16, v146
	v_ashrrev_i32_e32 v133, 31, v132
	v_cndmask_b32_e32 v130, 0, v130, vcc
	v_lshl_add_u64 v[134:135], v[130:131], 2, s[12:13]
	v_lshl_add_u64 v[134:135], v[132:133], 2, v[134:135]
	v_lshlrev_b32_e32 v130, 7, v149
	v_lshl_add_u64 v[134:135], v[134:135], 0, v[130:131]
	global_load_dwordx4 v[140:143], v[134:135], off
	global_load_dwordx4 v[154:157], v[134:135], off offset:16
	global_load_dwordx4 v[158:161], v[134:135], off offset:32
	global_load_dwordx4 v[162:165], v[134:135], off offset:48
	global_load_dwordx4 v[166:169], v[134:135], off offset:64
	global_load_dwordx4 v[170:173], v[134:135], off offset:80
	global_load_dwordx4 v[174:177], v[134:135], off offset:96
	global_load_dwordx4 v[178:181], v[134:135], off offset:112
	v_permlane32_swap_b32_e32 v114, v98
	v_permlane32_swap_b32_e32 v115, v99
	v_permlane32_swap_b32_e32 v116, v100
	v_permlane32_swap_b32_e32 v117, v101
	v_permlane32_swap_b32_e32 v118, v102
	v_permlane32_swap_b32_e32 v119, v103
	v_permlane32_swap_b32_e32 v120, v104
	v_permlane32_swap_b32_e32 v121, v105
	v_permlane32_swap_b32_e32 v122, v106
	v_permlane32_swap_b32_e32 v123, v107
	v_permlane32_swap_b32_e32 v124, v108
	v_permlane32_swap_b32_e32 v125, v109
	v_permlane32_swap_b32_e32 v126, v110
	v_permlane32_swap_b32_e32 v127, v111
	v_permlane32_swap_b32_e32 v128, v112
	v_permlane32_swap_b32_e32 v129, v113
	v_cmp_lt_i32_e32 vcc, s35, v132
	s_waitcnt vmcnt(8)
	v_fmamk_f32 v130, v139, 0x3a800000, v1
	v_mul_f32_e32 v139, 0x4b800000, v130
	v_cmp_gt_f32_e64 s[4:5], s36, v130
	s_nop 1
	v_cndmask_b32_e64 v130, v130, v139, s[4:5]
	v_rsq_f32_e32 v130, v130
	s_nop 0
	v_mul_f32_e32 v139, 0x45800000, v130
	v_cndmask_b32_e64 v130, v130, v139, s[4:5]
	s_waitcnt vmcnt(7)
	v_pk_fma_f32 v[114:115], v[130:131], v[114:115], v[140:141] op_sel_hi:[0,1,1]
	v_pk_fma_f32 v[116:117], v[130:131], v[116:117], v[142:143] op_sel_hi:[0,1,1]
	s_waitcnt vmcnt(6)
	v_pk_fma_f32 v[140:141], v[130:131], v[98:99], v[154:155] op_sel_hi:[0,1,1]
	v_pk_fma_f32 v[142:143], v[130:131], v[100:101], v[156:157] op_sel_hi:[0,1,1]
	s_waitcnt vmcnt(5)
	v_pk_fma_f32 v[118:119], v[130:131], v[118:119], v[158:159] op_sel_hi:[0,1,1]
	v_pk_fma_f32 v[120:121], v[130:131], v[120:121], v[160:161] op_sel_hi:[0,1,1]
	s_waitcnt vmcnt(4)
	v_pk_fma_f32 v[102:103], v[130:131], v[102:103], v[162:163] op_sel_hi:[0,1,1]
	v_pk_fma_f32 v[104:105], v[130:131], v[104:105], v[164:165] op_sel_hi:[0,1,1]
	s_waitcnt vmcnt(3)
	v_pk_fma_f32 v[122:123], v[130:131], v[122:123], v[166:167] op_sel_hi:[0,1,1]
	v_pk_fma_f32 v[124:125], v[130:131], v[124:125], v[168:169] op_sel_hi:[0,1,1]
	s_waitcnt vmcnt(2)
	v_pk_fma_f32 v[106:107], v[130:131], v[106:107], v[170:171] op_sel_hi:[0,1,1]
	v_pk_fma_f32 v[108:109], v[130:131], v[108:109], v[172:173] op_sel_hi:[0,1,1]
	s_waitcnt vmcnt(1)
	v_pk_fma_f32 v[126:127], v[130:131], v[126:127], v[174:175] op_sel_hi:[0,1,1]
	v_pk_fma_f32 v[128:129], v[130:131], v[128:129], v[176:177] op_sel_hi:[0,1,1]
	s_waitcnt vmcnt(0)
	v_pk_fma_f32 v[110:111], v[130:131], v[110:111], v[178:179] op_sel_hi:[0,1,1]
	v_pk_fma_f32 v[112:113], v[130:131], v[112:113], v[180:181] op_sel_hi:[0,1,1]
	s_and_saveexec_b64 s[4:5], vcc
	s_cbranch_execz .LBB0_706
	v_mul_f32_e32 v130, 0xbfb8aa3b, v116
	v_exp_f32_e32 v130, v130
	v_mul_f32_e32 v139, 0xbfb8aa3b, v142
	v_exp_f32_e32 v139, v139
	v_mul_f32_e32 v147, 0xbfb8aa3b, v117
	v_exp_f32_e32 v147, v147
	v_add_f32_e32 v130, 1.0, v130
	v_rcp_f32_e32 v150, v130
	v_add_f32_e32 v130, 1.0, v139
	v_mul_f32_e32 v139, 0xbfb8aa3b, v143
	v_rcp_f32_e32 v154, v130
	v_add_f32_e32 v130, 1.0, v147
	v_exp_f32_e32 v139, v139
	v_mul_f32_e32 v147, 0xbfb8aa3b, v118
	v_exp_f32_e32 v147, v147
	v_rcp_f32_e32 v151, v130
	v_add_f32_e32 v130, 1.0, v139
	v_mul_f32_e32 v139, 0xbfb8aa3b, v102
	v_rcp_f32_e32 v155, v130
	v_add_f32_e32 v130, 1.0, v147
	v_exp_f32_e32 v139, v139
	v_mul_f32_e32 v147, 0xbfb8aa3b, v119
	v_exp_f32_e32 v147, v147
	v_rcp_f32_e32 v156, v130
	v_add_f32_e32 v130, 1.0, v139
	v_mul_f32_e32 v139, 0xbfb8aa3b, v103
	v_rcp_f32_e32 v158, v130
	v_add_f32_e32 v130, 1.0, v147
	v_exp_f32_e32 v139, v139
	v_mul_f32_e32 v147, 0xbfb8aa3b, v120
	v_exp_f32_e32 v147, v147
	v_rcp_f32_e32 v157, v130
	v_add_f32_e32 v130, 1.0, v139
	v_mul_f32_e32 v139, 0xbfb8aa3b, v104
	v_rcp_f32_e32 v159, v130
	v_add_f32_e32 v130, 1.0, v147
	v_exp_f32_e32 v139, v139
	v_mul_f32_e32 v147, 0xbfb8aa3b, v121
	v_exp_f32_e32 v147, v147
	v_rcp_f32_e32 v160, v130
	v_add_f32_e32 v130, 1.0, v139
	v_mul_f32_e32 v139, 0xbfb8aa3b, v105
	v_rcp_f32_e32 v162, v130
	v_add_f32_e32 v130, 1.0, v147
	v_exp_f32_e32 v139, v139
	v_mul_f32_e32 v147, 0xbfb8aa3b, v122
	v_exp_f32_e32 v147, v147
	v_rcp_f32_e32 v161, v130
	v_add_f32_e32 v130, 1.0, v139
	v_mul_f32_e32 v139, 0xbfb8aa3b, v106
	v_rcp_f32_e32 v163, v130
	v_add_f32_e32 v130, 1.0, v147
	v_exp_f32_e32 v139, v139
	v_mul_f32_e32 v147, 0xbfb8aa3b, v123
	v_exp_f32_e32 v147, v147
	v_rcp_f32_e32 v164, v130
	v_add_f32_e32 v130, 1.0, v139
	v_mul_f32_e32 v139, 0xbfb8aa3b, v107
	v_rcp_f32_e32 v166, v130
	v_add_f32_e32 v130, 1.0, v147
	v_exp_f32_e32 v139, v139
	v_mul_f32_e32 v147, 0xbfb8aa3b, v124
	v_exp_f32_e32 v147, v147
	v_rcp_f32_e32 v165, v130
	v_add_f32_e32 v130, 1.0, v139
	v_mul_f32_e32 v139, 0xbfb8aa3b, v108
	v_rcp_f32_e32 v167, v130
	v_add_f32_e32 v130, 1.0, v147
	v_exp_f32_e32 v139, v139
	v_mul_f32_e32 v147, 0xbfb8aa3b, v125
	v_exp_f32_e32 v147, v147
	v_rcp_f32_e32 v168, v130
	v_add_f32_e32 v130, 1.0, v139
	v_mul_f32_e32 v139, 0xbfb8aa3b, v109
	v_rcp_f32_e32 v170, v130
	v_add_f32_e32 v130, 1.0, v147
	v_exp_f32_e32 v139, v139
	v_mul_f32_e32 v147, 0xbfb8aa3b, v126
	v_exp_f32_e32 v147, v147
	v_mul_f32_e32 v99, 0xbfb8aa3b, v140
	v_rcp_f32_e32 v169, v130
	v_add_f32_e32 v130, 1.0, v139
	v_mul_f32_e32 v139, 0xbfb8aa3b, v110
	v_mul_f32_e32 v98, 0xbfb8aa3b, v114
	v_mul_f32_e32 v100, 0xbfb8aa3b, v115
	v_exp_f32_e32 v99, v99
	v_rcp_f32_e32 v171, v130
	v_add_f32_e32 v130, 1.0, v147
	v_exp_f32_e32 v139, v139
	v_mul_f32_e32 v147, 0xbfb8aa3b, v127
	v_exp_f32_e32 v98, v98
	v_exp_f32_e32 v101, v100
	v_exp_f32_e32 v147, v147
	v_add_f32_e32 v99, 1.0, v99
	v_rcp_f32_e32 v172, v130
	v_add_f32_e32 v130, 1.0, v139
	v_mul_f32_e32 v139, 0xbfb8aa3b, v111
	v_add_f32_e32 v98, 1.0, v98
	v_rcp_f32_e32 v100, v99
	v_add_f32_e32 v99, 1.0, v101
	v_rcp_f32_e32 v174, v130
	v_add_f32_e32 v130, 1.0, v147
	v_exp_f32_e32 v139, v139
	v_mul_f32_e32 v147, 0xbfb8aa3b, v128
	v_rcp_f32_e32 v98, v98
	v_rcp_f32_e32 v99, v99
	v_exp_f32_e32 v147, v147
	v_rcp_f32_e32 v173, v130
	v_add_f32_e32 v130, 1.0, v139
	v_mul_f32_e32 v139, 0xbfb8aa3b, v112
	v_mul_f32_e32 v101, 0xbfb8aa3b, v141
	v_rcp_f32_e32 v175, v130
	v_add_f32_e32 v130, 1.0, v147
	v_exp_f32_e32 v139, v139
	v_mul_f32_e32 v147, 0xbfb8aa3b, v129
	v_pk_mul_f32 v[114:115], v[114:115], v[98:99]
	v_mul_f32_e32 v98, 0xbfb8aa3b, v113
	v_exp_f32_e32 v101, v101
	v_exp_f32_e32 v147, v147
	v_exp_f32_e32 v98, v98
	v_rcp_f32_e32 v176, v130
	v_add_f32_e32 v130, 1.0, v139
	v_add_f32_e32 v101, 1.0, v101
	v_rcp_f32_e32 v178, v130
	v_add_f32_e32 v130, 1.0, v147
	v_add_f32_e32 v98, 1.0, v98
	v_rcp_f32_e32 v101, v101
	v_rcp_f32_e32 v177, v130
	v_rcp_f32_e32 v179, v98
	v_pk_mul_f32 v[116:117], v[116:117], v[150:151]
	v_pk_mul_f32 v[118:119], v[118:119], v[156:157]
	v_pk_mul_f32 v[120:121], v[120:121], v[160:161]
	v_pk_mul_f32 v[122:123], v[122:123], v[164:165]
	v_pk_mul_f32 v[124:125], v[124:125], v[168:169]
	v_pk_mul_f32 v[126:127], v[126:127], v[172:173]
	v_pk_mul_f32 v[128:129], v[128:129], v[176:177]
	v_pk_mul_f32 v[140:141], v[140:141], v[100:101]
	v_pk_mul_f32 v[142:143], v[142:143], v[154:155]
	v_pk_mul_f32 v[102:103], v[102:103], v[158:159]
	v_pk_mul_f32 v[104:105], v[104:105], v[162:163]
	v_pk_mul_f32 v[106:107], v[106:107], v[166:167]
	v_pk_mul_f32 v[108:109], v[108:109], v[170:171]
	v_pk_mul_f32 v[110:111], v[110:111], v[174:175]
	v_pk_mul_f32 v[112:113], v[112:113], v[178:179]

.LBB0_808:
	s_and_b32 s14, s36, 3
	v_mov_b32_e32 v62, v212
	s_and_b32 s15, s21, 0xffffff80
	s_lshl_b32 s14, s14, 9
	s_lshl_b32 s1, s1, 17
	s_add_u32 s16, s3, s1
	v_ashrrev_i32_e32 v26, 3, v62
	v_ashrrev_i32_e32 v27, 31, v26
	s_addc_u32 s17, s20, 0
	v_lshlrev_b64 v[2:3], 9, v[26:27]
	v_lshlrev_b32_e32 v4, 4, v62
	v_lshl_add_u64 v[2:3], s[16:17], 0, v[2:3]
	v_and_b32_e32 v66, 0x70, v4
	s_ashr_i32 s1, s0, 31
	v_lshl_add_u64 v[50:51], v[2:3], 0, v[66:67]
	s_lshl_b64 s[0:1], s[0:1], 11
	v_add_co_u32_e32 v54, vcc, s25, v50
	s_add_u32 s0, s8, s0
	s_nop 0
	v_addc_co_u32_e32 v55, vcc, 0, v51, vcc
	s_addc_u32 s1, s9, s1
	s_lshl_b32 s18, s38, 1
	v_add_co_u32_e32 v56, vcc, s26, v50
	s_add_u32 s0, s0, s18
	s_nop 0
	v_addc_co_u32_e32 v57, vcc, 0, v51, vcc
	s_addc_u32 s1, s1, 0
	v_lshlrev_b64 v[2:3], 11, v[26:27]
	v_add_co_u32_e32 v58, vcc, s27, v50
	v_lshl_add_u64 v[2:3], s[0:1], 0, v[2:3]
	s_nop 0
	v_addc_co_u32_e32 v59, vcc, 0, v51, vcc
	v_lshl_add_u64 v[52:53], v[2:3], 0, v[66:67]
	global_load_dwordx4 v[2:5], v[50:51], off
	global_load_dwordx4 v[6:9], v[54:55], off
	global_load_dwordx4 v[10:13], v[56:57], off
	global_load_dwordx4 v[14:17], v[58:59], off
	global_load_dwordx4 v[18:21], v[52:53], off
	v_add_co_u32_e32 v60, vcc, s28, v52
	v_mad_u64_u32 v[152:153], s[0:1], v26, s23, v[66:67]
	s_nop 0
	v_addc_co_u32_e32 v61, vcc, 0, v53, vcc
	global_load_dwordx4 v[22:25], v[60:61], off
	global_load_dwordx4 v[26:29], v[50:51], off offset:128
	global_load_dwordx4 v[30:33], v[54:55], off offset:128
	global_load_dwordx4 v[34:37], v[58:59], off offset:128
	global_load_dwordx4 v[72:75], v[54:55], off offset:256
	global_load_dwordx4 v[38:41], v[56:57], off offset:128
	global_load_dwordx4 v[76:79], v[56:57], off offset:256
	global_load_dwordx4 v[80:83], v[50:51], off offset:256
	global_load_dwordx4 v[42:45], v[52:53], off offset:128
	global_load_dwordx4 v[84:87], v[52:53], off offset:256
	global_load_dwordx4 v[88:91], v[58:59], off offset:256
	global_load_dwordx4 v[46:49], v[60:61], off offset:128
	global_load_dwordx4 v[92:95], v[60:61], off offset:256
	v_add_u32_e32 v153, 0x12000, v152
	s_waitcnt vmcnt(17)
	ds_write_b128 v152, v[2:5]
	s_waitcnt vmcnt(16)
	ds_write_b128 v152, v[6:9] offset:9216
	s_waitcnt vmcnt(15)
	ds_write_b128 v152, v[10:13] offset:18432
	s_waitcnt vmcnt(14)
	ds_write_b128 v152, v[14:17] offset:27648
	s_waitcnt vmcnt(13)
	ds_write_b128 v152, v[18:21] offset:36864
	s_waitcnt vmcnt(12)
	ds_write_b128 v152, v[22:25] offset:46080
	s_waitcnt lgkmcnt(0)
	s_barrier
	global_load_dwordx4 v[96:99], v[54:55], off offset:384
	global_load_dwordx4 v[100:103], v[56:57], off offset:384
	global_load_dwordx4 v[104:107], v[50:51], off offset:384
	global_load_dwordx4 v[108:111], v[52:53], off offset:384
	global_load_dwordx4 v[112:115], v[58:59], off offset:384
	global_load_dwordx4 v[116:119], v[60:61], off offset:384
	v_and_b32_e32 v2, 31, v62
	v_lshrrev_b32_e32 v3, 1, v62
	v_and_or_b32 v4, v3, s24, v2
	v_and_b32_e32 v2, 16, v3
	v_and_b32_e32 v3, 0x5f, v62
	v_mad_u32_u24 v66, v3, s23, v2
	v_add_u32_e32 v71, 0x12000, v66
	s_waitcnt vmcnt(17)
	ds_write_b128 v153, v[26:29]
	s_waitcnt vmcnt(16)
	ds_write_b128 v153, v[30:33] offset:9216
	s_waitcnt vmcnt(13)
	ds_write_b128 v153, v[38:41] offset:18432
	ds_write_b128 v153, v[34:37] offset:27648
	s_waitcnt vmcnt(10)
	ds_write_b128 v153, v[42:45] offset:36864
	s_waitcnt vmcnt(7)
	ds_write_b128 v153, v[46:49] offset:46080
	v_mad_u64_u32 v[154:155], s[0:1], v4, s23, v[2:3]
	ds_read_b128 v[2:5], v66 offset:36864
	ds_read_b128 v[120:123], v66 offset:36896
	ds_read_b128 v[6:9], v66 offset:41472
	ds_read_b128 v[124:127], v66 offset:41504
	ds_read_b128 v[10:13], v154
	ds_read_b128 v[128:131], v154 offset:32
	ds_read_b128 v[14:17], v154 offset:4608
	ds_read_b128 v[132:135], v154 offset:4640
	s_waitcnt lgkmcnt(3)
	v_mfma_f32_32x32x16_bf16 v[50:65], v[10:13], v[2:5], 0
	v_mfma_f32_32x32x16_bf16 v[18:33], v[10:13], v[6:9], 0
	s_waitcnt lgkmcnt(1)
	v_mfma_f32_32x32x16_bf16 v[34:49], v[14:17], v[2:5], 0
	v_mfma_f32_32x32x16_bf16 v[2:17], v[14:17], v[6:9], 0
	ds_read_b128 v[136:139], v66 offset:36928
	ds_read_b128 v[140:143], v66 offset:41536
	ds_read_b128 v[144:147], v154 offset:64
	ds_read_b128 v[148:151], v154 offset:4672
	s_waitcnt lgkmcnt(4)
	v_mfma_f32_32x32x16_bf16 v[2:17], v[132:135], v[124:127], v[2:17]
	v_mfma_f32_32x32x16_bf16 v[50:65], v[128:131], v[120:123], v[50:65]
	v_mfma_f32_32x32x16_bf16 v[18:33], v[128:131], v[124:127], v[18:33]
	v_mfma_f32_32x32x16_bf16 v[34:49], v[132:135], v[120:123], v[34:49]
	ds_read_b128 v[120:123], v66 offset:36960
	ds_read_b128 v[124:127], v66 offset:41568
	ds_read_b128 v[128:131], v154 offset:96
	ds_read_b128 v[132:135], v154 offset:4704
	s_waitcnt lgkmcnt(4)
	v_mfma_f32_32x32x16_bf16 v[2:17], v[148:151], v[140:143], v[2:17]
	v_mfma_f32_32x32x16_bf16 v[50:65], v[144:147], v[136:139], v[50:65]
	v_mfma_f32_32x32x16_bf16 v[18:33], v[144:147], v[140:143], v[18:33]
	v_mfma_f32_32x32x16_bf16 v[34:49], v[148:151], v[136:139], v[34:49]
	s_waitcnt lgkmcnt(0)
	v_mfma_f32_32x32x16_bf16 v[2:17], v[132:135], v[124:127], v[2:17]
	v_mfma_f32_32x32x16_bf16 v[50:65], v[128:131], v[120:123], v[50:65]
	v_mfma_f32_32x32x16_bf16 v[18:33], v[128:131], v[124:127], v[18:33]
	v_mfma_f32_32x32x16_bf16 v[34:49], v[132:135], v[120:123], v[34:49]
	s_barrier
	ds_write_b128 v152, v[80:83]
	ds_write_b128 v152, v[72:75] offset:9216
	ds_write_b128 v152, v[76:79] offset:18432
	ds_write_b128 v152, v[88:91] offset:27648
	ds_write_b128 v152, v[84:87] offset:36864
	s_waitcnt vmcnt(6)
	ds_write_b128 v152, v[92:95] offset:46080
	v_add_u32_e32 v128, 0x12000, v154
	ds_read_b128 v[72:75], v71 offset:36864
	ds_read_b128 v[76:79], v71 offset:36896
	ds_read_b128 v[80:83], v71 offset:41472
	ds_read_b128 v[84:87], v71 offset:41504
	ds_read_b128 v[88:91], v128
	ds_read_b128 v[92:95], v128 offset:32
	ds_read_b128 v[120:123], v128 offset:4608
	ds_read_b128 v[124:127], v128 offset:4640
	s_waitcnt lgkmcnt(1)
	v_mfma_f32_32x32x16_bf16 v[2:17], v[120:123], v[80:83], v[2:17]
	v_mfma_f32_32x32x16_bf16 v[50:65], v[88:91], v[72:75], v[50:65]
	v_mfma_f32_32x32x16_bf16 v[18:33], v[88:91], v[80:83], v[18:33]
	v_mfma_f32_32x32x16_bf16 v[34:49], v[120:123], v[72:75], v[34:49]
	ds_read_b128 v[72:75], v71 offset:36928
	ds_read_b128 v[80:83], v71 offset:41536
	ds_read_b128 v[88:91], v128 offset:64
	ds_read_b128 v[120:123], v128 offset:4672
	s_waitcnt lgkmcnt(4)
	v_mfma_f32_32x32x16_bf16 v[2:17], v[124:127], v[84:87], v[2:17]
	v_mfma_f32_32x32x16_bf16 v[50:65], v[92:95], v[76:79], v[50:65]
	v_mfma_f32_32x32x16_bf16 v[18:33], v[92:95], v[84:87], v[18:33]
	v_mfma_f32_32x32x16_bf16 v[34:49], v[124:127], v[76:79], v[34:49]
	ds_read_b128 v[76:79], v71 offset:36960
	ds_read_b128 v[84:87], v71 offset:41568
	ds_read_b128 v[92:95], v128 offset:96
	ds_read_b128 v[124:127], v128 offset:4704
	s_waitcnt lgkmcnt(4)
	v_mfma_f32_32x32x16_bf16 v[2:17], v[120:123], v[80:83], v[2:17]
	v_mfma_f32_32x32x16_bf16 v[50:65], v[88:91], v[72:75], v[50:65]
	v_mfma_f32_32x32x16_bf16 v[18:33], v[88:91], v[80:83], v[18:33]
	v_mfma_f32_32x32x16_bf16 v[34:49], v[120:123], v[72:75], v[34:49]
	s_waitcnt lgkmcnt(0)
	v_mfma_f32_32x32x16_bf16 v[2:17], v[124:127], v[84:87], v[2:17]
	v_mfma_f32_32x32x16_bf16 v[50:65], v[92:95], v[76:79], v[50:65]
	v_mfma_f32_32x32x16_bf16 v[18:33], v[92:95], v[84:87], v[18:33]
	v_mfma_f32_32x32x16_bf16 v[34:49], v[124:127], v[76:79], v[34:49]
	s_barrier
	s_waitcnt vmcnt(3)
	ds_write_b128 v153, v[104:107]
	ds_write_b128 v153, v[96:99] offset:9216
	ds_write_b128 v153, v[100:103] offset:18432
	s_waitcnt vmcnt(1)
	ds_write_b128 v153, v[112:115] offset:27648
	ds_write_b128 v153, v[108:111] offset:36864
	s_waitcnt vmcnt(0)
	ds_write_b128 v153, v[116:119] offset:46080
	ds_read_b128 v[72:75], v66 offset:36864
	ds_read_b128 v[76:79], v66 offset:36896
	ds_read_b128 v[80:83], v66 offset:41472
	ds_read_b128 v[84:87], v66 offset:41504
	ds_read_b128 v[88:91], v154
	ds_read_b128 v[92:95], v154 offset:32
	ds_read_b128 v[96:99], v154 offset:4608
	ds_read_b128 v[100:103], v154 offset:4640
	s_waitcnt lgkmcnt(1)
	v_mfma_f32_32x32x16_bf16 v[2:17], v[96:99], v[80:83], v[2:17]
	v_mfma_f32_32x32x16_bf16 v[50:65], v[88:91], v[72:75], v[50:65]
	v_mfma_f32_32x32x16_bf16 v[18:33], v[88:91], v[80:83], v[18:33]
	v_mfma_f32_32x32x16_bf16 v[34:49], v[96:99], v[72:75], v[34:49]
	ds_read_b128 v[72:75], v66 offset:36928
	ds_read_b128 v[80:83], v66 offset:41536
	ds_read_b128 v[88:91], v154 offset:64
	ds_read_b128 v[96:99], v154 offset:4672
	s_waitcnt lgkmcnt(4)
	v_mfma_f32_32x32x16_bf16 v[2:17], v[100:103], v[84:87], v[2:17]
	v_mfma_f32_32x32x16_bf16 v[50:65], v[92:95], v[76:79], v[50:65]
	v_mfma_f32_32x32x16_bf16 v[18:33], v[92:95], v[84:87], v[18:33]
	v_mfma_f32_32x32x16_bf16 v[34:49], v[100:103], v[76:79], v[34:49]
	ds_read_b128 v[76:79], v66 offset:36960
	ds_read_b128 v[84:87], v66 offset:41568
	ds_read_b128 v[92:95], v154 offset:96
	ds_read_b128 v[100:103], v154 offset:4704
	s_waitcnt lgkmcnt(4)
	v_mfma_f32_32x32x16_bf16 v[2:17], v[96:99], v[80:83], v[2:17]
	v_mfma_f32_32x32x16_bf16 v[50:65], v[88:91], v[72:75], v[50:65]
	v_mfma_f32_32x32x16_bf16 v[18:33], v[88:91], v[80:83], v[18:33]
	v_mfma_f32_32x32x16_bf16 v[34:49], v[96:99], v[72:75], v[34:49]
	s_waitcnt lgkmcnt(0)
	v_mfma_f32_32x32x16_bf16 v[2:17], v[100:103], v[84:87], v[2:17]
	v_mfma_f32_32x32x16_bf16 v[50:65], v[92:95], v[76:79], v[50:65]
	v_mfma_f32_32x32x16_bf16 v[18:33], v[92:95], v[84:87], v[18:33]
	v_mfma_f32_32x32x16_bf16 v[34:49], v[100:103], v[76:79], v[34:49]
	s_barrier
	ds_read_b128 v[72:75], v71 offset:36864
	ds_read_b128 v[76:79], v71 offset:36896
	ds_read_b128 v[80:83], v71 offset:41472
	ds_read_b128 v[84:87], v71 offset:41504
	ds_read_b128 v[88:91], v128
	ds_read_b128 v[92:95], v128 offset:32
	ds_read_b128 v[96:99], v128 offset:4608
	ds_read_b128 v[100:103], v128 offset:4640
	s_waitcnt lgkmcnt(1)
	v_mfma_f32_32x32x16_bf16 v[2:17], v[96:99], v[80:83], v[2:17]
	v_mfma_f32_32x32x16_bf16 v[50:65], v[88:91], v[72:75], v[50:65]
	v_mfma_f32_32x32x16_bf16 v[18:33], v[88:91], v[80:83], v[18:33]
	v_mfma_f32_32x32x16_bf16 v[34:49], v[96:99], v[72:75], v[34:49]
	ds_read_b128 v[72:75], v71 offset:36928
	ds_read_b128 v[80:83], v71 offset:41536
	ds_read_b128 v[88:91], v128 offset:64
	ds_read_b128 v[96:99], v128 offset:4672
	s_waitcnt lgkmcnt(4)
	v_mfma_f32_32x32x16_bf16 v[2:17], v[100:103], v[84:87], v[2:17]
	v_mfma_f32_32x32x16_bf16 v[50:65], v[92:95], v[76:79], v[50:65]
	v_mfma_f32_32x32x16_bf16 v[18:33], v[92:95], v[84:87], v[18:33]
	v_mfma_f32_32x32x16_bf16 v[34:49], v[100:103], v[76:79], v[34:49]
	ds_read_b128 v[76:79], v71 offset:36960
	ds_read_b128 v[84:87], v71 offset:41568
	ds_read_b128 v[92:95], v128 offset:96
	ds_read_b128 v[100:103], v128 offset:4704
	s_waitcnt lgkmcnt(4)
	v_mfma_f32_32x32x16_bf16 v[2:17], v[96:99], v[80:83], v[2:17]
	v_mfma_f32_32x32x16_bf16 v[50:65], v[88:91], v[72:75], v[50:65]
	v_mfma_f32_32x32x16_bf16 v[18:33], v[88:91], v[80:83], v[18:33]
	v_mfma_f32_32x32x16_bf16 v[34:49], v[96:99], v[72:75], v[34:49]
	s_waitcnt lgkmcnt(0)
	v_mfma_f32_32x32x16_bf16 v[2:17], v[100:103], v[84:87], v[2:17]
	v_mfma_f32_32x32x16_bf16 v[50:65], v[92:95], v[76:79], v[50:65]
	v_mfma_f32_32x32x16_bf16 v[18:33], v[92:95], v[84:87], v[18:33]
	v_mfma_f32_32x32x16_bf16 v[34:49], v[100:103], v[76:79], v[34:49]
	v_readlane_b32 s40, v245, 0
	v_lshrrev_b32_e32 v71, 1, v69
	v_readlane_b32 s54, v245, 14
	v_readlane_b32 s55, v245, 15
	v_and_b32_e32 v66, 0x5f, v69
	v_lshlrev_b32_e32 v69, 1, v69
	v_and_b32_e32 v71, 16, v71
	s_lshl_b32 s0, s38, 2
	s_mov_b64 s[18:19], s[54:55]
	v_and_or_b32 v69, v69, s29, v71
	s_add_u32 s0, s18, s0
	v_mad_u32_u24 v66, v66, s30, v69
	s_addc_u32 s1, s19, 0
	v_mov_b32_e32 v69, v67
	v_lshl_add_u32 v208, v70, 4, s15
	v_ashrrev_i32_e32 v209, 31, v208
	v_lshlrev_b64 v[208:209], 11, v[208:209]
	v_lshlrev_b32_e32 v210, 3, v1
	v_or3_b32 v208, v208, s14, v210
	v_lshl_add_u64 v[208:209], s[96:97], 0, v[208:209]
	s_mov_b64 s[98:99], 0x73a1000
	v_lshl_add_u64 v[208:209], v[208:209], 0, s[98:99]
	s_mov_b64 s[98:99], 0x2000
	global_load_dwordx2 v[176:177], v[208:209], off offset:-4096
	global_load_dwordx2 v[178:179], v[208:209], off offset:-2048
	global_load_dwordx2 v[180:181], v[208:209], off
	global_load_dwordx2 v[182:183], v[208:209], off offset:2048
	v_lshl_add_u64 v[208:209], v[208:209], 0, s[98:99]
	global_load_dwordx2 v[184:185], v[208:209], off offset:-4096
	global_load_dwordx2 v[186:187], v[208:209], off offset:-2048
	global_load_dwordx2 v[188:189], v[208:209], off
	global_load_dwordx2 v[190:191], v[208:209], off offset:2048
	v_lshl_add_u64 v[208:209], v[208:209], 0, s[98:99]
	global_load_dwordx2 v[192:193], v[208:209], off offset:-4096
	global_load_dwordx2 v[194:195], v[208:209], off offset:-2048
	global_load_dwordx2 v[196:197], v[208:209], off
	global_load_dwordx2 v[198:199], v[208:209], off offset:2048
	v_lshl_add_u64 v[208:209], v[208:209], 0, s[98:99]
	global_load_dwordx2 v[200:201], v[208:209], off offset:-4096
	global_load_dwordx2 v[202:203], v[208:209], off offset:-2048
	global_load_dwordx2 v[204:205], v[208:209], off
	global_load_dwordx2 v[206:207], v[208:209], off offset:2048
	s_barrier
	ds_write_b128 v66, v[50:53]
	ds_write_b128 v66, v[54:57] offset:32
	ds_write_b128 v66, v[58:61] offset:64
	ds_write_b128 v66, v[62:65] offset:96
	ds_write_b128 v66, v[34:37] offset:128
	ds_write_b128 v66, v[38:41] offset:160
	ds_write_b128 v66, v[42:45] offset:192
	ds_write_b128 v66, v[46:49] offset:224
	ds_write_b128 v66, v[18:21] offset:33280
	ds_write_b128 v66, v[22:25] offset:33312
	ds_write_b128 v66, v[26:29] offset:33344
	ds_write_b128 v66, v[30:33] offset:33376
	ds_write_b128 v66, v[2:5] offset:33408
	ds_write_b128 v66, v[6:9] offset:33440
	ds_write_b128 v66, v[10:13] offset:33472
	ds_write_b128 v66, v[14:17] offset:33504
	v_lshl_add_u64 v[2:3], v[68:69], 2, s[0:1]
	s_waitcnt lgkmcnt(0)
	s_barrier
	global_load_dwordx4 v[2:5], v[2:3], off
	v_mul_lo_u32 v6, v70, s31
	v_lshl_add_u32 v8, v1, 4, v6
	v_lshl_add_u32 v6, v70, 4, s15
	v_ashrrev_i32_e32 v7, 31, v6
	v_lshlrev_b64 v[6:7], 11, v[6:7]
	v_lshlrev_b32_e32 v1, 3, v1
	v_or3_b32 v6, v6, s14, v1
	v_lshl_add_u64 v[6:7], s[96:97], 0, v[6:7]
	s_mov_b64 s[14:15], 0
	v_readlane_b32 s41, v245, 1
	v_readlane_b32 s42, v245, 2
	v_readlane_b32 s43, v245, 3
	v_readlane_b32 s44, v245, 4
	v_readlane_b32 s45, v245, 5
	v_readlane_b32 s46, v245, 6
	v_readlane_b32 s47, v245, 7
	v_readlane_b32 s48, v245, 8
	v_readlane_b32 s49, v245, 9
	v_readlane_b32 s50, v245, 10
	v_readlane_b32 s51, v245, 11
	v_readlane_b32 s52, v245, 12
	v_readlane_b32 s53, v245, 13

.LBB0_879:
	s_ashr_i32 s5, s4, 31
	s_lshr_b32 s5, s5, 30
	s_add_i32 s5, s4, s5
	s_and_b32 s5, s5, 0xfffffc
	s_sub_i32 s4, s4, s5
	s_lshl_b32 s6, s4, 8
	s_ashr_i32 s7, s6, 31
	v_mov_b32_e32 v48, v212
	s_lshl_b32 s4, s27, 7
	s_lshl_b64 s[28:29], s[6:7], 11
	s_add_u32 s28, s8, s28
	v_ashrrev_i32_e32 v24, 3, v48
	v_ashrrev_i32_e32 v25, 31, v24
	s_addc_u32 s29, s9, s29
	v_lshlrev_b64 v[0:1], 11, v[24:25]
	v_lshlrev_b32_e32 v4, 4, v48
	v_lshl_add_u64 v[2:3], s[28:29], 0, v[0:1]
	v_and_b32_e32 v64, 0x70, v4
	v_lshl_add_u64 v[70:71], v[2:3], 0, v[64:65]
	v_add_co_u32_e32 v74, vcc, s21, v70
	s_ashr_i32 s5, s4, 31
	s_nop 0
	v_addc_co_u32_e32 v75, vcc, 0, v71, vcc
	s_lshl_b64 s[30:31], s[4:5], 11
	v_add_co_u32_e32 v76, vcc, s22, v70
	s_add_u32 s30, s10, s30
	s_nop 0
	v_addc_co_u32_e32 v77, vcc, 0, v71, vcc
	s_addc_u32 s31, s11, s31
	v_add_co_u32_e32 v78, vcc, s23, v70
	v_lshl_add_u64 v[0:1], s[30:31], 0, v[0:1]
	s_nop 0
	v_addc_co_u32_e32 v79, vcc, 0, v71, vcc
	v_lshl_add_u64 v[72:73], v[0:1], 0, v[64:65]
	global_load_dwordx4 v[0:3], v[70:71], off
	global_load_dwordx4 v[4:7], v[74:75], off
	global_load_dwordx4 v[8:11], v[76:77], off
	global_load_dwordx4 v[12:15], v[78:79], off
	global_load_dwordx4 v[16:19], v[72:73], off
	v_add_co_u32_e32 v80, vcc, s21, v72
	v_mad_u64_u32 v[68:69], s[28:29], v24, s19, v[64:65]
	s_nop 0
	v_addc_co_u32_e32 v81, vcc, 0, v73, vcc
	global_load_dwordx4 v[20:23], v[80:81], off
	global_load_dwordx4 v[24:27], v[70:71], off offset:128
	global_load_dwordx4 v[28:31], v[74:75], off offset:128
	global_load_dwordx4 v[32:35], v[78:79], off offset:128
	global_load_dwordx4 v[84:87], v[74:75], off offset:256
	global_load_dwordx4 v[36:39], v[76:77], off offset:128
	global_load_dwordx4 v[88:91], v[76:77], off offset:256
	global_load_dwordx4 v[92:95], v[70:71], off offset:256
	global_load_dwordx4 v[40:43], v[72:73], off offset:128
	global_load_dwordx4 v[96:99], v[72:73], off offset:256
	global_load_dwordx4 v[100:103], v[78:79], off offset:256
	global_load_dwordx4 v[44:47], v[80:81], off offset:128
	global_load_dwordx4 v[104:107], v[80:81], off offset:256
	v_add_u32_e32 v83, 0x12000, v68
	s_waitcnt vmcnt(17)
	ds_write_b128 v68, v[0:3]
	s_waitcnt vmcnt(16)
	ds_write_b128 v68, v[4:7] offset:9216
	s_waitcnt vmcnt(15)
	ds_write_b128 v68, v[8:11] offset:18432
	s_waitcnt vmcnt(14)
	ds_write_b128 v68, v[12:15] offset:27648
	s_waitcnt vmcnt(13)
	ds_write_b128 v68, v[16:19] offset:36864
	s_waitcnt vmcnt(12)
	ds_write_b128 v68, v[20:23] offset:46080
	s_waitcnt lgkmcnt(0)
	s_barrier
	global_load_dwordx4 v[108:111], v[74:75], off offset:384
	global_load_dwordx4 v[112:115], v[76:77], off offset:384
	global_load_dwordx4 v[116:119], v[70:71], off offset:384
	global_load_dwordx4 v[120:123], v[72:73], off offset:384
	global_load_dwordx4 v[124:127], v[78:79], off offset:384
	global_load_dwordx4 v[128:131], v[80:81], off offset:384
	v_and_b32_e32 v0, 31, v48
	v_lshrrev_b32_e32 v1, 1, v48
	v_and_or_b32 v2, v1, s20, v0
	v_and_b32_e32 v0, 16, v1
	v_and_b32_e32 v1, 0x5f, v48
	v_mad_u32_u24 v69, v1, s19, v0
	v_add_u32_e32 v64, 0x12000, v69
	s_waitcnt vmcnt(17)
	ds_write_b128 v83, v[24:27]
	s_waitcnt vmcnt(16)
	ds_write_b128 v83, v[28:31] offset:9216
	s_waitcnt vmcnt(13)
	ds_write_b128 v83, v[36:39] offset:18432
	ds_write_b128 v83, v[32:35] offset:27648
	s_waitcnt vmcnt(10)
	ds_write_b128 v83, v[40:43] offset:36864
	s_waitcnt vmcnt(7)
	ds_write_b128 v83, v[44:47] offset:46080
	v_mad_u64_u32 v[66:67], s[28:29], v2, s19, v[0:1]
	ds_read_b128 v[0:3], v69 offset:36864
	ds_read_b128 v[132:135], v69 offset:36896
	ds_read_b128 v[4:7], v69 offset:41472
	ds_read_b128 v[136:139], v69 offset:41504
	ds_read_b128 v[8:11], v66
	ds_read_b128 v[140:143], v66 offset:32
	ds_read_b128 v[12:15], v66 offset:4608
	ds_read_b128 v[144:147], v66 offset:4640
	s_waitcnt lgkmcnt(3)
	v_mfma_f32_32x32x16_bf16 v[48:63], v[8:11], v[0:3], 0
	v_mfma_f32_32x32x16_bf16 v[16:31], v[8:11], v[4:7], 0
	s_waitcnt lgkmcnt(1)
	v_mfma_f32_32x32x16_bf16 v[32:47], v[12:15], v[0:3], 0
	v_mfma_f32_32x32x16_bf16 v[0:15], v[12:15], v[4:7], 0
	ds_read_b128 v[148:151], v69 offset:36928
	ds_read_b128 v[152:155], v69 offset:41536
	ds_read_b128 v[156:159], v66 offset:64
	ds_read_b128 v[160:163], v66 offset:4672
	v_mfma_f32_32x32x16_bf16 v[48:63], v[140:143], v[132:135], v[48:63]
	v_mfma_f32_32x32x16_bf16 v[16:31], v[140:143], v[136:139], v[16:31]
	s_waitcnt lgkmcnt(4)
	v_mfma_f32_32x32x16_bf16 v[32:47], v[144:147], v[132:135], v[32:47]
	v_mfma_f32_32x32x16_bf16 v[0:15], v[144:147], v[136:139], v[0:15]
	ds_read_b128 v[132:135], v69 offset:36960
	ds_read_b128 v[136:139], v69 offset:41568
	ds_read_b128 v[140:143], v66 offset:96
	ds_read_b128 v[144:147], v66 offset:4704
	s_waitcnt lgkmcnt(5)
	v_mfma_f32_32x32x16_bf16 v[48:63], v[156:159], v[148:151], v[48:63]
	v_mfma_f32_32x32x16_bf16 v[16:31], v[156:159], v[152:155], v[16:31]
	s_waitcnt lgkmcnt(4)
	v_mfma_f32_32x32x16_bf16 v[32:47], v[160:163], v[148:151], v[32:47]
	v_mfma_f32_32x32x16_bf16 v[0:15], v[160:163], v[152:155], v[0:15]
	s_waitcnt lgkmcnt(1)
	v_mfma_f32_32x32x16_bf16 v[48:63], v[140:143], v[132:135], v[48:63]
	v_mfma_f32_32x32x16_bf16 v[16:31], v[140:143], v[136:139], v[16:31]
	s_waitcnt lgkmcnt(0)
	v_mfma_f32_32x32x16_bf16 v[32:47], v[144:147], v[132:135], v[32:47]
	v_mfma_f32_32x32x16_bf16 v[0:15], v[144:147], v[136:139], v[0:15]
	s_barrier
	global_load_dwordx4 v[132:135], v[74:75], off offset:512
	global_load_dwordx4 v[136:139], v[76:77], off offset:512
	global_load_dwordx4 v[140:143], v[70:71], off offset:512
	global_load_dwordx4 v[144:147], v[72:73], off offset:512
	global_load_dwordx4 v[148:151], v[78:79], off offset:512
	global_load_dwordx4 v[152:155], v[80:81], off offset:512
	ds_write_b128 v68, v[92:95]
	ds_write_b128 v68, v[84:87] offset:9216
	ds_write_b128 v68, v[88:91] offset:18432
	ds_write_b128 v68, v[100:103] offset:27648
	ds_write_b128 v68, v[96:99] offset:36864
	s_waitcnt vmcnt(12)
	ds_write_b128 v68, v[104:107] offset:46080
	v_add_u32_e32 v67, 0x12000, v66
	ds_read_b128 v[84:87], v64 offset:36864
	ds_read_b128 v[88:91], v64 offset:36896
	ds_read_b128 v[92:95], v64 offset:41472
	ds_read_b128 v[96:99], v64 offset:41504
	ds_read_b128 v[100:103], v67
	ds_read_b128 v[104:107], v67 offset:32
	ds_read_b128 v[156:159], v67 offset:4608
	ds_read_b128 v[160:163], v67 offset:4640
	s_waitcnt lgkmcnt(3)
	v_mfma_f32_32x32x16_bf16 v[48:63], v[100:103], v[84:87], v[48:63]
	v_mfma_f32_32x32x16_bf16 v[16:31], v[100:103], v[92:95], v[16:31]
	s_waitcnt lgkmcnt(1)
	v_mfma_f32_32x32x16_bf16 v[32:47], v[156:159], v[84:87], v[32:47]
	v_mfma_f32_32x32x16_bf16 v[0:15], v[156:159], v[92:95], v[0:15]
	ds_read_b128 v[84:87], v64 offset:36928
	ds_read_b128 v[92:95], v64 offset:41536
	ds_read_b128 v[100:103], v67 offset:64
	ds_read_b128 v[156:159], v67 offset:4672
	v_mfma_f32_32x32x16_bf16 v[48:63], v[104:107], v[88:91], v[48:63]
	v_mfma_f32_32x32x16_bf16 v[16:31], v[104:107], v[96:99], v[16:31]
	s_waitcnt lgkmcnt(4)
	v_mfma_f32_32x32x16_bf16 v[32:47], v[160:163], v[88:91], v[32:47]
	v_mfma_f32_32x32x16_bf16 v[0:15], v[160:163], v[96:99], v[0:15]
	ds_read_b128 v[88:91], v64 offset:36960
	ds_read_b128 v[96:99], v64 offset:41568
	ds_read_b128 v[104:107], v67 offset:96
	ds_read_b128 v[160:163], v67 offset:4704
	s_waitcnt lgkmcnt(5)
	v_mfma_f32_32x32x16_bf16 v[48:63], v[100:103], v[84:87], v[48:63]
	v_mfma_f32_32x32x16_bf16 v[16:31], v[100:103], v[92:95], v[16:31]
	s_waitcnt lgkmcnt(4)
	v_mfma_f32_32x32x16_bf16 v[32:47], v[156:159], v[84:87], v[32:47]
	v_mfma_f32_32x32x16_bf16 v[0:15], v[156:159], v[92:95], v[0:15]
	s_waitcnt lgkmcnt(1)
	v_mfma_f32_32x32x16_bf16 v[48:63], v[104:107], v[88:91], v[48:63]
	v_mfma_f32_32x32x16_bf16 v[16:31], v[104:107], v[96:99], v[16:31]
	s_waitcnt lgkmcnt(0)
	v_mfma_f32_32x32x16_bf16 v[32:47], v[160:163], v[88:91], v[32:47]
	v_mfma_f32_32x32x16_bf16 v[0:15], v[160:163], v[96:99], v[0:15]
	s_barrier
	global_load_dwordx4 v[84:87], v[74:75], off offset:640
	global_load_dwordx4 v[88:91], v[76:77], off offset:640
	global_load_dwordx4 v[92:95], v[70:71], off offset:640
	global_load_dwordx4 v[96:99], v[72:73], off offset:640
	global_load_dwordx4 v[100:103], v[78:79], off offset:640
	global_load_dwordx4 v[104:107], v[80:81], off offset:640
	s_waitcnt vmcnt(15)
	ds_write_b128 v83, v[116:119]
	ds_write_b128 v83, v[108:111] offset:9216
	ds_write_b128 v83, v[112:115] offset:18432
	s_waitcnt vmcnt(13)
	ds_write_b128 v83, v[124:127] offset:27648
	ds_write_b128 v83, v[120:123] offset:36864
	s_waitcnt vmcnt(12)
	ds_write_b128 v83, v[128:131] offset:46080
	ds_read_b128 v[108:111], v69 offset:36864
	ds_read_b128 v[112:115], v69 offset:36896
	ds_read_b128 v[116:119], v69 offset:41472
	ds_read_b128 v[120:123], v69 offset:41504
	ds_read_b128 v[124:127], v66
	ds_read_b128 v[128:131], v66 offset:32
	ds_read_b128 v[156:159], v66 offset:4608
	ds_read_b128 v[160:163], v66 offset:4640
	s_waitcnt lgkmcnt(3)
	v_mfma_f32_32x32x16_bf16 v[48:63], v[124:127], v[108:111], v[48:63]
	v_mfma_f32_32x32x16_bf16 v[16:31], v[124:127], v[116:119], v[16:31]
	s_waitcnt lgkmcnt(1)
	v_mfma_f32_32x32x16_bf16 v[32:47], v[156:159], v[108:111], v[32:47]
	v_mfma_f32_32x32x16_bf16 v[0:15], v[156:159], v[116:119], v[0:15]
	ds_read_b128 v[108:111], v69 offset:36928
	ds_read_b128 v[116:119], v69 offset:41536
	ds_read_b128 v[124:127], v66 offset:64
	ds_read_b128 v[156:159], v66 offset:4672
	v_mfma_f32_32x32x16_bf16 v[48:63], v[128:131], v[112:115], v[48:63]
	v_mfma_f32_32x32x16_bf16 v[16:31], v[128:131], v[120:123], v[16:31]
	s_waitcnt lgkmcnt(4)
	v_mfma_f32_32x32x16_bf16 v[32:47], v[160:163], v[112:115], v[32:47]
	v_mfma_f32_32x32x16_bf16 v[0:15], v[160:163], v[120:123], v[0:15]
	ds_read_b128 v[112:115], v69 offset:36960
	ds_read_b128 v[120:123], v69 offset:41568
	ds_read_b128 v[128:131], v66 offset:96
	ds_read_b128 v[160:163], v66 offset:4704
	s_waitcnt lgkmcnt(5)
	v_mfma_f32_32x32x16_bf16 v[48:63], v[124:127], v[108:111], v[48:63]
	v_mfma_f32_32x32x16_bf16 v[16:31], v[124:127], v[116:119], v[16:31]
	s_waitcnt lgkmcnt(4)
	v_mfma_f32_32x32x16_bf16 v[32:47], v[156:159], v[108:111], v[32:47]
	v_mfma_f32_32x32x16_bf16 v[0:15], v[156:159], v[116:119], v[0:15]
	s_waitcnt lgkmcnt(1)
	v_mfma_f32_32x32x16_bf16 v[48:63], v[128:131], v[112:115], v[48:63]
	v_mfma_f32_32x32x16_bf16 v[16:31], v[128:131], v[120:123], v[16:31]
	s_waitcnt lgkmcnt(0)
	v_mfma_f32_32x32x16_bf16 v[32:47], v[160:163], v[112:115], v[32:47]
	v_mfma_f32_32x32x16_bf16 v[0:15], v[160:163], v[120:123], v[0:15]
	s_barrier
	global_load_dwordx4 v[108:111], v[74:75], off offset:768
	global_load_dwordx4 v[112:115], v[76:77], off offset:768
	global_load_dwordx4 v[116:119], v[70:71], off offset:768
	global_load_dwordx4 v[120:123], v[72:73], off offset:768
	global_load_dwordx4 v[124:127], v[78:79], off offset:768
	global_load_dwordx4 v[128:131], v[80:81], off offset:768
	s_waitcnt vmcnt(15)
	ds_write_b128 v68, v[140:143]
	ds_write_b128 v68, v[132:135] offset:9216
	ds_write_b128 v68, v[136:139] offset:18432
	s_waitcnt vmcnt(13)
	ds_write_b128 v68, v[148:151] offset:27648
	ds_write_b128 v68, v[144:147] offset:36864
	s_waitcnt vmcnt(12)
	ds_write_b128 v68, v[152:155] offset:46080
	ds_read_b128 v[132:135], v64 offset:36864
	ds_read_b128 v[136:139], v64 offset:36896
	ds_read_b128 v[140:143], v64 offset:41472
	ds_read_b128 v[144:147], v64 offset:41504
	ds_read_b128 v[148:151], v67
	ds_read_b128 v[152:155], v67 offset:32
	ds_read_b128 v[156:159], v67 offset:4608
	ds_read_b128 v[160:163], v67 offset:4640
	s_waitcnt lgkmcnt(3)
	v_mfma_f32_32x32x16_bf16 v[48:63], v[148:151], v[132:135], v[48:63]
	v_mfma_f32_32x32x16_bf16 v[16:31], v[148:151], v[140:143], v[16:31]
	s_waitcnt lgkmcnt(1)
	v_mfma_f32_32x32x16_bf16 v[32:47], v[156:159], v[132:135], v[32:47]
	v_mfma_f32_32x32x16_bf16 v[0:15], v[156:159], v[140:143], v[0:15]
	ds_read_b128 v[132:135], v64 offset:36928
	ds_read_b128 v[140:143], v64 offset:41536
	ds_read_b128 v[148:151], v67 offset:64
	ds_read_b128 v[156:159], v67 offset:4672
	v_mfma_f32_32x32x16_bf16 v[48:63], v[152:155], v[136:139], v[48:63]
	v_mfma_f32_32x32x16_bf16 v[16:31], v[152:155], v[144:147], v[16:31]
	s_waitcnt lgkmcnt(4)
	v_mfma_f32_32x32x16_bf16 v[32:47], v[160:163], v[136:139], v[32:47]
	v_mfma_f32_32x32x16_bf16 v[0:15], v[160:163], v[144:147], v[0:15]
	ds_read_b128 v[136:139], v64 offset:36960
	ds_read_b128 v[144:147], v64 offset:41568
	ds_read_b128 v[152:155], v67 offset:96
	ds_read_b128 v[160:163], v67 offset:4704
	s_waitcnt lgkmcnt(5)
	v_mfma_f32_32x32x16_bf16 v[48:63], v[148:151], v[132:135], v[48:63]
	v_mfma_f32_32x32x16_bf16 v[16:31], v[148:151], v[140:143], v[16:31]
	s_waitcnt lgkmcnt(4)
	v_mfma_f32_32x32x16_bf16 v[32:47], v[156:159], v[132:135], v[32:47]
	v_mfma_f32_32x32x16_bf16 v[0:15], v[156:159], v[140:143], v[0:15]
	s_waitcnt lgkmcnt(1)
	v_mfma_f32_32x32x16_bf16 v[48:63], v[152:155], v[136:139], v[48:63]
	v_mfma_f32_32x32x16_bf16 v[16:31], v[152:155], v[144:147], v[16:31]
	s_waitcnt lgkmcnt(0)
	v_mfma_f32_32x32x16_bf16 v[32:47], v[160:163], v[136:139], v[32:47]
	v_mfma_f32_32x32x16_bf16 v[0:15], v[160:163], v[144:147], v[0:15]
	s_barrier
	global_load_dwordx4 v[132:135], v[74:75], off offset:896
	global_load_dwordx4 v[136:139], v[76:77], off offset:896
	global_load_dwordx4 v[140:143], v[70:71], off offset:896
	global_load_dwordx4 v[144:147], v[72:73], off offset:896
	global_load_dwordx4 v[148:151], v[78:79], off offset:896
	global_load_dwordx4 v[152:155], v[80:81], off offset:896
	s_waitcnt vmcnt(15)
	ds_write_b128 v83, v[92:95]
	ds_write_b128 v83, v[84:87] offset:9216
	ds_write_b128 v83, v[88:91] offset:18432
	s_waitcnt vmcnt(13)
	ds_write_b128 v83, v[100:103] offset:27648
	ds_write_b128 v83, v[96:99] offset:36864
	s_waitcnt vmcnt(12)
	ds_write_b128 v83, v[104:107] offset:46080
	ds_read_b128 v[84:87], v69 offset:36864
	ds_read_b128 v[88:91], v69 offset:36896
	ds_read_b128 v[92:95], v69 offset:41472
	ds_read_b128 v[96:99], v69 offset:41504
	ds_read_b128 v[100:103], v66
	ds_read_b128 v[104:107], v66 offset:32
	ds_read_b128 v[156:159], v66 offset:4608
	ds_read_b128 v[160:163], v66 offset:4640
	s_waitcnt lgkmcnt(3)
	v_mfma_f32_32x32x16_bf16 v[48:63], v[100:103], v[84:87], v[48:63]
	v_mfma_f32_32x32x16_bf16 v[16:31], v[100:103], v[92:95], v[16:31]
	s_waitcnt lgkmcnt(1)
	v_mfma_f32_32x32x16_bf16 v[32:47], v[156:159], v[84:87], v[32:47]
	v_mfma_f32_32x32x16_bf16 v[0:15], v[156:159], v[92:95], v[0:15]
	ds_read_b128 v[84:87], v69 offset:36928
	ds_read_b128 v[92:95], v69 offset:41536
	ds_read_b128 v[100:103], v66 offset:64
	ds_read_b128 v[156:159], v66 offset:4672
	v_mfma_f32_32x32x16_bf16 v[48:63], v[104:107], v[88:91], v[48:63]
	v_mfma_f32_32x32x16_bf16 v[16:31], v[104:107], v[96:99], v[16:31]
	s_waitcnt lgkmcnt(4)
	v_mfma_f32_32x32x16_bf16 v[32:47], v[160:163], v[88:91], v[32:47]
	v_mfma_f32_32x32x16_bf16 v[0:15], v[160:163], v[96:99], v[0:15]
	ds_read_b128 v[88:91], v69 offset:36960
	ds_read_b128 v[96:99], v69 offset:41568
	ds_read_b128 v[104:107], v66 offset:96
	ds_read_b128 v[160:163], v66 offset:4704
	s_waitcnt lgkmcnt(5)
	v_mfma_f32_32x32x16_bf16 v[48:63], v[100:103], v[84:87], v[48:63]
	v_mfma_f32_32x32x16_bf16 v[16:31], v[100:103], v[92:95], v[16:31]
	s_waitcnt lgkmcnt(4)
	v_mfma_f32_32x32x16_bf16 v[32:47], v[156:159], v[84:87], v[32:47]
	v_mfma_f32_32x32x16_bf16 v[0:15], v[156:159], v[92:95], v[0:15]
	s_waitcnt lgkmcnt(1)
	v_mfma_f32_32x32x16_bf16 v[48:63], v[104:107], v[88:91], v[48:63]
	v_mfma_f32_32x32x16_bf16 v[16:31], v[104:107], v[96:99], v[16:31]
	s_waitcnt lgkmcnt(0)
	v_mfma_f32_32x32x16_bf16 v[32:47], v[160:163], v[88:91], v[32:47]
	v_mfma_f32_32x32x16_bf16 v[0:15], v[160:163], v[96:99], v[0:15]
	s_barrier
	global_load_dwordx4 v[84:87], v[74:75], off offset:1024
	global_load_dwordx4 v[88:91], v[76:77], off offset:1024
	global_load_dwordx4 v[92:95], v[70:71], off offset:1024
	global_load_dwordx4 v[96:99], v[72:73], off offset:1024
	global_load_dwordx4 v[100:103], v[78:79], off offset:1024
	global_load_dwordx4 v[104:107], v[80:81], off offset:1024
	s_waitcnt vmcnt(15)
	ds_write_b128 v68, v[116:119]
	ds_write_b128 v68, v[108:111] offset:9216
	ds_write_b128 v68, v[112:115] offset:18432
	s_waitcnt vmcnt(13)
	ds_write_b128 v68, v[124:127] offset:27648
	ds_write_b128 v68, v[120:123] offset:36864
	s_waitcnt vmcnt(12)
	ds_write_b128 v68, v[128:131] offset:46080
	ds_read_b128 v[108:111], v64 offset:36864
	ds_read_b128 v[112:115], v64 offset:36896
	ds_read_b128 v[116:119], v64 offset:41472
	ds_read_b128 v[120:123], v64 offset:41504
	ds_read_b128 v[124:127], v67
	ds_read_b128 v[128:131], v67 offset:32
	ds_read_b128 v[156:159], v67 offset:4608
	ds_read_b128 v[160:163], v67 offset:4640
	s_waitcnt lgkmcnt(3)
	v_mfma_f32_32x32x16_bf16 v[48:63], v[124:127], v[108:111], v[48:63]
	v_mfma_f32_32x32x16_bf16 v[16:31], v[124:127], v[116:119], v[16:31]
	s_waitcnt lgkmcnt(1)
	v_mfma_f32_32x32x16_bf16 v[32:47], v[156:159], v[108:111], v[32:47]
	v_mfma_f32_32x32x16_bf16 v[0:15], v[156:159], v[116:119], v[0:15]
	ds_read_b128 v[108:111], v64 offset:36928
	ds_read_b128 v[116:119], v64 offset:41536
	ds_read_b128 v[124:127], v67 offset:64
	ds_read_b128 v[156:159], v67 offset:4672
	v_mfma_f32_32x32x16_bf16 v[48:63], v[128:131], v[112:115], v[48:63]
	v_mfma_f32_32x32x16_bf16 v[16:31], v[128:131], v[120:123], v[16:31]
	s_waitcnt lgkmcnt(4)
	v_mfma_f32_32x32x16_bf16 v[32:47], v[160:163], v[112:115], v[32:47]
	v_mfma_f32_32x32x16_bf16 v[0:15], v[160:163], v[120:123], v[0:15]
	ds_read_b128 v[112:115], v64 offset:36960
	ds_read_b128 v[120:123], v64 offset:41568
	ds_read_b128 v[128:131], v67 offset:96
	ds_read_b128 v[160:163], v67 offset:4704
	s_waitcnt lgkmcnt(5)
	v_mfma_f32_32x32x16_bf16 v[48:63], v[124:127], v[108:111], v[48:63]
	v_mfma_f32_32x32x16_bf16 v[16:31], v[124:127], v[116:119], v[16:31]
	s_waitcnt lgkmcnt(4)
	v_mfma_f32_32x32x16_bf16 v[32:47], v[156:159], v[108:111], v[32:47]
	v_mfma_f32_32x32x16_bf16 v[0:15], v[156:159], v[116:119], v[0:15]
	s_waitcnt lgkmcnt(1)
	v_mfma_f32_32x32x16_bf16 v[48:63], v[128:131], v[112:115], v[48:63]
	v_mfma_f32_32x32x16_bf16 v[16:31], v[128:131], v[120:123], v[16:31]
	s_waitcnt lgkmcnt(0)
	v_mfma_f32_32x32x16_bf16 v[32:47], v[160:163], v[112:115], v[32:47]
	v_mfma_f32_32x32x16_bf16 v[0:15], v[160:163], v[120:123], v[0:15]
	s_barrier
	global_load_dwordx4 v[108:111], v[74:75], off offset:1152
	global_load_dwordx4 v[112:115], v[76:77], off offset:1152
	global_load_dwordx4 v[116:119], v[70:71], off offset:1152
	global_load_dwordx4 v[120:123], v[72:73], off offset:1152
	global_load_dwordx4 v[124:127], v[78:79], off offset:1152
	global_load_dwordx4 v[128:131], v[80:81], off offset:1152
	s_waitcnt vmcnt(15)
	ds_write_b128 v83, v[140:143]
	ds_write_b128 v83, v[132:135] offset:9216
	ds_write_b128 v83, v[136:139] offset:18432
	s_waitcnt vmcnt(13)
	ds_write_b128 v83, v[148:151] offset:27648
	ds_write_b128 v83, v[144:147] offset:36864
	s_waitcnt vmcnt(12)
	ds_write_b128 v83, v[152:155] offset:46080
	ds_read_b128 v[132:135], v69 offset:36864
	ds_read_b128 v[136:139], v69 offset:36896
	ds_read_b128 v[140:143], v69 offset:41472
	ds_read_b128 v[144:147], v69 offset:41504
	ds_read_b128 v[148:151], v66
	ds_read_b128 v[152:155], v66 offset:32
	ds_read_b128 v[156:159], v66 offset:4608
	ds_read_b128 v[160:163], v66 offset:4640
	s_waitcnt lgkmcnt(3)
	v_mfma_f32_32x32x16_bf16 v[48:63], v[148:151], v[132:135], v[48:63]
	v_mfma_f32_32x32x16_bf16 v[16:31], v[148:151], v[140:143], v[16:31]
	s_waitcnt lgkmcnt(1)
	v_mfma_f32_32x32x16_bf16 v[32:47], v[156:159], v[132:135], v[32:47]
	v_mfma_f32_32x32x16_bf16 v[0:15], v[156:159], v[140:143], v[0:15]
	ds_read_b128 v[132:135], v69 offset:36928
	ds_read_b128 v[140:143], v69 offset:41536
	ds_read_b128 v[148:151], v66 offset:64
	ds_read_b128 v[156:159], v66 offset:4672
	v_mfma_f32_32x32x16_bf16 v[48:63], v[152:155], v[136:139], v[48:63]
	v_mfma_f32_32x32x16_bf16 v[16:31], v[152:155], v[144:147], v[16:31]
	s_waitcnt lgkmcnt(4)
	v_mfma_f32_32x32x16_bf16 v[32:47], v[160:163], v[136:139], v[32:47]
	v_mfma_f32_32x32x16_bf16 v[0:15], v[160:163], v[144:147], v[0:15]
	ds_read_b128 v[136:139], v69 offset:36960
	ds_read_b128 v[144:147], v69 offset:41568
	ds_read_b128 v[152:155], v66 offset:96
	ds_read_b128 v[160:163], v66 offset:4704
	s_waitcnt lgkmcnt(5)
	v_mfma_f32_32x32x16_bf16 v[48:63], v[148:151], v[132:135], v[48:63]
	v_mfma_f32_32x32x16_bf16 v[16:31], v[148:151], v[140:143], v[16:31]
	s_waitcnt lgkmcnt(4)
	v_mfma_f32_32x32x16_bf16 v[32:47], v[156:159], v[132:135], v[32:47]
	v_mfma_f32_32x32x16_bf16 v[0:15], v[156:159], v[140:143], v[0:15]
	s_waitcnt lgkmcnt(1)
	v_mfma_f32_32x32x16_bf16 v[48:63], v[152:155], v[136:139], v[48:63]
	v_mfma_f32_32x32x16_bf16 v[16:31], v[152:155], v[144:147], v[16:31]
	s_waitcnt lgkmcnt(0)
	v_mfma_f32_32x32x16_bf16 v[32:47], v[160:163], v[136:139], v[32:47]
	v_mfma_f32_32x32x16_bf16 v[0:15], v[160:163], v[144:147], v[0:15]
	s_barrier
	global_load_dwordx4 v[132:135], v[74:75], off offset:1280
	global_load_dwordx4 v[136:139], v[76:77], off offset:1280
	global_load_dwordx4 v[140:143], v[70:71], off offset:1280
	global_load_dwordx4 v[144:147], v[72:73], off offset:1280
	global_load_dwordx4 v[148:151], v[78:79], off offset:1280
	global_load_dwordx4 v[152:155], v[80:81], off offset:1280
	s_waitcnt vmcnt(15)
	ds_write_b128 v68, v[92:95]
	ds_write_b128 v68, v[84:87] offset:9216
	ds_write_b128 v68, v[88:91] offset:18432
	s_waitcnt vmcnt(13)
	ds_write_b128 v68, v[100:103] offset:27648
	ds_write_b128 v68, v[96:99] offset:36864
	s_waitcnt vmcnt(12)
	ds_write_b128 v68, v[104:107] offset:46080
	ds_read_b128 v[84:87], v64 offset:36864
	ds_read_b128 v[88:91], v64 offset:36896
	ds_read_b128 v[92:95], v64 offset:41472
	ds_read_b128 v[96:99], v64 offset:41504
	ds_read_b128 v[100:103], v67
	ds_read_b128 v[104:107], v67 offset:32
	ds_read_b128 v[156:159], v67 offset:4608
	ds_read_b128 v[160:163], v67 offset:4640
	s_waitcnt lgkmcnt(3)
	v_mfma_f32_32x32x16_bf16 v[48:63], v[100:103], v[84:87], v[48:63]
	v_mfma_f32_32x32x16_bf16 v[16:31], v[100:103], v[92:95], v[16:31]
	s_waitcnt lgkmcnt(1)
	v_mfma_f32_32x32x16_bf16 v[32:47], v[156:159], v[84:87], v[32:47]
	v_mfma_f32_32x32x16_bf16 v[0:15], v[156:159], v[92:95], v[0:15]
	ds_read_b128 v[84:87], v64 offset:36928
	ds_read_b128 v[92:95], v64 offset:41536
	ds_read_b128 v[100:103], v67 offset:64
	ds_read_b128 v[156:159], v67 offset:4672
	v_mfma_f32_32x32x16_bf16 v[48:63], v[104:107], v[88:91], v[48:63]
	v_mfma_f32_32x32x16_bf16 v[16:31], v[104:107], v[96:99], v[16:31]
	s_waitcnt lgkmcnt(4)
	v_mfma_f32_32x32x16_bf16 v[32:47], v[160:163], v[88:91], v[32:47]
	v_mfma_f32_32x32x16_bf16 v[0:15], v[160:163], v[96:99], v[0:15]
	ds_read_b128 v[88:91], v64 offset:36960
	ds_read_b128 v[96:99], v64 offset:41568
	ds_read_b128 v[104:107], v67 offset:96
	ds_read_b128 v[160:163], v67 offset:4704
	s_waitcnt lgkmcnt(5)
	v_mfma_f32_32x32x16_bf16 v[48:63], v[100:103], v[84:87], v[48:63]
	v_mfma_f32_32x32x16_bf16 v[16:31], v[100:103], v[92:95], v[16:31]
	s_waitcnt lgkmcnt(4)
	v_mfma_f32_32x32x16_bf16 v[32:47], v[156:159], v[84:87], v[32:47]
	v_mfma_f32_32x32x16_bf16 v[0:15], v[156:159], v[92:95], v[0:15]
	s_waitcnt lgkmcnt(1)
	v_mfma_f32_32x32x16_bf16 v[48:63], v[104:107], v[88:91], v[48:63]
	v_mfma_f32_32x32x16_bf16 v[16:31], v[104:107], v[96:99], v[16:31]
	s_waitcnt lgkmcnt(0)
	v_mfma_f32_32x32x16_bf16 v[32:47], v[160:163], v[88:91], v[32:47]
	v_mfma_f32_32x32x16_bf16 v[0:15], v[160:163], v[96:99], v[0:15]
	s_barrier
	global_load_dwordx4 v[84:87], v[74:75], off offset:1408
	global_load_dwordx4 v[88:91], v[76:77], off offset:1408
	global_load_dwordx4 v[92:95], v[70:71], off offset:1408
	global_load_dwordx4 v[96:99], v[72:73], off offset:1408
	global_load_dwordx4 v[100:103], v[78:79], off offset:1408
	global_load_dwordx4 v[104:107], v[80:81], off offset:1408
	s_waitcnt vmcnt(15)
	ds_write_b128 v83, v[116:119]
	ds_write_b128 v83, v[108:111] offset:9216
	ds_write_b128 v83, v[112:115] offset:18432
	s_waitcnt vmcnt(13)
	ds_write_b128 v83, v[124:127] offset:27648
	ds_write_b128 v83, v[120:123] offset:36864
	s_waitcnt vmcnt(12)
	ds_write_b128 v83, v[128:131] offset:46080
	ds_read_b128 v[108:111], v69 offset:36864
	ds_read_b128 v[112:115], v69 offset:36896
	ds_read_b128 v[116:119], v69 offset:41472
	ds_read_b128 v[120:123], v69 offset:41504
	ds_read_b128 v[124:127], v66
	ds_read_b128 v[128:131], v66 offset:32
	ds_read_b128 v[156:159], v66 offset:4608
	ds_read_b128 v[160:163], v66 offset:4640
	s_waitcnt lgkmcnt(3)
	v_mfma_f32_32x32x16_bf16 v[48:63], v[124:127], v[108:111], v[48:63]
	v_mfma_f32_32x32x16_bf16 v[16:31], v[124:127], v[116:119], v[16:31]
	s_waitcnt lgkmcnt(1)
	v_mfma_f32_32x32x16_bf16 v[32:47], v[156:159], v[108:111], v[32:47]
	v_mfma_f32_32x32x16_bf16 v[0:15], v[156:159], v[116:119], v[0:15]
	ds_read_b128 v[108:111], v69 offset:36928
	ds_read_b128 v[116:119], v69 offset:41536
	ds_read_b128 v[124:127], v66 offset:64
	ds_read_b128 v[156:159], v66 offset:4672
	v_mfma_f32_32x32x16_bf16 v[48:63], v[128:131], v[112:115], v[48:63]
	v_mfma_f32_32x32x16_bf16 v[16:31], v[128:131], v[120:123], v[16:31]
	s_waitcnt lgkmcnt(4)
	v_mfma_f32_32x32x16_bf16 v[32:47], v[160:163], v[112:115], v[32:47]
	v_mfma_f32_32x32x16_bf16 v[0:15], v[160:163], v[120:123], v[0:15]
	ds_read_b128 v[112:115], v69 offset:36960
	ds_read_b128 v[120:123], v69 offset:41568
	ds_read_b128 v[128:131], v66 offset:96
	ds_read_b128 v[160:163], v66 offset:4704
	s_waitcnt lgkmcnt(5)
	v_mfma_f32_32x32x16_bf16 v[48:63], v[124:127], v[108:111], v[48:63]
	v_mfma_f32_32x32x16_bf16 v[16:31], v[124:127], v[116:119], v[16:31]
	s_waitcnt lgkmcnt(4)
	v_mfma_f32_32x32x16_bf16 v[32:47], v[156:159], v[108:111], v[32:47]
	v_mfma_f32_32x32x16_bf16 v[0:15], v[156:159], v[116:119], v[0:15]
	s_waitcnt lgkmcnt(1)
	v_mfma_f32_32x32x16_bf16 v[48:63], v[128:131], v[112:115], v[48:63]
	v_mfma_f32_32x32x16_bf16 v[16:31], v[128:131], v[120:123], v[16:31]
	s_waitcnt lgkmcnt(0)
	v_mfma_f32_32x32x16_bf16 v[32:47], v[160:163], v[112:115], v[32:47]
	v_mfma_f32_32x32x16_bf16 v[0:15], v[160:163], v[120:123], v[0:15]
	s_barrier
	global_load_dwordx4 v[108:111], v[74:75], off offset:1536
	global_load_dwordx4 v[112:115], v[76:77], off offset:1536
	global_load_dwordx4 v[116:119], v[70:71], off offset:1536
	global_load_dwordx4 v[120:123], v[72:73], off offset:1536
	global_load_dwordx4 v[124:127], v[78:79], off offset:1536
	global_load_dwordx4 v[128:131], v[80:81], off offset:1536
	s_waitcnt vmcnt(15)
	ds_write_b128 v68, v[140:143]
	ds_write_b128 v68, v[132:135] offset:9216
	ds_write_b128 v68, v[136:139] offset:18432
	s_waitcnt vmcnt(13)
	ds_write_b128 v68, v[148:151] offset:27648
	ds_write_b128 v68, v[144:147] offset:36864
	s_waitcnt vmcnt(12)
	ds_write_b128 v68, v[152:155] offset:46080
	ds_read_b128 v[132:135], v64 offset:36864
	ds_read_b128 v[136:139], v64 offset:36896
	ds_read_b128 v[140:143], v64 offset:41472
	ds_read_b128 v[144:147], v64 offset:41504
	ds_read_b128 v[148:151], v67
	ds_read_b128 v[152:155], v67 offset:32
	ds_read_b128 v[156:159], v67 offset:4608
	ds_read_b128 v[160:163], v67 offset:4640
	s_waitcnt lgkmcnt(3)
	v_mfma_f32_32x32x16_bf16 v[48:63], v[148:151], v[132:135], v[48:63]
	v_mfma_f32_32x32x16_bf16 v[16:31], v[148:151], v[140:143], v[16:31]
	s_waitcnt lgkmcnt(1)
	v_mfma_f32_32x32x16_bf16 v[32:47], v[156:159], v[132:135], v[32:47]
	v_mfma_f32_32x32x16_bf16 v[0:15], v[156:159], v[140:143], v[0:15]
	ds_read_b128 v[132:135], v64 offset:36928
	ds_read_b128 v[140:143], v64 offset:41536
	ds_read_b128 v[148:151], v67 offset:64
	ds_read_b128 v[156:159], v67 offset:4672
	v_mfma_f32_32x32x16_bf16 v[48:63], v[152:155], v[136:139], v[48:63]
	v_mfma_f32_32x32x16_bf16 v[16:31], v[152:155], v[144:147], v[16:31]
	s_waitcnt lgkmcnt(4)
	v_mfma_f32_32x32x16_bf16 v[32:47], v[160:163], v[136:139], v[32:47]
	v_mfma_f32_32x32x16_bf16 v[0:15], v[160:163], v[144:147], v[0:15]
	ds_read_b128 v[136:139], v64 offset:36960
	ds_read_b128 v[144:147], v64 offset:41568
	ds_read_b128 v[152:155], v67 offset:96
	ds_read_b128 v[160:163], v67 offset:4704
	s_waitcnt lgkmcnt(5)
	v_mfma_f32_32x32x16_bf16 v[48:63], v[148:151], v[132:135], v[48:63]
	v_mfma_f32_32x32x16_bf16 v[16:31], v[148:151], v[140:143], v[16:31]
	s_waitcnt lgkmcnt(4)
	v_mfma_f32_32x32x16_bf16 v[32:47], v[156:159], v[132:135], v[32:47]
	v_mfma_f32_32x32x16_bf16 v[0:15], v[156:159], v[140:143], v[0:15]
	s_waitcnt lgkmcnt(1)
	v_mfma_f32_32x32x16_bf16 v[48:63], v[152:155], v[136:139], v[48:63]
	v_mfma_f32_32x32x16_bf16 v[16:31], v[152:155], v[144:147], v[16:31]
	s_waitcnt lgkmcnt(0)
	v_mfma_f32_32x32x16_bf16 v[32:47], v[160:163], v[136:139], v[32:47]
	v_mfma_f32_32x32x16_bf16 v[0:15], v[160:163], v[144:147], v[0:15]
	s_barrier
	global_load_dwordx4 v[132:135], v[74:75], off offset:1664
	global_load_dwordx4 v[136:139], v[76:77], off offset:1664
	global_load_dwordx4 v[140:143], v[70:71], off offset:1664
	global_load_dwordx4 v[144:147], v[72:73], off offset:1664
	global_load_dwordx4 v[148:151], v[78:79], off offset:1664
	global_load_dwordx4 v[152:155], v[80:81], off offset:1664
	s_waitcnt vmcnt(15)
	ds_write_b128 v83, v[92:95]
	ds_write_b128 v83, v[84:87] offset:9216
	ds_write_b128 v83, v[88:91] offset:18432
	s_waitcnt vmcnt(13)
	ds_write_b128 v83, v[100:103] offset:27648
	ds_write_b128 v83, v[96:99] offset:36864
	s_waitcnt vmcnt(12)
	ds_write_b128 v83, v[104:107] offset:46080
	ds_read_b128 v[84:87], v69 offset:36864
	ds_read_b128 v[88:91], v69 offset:36896
	ds_read_b128 v[92:95], v69 offset:41472
	ds_read_b128 v[96:99], v69 offset:41504
	ds_read_b128 v[100:103], v66
	ds_read_b128 v[104:107], v66 offset:32
	ds_read_b128 v[156:159], v66 offset:4608
	ds_read_b128 v[160:163], v66 offset:4640
	s_waitcnt lgkmcnt(3)
	v_mfma_f32_32x32x16_bf16 v[48:63], v[100:103], v[84:87], v[48:63]
	v_mfma_f32_32x32x16_bf16 v[16:31], v[100:103], v[92:95], v[16:31]
	s_waitcnt lgkmcnt(1)
	v_mfma_f32_32x32x16_bf16 v[32:47], v[156:159], v[84:87], v[32:47]
	v_mfma_f32_32x32x16_bf16 v[0:15], v[156:159], v[92:95], v[0:15]
	ds_read_b128 v[84:87], v69 offset:36928
	ds_read_b128 v[92:95], v69 offset:41536
	ds_read_b128 v[100:103], v66 offset:64
	ds_read_b128 v[156:159], v66 offset:4672
	v_mfma_f32_32x32x16_bf16 v[48:63], v[104:107], v[88:91], v[48:63]
	v_mfma_f32_32x32x16_bf16 v[16:31], v[104:107], v[96:99], v[16:31]
	s_waitcnt lgkmcnt(4)
	v_mfma_f32_32x32x16_bf16 v[32:47], v[160:163], v[88:91], v[32:47]
	v_mfma_f32_32x32x16_bf16 v[0:15], v[160:163], v[96:99], v[0:15]
	ds_read_b128 v[88:91], v69 offset:36960
	ds_read_b128 v[96:99], v69 offset:41568
	ds_read_b128 v[104:107], v66 offset:96
	ds_read_b128 v[160:163], v66 offset:4704
	s_waitcnt lgkmcnt(5)
	v_mfma_f32_32x32x16_bf16 v[48:63], v[100:103], v[84:87], v[48:63]
	v_mfma_f32_32x32x16_bf16 v[16:31], v[100:103], v[92:95], v[16:31]
	s_waitcnt lgkmcnt(4)
	v_mfma_f32_32x32x16_bf16 v[32:47], v[156:159], v[84:87], v[32:47]
	v_mfma_f32_32x32x16_bf16 v[0:15], v[156:159], v[92:95], v[0:15]
	s_waitcnt lgkmcnt(1)
	v_mfma_f32_32x32x16_bf16 v[48:63], v[104:107], v[88:91], v[48:63]
	v_mfma_f32_32x32x16_bf16 v[16:31], v[104:107], v[96:99], v[16:31]
	s_waitcnt lgkmcnt(0)
	v_mfma_f32_32x32x16_bf16 v[32:47], v[160:163], v[88:91], v[32:47]
	v_mfma_f32_32x32x16_bf16 v[0:15], v[160:163], v[96:99], v[0:15]
	s_barrier
	global_load_dwordx4 v[84:87], v[74:75], off offset:1792
	global_load_dwordx4 v[88:91], v[76:77], off offset:1792
	global_load_dwordx4 v[92:95], v[70:71], off offset:1792
	global_load_dwordx4 v[96:99], v[72:73], off offset:1792
	global_load_dwordx4 v[100:103], v[78:79], off offset:1792
	global_load_dwordx4 v[104:107], v[80:81], off offset:1792
	s_waitcnt vmcnt(15)
	ds_write_b128 v68, v[116:119]
	ds_write_b128 v68, v[108:111] offset:9216
	ds_write_b128 v68, v[112:115] offset:18432
	s_waitcnt vmcnt(13)
	ds_write_b128 v68, v[124:127] offset:27648
	ds_write_b128 v68, v[120:123] offset:36864
	s_waitcnt vmcnt(12)
	ds_write_b128 v68, v[128:131] offset:46080
	ds_read_b128 v[108:111], v64 offset:36864
	ds_read_b128 v[112:115], v64 offset:36896
	ds_read_b128 v[116:119], v64 offset:41472
	ds_read_b128 v[120:123], v64 offset:41504
	ds_read_b128 v[124:127], v67
	ds_read_b128 v[128:131], v67 offset:32
	ds_read_b128 v[156:159], v67 offset:4608
	ds_read_b128 v[160:163], v67 offset:4640
	s_waitcnt lgkmcnt(3)
	v_mfma_f32_32x32x16_bf16 v[48:63], v[124:127], v[108:111], v[48:63]
	v_mfma_f32_32x32x16_bf16 v[16:31], v[124:127], v[116:119], v[16:31]
	s_waitcnt lgkmcnt(1)
	v_mfma_f32_32x32x16_bf16 v[32:47], v[156:159], v[108:111], v[32:47]
	v_mfma_f32_32x32x16_bf16 v[0:15], v[156:159], v[116:119], v[0:15]
	ds_read_b128 v[108:111], v64 offset:36928
	ds_read_b128 v[116:119], v64 offset:41536
	ds_read_b128 v[124:127], v67 offset:64
	ds_read_b128 v[156:159], v67 offset:4672
	v_mfma_f32_32x32x16_bf16 v[48:63], v[128:131], v[112:115], v[48:63]
	v_mfma_f32_32x32x16_bf16 v[16:31], v[128:131], v[120:123], v[16:31]
	s_waitcnt lgkmcnt(4)
	v_mfma_f32_32x32x16_bf16 v[32:47], v[160:163], v[112:115], v[32:47]
	v_mfma_f32_32x32x16_bf16 v[0:15], v[160:163], v[120:123], v[0:15]
	ds_read_b128 v[112:115], v64 offset:36960
	ds_read_b128 v[120:123], v64 offset:41568
	ds_read_b128 v[128:131], v67 offset:96
	ds_read_b128 v[160:163], v67 offset:4704
	s_waitcnt lgkmcnt(5)
	v_mfma_f32_32x32x16_bf16 v[48:63], v[124:127], v[108:111], v[48:63]
	v_mfma_f32_32x32x16_bf16 v[16:31], v[124:127], v[116:119], v[16:31]
	s_waitcnt lgkmcnt(4)
	v_mfma_f32_32x32x16_bf16 v[32:47], v[156:159], v[108:111], v[32:47]
	v_mfma_f32_32x32x16_bf16 v[0:15], v[156:159], v[116:119], v[0:15]
	s_waitcnt lgkmcnt(1)
	v_mfma_f32_32x32x16_bf16 v[48:63], v[128:131], v[112:115], v[48:63]
	v_mfma_f32_32x32x16_bf16 v[16:31], v[128:131], v[120:123], v[16:31]
	s_waitcnt lgkmcnt(0)
	v_mfma_f32_32x32x16_bf16 v[32:47], v[160:163], v[112:115], v[32:47]
	v_mfma_f32_32x32x16_bf16 v[0:15], v[160:163], v[120:123], v[0:15]
	s_barrier
	global_load_dwordx4 v[108:111], v[74:75], off offset:1920
	s_nop 0
	global_load_dwordx4 v[74:77], v[76:77], off offset:1920
	s_nop 0
	global_load_dwordx4 v[112:115], v[70:71], off offset:1920
	s_nop 0
	global_load_dwordx4 v[70:73], v[72:73], off offset:1920
	s_nop 0
	global_load_dwordx4 v[116:119], v[78:79], off offset:1920
	s_nop 0
	global_load_dwordx4 v[78:81], v[80:81], off offset:1920
	s_waitcnt vmcnt(15)
	ds_write_b128 v83, v[140:143]
	ds_write_b128 v83, v[132:135] offset:9216
	ds_write_b128 v83, v[136:139] offset:18432
	s_waitcnt vmcnt(13)
	ds_write_b128 v83, v[148:151] offset:27648
	ds_write_b128 v83, v[144:147] offset:36864
	s_waitcnt vmcnt(12)
	ds_write_b128 v83, v[152:155] offset:46080
	ds_read_b128 v[120:123], v69 offset:36864
	ds_read_b128 v[124:127], v69 offset:36896
	ds_read_b128 v[128:131], v69 offset:41472
	ds_read_b128 v[132:135], v69 offset:41504
	ds_read_b128 v[136:139], v66
	ds_read_b128 v[140:143], v66 offset:32
	ds_read_b128 v[144:147], v66 offset:4608
	ds_read_b128 v[148:151], v66 offset:4640
	s_waitcnt lgkmcnt(3)
	v_mfma_f32_32x32x16_bf16 v[48:63], v[136:139], v[120:123], v[48:63]
	v_mfma_f32_32x32x16_bf16 v[16:31], v[136:139], v[128:131], v[16:31]
	s_waitcnt lgkmcnt(1)
	v_mfma_f32_32x32x16_bf16 v[32:47], v[144:147], v[120:123], v[32:47]
	v_mfma_f32_32x32x16_bf16 v[0:15], v[144:147], v[128:131], v[0:15]
	ds_read_b128 v[120:123], v69 offset:36928
	ds_read_b128 v[128:131], v69 offset:41536
	ds_read_b128 v[136:139], v66 offset:64
	ds_read_b128 v[144:147], v66 offset:4672
	v_mfma_f32_32x32x16_bf16 v[48:63], v[140:143], v[124:127], v[48:63]
	v_mfma_f32_32x32x16_bf16 v[16:31], v[140:143], v[132:135], v[16:31]
	s_waitcnt lgkmcnt(4)
	v_mfma_f32_32x32x16_bf16 v[32:47], v[148:151], v[124:127], v[32:47]
	v_mfma_f32_32x32x16_bf16 v[0:15], v[148:151], v[132:135], v[0:15]
	ds_read_b128 v[124:127], v69 offset:36960
	ds_read_b128 v[132:135], v69 offset:41568
	ds_read_b128 v[140:143], v66 offset:96
	ds_read_b128 v[148:151], v66 offset:4704
	s_waitcnt lgkmcnt(5)
	v_mfma_f32_32x32x16_bf16 v[48:63], v[136:139], v[120:123], v[48:63]
	v_mfma_f32_32x32x16_bf16 v[16:31], v[136:139], v[128:131], v[16:31]
	s_waitcnt lgkmcnt(4)
	v_mfma_f32_32x32x16_bf16 v[32:47], v[144:147], v[120:123], v[32:47]
	v_mfma_f32_32x32x16_bf16 v[0:15], v[144:147], v[128:131], v[0:15]
	s_waitcnt lgkmcnt(1)
	v_mfma_f32_32x32x16_bf16 v[48:63], v[140:143], v[124:127], v[48:63]
	v_mfma_f32_32x32x16_bf16 v[16:31], v[140:143], v[132:135], v[16:31]
	s_waitcnt lgkmcnt(0)
	v_mfma_f32_32x32x16_bf16 v[32:47], v[148:151], v[124:127], v[32:47]
	v_mfma_f32_32x32x16_bf16 v[0:15], v[148:151], v[132:135], v[0:15]
	s_barrier
	s_waitcnt vmcnt(9)
	ds_write_b128 v68, v[92:95]
	ds_write_b128 v68, v[84:87] offset:9216
	ds_write_b128 v68, v[88:91] offset:18432
	s_waitcnt vmcnt(7)
	ds_write_b128 v68, v[100:103] offset:27648
	ds_write_b128 v68, v[96:99] offset:36864
	s_waitcnt vmcnt(6)
	ds_write_b128 v68, v[104:107] offset:46080
	ds_read_b128 v[84:87], v64 offset:36864
	ds_read_b128 v[88:91], v64 offset:36896
	ds_read_b128 v[92:95], v64 offset:41472
	ds_read_b128 v[96:99], v64 offset:41504
	ds_read_b128 v[100:103], v67
	ds_read_b128 v[104:107], v67 offset:32
	ds_read_b128 v[120:123], v67 offset:4608
	ds_read_b128 v[124:127], v67 offset:4640
	s_waitcnt lgkmcnt(3)
	v_mfma_f32_32x32x16_bf16 v[48:63], v[100:103], v[84:87], v[48:63]
	v_mfma_f32_32x32x16_bf16 v[16:31], v[100:103], v[92:95], v[16:31]
	s_waitcnt lgkmcnt(1)
	v_mfma_f32_32x32x16_bf16 v[32:47], v[120:123], v[84:87], v[32:47]
	v_mfma_f32_32x32x16_bf16 v[0:15], v[120:123], v[92:95], v[0:15]
	ds_read_b128 v[84:87], v64 offset:36928
	ds_read_b128 v[92:95], v64 offset:41536
	ds_read_b128 v[100:103], v67 offset:64
	ds_read_b128 v[120:123], v67 offset:4672
	v_mfma_f32_32x32x16_bf16 v[48:63], v[104:107], v[88:91], v[48:63]
	v_mfma_f32_32x32x16_bf16 v[16:31], v[104:107], v[96:99], v[16:31]
	s_waitcnt lgkmcnt(4)
	v_mfma_f32_32x32x16_bf16 v[32:47], v[124:127], v[88:91], v[32:47]
	v_mfma_f32_32x32x16_bf16 v[0:15], v[124:127], v[96:99], v[0:15]
	ds_read_b128 v[88:91], v64 offset:36960
	ds_read_b128 v[96:99], v64 offset:41568
	ds_read_b128 v[104:107], v67 offset:96
	ds_read_b128 v[124:127], v67 offset:4704
	s_waitcnt lgkmcnt(5)
	v_mfma_f32_32x32x16_bf16 v[48:63], v[100:103], v[84:87], v[48:63]
	v_mfma_f32_32x32x16_bf16 v[16:31], v[100:103], v[92:95], v[16:31]
	s_waitcnt lgkmcnt(4)
	v_mfma_f32_32x32x16_bf16 v[32:47], v[120:123], v[84:87], v[32:47]
	v_mfma_f32_32x32x16_bf16 v[0:15], v[120:123], v[92:95], v[0:15]
	s_waitcnt lgkmcnt(1)
	v_mfma_f32_32x32x16_bf16 v[48:63], v[104:107], v[88:91], v[48:63]
	v_mfma_f32_32x32x16_bf16 v[16:31], v[104:107], v[96:99], v[16:31]
	s_waitcnt lgkmcnt(0)
	v_mfma_f32_32x32x16_bf16 v[32:47], v[124:127], v[88:91], v[32:47]
	v_mfma_f32_32x32x16_bf16 v[0:15], v[124:127], v[96:99], v[0:15]
	s_barrier
	s_waitcnt vmcnt(3)
	ds_write_b128 v83, v[112:115]
	ds_write_b128 v83, v[108:111] offset:9216
	ds_write_b128 v83, v[74:77] offset:18432
	s_waitcnt vmcnt(1)
	ds_write_b128 v83, v[116:119] offset:27648
	ds_write_b128 v83, v[70:73] offset:36864
	s_waitcnt vmcnt(0)
	ds_write_b128 v83, v[78:81] offset:46080
	ds_read_b128 v[70:73], v69 offset:36864
	ds_read_b128 v[74:77], v69 offset:36896
	ds_read_b128 v[78:81], v69 offset:41472
	ds_read_b128 v[84:87], v69 offset:41504
	ds_read_b128 v[88:91], v66
	ds_read_b128 v[92:95], v66 offset:32
	ds_read_b128 v[96:99], v66 offset:4608
	ds_read_b128 v[100:103], v66 offset:4640
	s_waitcnt lgkmcnt(3)
	v_mfma_f32_32x32x16_bf16 v[48:63], v[88:91], v[70:73], v[48:63]
	v_mfma_f32_32x32x16_bf16 v[16:31], v[88:91], v[78:81], v[16:31]
	s_waitcnt lgkmcnt(1)
	v_mfma_f32_32x32x16_bf16 v[32:47], v[96:99], v[70:73], v[32:47]
	v_mfma_f32_32x32x16_bf16 v[0:15], v[96:99], v[78:81], v[0:15]
	ds_read_b128 v[70:73], v69 offset:36928
	ds_read_b128 v[78:81], v69 offset:41536
	ds_read_b128 v[88:91], v66 offset:64
	ds_read_b128 v[96:99], v66 offset:4672
	v_mfma_f32_32x32x16_bf16 v[48:63], v[92:95], v[74:77], v[48:63]
	v_mfma_f32_32x32x16_bf16 v[16:31], v[92:95], v[84:87], v[16:31]
	s_waitcnt lgkmcnt(4)
	v_mfma_f32_32x32x16_bf16 v[32:47], v[100:103], v[74:77], v[32:47]
	v_mfma_f32_32x32x16_bf16 v[0:15], v[100:103], v[84:87], v[0:15]
	ds_read_b128 v[74:77], v69 offset:36960
	ds_read_b128 v[84:87], v69 offset:41568
	ds_read_b128 v[92:95], v66 offset:96
	ds_read_b128 v[100:103], v66 offset:4704
	s_waitcnt lgkmcnt(5)
	v_mfma_f32_32x32x16_bf16 v[48:63], v[88:91], v[70:73], v[48:63]
	v_mfma_f32_32x32x16_bf16 v[16:31], v[88:91], v[78:81], v[16:31]
	s_waitcnt lgkmcnt(4)
	v_mfma_f32_32x32x16_bf16 v[32:47], v[96:99], v[70:73], v[32:47]
	v_mfma_f32_32x32x16_bf16 v[0:15], v[96:99], v[78:81], v[0:15]
	s_waitcnt lgkmcnt(1)
	v_mfma_f32_32x32x16_bf16 v[48:63], v[92:95], v[74:77], v[48:63]
	v_mfma_f32_32x32x16_bf16 v[16:31], v[92:95], v[84:87], v[16:31]
	s_waitcnt lgkmcnt(0)
	v_mfma_f32_32x32x16_bf16 v[32:47], v[100:103], v[74:77], v[32:47]
	v_mfma_f32_32x32x16_bf16 v[0:15], v[100:103], v[84:87], v[0:15]
	s_barrier
	ds_read_b128 v[68:71], v64 offset:36864
	ds_read_b128 v[72:75], v64 offset:36896
	ds_read_b128 v[76:79], v64 offset:41472
	ds_read_b128 v[84:87], v64 offset:41504
	ds_read_b128 v[88:91], v67
	ds_read_b128 v[92:95], v67 offset:32
	ds_read_b128 v[96:99], v67 offset:4608
	ds_read_b128 v[100:103], v67 offset:4640
	s_waitcnt lgkmcnt(3)
	v_mfma_f32_32x32x16_bf16 v[48:63], v[88:91], v[68:71], v[48:63]
	v_mfma_f32_32x32x16_bf16 v[16:31], v[88:91], v[76:79], v[16:31]
	s_waitcnt lgkmcnt(1)
	v_mfma_f32_32x32x16_bf16 v[32:47], v[96:99], v[68:71], v[32:47]
	v_mfma_f32_32x32x16_bf16 v[0:15], v[96:99], v[76:79], v[0:15]
	ds_read_b128 v[68:71], v64 offset:36928
	ds_read_b128 v[76:79], v64 offset:41536
	ds_read_b128 v[88:91], v67 offset:64
	ds_read_b128 v[96:99], v67 offset:4672
	v_mfma_f32_32x32x16_bf16 v[48:63], v[92:95], v[72:75], v[48:63]
	v_mfma_f32_32x32x16_bf16 v[16:31], v[92:95], v[84:87], v[16:31]
	s_waitcnt lgkmcnt(4)
	v_mfma_f32_32x32x16_bf16 v[32:47], v[100:103], v[72:75], v[32:47]
	v_mfma_f32_32x32x16_bf16 v[0:15], v[100:103], v[84:87], v[0:15]
	ds_read_b128 v[72:75], v64 offset:36960
	ds_read_b128 v[84:87], v64 offset:41568
	ds_read_b128 v[92:95], v67 offset:96
	ds_read_b128 v[100:103], v67 offset:4704
	s_waitcnt lgkmcnt(5)
	v_mfma_f32_32x32x16_bf16 v[48:63], v[88:91], v[68:71], v[48:63]
	v_mfma_f32_32x32x16_bf16 v[16:31], v[88:91], v[76:79], v[16:31]
	s_waitcnt lgkmcnt(4)
	v_mfma_f32_32x32x16_bf16 v[32:47], v[96:99], v[68:71], v[32:47]
	v_mfma_f32_32x32x16_bf16 v[0:15], v[96:99], v[76:79], v[0:15]
	s_waitcnt lgkmcnt(1)
	v_mfma_f32_32x32x16_bf16 v[48:63], v[92:95], v[72:75], v[48:63]
	v_mfma_f32_32x32x16_bf16 v[16:31], v[92:95], v[84:87], v[16:31]
	s_waitcnt lgkmcnt(0)
	v_mfma_f32_32x32x16_bf16 v[32:47], v[100:103], v[72:75], v[32:47]
	v_mfma_f32_32x32x16_bf16 v[0:15], v[100:103], v[84:87], v[0:15]
	s_add_i32 s5, s4, 0xffffe000
	s_lshr_b32 s5, s5, 12
	s_add_i32 s5, s5, 6
	s_cmp_gt_i32 s27, 63
	s_cselect_b32 s5, s5, 5
	v_lshrrev_b32_e32 v66, 1, v82
	s_mul_hi_u32 s27, s5, 0x3000
	s_mulk_i32 s5, 0x3000
	v_lshlrev_b32_e32 v67, 1, v82
	v_and_b32_e32 v66, 16, v66
	s_add_u32 s5, s96, s5
	v_and_b32_e32 v64, 0x5f, v82
	v_and_or_b32 v66, v67, s24, v66
	s_addc_u32 s27, s97, s27
	s_lshl_b64 s[6:7], s[6:7], 2
	v_mad_u32_u24 v64, v64, s25, v66
	s_add_u32 s28, s5, s6
	v_ashrrev_i32_e32 v78, 2, v82
	s_barrier
	ds_write_b128 v64, v[48:51]
	ds_write_b128 v64, v[52:55] offset:32
	ds_write_b128 v64, v[56:59] offset:64
	ds_write_b128 v64, v[60:63] offset:96
	ds_write_b128 v64, v[32:35] offset:128
	ds_write_b128 v64, v[36:39] offset:160
	ds_write_b128 v64, v[40:43] offset:192
	ds_write_b128 v64, v[44:47] offset:224
	ds_write_b128 v64, v[16:19] offset:33280
	ds_write_b128 v64, v[20:23] offset:33312
	ds_write_b128 v64, v[24:27] offset:33344
	ds_write_b128 v64, v[28:31] offset:33376
	ds_write_b128 v64, v[0:3] offset:33408
	ds_write_b128 v64, v[4:7] offset:33440
	ds_write_b128 v64, v[8:11] offset:33472
	ds_write_b128 v64, v[12:15] offset:33504
	s_addc_u32 s29, s27, s7
	v_lshlrev_b32_e32 v0, 4, v82
	v_and_b32_e32 v82, -16, v78
	s_add_u32 s6, s74, s6
	v_add_u32_e32 v16, s4, v82
	v_and_b32_e32 v64, 0x3f0, v0
	s_addc_u32 s7, s75, s7
	v_ashrrev_i32_e32 v17, 31, v16
	v_lshl_add_u64 v[14:15], s[6:7], 0, v[64:65]
	v_lshlrev_b64 v[2:3], 12, v[16:17]
	v_lshl_add_u64 v[4:5], v[14:15], 0, v[2:3]
	v_or_b32_e32 v2, 1, v16
	v_ashrrev_i32_e32 v3, 31, v2
	v_lshlrev_b64 v[2:3], 12, v[2:3]
	v_lshl_add_u64 v[6:7], v[14:15], 0, v[2:3]
	v_or_b32_e32 v2, 2, v16
	v_ashrrev_i32_e32 v3, 31, v2
	v_lshlrev_b64 v[2:3], 12, v[2:3]
	v_lshl_add_u64 v[8:9], v[14:15], 0, v[2:3]
	v_or_b32_e32 v2, 3, v16
	v_ashrrev_i32_e32 v3, 31, v2
	v_lshlrev_b64 v[2:3], 12, v[2:3]
	v_lshl_add_u64 v[0:1], s[28:29], 0, v[64:65]
	v_lshl_add_u64 v[10:11], v[14:15], 0, v[2:3]
	v_or_b32_e32 v2, 4, v16
	v_ashrrev_i32_e32 v3, 31, v2
	v_add_co_u32_e32 v0, vcc, s26, v0
	v_lshlrev_b64 v[2:3], 12, v[2:3]
	s_nop 0
	v_addc_co_u32_e32 v1, vcc, 0, v1, vcc
	s_waitcnt lgkmcnt(0)
	s_barrier
	v_lshl_add_u64 v[12:13], v[14:15], 0, v[2:3]
	global_load_dwordx4 v[0:3], v[0:1], off
	s_nop 0
	global_load_dwordx4 v[20:23], v[4:5], off
	v_or_b32_e32 v28, 6, v16
	global_load_dwordx4 v[24:27], v[6:7], off
	v_ashrrev_i32_e32 v29, 31, v28
	v_lshlrev_b64 v[32:33], 12, v[28:29]
	global_load_dwordx4 v[28:31], v[8:9], off
	v_or_b32_e32 v36, 7, v16
	v_ashrrev_i32_e32 v37, 31, v36
	v_lshl_add_u64 v[90:91], v[14:15], 0, v[32:33]
	global_load_dwordx4 v[32:35], v[10:11], off
	v_lshlrev_b64 v[36:37], 12, v[36:37]
	v_lshl_add_u64 v[92:93], v[14:15], 0, v[36:37]
	global_load_dwordx4 v[36:39], v[12:13], off
	v_or_b32_e32 v18, 5, v16
	v_ashrrev_i32_e32 v19, 31, v18
	v_or_b32_e32 v40, 8, v16
	v_lshlrev_b64 v[18:19], 12, v[18:19]
	v_ashrrev_i32_e32 v41, 31, v40
	v_lshl_add_u64 v[18:19], v[14:15], 0, v[18:19]
	v_lshlrev_b64 v[40:41], 12, v[40:41]
	v_or_b32_e32 v44, 9, v16
	v_lshl_add_u64 v[94:95], v[14:15], 0, v[40:41]
	global_load_dwordx4 v[40:43], v[18:19], off
	v_ashrrev_i32_e32 v45, 31, v44
	v_lshlrev_b64 v[48:49], 12, v[44:45]
	global_load_dwordx4 v[44:47], v[90:91], off
	v_or_b32_e32 v52, 10, v16
	v_ashrrev_i32_e32 v53, 31, v52
	v_lshl_add_u64 v[96:97], v[14:15], 0, v[48:49]
	global_load_dwordx4 v[48:51], v[92:93], off
	v_lshlrev_b64 v[52:53], 12, v[52:53]
	v_lshl_add_u64 v[98:99], v[14:15], 0, v[52:53]
	global_load_dwordx4 v[52:55], v[94:95], off
	v_or_b32_e32 v56, 11, v16
	v_ashrrev_i32_e32 v57, 31, v56
	v_lshlrev_b64 v[56:57], 12, v[56:57]
	v_or_b32_e32 v60, 12, v16
	v_lshl_add_u64 v[100:101], v[14:15], 0, v[56:57]
	global_load_dwordx4 v[56:59], v[96:97], off
	v_ashrrev_i32_e32 v61, 31, v60
	v_lshlrev_b64 v[66:67], 12, v[60:61]
	global_load_dwordx4 v[60:63], v[98:99], off
	v_or_b32_e32 v70, 13, v16
	v_ashrrev_i32_e32 v71, 31, v70
	v_lshl_add_u64 v[102:103], v[14:15], 0, v[66:67]
	global_load_dwordx4 v[66:69], v[100:101], off
	v_lshlrev_b64 v[70:71], 12, v[70:71]
	v_or_b32_e32 v16, 14, v16
	v_lshl_add_u64 v[104:105], v[14:15], 0, v[70:71]
	global_load_dwordx4 v[70:73], v[102:103], off
	v_ashrrev_i32_e32 v17, 31, v16
	v_lshlrev_b64 v[16:17], 12, v[16:17]
	v_or_b32_e32 v86, 15, v78
	v_lshl_add_u64 v[106:107], v[14:15], 0, v[16:17]
	v_add_u32_e32 v16, s4, v86
	v_ashrrev_i32_e32 v17, 31, v16
	v_lshlrev_b64 v[16:17], 12, v[16:17]
	global_load_dwordx4 v[74:77], v[104:105], off
	global_load_dwordx4 v[78:81], v[106:107], off
	v_lshl_add_u64 v[108:109], v[14:15], 0, v[16:17]
	global_load_dwordx4 v[14:17], v[108:109], off
	v_mad_u64_u32 v[110:111], s[4:5], v82, s25, v[64:65]
	ds_read_b128 v[82:85], v110
	v_mad_u64_u32 v[112:113], s[4:5], v86, s25, v[64:65]
	ds_read_b128 v[86:89], v110 offset:1040
	s_add_i32 s2, s2, s62
	s_add_i32 s16, s16, s15
	s_cmpk_lt_i32 s2, 0x300
	s_waitcnt vmcnt(15) lgkmcnt(1)
	v_pk_fma_f32 v[20:21], v[0:1], v[82:83], v[20:21]
	v_pk_fma_f32 v[22:23], v[2:3], v[84:85], v[22:23]
	global_store_dwordx4 v[4:5], v[20:23], off
	ds_read_b128 v[20:23], v110 offset:2080
	s_waitcnt vmcnt(15) lgkmcnt(1)
	v_pk_fma_f32 v[24:25], v[0:1], v[86:87], v[24:25]
	v_pk_fma_f32 v[26:27], v[2:3], v[88:89], v[26:27]
	global_store_dwordx4 v[6:7], v[24:27], off
	ds_read_b128 v[4:7], v110 offset:3120
	s_waitcnt vmcnt(15) lgkmcnt(1)
	v_pk_fma_f32 v[20:21], v[0:1], v[20:21], v[28:29]
	v_pk_fma_f32 v[22:23], v[2:3], v[22:23], v[30:31]
	global_store_dwordx4 v[8:9], v[20:23], off
	ds_read_b128 v[20:23], v110 offset:4160
	s_waitcnt vmcnt(15) lgkmcnt(1)
	v_pk_fma_f32 v[4:5], v[0:1], v[4:5], v[32:33]
	v_pk_fma_f32 v[6:7], v[2:3], v[6:7], v[34:35]
	global_store_dwordx4 v[10:11], v[4:7], off
	ds_read_b128 v[4:7], v110 offset:5200
	s_waitcnt vmcnt(15) lgkmcnt(1)
	v_pk_fma_f32 v[8:9], v[0:1], v[20:21], v[36:37]
	v_pk_fma_f32 v[10:11], v[2:3], v[22:23], v[38:39]
	global_store_dwordx4 v[12:13], v[8:11], off
	ds_read_b128 v[8:11], v110 offset:6240
	s_waitcnt vmcnt(15) lgkmcnt(1)
	v_pk_fma_f32 v[4:5], v[0:1], v[4:5], v[40:41]
	v_pk_fma_f32 v[6:7], v[2:3], v[6:7], v[42:43]
	global_store_dwordx4 v[18:19], v[4:7], off
	ds_read_b128 v[4:7], v110 offset:7280
	s_waitcnt vmcnt(15) lgkmcnt(1)
	v_pk_fma_f32 v[8:9], v[0:1], v[8:9], v[44:45]
	v_pk_fma_f32 v[10:11], v[2:3], v[10:11], v[46:47]
	global_store_dwordx4 v[90:91], v[8:11], off
	ds_read_b128 v[8:11], v110 offset:8320
	s_waitcnt vmcnt(15) lgkmcnt(1)
	v_pk_fma_f32 v[4:5], v[0:1], v[4:5], v[48:49]
	v_pk_fma_f32 v[6:7], v[2:3], v[6:7], v[50:51]
	global_store_dwordx4 v[92:93], v[4:7], off
	ds_read_b128 v[4:7], v110 offset:9360
	s_waitcnt vmcnt(15) lgkmcnt(1)
	v_pk_fma_f32 v[8:9], v[0:1], v[8:9], v[52:53]
	v_pk_fma_f32 v[10:11], v[2:3], v[10:11], v[54:55]
	global_store_dwordx4 v[94:95], v[8:11], off
	ds_read_b128 v[8:11], v110 offset:10400
	s_waitcnt vmcnt(15) lgkmcnt(1)
	v_pk_fma_f32 v[4:5], v[0:1], v[4:5], v[56:57]
	v_pk_fma_f32 v[6:7], v[2:3], v[6:7], v[58:59]
	global_store_dwordx4 v[96:97], v[4:7], off
	ds_read_b128 v[4:7], v110 offset:11440
	s_waitcnt vmcnt(15) lgkmcnt(1)
	v_pk_fma_f32 v[8:9], v[0:1], v[8:9], v[60:61]
	v_pk_fma_f32 v[10:11], v[2:3], v[10:11], v[62:63]
	global_store_dwordx4 v[98:99], v[8:11], off
	ds_read_b128 v[8:11], v110 offset:12480
	s_waitcnt vmcnt(15) lgkmcnt(1)
	v_pk_fma_f32 v[4:5], v[0:1], v[4:5], v[66:67]
	v_pk_fma_f32 v[6:7], v[2:3], v[6:7], v[68:69]
	global_store_dwordx4 v[100:101], v[4:7], off
	ds_read_b128 v[4:7], v110 offset:13520
	s_waitcnt vmcnt(15) lgkmcnt(1)
	v_pk_fma_f32 v[8:9], v[0:1], v[8:9], v[70:71]
	v_pk_fma_f32 v[10:11], v[2:3], v[10:11], v[72:73]
	global_store_dwordx4 v[102:103], v[8:11], off
	ds_read_b128 v[8:11], v110 offset:14560
	ds_read_b128 v[18:21], v112
	s_waitcnt vmcnt(15) lgkmcnt(2)
	v_pk_fma_f32 v[4:5], v[0:1], v[4:5], v[74:75]
	v_pk_fma_f32 v[6:7], v[2:3], v[6:7], v[76:77]
	global_store_dwordx4 v[104:105], v[4:7], off
	s_waitcnt vmcnt(15) lgkmcnt(1)
	s_nop 0
	v_pk_fma_f32 v[4:5], v[0:1], v[8:9], v[78:79]
	v_pk_fma_f32 v[6:7], v[2:3], v[10:11], v[80:81]
	s_waitcnt vmcnt(14) lgkmcnt(0)
	v_pk_fma_f32 v[0:1], v[0:1], v[18:19], v[14:15]
	v_pk_fma_f32 v[2:3], v[2:3], v[20:21], v[16:17]
	global_store_dwordx4 v[106:107], v[4:7], off
	global_store_dwordx4 v[108:109], v[0:3], off
	s_cbranch_scc0 .LBB0_884
